# collapse IEEE div sequences to v_rcp+mul in conv/GLU/retout/s5out/P0 epilogues; pk_mul+2add -> 2 fma in conv
# speedup vs baseline: 1.0152x; 1.0152x over previous
; __device__ __forceinline__ float sigmoidf_(float x) { return 1.f / (1.f + __expf(-x)); }
; __device__ __forceinline__ void phase_p0(PRef p, unsigned char* shm) {
;     ...
;     for (int it = blockIdx.x; it < N_MODIT + N_HIDIT; it += gridDim.x) {
;         if (it < N_MODIT) {
;             const int layer = it / 384, col0 = (it % 384) * 32;
; #pragma unroll 10
;             for (int i = tid; i < 5 * 2048; i += 512) { const int r = i >> 11, k = i & 2047; const float v = r < 4 ? p.in[1][r * 2048 + k] : p.in[3][k]; sl[i] = v * sigmoidf_(v); }
.LBB0_55:
	s_movk_i32 s10, 0xb800
	v_and_b32_e32 v3, 0x7ff, v2
	v_add_u32_e32 v21, 0x200, v2
	s_movk_i32 s12, 0x13ff
	s_mov_b32 s11, -1
	v_add_u32_e32 v26, 0x400, v2
	v_add_u32_e32 v27, 0x600, v2
	s_movk_i32 s13, 0x1800
	v_cmp_lt_i32_e32 vcc, s12, v2
	v_lshlrev_b32_e32 v86, 2, v3
	v_and_b32_e32 v3, 0x7ff, v21
	v_add_u32_e32 v28, 0xa00, v2
	v_add_u32_e32 v29, 0xc00, v2
	s_movk_i32 s16, 0x1e00
	v_lshl_add_u64 v[24:25], v[4:5], 0, s[10:11]
	v_and_b32_e32 v21, 0x7ff, v26
	v_and_b32_e32 v32, 0x7ff, v27
	s_or_b64 s[72:73], vcc, s[72:73]
	v_lshl_add_u64 v[26:27], s[44:45], 0, v[86:87]
	v_cmp_gt_i32_e32 vcc, s13, v2
	v_cmp_gt_i32_e64 s[12:13], s84, v2
	v_lshlrev_b32_e32 v86, 2, v3
	v_lshl_add_u64 v[6:7], v[4:5], 0, s[52:53]
	v_lshl_add_u64 v[14:15], v[4:5], 0, s[58:59]
	v_lshl_add_u64 v[22:23], v[4:5], 0, s[66:67]
	s_movk_i32 s18, 0x1c00
	v_and_b32_e32 v33, 0x7ff, v28
	v_and_b32_e32 v34, 0x7ff, v29
	v_cmp_gt_i32_e64 s[10:11], s14, v2
	v_lshl_add_u64 v[28:29], s[44:45], 0, v[86:87]
	v_cmp_gt_i32_e64 s[16:17], s16, v2
	v_cndmask_b32_e64 v25, v27, v25, s[12:13]
	v_cndmask_b32_e64 v24, v26, v24, s[12:13]
	v_lshlrev_b32_e32 v86, 2, v21
	v_lshl_add_u64 v[8:9], v[4:5], 0, s[54:55]
	s_movk_i32 s19, 0x1a00
	v_cndmask_b32_e32 v15, v27, v15, vcc
	v_cndmask_b32_e32 v14, v26, v14, vcc
	v_cndmask_b32_e64 v23, v27, v23, s[10:11]
	v_cndmask_b32_e64 v22, v26, v22, s[10:11]
	v_lshl_add_u64 v[26:27], s[44:45], 0, v[86:87]
	v_cmp_gt_i32_e32 vcc, s18, v2
	global_load_dword v3, v[24:25], off
	v_cndmask_b32_e64 v7, v29, v7, s[16:17]
	v_cndmask_b32_e64 v6, v28, v6, s[16:17]
	v_lshlrev_b32_e32 v86, 2, v32
	v_lshl_add_u64 v[10:11], v[4:5], 0, s[56:57]
	global_load_dword v21, v[14:15], off
	s_nop 0
	global_load_dword v22, v[22:23], off
	v_lshl_add_u64 v[14:15], s[44:45], 0, v[86:87]
	v_cmp_gt_i32_e64 s[10:11], s19, v2
	global_load_dword v23, v[6:7], off
	v_cndmask_b32_e32 v7, v27, v9, vcc
	v_cndmask_b32_e32 v6, v26, v8, vcc
	v_add_u32_e32 v30, 0xe00, v2
	s_movk_i32 s20, 0x1600
	v_lshlrev_b32_e32 v86, 2, v33
	global_load_dword v24, v[6:7], off
	v_cndmask_b32_e64 v7, v15, v11, s[10:11]
	v_cndmask_b32_e64 v6, v14, v10, s[10:11]
	v_lshl_add_u64 v[12:13], v[4:5], 0, s[60:61]
	s_movk_i32 s21, 0x1400
	v_and_b32_e32 v30, 0x7ff, v30
	v_lshl_add_u64 v[8:9], s[44:45], 0, v[86:87]
	v_cmp_gt_i32_e32 vcc, s20, v2
	v_lshlrev_b32_e32 v86, 2, v34
	global_load_dword v14, v[6:7], off
	v_lshl_add_u64 v[16:17], v[4:5], 0, s[62:63]
	v_add_u32_e32 v31, 0x1200, v2
	s_movk_i32 s22, 0x1200
	v_lshl_add_u64 v[10:11], s[44:45], 0, v[86:87]
	v_cmp_gt_i32_e64 s[10:11], s21, v2
	v_cndmask_b32_e32 v7, v9, v13, vcc
	v_cndmask_b32_e32 v6, v8, v12, vcc
	v_lshlrev_b32_e32 v86, 2, v30
	v_lshl_add_u64 v[18:19], v[4:5], 0, s[64:65]
	v_and_b32_e32 v31, 0x7ff, v31
	v_lshl_add_u64 v[8:9], s[44:45], 0, v[86:87]
	v_cmp_gt_i32_e32 vcc, s22, v2
	global_load_dword v12, v[6:7], off
	v_cndmask_b32_e64 v7, v11, v17, s[10:11]
	v_cndmask_b32_e64 v6, v10, v16, s[10:11]
	s_movk_i32 s23, 0xe00
	v_lshlrev_b32_e32 v86, 2, v31
	global_load_dword v10, v[6:7], off
	v_cndmask_b32_e32 v9, v9, v19, vcc
	v_cndmask_b32_e32 v8, v8, v18, vcc
	v_lshl_add_u64 v[6:7], s[44:45], 0, v[86:87]
	v_cmp_gt_i32_e64 s[10:11], s23, v2
	global_load_dword v8, v[8:9], off
	v_add_u32_e32 v2, 0x1400, v2
	v_cndmask_b32_e64 v7, v7, v5, s[10:11]
	v_cndmask_b32_e64 v6, v6, v4, s[10:11]
	global_load_dword v6, v[6:7], off
	v_lshl_add_u64 v[4:5], v[4:5], 0, s[68:69]
	s_waitcnt vmcnt(9)
	v_mul_f32_e32 v7, 0xbfb8aa3b, v3
	v_exp_f32_e32 v7, v7
	s_waitcnt vmcnt(8)
	v_mul_f32_e32 v9, 0xbfb8aa3b, v21
	s_waitcnt vmcnt(7)
	v_mul_f32_e32 v11, 0xbfb8aa3b, v22
	v_exp_f32_e32 v9, v9
	v_exp_f32_e32 v11, v11
	s_waitcnt vmcnt(6)
	v_mul_f32_e32 v13, 0xbfb8aa3b, v23
	v_exp_f32_e32 v13, v13
	v_add_f32_e32 v7, 1.0, v7
	v_add_f32_e32 v9, 1.0, v9
	v_add_f32_e32 v11, 1.0, v11
	s_waitcnt vmcnt(5)
	v_mul_f32_e32 v15, 0xbfb8aa3b, v24
	v_exp_f32_e32 v15, v15
	v_add_f32_e32 v13, 1.0, v13
	v_rcp_f32_e32 v7, v7
	s_waitcnt vmcnt(4)
	v_mul_f32_e32 v16, 0xbfb8aa3b, v14
	v_exp_f32_e32 v16, v16
	v_add_f32_e32 v15, 1.0, v15
	v_rcp_f32_e32 v9, v9
	v_rcp_f32_e32 v35, v11
	v_rcp_f32_e32 v37, v13
	v_add_f32_e32 v16, 1.0, v16
	v_rcp_f32_e32 v40, v15
	s_waitcnt vmcnt(3)
	v_mul_f32_e32 v17, 0xbfb8aa3b, v12
	v_exp_f32_e32 v17, v17
	v_rcp_f32_e32 v43, v16
	s_waitcnt vmcnt(2)
	v_mul_f32_e32 v18, 0xbfb8aa3b, v10
	v_exp_f32_e32 v18, v18
	v_add_f32_e32 v17, 1.0, v17
	s_waitcnt vmcnt(1)
	v_mul_f32_e32 v28, 0xbfb8aa3b, v8
	v_exp_f32_e32 v28, v28
	v_add_f32_e32 v18, 1.0, v18
	s_waitcnt vmcnt(0)
	v_mul_f32_e32 v36, 0xbfb8aa3b, v6
	v_exp_f32_e32 v36, v36
	v_rcp_f32_e32 v48, v17
	v_add_f32_e32 v28, 1.0, v28
	v_rcp_f32_e32 v47, v18
	v_add_f32_e32 v36, 1.0, v36
	v_rcp_f32_e32 v55, v28
	v_rcp_f32_e32 v63, v36
	v_mul_f32_e32 v3, v3, v7
	v_mov_b32_e32 v7, v37
	v_mul_f32_e32 v7, v23, v7
	v_mov_b32_e32 v13, v40
	ds_write2st64_b32 v20, v3, v7 offset1:8
	v_mul_f32_e32 v3, v24, v13
	v_mov_b32_e32 v7, v43
	v_mul_f32_e32 v7, v14, v7
	ds_write2st64_b32 v20, v3, v7 offset0:16 offset1:24
	v_mul_f32_e32 v3, v21, v9
	v_mov_b32_e32 v7, v48
	v_mul_f32_e32 v7, v12, v7
	v_mov_b32_e32 v9, v47
	ds_write2st64_b32 v20, v3, v7 offset0:32 offset1:40
	v_mul_f32_e32 v3, v10, v9
	v_mov_b32_e32 v7, v55
	v_mul_f32_e32 v7, v8, v7
	v_mov_b32_e32 v8, v35
	ds_write2st64_b32 v20, v3, v7 offset0:48 offset1:56
	v_mov_b32_e32 v7, v63
	v_mul_f32_e32 v3, v22, v8
	v_mul_f32_e32 v6, v6, v7
	ds_write2st64_b32 v20, v3, v6 offset0:64 offset1:72
	v_add_u32_e32 v20, 0x5000, v20
	s_andn2_b64 exec, exec, s[72:73]
	s_cbranch_execnz .LBB0_55

; __device__ __forceinline__ unsigned short f2bf(float f) { return (unsigned short)(cvt_pk_bf16(f, 0.f) & 0xffffu); }
; __device__ __forceinline__ void retout_item(PRef p, int layer, int item, unsigned char* shm) {
;     ...
;     { const float* SF = (const float*)(p.ws + O_RETST) + ((size_t)((b * 8 + h) * 2 + 0) * 34 + cidx) * 8192;
;       const float* SB = (const float*)(p.ws + O_RETST) + ((size_t)((b * 8 + h) * 2 + 1) * 34 + cidx) * 8192;
; #pragma unroll 4
;       for (int i = 0; i < 16; ++i) { const int idx = tid + 512 * i, d = idx >> 7, e = idx & 127;
;           sTf[e * 72 + d] = f2bf(SF[idx]); sTb[e * 72 + d] = f2bf(SB[idx]); } }
;     __syncthreads();
;     bf16x8 qa[2];
; #pragma unroll
;     for (int kk = 0; kk < 2; ++kk) qa[kk] = *(const bf16x8*)(A + (size_t)(row0 + 16 * wave + fr) * NIN + C_Q + h * 64 + kk * 32 + fq * 8);
; #pragma unroll
;     for (int nt = 0; nt < 8; ++nt) { f32x4 s = (f32x4){0.f, 0.f, 0.f, 0.f};
; #pragma unroll
;         for (int kk = 0; kk < 2; ++kk) { const bf16x8 kb = *(const bf16x8*)(A + (size_t)(row0 + 16 * nt + fr) * NIN + C_K + h * 64 + kk * 32 + fq * 8);
;             s = __builtin_amdgcn_mfma_f32_16x16x32_bf16(qa[kk], kb, s, 0, 0, 0); }
;         const int m = 16 * nt + fr;
; #pragma unroll
;         for (int r = 0; r < 4; ++r) { const int c = 16 * wave + fq * 4 + r; const float dd = (float)(c - m);
;             const float dec = (m <= c) ? expf(dd * lgf) : expf(-dd * lgb);
;             Pw[(fq * 4 + r) * LDK + m] = f2bf(s[r] * 0.125f * dec); } }
.LBB0_408:
	v_add_u32_e32 v3, s12, v8
	v_add_co_u32_e32 v4, vcc, 0x110000, v0
	v_add_u32_e32 v6, 0x400, v3
	s_nop 0
	v_addc_co_u32_e32 v5, vcc, 0, v1, vcc
	v_add_u32_e32 v14, 0x600, v3
	v_ashrrev_i32_e32 v7, 31, v6
	global_load_dword v9, v[0:1], off
	global_load_dword v10, v[0:1], off offset:2048
	global_load_dword v13, v[4:5], off
	global_load_dword v22, v[4:5], off offset:2048
	v_ashrrev_i32_e32 v15, 31, v14
	v_lshlrev_b64 v[4:5], 2, v[6:7]
	v_lshlrev_b64 v[16:17], 2, v[14:15]
	v_lshl_add_u64 v[18:19], s[4:5], 0, v[4:5]
	v_lshl_add_u64 v[4:5], s[44:45], 0, v[4:5]
	v_lshl_add_u64 v[20:21], s[4:5], 0, v[16:17]
	v_lshl_add_u64 v[16:17], s[44:45], 0, v[16:17]
	global_load_dword v7, v[18:19], off
	s_nop 0
	global_load_dword v4, v[4:5], off
	s_nop 0
	global_load_dword v5, v[20:21], off
	global_load_dword v15, v[16:17], off
	v_ashrrev_i32_e32 v16, 7, v3
	v_add_u32_e32 v3, 0x200, v3
	v_add_u32_e32 v16, v16, v2
	v_ashrrev_i32_e32 v3, 7, v3
	v_ashrrev_i32_e32 v6, 7, v6
	v_lshl_add_u32 v16, v16, 1, 0
	v_add_u32_e32 v3, v3, v2
	s_addk_i32 s12, 0x800
	v_ashrrev_i32_e32 v14, 7, v14
	v_add_u32_e32 v6, v6, v2
	v_lshl_add_u32 v3, v3, 1, 0
	v_lshl_add_u64 v[0:1], v[0:1], 0, s[24:25]
	s_cmpk_lg_i32 s12, 0x2000
	v_add_u32_e32 v14, v14, v2
	v_lshl_add_u32 v6, v6, 1, 0
	v_lshl_add_u32 v14, v14, 1, 0
	s_waitcnt vmcnt(7)
	v_cvt_pk_bf16_f32 v9, v9, v33
	ds_write_b16 v16, v9 offset:34816
	s_waitcnt vmcnt(5)
	v_cvt_pk_bf16_f32 v9, v13, v33
	v_cvt_pk_bf16_f32 v10, v10, v33
	s_waitcnt vmcnt(4)
	v_cvt_pk_bf16_f32 v13, v22, v33
	ds_write_b16 v16, v9 offset:53248
	ds_write_b16 v3, v10 offset:34816
	ds_write_b16 v3, v13 offset:53248
	s_waitcnt vmcnt(3)
	v_cvt_pk_bf16_f32 v3, v7, v33
	s_waitcnt vmcnt(2)
	v_cvt_pk_bf16_f32 v4, v4, v33
	s_waitcnt vmcnt(1)
	v_cvt_pk_bf16_f32 v5, v5, v33
	s_waitcnt vmcnt(0)
	v_cvt_pk_bf16_f32 v7, v15, v33
	ds_write_b16 v6, v3 offset:34816
	ds_write_b16 v6, v4 offset:53248
	ds_write_b16 v14, v5 offset:34816
	ds_write_b16 v14, v7 offset:53248
	s_cbranch_scc1 .LBB0_408
	v_ashrrev_i32_e32 v10, 2, v8
	v_and_b32_e32 v9, 15, v8
	v_and_b32_e32 v14, -16, v10
	v_add_u32_e32 v15, s46, v9
	v_add_u32_e32 v0, v15, v14
	v_mov_b64_e32 v[36:37], s[16:17]
	v_bfe_u32 v13, v8, 4, 2
	v_mad_i64_i32 v[0:1], s[4:5], v0, s37, v[36:37]
	s_mov_b32 s3, s23
	v_lshl_add_u64 v[0:1], v[0:1], 0, s[2:3]
	v_lshlrev_b32_e32 v32, 4, v13
	v_lshl_add_u64 v[0:1], v[0:1], 0, v[32:33]
	s_waitcnt lgkmcnt(0)
	s_barrier
	global_load_dwordx4 v[4:7], v[0:1], off offset:3072
	v_mad_u64_u32 v[2:3], s[4:5], v15, s37, v[36:37]
	v_lshl_add_u64 v[2:3], v[2:3], 0, s[2:3]
	v_lshl_add_u64 v[16:17], v[2:3], 0, v[32:33]
	v_add_co_u32_e32 v2, vcc, s39, v16
	v_mul_lo_u32 v30, v14, s38
	s_nop 0
	v_addc_co_u32_e32 v3, vcc, 0, v17, vcc
	global_load_dwordx4 v[20:23], v[2:3], off
	s_nop 0
	global_load_dwordx4 v[0:3], v[0:1], off offset:3136
	v_lshl_add_u64 v[16:17], v[16:17], 0, s[26:27]
	global_load_dwordx4 v[24:27], v[16:17], off offset:64
	v_mul_f32_e32 v16, 0x3fb8aa3b, v11
	v_mul_f32_e32 v17, 0x3fb8aa3b, v12
	v_rndne_f32_e32 v18, v16
	v_fma_f32 v19, v11, s54, -v16
	v_rndne_f32_e32 v28, v17
	v_fma_f32 v29, v12, s54, -v17
	v_sub_f32_e32 v31, v16, v18
	v_fmac_f32_e32 v19, 0x32a5705f, v11
	v_sub_f32_e32 v17, v17, v28
	v_fmac_f32_e32 v29, 0x32a5705f, v12
	v_add_f32_e32 v19, v31, v19
	v_cvt_i32_f32_e32 v35, v18
	v_add_f32_e32 v17, v17, v29
	v_exp_f32_e32 v19, v19
	v_cvt_i32_f32_e32 v40, v28
	v_exp_f32_e32 v17, v17
	v_lshl_or_b32 v16, v13, 2, v14
	v_ldexp_f32 v19, v19, v35
	v_cmp_ngt_f32_e32 vcc, s55, v11
	v_add_u32_e32 v14, s57, v30
	v_sub_u32_e32 v30, v16, v9
	v_ldexp_f32 v17, v17, v40
	v_cndmask_b32_e32 v19, 0, v19, vcc
	v_cmp_ngt_f32_e32 vcc, s55, v12
	v_cvt_f32_i32_e32 v30, v30
	v_add_u32_e32 v28, 16, v15
	v_cndmask_b32_e32 v17, 0, v17, vcc
	v_cmp_nlt_f32_e32 vcc, s56, v11
	v_mad_u64_u32 v[28:29], s[4:5], v28, s37, v[36:37]
	s_nop 0
	v_cndmask_b32_e32 v11, v51, v19, vcc
	v_cmp_nlt_f32_e32 vcc, s56, v12
	v_lshl_add_u64 v[28:29], v[28:29], 0, s[2:3]
	v_lshl_add_u64 v[38:39], v[28:29], 0, v[32:33]
	v_cndmask_b32_e32 v12, v51, v17, vcc
	v_cmp_lt_i32_e32 vcc, v16, v9
	v_or_b32_e32 v18, 1, v16
	v_sub_u32_e32 v31, v18, v9
	v_cndmask_b32_e64 v17, -v12, v11, vcc
	v_mul_f32_e32 v17, v17, v30
	v_mul_f32_e32 v19, 0x3fb8aa3b, v17
	v_fma_f32 v28, v17, s54, -v19
	v_rndne_f32_e32 v29, v19
	v_fmac_f32_e32 v28, 0x32a5705f, v17
	v_sub_f32_e32 v19, v19, v29
	v_add_f32_e32 v19, v19, v28
	v_add_co_u32_e32 v28, vcc, s39, v38
	v_cvt_i32_f32_e32 v35, v29
	s_nop 0
	v_addc_co_u32_e32 v29, vcc, 0, v39, vcc
	v_cvt_f32_i32_e32 v41, v31
	global_load_dwordx4 v[28:31], v[28:29], off
	v_lshl_add_u64 v[38:39], v[38:39], 0, s[26:27]
	v_exp_f32_e32 v19, v19
	v_cmp_ngt_f32_e32 vcc, s55, v17
	v_lshlrev_b32_e32 v34, 1, v9
	v_mad_u32_u24 v63, v9, s38, v52
	v_ldexp_f32 v19, v19, v35
	v_cndmask_b32_e32 v19, 0, v19, vcc
	v_cmp_nlt_f32_e32 vcc, s56, v17
	s_waitcnt vmcnt(3)
	v_mfma_f32_16x16x32_bf16 v[20:23], v[4:7], v[20:23], 0
	v_cndmask_b32_e32 v17, v51, v19, vcc
	v_cmp_lt_i32_e32 vcc, v18, v9
	v_bitop3_b32 v103, v9, s59, v58 bitop3:0xc8
	s_waitcnt vmcnt(1)
	v_mfma_f32_16x16x32_bf16 v[20:23], v[0:3], v[24:27], v[20:23]
	global_load_dwordx4 v[24:27], v[38:39], off offset:64
	v_cndmask_b32_e64 v19, -v12, v11, vcc
	v_mul_f32_e32 v19, v19, v41
	v_mul_f32_e32 v35, 0x3fb8aa3b, v19
	v_fma_f32 v40, v19, s54, -v35
	s_nop 2
	v_mul_f32_e32 v20, 0x3e000000, v20
	v_mul_f32_e32 v17, v17, v20
	v_cvt_pk_bf16_f32 v20, v17, v33
	v_rndne_f32_e32 v17, v35
	v_fmac_f32_e32 v40, 0x32a5705f, v19
	v_sub_f32_e32 v35, v35, v17
	v_add_f32_e32 v35, v35, v40
	v_exp_f32_e32 v35, v35
	v_cvt_i32_f32_e32 v38, v17
	v_mul_u32_u24_e32 v17, 0x440, v13
	v_add3_u32 v17, v14, v34, v17
	ds_write_b16 v17, v20
	v_ldexp_f32 v20, v35, v38
	v_cmp_ngt_f32_e32 vcc, s55, v19
	v_mul_f32_e32 v21, 0x3e000000, v21
	v_mul_f32_e32 v22, 0x3e000000, v22
	v_cndmask_b32_e32 v20, 0, v20, vcc
	v_cmp_nlt_f32_e32 vcc, s56, v19
	s_waitcnt vmcnt(1)
; __device__ __forceinline__ unsigned short f2bf(float f) { return (unsigned short)(cvt_pk_bf16(f, 0.f) & 0xffffu); }
; __device__ __forceinline__ void retout_item(PRef p, int layer, int item, unsigned char* shm) {
;     ...
;     for (int nt = 0; nt < 8; ++nt) { f32x4 s = (f32x4){0.f, 0.f, 0.f, 0.f};
; #pragma unroll
;         for (int kk = 0; kk < 2; ++kk) { const bf16x8 kb = *(const bf16x8*)(A + (size_t)(row0 + 16 * nt + fr) * NIN + C_K + h * 64 + kk * 32 + fq * 8);
;             s = __builtin_amdgcn_mfma_f32_16x16x32_bf16(qa[kk], kb, s, 0, 0, 0); }
;         const int m = 16 * nt + fr;
; #pragma unroll
;         for (int r = 0; r < 4; ++r) { const int c = 16 * wave + fq * 4 + r; const float dd = (float)(c - m);
;             const float dec = (m <= c) ? expf(dd * lgf) : expf(-dd * lgb);
;             Pw[(fq * 4 + r) * LDK + m] = f2bf(s[r] * 0.125f * dec); } }
	v_mfma_f32_16x16x32_bf16 v[28:31], v[4:7], v[28:31], 0
	v_cndmask_b32_e32 v19, v51, v20, vcc
	v_or_b32_e32 v20, 2, v16
	v_sub_u32_e32 v35, v20, v9
	v_cvt_f32_i32_e32 v35, v35
	v_cmp_lt_i32_e32 vcc, v20, v9
	v_mul_f32_e32 v19, v19, v21
	v_cvt_pk_bf16_f32 v19, v19, v33
	ds_write_b16 v17, v19 offset:272
	v_cndmask_b32_e64 v38, -v12, v11, vcc
	v_mul_f32_e32 v35, v38, v35
	v_mul_f32_e32 v38, 0x3fb8aa3b, v35
	v_fma_f32 v39, v35, s54, -v38
	v_rndne_f32_e32 v40, v38
	v_fmac_f32_e32 v39, 0x32a5705f, v35
	v_sub_f32_e32 v38, v38, v40
	v_add_f32_e32 v38, v38, v39
	v_exp_f32_e32 v38, v38
	v_cvt_i32_f32_e32 v39, v40
	v_cmp_ngt_f32_e32 vcc, s55, v35
	v_lshlrev_b32_e32 v13, 3, v13
	v_bitop3_b32 v105, v9, s13, v60 bitop3:0xc8
	v_ldexp_f32 v19, v38, v39
	v_cndmask_b32_e32 v19, 0, v19, vcc
	v_cmp_nlt_f32_e32 vcc, s56, v35
	v_add_u32_e32 v88, v13, v103
	v_add_u32_e32 v92, v13, v105
	v_cndmask_b32_e32 v21, v51, v19, vcc
	v_or_b32_e32 v19, 3, v16
	v_sub_u32_e32 v35, v19, v9
	v_cvt_f32_i32_e32 v35, v35
	v_cmp_lt_i32_e32 vcc, v19, v9
	v_mul_f32_e32 v21, v21, v22
	v_cvt_pk_bf16_f32 v21, v21, v33
	ds_write_b16 v17, v21 offset:544
	v_cndmask_b32_e64 v38, -v12, v11, vcc
	v_mul_f32_e32 v35, v38, v35
	v_mul_f32_e32 v38, 0x3fb8aa3b, v35
	v_fma_f32 v39, v35, s54, -v38
	v_rndne_f32_e32 v40, v38
	v_fmac_f32_e32 v39, 0x32a5705f, v35
	v_sub_f32_e32 v38, v38, v40
	v_add_f32_e32 v38, v38, v39
	v_exp_f32_e32 v38, v38
	v_cvt_i32_f32_e32 v39, v40
	v_cmp_ngt_f32_e32 vcc, s55, v35
	v_mul_f32_e32 v22, 0x3e000000, v23
	v_bitop3_b32 v97, v9, 56, 48 bitop3:0xc8
	v_ldexp_f32 v21, v38, v39
	v_cndmask_b32_e32 v21, 0, v21, vcc
	v_cmp_nlt_f32_e32 vcc, s56, v35
	v_or_b32_e32 v35, 16, v9
	v_bitop3_b32 v99, v9, s52, 64 bitop3:0xc8
	v_cndmask_b32_e32 v21, v51, v21, vcc
	v_mul_f32_e32 v21, v21, v22
	v_sub_u32_e32 v22, v16, v35
	v_cvt_f32_i32_e32 v22, v22
	v_cmp_lt_i32_e32 vcc, v16, v35
	v_cvt_pk_bf16_f32 v21, v21, v33
	ds_write_b16 v17, v21 offset:816
	v_bitop3_b32 v101, v9, s58, v56 bitop3:0xc8
	v_cndmask_b32_e64 v23, -v12, v11, vcc
	v_mul_f32_e32 v38, v23, v22
	v_mul_f32_e32 v22, 0x3fb8aa3b, v38
	v_fma_f32 v23, v38, s54, -v22
	v_rndne_f32_e32 v39, v22
	v_fmac_f32_e32 v23, 0x32a5705f, v38
	v_sub_f32_e32 v22, v22, v39
	v_add_f32_e32 v22, v22, v23
	v_exp_f32_e32 v40, v22
	s_waitcnt vmcnt(0)
	v_mfma_f32_16x16x32_bf16 v[22:25], v[0:3], v[24:27], v[28:31]
	v_add_u32_e32 v26, 32, v15
	v_mad_u64_u32 v[26:27], s[4:5], v26, s37, v[36:37]
	v_lshl_add_u64 v[26:27], v[26:27], 0, s[2:3]
	v_lshl_add_u64 v[30:31], v[26:27], 0, v[32:33]
	v_add_co_u32_e32 v26, vcc, s39, v30
	v_cvt_i32_f32_e32 v39, v39
	s_nop 0
	v_addc_co_u32_e32 v27, vcc, 0, v31, vcc
	global_load_dwordx4 v[26:29], v[26:27], off
	v_ldexp_f32 v21, v40, v39
	v_cmp_ngt_f32_e32 vcc, s55, v38
	v_mul_f32_e32 v22, 0x3e000000, v22
	v_lshl_add_u64 v[30:31], v[30:31], 0, s[26:27]
	v_cndmask_b32_e32 v21, 0, v21, vcc
	v_cmp_nlt_f32_e32 vcc, s56, v38
	v_mul_f32_e32 v23, 0x3e000000, v23
	v_and_b32_e32 v88, 0x78, v88
	v_cndmask_b32_e32 v21, v51, v21, vcc
	v_mul_f32_e32 v21, v21, v22
	v_sub_u32_e32 v22, v18, v35
	v_cvt_f32_i32_e32 v22, v22
	v_cmp_lt_i32_e32 vcc, v18, v35
	v_cvt_pk_bf16_f32 v21, v21, v33
	ds_write_b16 v17, v21 offset:32
	v_and_b32_e32 v92, 0x78, v92
	v_cndmask_b32_e64 v38, -v12, v11, vcc
	v_mul_f32_e32 v22, v38, v22
	v_mul_f32_e32 v38, 0x3fb8aa3b, v22
	v_fma_f32 v39, v22, s54, -v38
	v_rndne_f32_e32 v40, v38
	v_fmac_f32_e32 v39, 0x32a5705f, v22
	v_sub_f32_e32 v38, v38, v40
	v_add_f32_e32 v38, v38, v39
	v_exp_f32_e32 v42, v38
	v_cvt_i32_f32_e32 v43, v40
	global_load_dwordx4 v[38:41], v[30:31], off offset:64
	v_cmp_ngt_f32_e32 vcc, s55, v22
	v_mad_u32_u24 v96, v9, s38, v53
	v_ldexp_f32 v21, v42, v43
	v_cndmask_b32_e32 v21, 0, v21, vcc
	v_cmp_nlt_f32_e32 vcc, s56, v22
	v_sub_u32_e32 v22, v20, v35
	v_cvt_f32_i32_e32 v22, v22
	v_cndmask_b32_e32 v21, v51, v21, vcc
	v_cmp_lt_i32_e32 vcc, v20, v35
	v_mul_f32_e32 v21, v21, v23
	v_cvt_pk_bf16_f32 v21, v21, v33
	ds_write_b16 v17, v21 offset:304
	v_cndmask_b32_e64 v30, -v12, v11, vcc
	v_mul_f32_e32 v22, v30, v22
	v_mul_f32_e32 v30, 0x3fb8aa3b, v22
	v_fma_f32 v31, v22, s54, -v30
	v_rndne_f32_e32 v42, v30
	v_fmac_f32_e32 v31, 0x32a5705f, v22
	v_sub_f32_e32 v30, v30, v42
	v_add_f32_e32 v30, v30, v31
	v_exp_f32_e32 v30, v30
	v_cvt_i32_f32_e32 v31, v42
	v_cmp_ngt_f32_e32 vcc, s55, v22
	v_mul_f32_e32 v23, 0x3e000000, v24
	v_lshlrev_b32_e32 v72, 1, v97
	v_ldexp_f32 v21, v30, v31
	v_cndmask_b32_e32 v21, 0, v21, vcc
	v_cmp_nlt_f32_e32 vcc, s56, v22
	v_sub_u32_e32 v22, v19, v35
	v_cvt_f32_i32_e32 v22, v22
	v_cndmask_b32_e32 v21, v51, v21, vcc
	v_cmp_lt_i32_e32 vcc, v19, v35
	v_mul_f32_e32 v21, v21, v23
	v_cvt_pk_bf16_f32 v21, v21, v33
	ds_write_b16 v17, v21 offset:576
	v_cndmask_b32_e64 v24, -v12, v11, vcc
	v_mul_f32_e32 v22, v24, v22
	v_mul_f32_e32 v24, 0x3fb8aa3b, v22
	v_fma_f32 v30, v22, s54, -v24
	v_rndne_f32_e32 v31, v24
	v_fmac_f32_e32 v30, 0x32a5705f, v22
	v_sub_f32_e32 v24, v24, v31
	v_add_f32_e32 v24, v24, v30
	v_exp_f32_e32 v24, v24
	v_cvt_i32_f32_e32 v30, v31
	v_cmp_ngt_f32_e32 vcc, s55, v22
	v_mad_u32_u24 v98, v9, s38, v54
	v_lshlrev_b32_e32 v80, 1, v99
	v_ldexp_f32 v21, v24, v30
	v_cndmask_b32_e32 v21, 0, v21, vcc
	v_cmp_nlt_f32_e32 vcc, s56, v22
	v_mul_f32_e32 v22, 0x3e000000, v25
	v_mad_u32_u24 v100, v9, s38, v55
	v_cndmask_b32_e32 v21, v51, v21, vcc
	v_mul_f32_e32 v21, v21, v22
	v_cvt_pk_bf16_f32 v21, v21, v33
	ds_write_b16 v17, v21 offset:848
	v_or_b32_e32 v21, 32, v9
	v_sub_u32_e32 v22, v16, v21
	v_cvt_f32_i32_e32 v30, v22
	v_cmp_lt_i32_e32 vcc, v16, v21
	s_waitcnt vmcnt(1)
; __device__ __forceinline__ unsigned short f2bf(float f) { return (unsigned short)(cvt_pk_bf16(f, 0.f) & 0xffffu); }
; __device__ __forceinline__ void retout_item(PRef p, int layer, int item, unsigned char* shm) {
;     ...
;     for (int nt = 0; nt < 8; ++nt) { f32x4 s = (f32x4){0.f, 0.f, 0.f, 0.f};
; #pragma unroll
;         for (int kk = 0; kk < 2; ++kk) { const bf16x8 kb = *(const bf16x8*)(A + (size_t)(row0 + 16 * nt + fr) * NIN + C_K + h * 64 + kk * 32 + fq * 8);
;             s = __builtin_amdgcn_mfma_f32_16x16x32_bf16(qa[kk], kb, s, 0, 0, 0); }
;         const int m = 16 * nt + fr;
; #pragma unroll
;         for (int r = 0; r < 4; ++r) { const int c = 16 * wave + fq * 4 + r; const float dd = (float)(c - m);
;             const float dec = (m <= c) ? expf(dd * lgf) : expf(-dd * lgb);
;             Pw[(fq * 4 + r) * LDK + m] = f2bf(s[r] * 0.125f * dec); } }
	v_mfma_f32_16x16x32_bf16 v[22:25], v[4:7], v[26:29], 0
	v_lshlrev_b32_e32 v84, 1, v101
	v_cndmask_b32_e64 v26, -v12, v11, vcc
	v_mul_f32_e32 v35, v26, v30
	v_mul_f32_e32 v26, 0x3fb8aa3b, v35
	v_fma_f32 v27, v35, s54, -v26
	v_rndne_f32_e32 v28, v26
	v_fmac_f32_e32 v27, 0x32a5705f, v35
	v_sub_f32_e32 v26, v26, v28
	v_add_f32_e32 v26, v26, v27
	v_exp_f32_e32 v42, v26
	v_add_u32_e32 v26, 48, v15
	v_mad_u64_u32 v[26:27], s[4:5], v26, s37, v[36:37]
	v_lshl_add_u64 v[26:27], v[26:27], 0, s[2:3]
	v_lshl_add_u64 v[30:31], v[26:27], 0, v[32:33]
	v_add_co_u32_e32 v26, vcc, s39, v30
	v_cvt_i32_f32_e32 v43, v28
	s_nop 0
	v_addc_co_u32_e32 v27, vcc, 0, v31, vcc
	global_load_dwordx4 v[26:29], v[26:27], off
	s_waitcnt vmcnt(1)
	v_mfma_f32_16x16x32_bf16 v[22:25], v[0:3], v[38:41], v[22:25]
	v_ldexp_f32 v38, v42, v43
	v_cmp_ngt_f32_e32 vcc, s55, v35
	v_lshl_add_u64 v[30:31], v[30:31], 0, s[26:27]
	v_mad_u32_u24 v102, v9, s38, v57
	v_cndmask_b32_e32 v38, 0, v38, vcc
	v_cmp_nlt_f32_e32 vcc, s56, v35
	s_nop 1
	v_mul_f32_e32 v22, 0x3e000000, v22
	v_mul_f32_e32 v23, 0x3e000000, v23
	v_cndmask_b32_e32 v35, v51, v38, vcc
	v_sub_u32_e32 v38, v18, v21
	v_cvt_f32_i32_e32 v38, v38
	v_cmp_lt_i32_e32 vcc, v18, v21
	v_mul_f32_e32 v22, v35, v22
	v_cvt_pk_bf16_f32 v22, v22, v33
	ds_write_b16 v17, v22 offset:64
	v_cndmask_b32_e64 v39, -v12, v11, vcc
	v_mul_f32_e32 v42, v39, v38
	global_load_dwordx4 v[38:41], v[30:31], off offset:64
	v_mul_f32_e32 v30, 0x3fb8aa3b, v42
	v_fma_f32 v31, v42, s54, -v30
	v_rndne_f32_e32 v43, v30
	v_fmac_f32_e32 v31, 0x32a5705f, v42
	v_sub_f32_e32 v30, v30, v43
	v_add_f32_e32 v30, v30, v31
	v_exp_f32_e32 v30, v30
	v_cvt_i32_f32_e32 v31, v43
	v_cmp_ngt_f32_e32 vcc, s55, v42
	v_mul_f32_e32 v24, 0x3e000000, v24
	v_lshlrev_b32_e32 v88, 1, v88
	v_ldexp_f32 v22, v30, v31
	v_sub_u32_e32 v30, v20, v21
	v_cvt_f32_i32_e32 v30, v30
	v_cndmask_b32_e32 v22, 0, v22, vcc
	v_cmp_nlt_f32_e32 vcc, s56, v42
	v_mad_u32_u24 v104, v9, s38, v59
	v_lshlrev_b32_e32 v92, 1, v92
	v_cndmask_b32_e32 v22, v51, v22, vcc
	v_cmp_lt_i32_e32 vcc, v20, v21
	v_mul_f32_e32 v22, v22, v23
	v_cvt_pk_bf16_f32 v22, v22, v33
	v_sub_u32_e32 v23, v19, v21
	v_cndmask_b32_e64 v31, -v12, v11, vcc
	v_mul_f32_e32 v30, v31, v30
	v_mul_f32_e32 v31, 0x3fb8aa3b, v30
	v_fma_f32 v35, v30, s54, -v31
	v_rndne_f32_e32 v42, v31
	v_fmac_f32_e32 v35, 0x32a5705f, v30
	v_sub_f32_e32 v31, v31, v42
	v_add_f32_e32 v31, v31, v35
	v_exp_f32_e32 v31, v31
	v_cvt_i32_f32_e32 v35, v42
	ds_write_b16 v17, v22 offset:336
	v_cmp_ngt_f32_e32 vcc, s55, v30
	v_cvt_f32_i32_e32 v23, v23
	v_ldexp_f32 v22, v31, v35
	v_cndmask_b32_e32 v22, 0, v22, vcc
	v_cmp_nlt_f32_e32 vcc, s56, v30
	v_or_b32_e32 v35, 48, v9
	v_mad_u32_u24 v106, v9, s38, v61
	v_cndmask_b32_e32 v22, v51, v22, vcc
	v_cmp_lt_i32_e32 vcc, v19, v21
	v_mul_f32_e32 v22, v22, v24
	v_cvt_pk_bf16_f32 v22, v22, v33
	ds_write_b16 v17, v22 offset:608
	v_cndmask_b32_e64 v21, -v12, v11, vcc
	v_mul_f32_e32 v21, v21, v23
	v_mul_f32_e32 v23, 0x3fb8aa3b, v21
	v_fma_f32 v30, v21, s54, -v23
	v_rndne_f32_e32 v31, v23
	v_fmac_f32_e32 v30, 0x32a5705f, v21
	v_sub_f32_e32 v23, v23, v31
	v_add_f32_e32 v23, v23, v30
	v_exp_f32_e32 v23, v23
	v_cvt_i32_f32_e32 v30, v31
	v_cmp_ngt_f32_e32 vcc, s55, v21
	v_add3_u32 v88, 0, v88, v104
	v_add3_u32 v92, 0, v92, v106
	v_ldexp_f32 v22, v23, v30
	v_cndmask_b32_e32 v22, 0, v22, vcc
	v_cmp_nlt_f32_e32 vcc, s56, v21
	s_lshl_b32 s22, s2, 1
	s_nop 0
	v_cndmask_b32_e32 v21, v51, v22, vcc
	v_mul_f32_e32 v22, 0x3e000000, v25
	v_mul_f32_e32 v21, v21, v22
	v_sub_u32_e32 v22, v16, v35
	v_cvt_f32_i32_e32 v30, v22
	v_cmp_lt_i32_e32 vcc, v16, v35
	s_waitcnt vmcnt(1)
	v_mfma_f32_16x16x32_bf16 v[22:25], v[4:7], v[26:29], 0
	v_cvt_pk_bf16_f32 v21, v21, v33
	ds_write_b16 v17, v21 offset:880
	v_cndmask_b32_e64 v26, -v12, v11, vcc
	v_mul_f32_e32 v42, v26, v30
	v_mul_f32_e32 v26, 0x3fb8aa3b, v42
	v_fma_f32 v27, v42, s54, -v26
	v_rndne_f32_e32 v28, v26
	v_fmac_f32_e32 v27, 0x32a5705f, v42
	v_sub_f32_e32 v26, v26, v28
	v_add_f32_e32 v26, v26, v27
	v_exp_f32_e32 v26, v26
	v_cvt_i32_f32_e32 v27, v28
	s_waitcnt vmcnt(0)
	v_mfma_f32_16x16x32_bf16 v[22:25], v[0:3], v[38:41], v[22:25]
	v_ldexp_f32 v21, v26, v27
	v_add_u32_e32 v26, 64, v15
	v_mad_u64_u32 v[26:27], s[4:5], v26, s37, v[36:37]
	v_lshl_add_u64 v[26:27], v[26:27], 0, s[2:3]
	v_lshl_add_u64 v[30:31], v[26:27], 0, v[32:33]
	v_add_co_u32_e32 v26, vcc, s39, v30
	s_nop 1
	v_mul_f32_e32 v22, 0x3e000000, v22
	v_addc_co_u32_e32 v27, vcc, 0, v31, vcc
	global_load_dwordx4 v[26:29], v[26:27], off
	v_cmp_ngt_f32_e32 vcc, s55, v42
	v_lshl_add_u64 v[30:31], v[30:31], 0, s[26:27]
	v_mul_f32_e32 v23, 0x3e000000, v23
	v_cndmask_b32_e32 v21, 0, v21, vcc
	v_cmp_nlt_f32_e32 vcc, s56, v42
	s_nop 1
	v_cndmask_b32_e32 v21, v51, v21, vcc
	v_mul_f32_e32 v21, v21, v22
	v_sub_u32_e32 v22, v18, v35
	v_cvt_f32_i32_e32 v22, v22
	v_cmp_lt_i32_e32 vcc, v18, v35
	v_cvt_pk_bf16_f32 v21, v21, v33
	ds_write_b16 v17, v21 offset:96
	s_nop 0
	v_cndmask_b32_e64 v38, -v12, v11, vcc
	v_mul_f32_e32 v22, v38, v22
	v_mul_f32_e32 v38, 0x3fb8aa3b, v22
	v_fma_f32 v39, v22, s54, -v38
	v_rndne_f32_e32 v40, v38
	v_fmac_f32_e32 v39, 0x32a5705f, v22
	v_sub_f32_e32 v38, v38, v40
	v_add_f32_e32 v38, v38, v39
	v_exp_f32_e32 v42, v38
	v_cvt_i32_f32_e32 v43, v40
	global_load_dwordx4 v[38:41], v[30:31], off offset:64
	v_cmp_ngt_f32_e32 vcc, s55, v22
	v_ldexp_f32 v21, v42, v43
	s_nop 0
	v_cndmask_b32_e32 v21, 0, v21, vcc
	v_cmp_nlt_f32_e32 vcc, s56, v22
	v_sub_u32_e32 v22, v20, v35
	v_cvt_f32_i32_e32 v22, v22
	v_cndmask_b32_e32 v21, v51, v21, vcc
	v_cmp_lt_i32_e32 vcc, v20, v35
	v_mul_f32_e32 v21, v21, v23
	v_cvt_pk_bf16_f32 v21, v21, v33
	ds_write_b16 v17, v21 offset:368
; __device__ __forceinline__ unsigned short f2bf(float f) { return (unsigned short)(cvt_pk_bf16(f, 0.f) & 0xffffu); }
; __device__ __forceinline__ void retout_item(PRef p, int layer, int item, unsigned char* shm) {
;     ...
;     for (int nt = 0; nt < 8; ++nt) { f32x4 s = (f32x4){0.f, 0.f, 0.f, 0.f};
; #pragma unroll
;         for (int kk = 0; kk < 2; ++kk) { const bf16x8 kb = *(const bf16x8*)(A + (size_t)(row0 + 16 * nt + fr) * NIN + C_K + h * 64 + kk * 32 + fq * 8);
;             s = __builtin_amdgcn_mfma_f32_16x16x32_bf16(qa[kk], kb, s, 0, 0, 0); }
;         const int m = 16 * nt + fr;
; #pragma unroll
;         for (int r = 0; r < 4; ++r) { const int c = 16 * wave + fq * 4 + r; const float dd = (float)(c - m);
;             const float dec = (m <= c) ? expf(dd * lgf) : expf(-dd * lgb);
;             Pw[(fq * 4 + r) * LDK + m] = f2bf(s[r] * 0.125f * dec); } }
	v_cndmask_b32_e64 v30, -v12, v11, vcc
	v_mul_f32_e32 v22, v30, v22
	v_mul_f32_e32 v30, 0x3fb8aa3b, v22
	v_fma_f32 v31, v22, s54, -v30
	v_rndne_f32_e32 v42, v30
	v_fmac_f32_e32 v31, 0x32a5705f, v22
	v_sub_f32_e32 v30, v30, v42
	v_add_f32_e32 v30, v30, v31
	v_exp_f32_e32 v30, v30
	v_cvt_i32_f32_e32 v31, v42
	v_cmp_ngt_f32_e32 vcc, s55, v22
	v_mul_f32_e32 v23, 0x3e000000, v24
	v_ldexp_f32 v21, v30, v31
	v_cndmask_b32_e32 v21, 0, v21, vcc
	v_cmp_nlt_f32_e32 vcc, s56, v22
	v_sub_u32_e32 v22, v19, v35
	v_cvt_f32_i32_e32 v22, v22
	v_cndmask_b32_e32 v21, v51, v21, vcc
	v_cmp_lt_i32_e32 vcc, v19, v35
	v_mul_f32_e32 v21, v21, v23
	v_cvt_pk_bf16_f32 v21, v21, v33
	ds_write_b16 v17, v21 offset:640
	v_cndmask_b32_e64 v24, -v12, v11, vcc
	v_mul_f32_e32 v22, v24, v22
	v_mul_f32_e32 v24, 0x3fb8aa3b, v22
	v_fma_f32 v30, v22, s54, -v24
	v_rndne_f32_e32 v31, v24
	v_fmac_f32_e32 v30, 0x32a5705f, v22
	v_sub_f32_e32 v24, v24, v31
	v_add_f32_e32 v24, v24, v30
	v_exp_f32_e32 v24, v24
	v_cvt_i32_f32_e32 v30, v31
	v_cmp_ngt_f32_e32 vcc, s55, v22
	v_ldexp_f32 v21, v24, v30
	s_nop 0
	v_cndmask_b32_e32 v21, 0, v21, vcc
	v_cmp_nlt_f32_e32 vcc, s56, v22
	v_mul_f32_e32 v22, 0x3e000000, v25
	s_nop 0
	v_cndmask_b32_e32 v21, v51, v21, vcc
	v_mul_f32_e32 v21, v21, v22
	v_cvt_pk_bf16_f32 v21, v21, v33
	ds_write_b16 v17, v21 offset:912
	v_or_b32_e32 v21, 64, v9
	v_sub_u32_e32 v22, v16, v21
	v_cvt_f32_i32_e32 v30, v22
	v_cmp_lt_i32_e32 vcc, v16, v21
	s_waitcnt vmcnt(1)
	v_mfma_f32_16x16x32_bf16 v[22:25], v[4:7], v[26:29], 0
	v_cndmask_b32_e64 v26, -v12, v11, vcc
	v_mul_f32_e32 v35, v26, v30
	v_mul_f32_e32 v26, 0x3fb8aa3b, v35
	v_fma_f32 v27, v35, s54, -v26
	v_rndne_f32_e32 v28, v26
	v_fmac_f32_e32 v27, 0x32a5705f, v35
	v_sub_f32_e32 v26, v26, v28
	v_add_f32_e32 v26, v26, v27
	v_exp_f32_e32 v42, v26
	v_add_u32_e32 v26, 0x50, v15
	v_mad_u64_u32 v[26:27], s[4:5], v26, s37, v[36:37]
	v_lshl_add_u64 v[26:27], v[26:27], 0, s[2:3]
	v_lshl_add_u64 v[30:31], v[26:27], 0, v[32:33]
	v_add_co_u32_e32 v26, vcc, s39, v30
	v_cvt_i32_f32_e32 v43, v28
	s_nop 0
	v_addc_co_u32_e32 v27, vcc, 0, v31, vcc
	global_load_dwordx4 v[26:29], v[26:27], off
	s_waitcnt vmcnt(1)
	v_mfma_f32_16x16x32_bf16 v[22:25], v[0:3], v[38:41], v[22:25]
	v_ldexp_f32 v38, v42, v43
	v_cmp_ngt_f32_e32 vcc, s55, v35
	v_lshl_add_u64 v[30:31], v[30:31], 0, s[26:27]
	s_nop 0
	v_cndmask_b32_e32 v38, 0, v38, vcc
	v_cmp_nlt_f32_e32 vcc, s56, v35
	s_nop 1
	v_mul_f32_e32 v22, 0x3e000000, v22
	v_mul_f32_e32 v23, 0x3e000000, v23
	v_cndmask_b32_e32 v35, v51, v38, vcc
	v_sub_u32_e32 v38, v18, v21
	v_cvt_f32_i32_e32 v38, v38
	v_cmp_lt_i32_e32 vcc, v18, v21
	v_mul_f32_e32 v22, v35, v22
	v_cvt_pk_bf16_f32 v22, v22, v33
	ds_write_b16 v17, v22 offset:128
	v_cndmask_b32_e64 v39, -v12, v11, vcc
	v_mul_f32_e32 v42, v39, v38
	global_load_dwordx4 v[38:41], v[30:31], off offset:64
	v_mul_f32_e32 v30, 0x3fb8aa3b, v42
	v_fma_f32 v31, v42, s54, -v30
	v_rndne_f32_e32 v43, v30
	v_fmac_f32_e32 v31, 0x32a5705f, v42
	v_sub_f32_e32 v30, v30, v43
	v_add_f32_e32 v30, v30, v31
	v_exp_f32_e32 v30, v30
	v_cvt_i32_f32_e32 v31, v43
	v_cmp_ngt_f32_e32 vcc, s55, v42
	v_mul_f32_e32 v24, 0x3e000000, v24
	v_ldexp_f32 v22, v30, v31
	v_sub_u32_e32 v30, v20, v21
	v_cvt_f32_i32_e32 v30, v30
	v_cndmask_b32_e32 v22, 0, v22, vcc
	v_cmp_nlt_f32_e32 vcc, s56, v42
	s_nop 1
	v_cndmask_b32_e32 v22, v51, v22, vcc
	v_cmp_lt_i32_e32 vcc, v20, v21
	v_mul_f32_e32 v22, v22, v23
	v_cvt_pk_bf16_f32 v22, v22, v33
	v_sub_u32_e32 v23, v19, v21
	v_cndmask_b32_e64 v31, -v12, v11, vcc
	v_mul_f32_e32 v30, v31, v30
	v_mul_f32_e32 v31, 0x3fb8aa3b, v30
	v_fma_f32 v35, v30, s54, -v31
	v_rndne_f32_e32 v42, v31
	v_fmac_f32_e32 v35, 0x32a5705f, v30
	v_sub_f32_e32 v31, v31, v42
	v_add_f32_e32 v31, v31, v35
	v_exp_f32_e32 v31, v31
	v_cvt_i32_f32_e32 v35, v42
	ds_write_b16 v17, v22 offset:400
	v_cmp_ngt_f32_e32 vcc, s55, v30
	v_cvt_f32_i32_e32 v23, v23
	v_ldexp_f32 v22, v31, v35
	v_cndmask_b32_e32 v22, 0, v22, vcc
	v_cmp_nlt_f32_e32 vcc, s56, v30
	v_or_b32_e32 v35, 0x50, v9
	s_nop 0
	v_cndmask_b32_e32 v22, v51, v22, vcc
	v_cmp_lt_i32_e32 vcc, v19, v21
	v_mul_f32_e32 v22, v22, v24
	v_cvt_pk_bf16_f32 v22, v22, v33
	ds_write_b16 v17, v22 offset:672
	v_cndmask_b32_e64 v21, -v12, v11, vcc
	v_mul_f32_e32 v21, v21, v23
	v_mul_f32_e32 v23, 0x3fb8aa3b, v21
	v_fma_f32 v30, v21, s54, -v23
	v_rndne_f32_e32 v31, v23
	v_fmac_f32_e32 v30, 0x32a5705f, v21
	v_sub_f32_e32 v23, v23, v31
	v_add_f32_e32 v23, v23, v30
	v_exp_f32_e32 v23, v23
	v_cvt_i32_f32_e32 v30, v31
	v_cmp_ngt_f32_e32 vcc, s55, v21
	v_ldexp_f32 v22, v23, v30
	s_nop 0
	v_cndmask_b32_e32 v22, 0, v22, vcc
	v_cmp_nlt_f32_e32 vcc, s56, v21
	s_nop 1
	v_cndmask_b32_e32 v21, v51, v22, vcc
	v_mul_f32_e32 v22, 0x3e000000, v25
	v_mul_f32_e32 v21, v21, v22
	v_sub_u32_e32 v22, v16, v35
	v_cvt_f32_i32_e32 v30, v22
	v_cmp_lt_i32_e32 vcc, v16, v35
	s_waitcnt vmcnt(1)
	v_mfma_f32_16x16x32_bf16 v[22:25], v[4:7], v[26:29], 0
	v_cvt_pk_bf16_f32 v21, v21, v33
	ds_write_b16 v17, v21 offset:944
	v_cndmask_b32_e64 v26, -v12, v11, vcc
	v_mul_f32_e32 v42, v26, v30
	v_mul_f32_e32 v26, 0x3fb8aa3b, v42
	v_fma_f32 v27, v42, s54, -v26
	v_rndne_f32_e32 v28, v26
	v_fmac_f32_e32 v27, 0x32a5705f, v42
	v_sub_f32_e32 v26, v26, v28
	v_add_f32_e32 v26, v26, v27
	v_exp_f32_e32 v26, v26
	v_cvt_i32_f32_e32 v27, v28
	s_waitcnt vmcnt(0)
; __device__ __forceinline__ unsigned short f2bf(float f) { return (unsigned short)(cvt_pk_bf16(f, 0.f) & 0xffffu); }
; __device__ __forceinline__ void retout_item(PRef p, int layer, int item, unsigned char* shm) {
;     ...
;     for (int nt = 0; nt < 8; ++nt) { f32x4 s = (f32x4){0.f, 0.f, 0.f, 0.f};
; #pragma unroll
;         for (int kk = 0; kk < 2; ++kk) { const bf16x8 kb = *(const bf16x8*)(A + (size_t)(row0 + 16 * nt + fr) * NIN + C_K + h * 64 + kk * 32 + fq * 8);
;             s = __builtin_amdgcn_mfma_f32_16x16x32_bf16(qa[kk], kb, s, 0, 0, 0); }
;         const int m = 16 * nt + fr;
; #pragma unroll
;         for (int r = 0; r < 4; ++r) { const int c = 16 * wave + fq * 4 + r; const float dd = (float)(c - m);
;             const float dec = (m <= c) ? expf(dd * lgf) : expf(-dd * lgb);
;             Pw[(fq * 4 + r) * LDK + m] = f2bf(s[r] * 0.125f * dec); } }
	v_mfma_f32_16x16x32_bf16 v[22:25], v[0:3], v[38:41], v[22:25]
	v_ldexp_f32 v21, v26, v27
	v_add_u32_e32 v26, 0x60, v15
	v_mad_u64_u32 v[26:27], s[4:5], v26, s37, v[36:37]
	v_lshl_add_u64 v[26:27], v[26:27], 0, s[2:3]
	v_lshl_add_u64 v[30:31], v[26:27], 0, v[32:33]
	v_add_co_u32_e32 v26, vcc, s39, v30
	s_nop 1
	v_mul_f32_e32 v22, 0x3e000000, v22
	v_addc_co_u32_e32 v27, vcc, 0, v31, vcc
	global_load_dwordx4 v[26:29], v[26:27], off
	v_cmp_ngt_f32_e32 vcc, s55, v42
	v_lshl_add_u64 v[30:31], v[30:31], 0, s[26:27]
	v_mul_f32_e32 v23, 0x3e000000, v23
	v_cndmask_b32_e32 v21, 0, v21, vcc
	v_cmp_nlt_f32_e32 vcc, s56, v42
	v_add_u32_e32 v15, 0x70, v15
	s_nop 0
	v_cndmask_b32_e32 v21, v51, v21, vcc
	v_mul_f32_e32 v21, v21, v22
	v_sub_u32_e32 v22, v18, v35
	v_cvt_f32_i32_e32 v22, v22
	v_cmp_lt_i32_e32 vcc, v18, v35
	v_cvt_pk_bf16_f32 v21, v21, v33
	ds_write_b16 v17, v21 offset:160
	s_nop 0
	v_cndmask_b32_e64 v38, -v12, v11, vcc
	v_mul_f32_e32 v22, v38, v22
	v_mul_f32_e32 v38, 0x3fb8aa3b, v22
	v_fma_f32 v39, v22, s54, -v38
	v_rndne_f32_e32 v40, v38
	v_fmac_f32_e32 v39, 0x32a5705f, v22
	v_sub_f32_e32 v38, v38, v40
	v_add_f32_e32 v38, v38, v39
	v_exp_f32_e32 v42, v38
	v_cvt_i32_f32_e32 v43, v40
	global_load_dwordx4 v[38:41], v[30:31], off offset:64
	v_cmp_ngt_f32_e32 vcc, s55, v22
	v_ldexp_f32 v21, v42, v43
	s_nop 0
	v_cndmask_b32_e32 v21, 0, v21, vcc
	v_cmp_nlt_f32_e32 vcc, s56, v22
	v_sub_u32_e32 v22, v20, v35
	v_cvt_f32_i32_e32 v22, v22
	v_cndmask_b32_e32 v21, v51, v21, vcc
	v_cmp_lt_i32_e32 vcc, v20, v35
	v_mul_f32_e32 v21, v21, v23
	v_cvt_pk_bf16_f32 v21, v21, v33
	ds_write_b16 v17, v21 offset:432
	v_cndmask_b32_e64 v30, -v12, v11, vcc
	v_mul_f32_e32 v22, v30, v22
	v_mul_f32_e32 v30, 0x3fb8aa3b, v22
	v_fma_f32 v31, v22, s54, -v30
	v_rndne_f32_e32 v42, v30
	v_fmac_f32_e32 v31, 0x32a5705f, v22
	v_sub_f32_e32 v30, v30, v42
	v_add_f32_e32 v30, v30, v31
	v_exp_f32_e32 v30, v30
	v_cvt_i32_f32_e32 v31, v42
	v_cmp_ngt_f32_e32 vcc, s55, v22
	v_mul_f32_e32 v23, 0x3e000000, v24
	v_ldexp_f32 v21, v30, v31
	v_cndmask_b32_e32 v21, 0, v21, vcc
	v_cmp_nlt_f32_e32 vcc, s56, v22
	v_sub_u32_e32 v22, v19, v35
	v_cvt_f32_i32_e32 v22, v22
	v_cndmask_b32_e32 v21, v51, v21, vcc
	v_cmp_lt_i32_e32 vcc, v19, v35
	v_mul_f32_e32 v21, v21, v23
	v_cvt_pk_bf16_f32 v21, v21, v33
	ds_write_b16 v17, v21 offset:704
	v_cndmask_b32_e64 v24, -v12, v11, vcc
	v_mul_f32_e32 v22, v24, v22
	v_mul_f32_e32 v24, 0x3fb8aa3b, v22
	v_fma_f32 v30, v22, s54, -v24
	v_rndne_f32_e32 v31, v24
	v_fmac_f32_e32 v30, 0x32a5705f, v22
	v_sub_f32_e32 v24, v24, v31
	v_add_f32_e32 v24, v24, v30
	v_exp_f32_e32 v24, v24
	v_cvt_i32_f32_e32 v30, v31
	v_cmp_ngt_f32_e32 vcc, s55, v22
	v_ldexp_f32 v21, v24, v30
	s_nop 0
	v_cndmask_b32_e32 v21, 0, v21, vcc
	v_cmp_nlt_f32_e32 vcc, s56, v22
	v_mul_f32_e32 v22, 0x3e000000, v25
	s_nop 0
	v_cndmask_b32_e32 v21, v51, v21, vcc
	v_mul_f32_e32 v21, v21, v22
	v_cvt_pk_bf16_f32 v21, v21, v33
	ds_write_b16 v17, v21 offset:976
	v_or_b32_e32 v21, 0x60, v9
	v_sub_u32_e32 v22, v16, v21
	v_cvt_f32_i32_e32 v30, v22
	v_cmp_lt_i32_e32 vcc, v16, v21
	s_waitcnt vmcnt(1)
	v_mfma_f32_16x16x32_bf16 v[22:25], v[4:7], v[26:29], 0
	v_cndmask_b32_e64 v26, -v12, v11, vcc
	v_mul_f32_e32 v35, v26, v30
	v_mul_f32_e32 v26, 0x3fb8aa3b, v35
	v_fma_f32 v27, v35, s54, -v26
	v_rndne_f32_e32 v28, v26
	v_fmac_f32_e32 v27, 0x32a5705f, v35
	v_sub_f32_e32 v26, v26, v28
	v_add_f32_e32 v26, v26, v27
	v_exp_f32_e32 v42, v26
	v_mad_u64_u32 v[26:27], s[4:5], v15, s37, v[36:37]
	v_lshl_add_u64 v[26:27], v[26:27], 0, s[2:3]
	v_lshl_add_u64 v[30:31], v[26:27], 0, v[32:33]
	v_add_co_u32_e32 v26, vcc, s39, v30
	v_cvt_i32_f32_e32 v43, v28
	s_nop 0
	v_addc_co_u32_e32 v27, vcc, 0, v31, vcc
	global_load_dwordx4 v[26:29], v[26:27], off
	v_ldexp_f32 v15, v42, v43
	v_cmp_ngt_f32_e32 vcc, s55, v35
	s_waitcnt vmcnt(1)
	v_mfma_f32_16x16x32_bf16 v[22:25], v[0:3], v[38:41], v[22:25]
	v_lshl_add_u64 v[30:31], v[30:31], 0, s[26:27]
	v_cndmask_b32_e32 v15, 0, v15, vcc
	v_cmp_nlt_f32_e32 vcc, s56, v35
	v_sub_u32_e32 v35, v18, v21
	v_cvt_f32_i32_e32 v35, v35
	v_cndmask_b32_e32 v15, v51, v15, vcc
	v_cmp_lt_i32_e32 vcc, v18, v21
	s_nop 0
	v_mul_f32_e32 v22, 0x3e000000, v22
	v_mul_f32_e32 v15, v15, v22
	v_cndmask_b32_e64 v38, -v12, v11, vcc
	v_mul_f32_e32 v35, v38, v35
	global_load_dwordx4 v[38:41], v[30:31], off offset:64
	v_mul_f32_e32 v30, 0x3fb8aa3b, v35
	v_fma_f32 v31, v35, s54, -v30
	v_rndne_f32_e32 v42, v30
	v_fmac_f32_e32 v31, 0x32a5705f, v35
	v_sub_f32_e32 v30, v30, v42
	v_add_f32_e32 v30, v30, v31
	v_exp_f32_e32 v30, v30
	v_cvt_i32_f32_e32 v31, v42
	v_cvt_pk_bf16_f32 v15, v15, v33
	v_sub_u32_e32 v22, v20, v21
	ds_write_b16 v17, v15 offset:192
	v_ldexp_f32 v15, v30, v31
	v_cmp_ngt_f32_e32 vcc, s55, v35
	v_cvt_f32_i32_e32 v22, v22
	v_mul_f32_e32 v23, 0x3e000000, v23
	v_cndmask_b32_e32 v15, 0, v15, vcc
	v_cmp_nlt_f32_e32 vcc, s56, v35
	s_nop 1
	v_cndmask_b32_e32 v15, v51, v15, vcc
	v_cmp_lt_i32_e32 vcc, v20, v21
	v_mul_f32_e32 v15, v15, v23
	v_cvt_pk_bf16_f32 v15, v15, v33
	ds_write_b16 v17, v15 offset:464
	v_cndmask_b32_e64 v30, -v12, v11, vcc
	v_mul_f32_e32 v22, v30, v22
	v_mul_f32_e32 v30, 0x3fb8aa3b, v22
	v_fma_f32 v31, v22, s54, -v30
	v_rndne_f32_e32 v35, v30
	v_fmac_f32_e32 v31, 0x32a5705f, v22
	v_sub_f32_e32 v30, v30, v35
	v_add_f32_e32 v30, v30, v31
	v_exp_f32_e32 v30, v30
	v_cvt_i32_f32_e32 v31, v35
	v_cmp_ngt_f32_e32 vcc, s55, v22
	v_mul_f32_e32 v23, 0x3e000000, v24
	v_ldexp_f32 v15, v30, v31
	v_cndmask_b32_e32 v15, 0, v15, vcc
	v_cmp_nlt_f32_e32 vcc, s56, v22
	v_sub_u32_e32 v22, v19, v21
	v_cvt_f32_i32_e32 v22, v22
	v_cndmask_b32_e32 v15, v51, v15, vcc
	v_cmp_lt_i32_e32 vcc, v19, v21
	v_mul_f32_e32 v15, v15, v23
	v_cvt_pk_bf16_f32 v15, v15, v33
	ds_write_b16 v17, v15 offset:736
	v_cndmask_b32_e64 v21, -v12, v11, vcc
	v_mul_f32_e32 v21, v21, v22
	v_mul_f32_e32 v22, 0x3fb8aa3b, v21
	v_fma_f32 v24, v21, s54, -v22
	v_rndne_f32_e32 v30, v22
	v_fmac_f32_e32 v24, 0x32a5705f, v21
	v_sub_f32_e32 v22, v22, v30
	v_add_f32_e32 v22, v22, v24
	v_exp_f32_e32 v22, v22
	v_cvt_i32_f32_e32 v24, v30
	v_cmp_ngt_f32_e32 vcc, s55, v21
	v_ldexp_f32 v15, v22, v24
	s_nop 0
	v_cndmask_b32_e32 v15, 0, v15, vcc
	v_cmp_nlt_f32_e32 vcc, s56, v21
	v_mul_f32_e32 v21, 0x3e000000, v25
	s_nop 0
	v_cndmask_b32_e32 v15, v51, v15, vcc
	v_mul_f32_e32 v15, v15, v21
	v_or_b32_e32 v21, 0x70, v9
	v_sub_u32_e32 v22, v16, v21
	v_cvt_f32_i32_e32 v30, v22
	v_cmp_lt_i32_e32 vcc, v16, v21
	s_waitcnt vmcnt(1)
; __device__ __forceinline__ unsigned short f2bf(float f) { return (unsigned short)(cvt_pk_bf16(f, 0.f) & 0xffffu); }
; __device__ __forceinline__ void retout_item(PRef p, int layer, int item, unsigned char* shm) {
;     ...
;     for (int nt = 0; nt < 8; ++nt) { f32x4 s = (f32x4){0.f, 0.f, 0.f, 0.f};
; #pragma unroll
;         for (int kk = 0; kk < 2; ++kk) { const bf16x8 kb = *(const bf16x8*)(A + (size_t)(row0 + 16 * nt + fr) * NIN + C_K + h * 64 + kk * 32 + fq * 8);
;             s = __builtin_amdgcn_mfma_f32_16x16x32_bf16(qa[kk], kb, s, 0, 0, 0); }
;         const int m = 16 * nt + fr;
; #pragma unroll
;         for (int r = 0; r < 4; ++r) { const int c = 16 * wave + fq * 4 + r; const float dd = (float)(c - m);
;             const float dec = (m <= c) ? expf(dd * lgf) : expf(-dd * lgb);
;             Pw[(fq * 4 + r) * LDK + m] = f2bf(s[r] * 0.125f * dec); } }
;     __syncthreads();
;     f32x4 acc[8];
; #pragma unroll
;     for (int et = 0; et < 8; ++et) acc[et] = (f32x4){0.f, 0.f, 0.f, 0.f};
; #pragma unroll
;     for (int kk = 0; kk < 4; ++kk) { const bf16x8 af = *(const bf16x8*)(Pw + fr * LDK + kk * 32 + fq * 8);
; #pragma unroll
;         for (int et = 0; et < 8; ++et) { const bf16x8 bf = *(const bf16x8*)(vT + tsw(16 * et + fr, kk * 32 + fq * 8));
;             acc[et] = __builtin_amdgcn_mfma_f32_16x16x32_bf16(af, bf, acc[et], 0, 0, 0); } }
;     { const int ca = 16 * wave + fr;
;       const float sf = expf((float)(ca + 1) * lgf), sb = expf((float)(128 - ca) * lgb);
	v_mfma_f32_16x16x32_bf16 v[22:25], v[4:7], v[26:29], 0
	v_cvt_pk_bf16_f32 v15, v15, v33
	ds_write_b16 v17, v15 offset:1008
	v_cndmask_b32_e64 v26, -v12, v11, vcc
	v_mul_f32_e32 v26, v26, v30
	v_mul_f32_e32 v27, 0x3fb8aa3b, v26
	v_fma_f32 v28, v26, s54, -v27
	v_rndne_f32_e32 v29, v27
	v_fmac_f32_e32 v28, 0x32a5705f, v26
	v_sub_f32_e32 v27, v27, v29
	v_add_f32_e32 v27, v27, v28
	v_exp_f32_e32 v27, v27
	v_cvt_i32_f32_e32 v28, v29
	v_cmp_ngt_f32_e32 vcc, s55, v26
	s_waitcnt vmcnt(0)
	v_mfma_f32_16x16x32_bf16 v[22:25], v[0:3], v[38:41], v[22:25]
	v_add_u32_e32 v30, 0, v32
	v_ldexp_f32 v15, v27, v28
	v_cndmask_b32_e32 v15, 0, v15, vcc
	v_cmp_nlt_f32_e32 vcc, s56, v26
	v_sub_u32_e32 v26, v18, v21
	v_cvt_f32_i32_e32 v26, v26
	v_cndmask_b32_e32 v15, v51, v15, vcc
	v_cmp_lt_i32_e32 vcc, v18, v21
	v_mul_f32_e32 v22, 0x3e000000, v22
	v_mul_f32_e32 v15, v15, v22
	v_cndmask_b32_e64 v18, -v12, v11, vcc
	v_mul_f32_e32 v18, v18, v26
	v_mul_f32_e32 v26, 0x3fb8aa3b, v18
	v_fma_f32 v27, v18, s54, -v26
	v_rndne_f32_e32 v28, v26
	v_fmac_f32_e32 v27, 0x32a5705f, v18
	v_sub_f32_e32 v26, v26, v28
	v_add_f32_e32 v26, v26, v27
	v_exp_f32_e32 v26, v26
	v_cvt_i32_f32_e32 v27, v28
	v_cvt_pk_bf16_f32 v15, v15, v33
	ds_write_b16 v17, v15 offset:224
	v_cmp_ngt_f32_e32 vcc, s55, v18
	v_ldexp_f32 v15, v26, v27
	v_mul_f32_e32 v22, 0x3e000000, v23
	v_cndmask_b32_e32 v15, 0, v15, vcc
	v_cmp_nlt_f32_e32 vcc, s56, v18
	v_sub_u32_e32 v18, v20, v21
	v_cvt_f32_i32_e32 v18, v18
	v_cndmask_b32_e32 v15, v51, v15, vcc
	v_cmp_lt_i32_e32 vcc, v20, v21
	v_mul_f32_e32 v15, v15, v22
	v_cvt_pk_bf16_f32 v15, v15, v33
	ds_write_b16 v17, v15 offset:496
	v_cndmask_b32_e64 v20, -v12, v11, vcc
	v_mul_f32_e32 v18, v20, v18
	v_mul_f32_e32 v20, 0x3fb8aa3b, v18
	v_fma_f32 v23, v18, s54, -v20
	v_rndne_f32_e32 v26, v20
	v_fmac_f32_e32 v23, 0x32a5705f, v18
	v_sub_f32_e32 v20, v20, v26
	v_add_f32_e32 v20, v20, v23
	v_exp_f32_e32 v20, v20
	v_cvt_i32_f32_e32 v23, v26
	v_cmp_ngt_f32_e32 vcc, s55, v18
	v_add3_u32 v76, v30, v72, v98
	v_add3_u32 v80, v30, v80, v100
	v_ldexp_f32 v15, v20, v23
	v_cndmask_b32_e32 v15, 0, v15, vcc
	v_cmp_nlt_f32_e32 vcc, s56, v18
	v_sub_u32_e32 v18, v19, v21
	v_cvt_f32_i32_e32 v18, v18
	v_cndmask_b32_e32 v15, v51, v15, vcc
	v_cmp_lt_i32_e32 vcc, v19, v21
	v_mul_f32_e32 v20, 0x3e000000, v24
	v_mul_f32_e32 v15, v15, v20
	v_cndmask_b32_e64 v19, -v12, v11, vcc
	v_mul_f32_e32 v18, v19, v18
	v_mul_f32_e32 v19, 0x3fb8aa3b, v18
	v_fma_f32 v21, v18, s54, -v19
	v_rndne_f32_e32 v22, v19
	v_fmac_f32_e32 v21, 0x32a5705f, v18
	v_sub_f32_e32 v19, v19, v22
	v_add_f32_e32 v19, v19, v21
	v_exp_f32_e32 v19, v19
	v_cvt_i32_f32_e32 v21, v22
	v_cvt_pk_bf16_f32 v15, v15, v33
	ds_write_b16 v17, v15 offset:768
	v_cmp_ngt_f32_e32 vcc, s55, v18
	v_ldexp_f32 v15, v19, v21
	v_add3_u32 v84, v30, v84, v102
	v_cndmask_b32_e32 v15, 0, v15, vcc
	v_cmp_nlt_f32_e32 vcc, s56, v18
	v_mul_f32_e32 v18, 0x3e000000, v25
	s_nop 0
	v_cndmask_b32_e32 v15, v51, v15, vcc
	v_mul_f32_e32 v15, v15, v18
	v_cvt_pk_bf16_f32 v15, v15, v33
	ds_write_b16 v17, v15 offset:1040
	v_mul_u32_u24_e32 v15, 0x110, v9
	v_add3_u32 v14, v14, v15, v32
	s_waitcnt lgkmcnt(0)
	s_barrier
	ds_read_b128 v[18:21], v14
	v_and_b32_e32 v17, 8, v8
	v_bitop3_b32 v32, v9, 24, 16 bitop3:0xc8
	v_lshlrev_b32_e32 v22, 1, v17
	v_lshlrev_b32_e32 v35, 1, v32
	v_add3_u32 v31, v30, v22, v15
	v_add3_u32 v35, v30, v35, v63
	ds_read_b128 v[22:25], v31
	ds_read_b128 v[26:29], v14 offset:64
	ds_read_b128 v[38:41], v31 offset:64
	ds_read_b128 v[42:45], v35
	ds_read_b128 v[46:49], v31 offset:128
	v_bitop3_b32 v31, v9, 40, 32 bitop3:0xc8
	v_lshlrev_b32_e32 v64, 1, v31
	v_add3_u32 v68, v30, v64, v96
	ds_read_b128 v[64:67], v68
	ds_read_b128 v[68:71], v68 offset:64
	ds_read_b128 v[72:75], v76
	ds_read_b128 v[76:79], v76 offset:64
	ds_read_b128 v[80:83], v80
	ds_read_b128 v[84:87], v84
	ds_read_b128 v[88:91], v88
	ds_read_b128 v[92:95], v92
	s_waitcnt lgkmcnt(12)
	v_mfma_f32_16x16x32_bf16 v[22:25], v[18:21], v[22:25], 0
	v_bfi_b32 v8, -16, v10, v8
	v_add_u32_e32 v10, 1, v8
	v_cvt_f32_i32_e32 v10, v10
	s_waitcnt lgkmcnt(9)
	v_mfma_f32_16x16x32_bf16 v[42:45], v[18:21], v[42:45], 0
	v_sub_u32_e32 v8, 0x80, v8
	v_cvt_f32_i32_e32 v8, v8
	v_mul_f32_e64 v10, v10, -v12
	s_waitcnt lgkmcnt(7)
	v_mfma_f32_16x16x32_bf16 v[64:67], v[18:21], v[64:67], 0
	v_mul_f32_e32 v12, 0x3fb8aa3b, v10
	v_mul_f32_e64 v8, v8, -v11
	v_mul_f32_e32 v11, 0x3fb8aa3b, v8
	s_waitcnt lgkmcnt(5)
	v_mfma_f32_16x16x32_bf16 v[72:75], v[18:21], v[72:75], 0
	v_cmp_ngt_f32_e32 vcc, s55, v10
	s_waitcnt lgkmcnt(3)
	v_mfma_f32_16x16x32_bf16 v[80:83], v[18:21], v[80:83], 0
	s_waitcnt lgkmcnt(2)
	v_mfma_f32_16x16x32_bf16 v[84:87], v[18:21], v[84:87], 0
	s_waitcnt lgkmcnt(1)
	v_mfma_f32_16x16x32_bf16 v[88:91], v[18:21], v[88:91], 0
	s_waitcnt lgkmcnt(0)
	v_mfma_f32_16x16x32_bf16 v[18:21], v[18:21], v[92:95], 0
	v_mfma_f32_16x16x32_bf16 v[22:25], v[26:29], v[38:41], v[22:25]
	ds_read_b128 v[38:41], v35 offset:64
	ds_read_b128 v[92:95], v35 offset:128
	v_or_b32_e32 v35, 32, v13
	s_waitcnt lgkmcnt(1)
	v_mfma_f32_16x16x32_bf16 v[38:41], v[26:29], v[38:41], v[42:45]
	v_mfma_f32_16x16x32_bf16 v[42:45], v[26:29], v[68:71], v[64:67]
	v_add_u32_e32 v68, v35, v99
	v_and_b32_e32 v68, 0x78, v68
	v_lshlrev_b32_e32 v68, 1, v68
	v_add3_u32 v68, 0, v68, v100
	ds_read_b128 v[68:71], v68
	v_mfma_f32_16x16x32_bf16 v[64:67], v[26:29], v[76:79], v[72:75]
	v_add_u32_e32 v76, v35, v103
	v_and_b32_e32 v76, 56, v76
	v_lshlrev_b32_e32 v76, 1, v76
	v_add_u32_e32 v72, v35, v101
	v_add_u32_e32 v35, v35, v105
	v_and_b32_e32 v72, 0x78, v72
	v_and_b32_e32 v35, 56, v35
	v_lshlrev_b32_e32 v72, 1, v72
	v_lshlrev_b32_e32 v35, 1, v35
	v_add3_u32 v72, 0, v72, v102
	v_add3_u32 v76, 0, v76, v104
	v_add3_u32 v35, 0, v35, v106
	ds_read_b128 v[72:75], v72
	ds_read_b128 v[76:79], v76
	s_waitcnt lgkmcnt(2)
; __device__ __forceinline__ void retout_item(PRef p, int layer, int item, unsigned char* shm) {
;     ...
;     for (int kk = 0; kk < 4; ++kk) { const bf16x8 af = *(const bf16x8*)(Pw + fr * LDK + kk * 32 + fq * 8);
; #pragma unroll
;         for (int et = 0; et < 8; ++et) { const bf16x8 bf = *(const bf16x8*)(vT + tsw(16 * et + fr, kk * 32 + fq * 8));
;             acc[et] = __builtin_amdgcn_mfma_f32_16x16x32_bf16(af, bf, acc[et], 0, 0, 0); } }
;     { const int ca = 16 * wave + fr;
;       const float sf = expf((float)(ca + 1) * lgf), sb = expf((float)(128 - ca) * lgb);
; #pragma unroll
;       for (int kk = 0; kk < 2; ++kk) { const bf16x8 af = scale8(qa[kk], sf), ab = scale8(qa[kk], sb);
; #pragma unroll
;           for (int et = 0; et < 8; ++et) { const bf16x8 b1 = *(const bf16x8*)(sTf + (16 * et + fr) * 72 + kk * 32 + fq * 8);
;               acc[et] = __builtin_amdgcn_mfma_f32_16x16x32_bf16(af, b1, acc[et], 0, 0, 0);
;               const bf16x8 b2 = *(const bf16x8*)(sTb + (16 * et + fr) * 72 + kk * 32 + fq * 8);
;               acc[et] = __builtin_amdgcn_mfma_f32_16x16x32_bf16(ab, b2, acc[et], 0, 0, 0); } } }
	v_mfma_f32_16x16x32_bf16 v[68:71], v[26:29], v[68:71], v[80:83]
	s_nop 2
	ds_read_b128 v[80:83], v35
	s_waitcnt lgkmcnt(2)
	v_mfma_f32_16x16x32_bf16 v[72:75], v[26:29], v[72:75], v[84:87]
	s_waitcnt lgkmcnt(1)
	v_mfma_f32_16x16x32_bf16 v[76:79], v[26:29], v[76:79], v[88:91]
	s_waitcnt lgkmcnt(0)
	v_mfma_f32_16x16x32_bf16 v[18:21], v[26:29], v[80:83], v[18:21]
	ds_read_b128 v[26:29], v14 offset:128
	ds_read_b128 v[80:83], v14 offset:192
	v_or_b32_e32 v14, 64, v13
	v_add_u32_e32 v35, v14, v31
	v_and_b32_e32 v35, 0x78, v35
	v_lshlrev_b32_e32 v35, 1, v35
	v_add3_u32 v35, 0, v35, v96
	s_waitcnt lgkmcnt(1)
	v_mfma_f32_16x16x32_bf16 v[22:25], v[26:29], v[46:49], v[22:25]
	ds_read_b128 v[46:49], v35
	v_add_u32_e32 v35, v14, v97
	v_and_b32_e32 v35, 0x78, v35
	v_lshlrev_b32_e32 v35, 1, v35
	v_add3_u32 v35, 0, v35, v98
	ds_read_b128 v[84:87], v35
	v_add_u32_e32 v35, v13, v99
	v_and_b32_e32 v35, 56, v35
	v_lshlrev_b32_e32 v35, 1, v35
	v_add3_u32 v35, 0, v35, v100
	s_waitcnt lgkmcnt(1)
	v_mfma_f32_16x16x32_bf16 v[42:45], v[26:29], v[46:49], v[42:45]
	s_waitcnt lgkmcnt(0)
	v_mfma_f32_16x16x32_bf16 v[46:49], v[26:29], v[84:87], v[64:67]
	s_nop 2
	ds_read_b128 v[64:67], v35
	v_add_u32_e32 v35, v13, v101
	v_and_b32_e32 v35, 56, v35
	v_lshlrev_b32_e32 v35, 1, v35
	v_add3_u32 v35, 0, v35, v102
	ds_read_b128 v[84:87], v35
	v_add_u32_e32 v35, v14, v103
	v_add_u32_e32 v14, v14, v105
	v_and_b32_e32 v35, 0x78, v35
	v_and_b32_e32 v14, 0x78, v14
	v_lshlrev_b32_e32 v35, 1, v35
	v_lshlrev_b32_e32 v14, 1, v14
	v_add3_u32 v35, 0, v35, v104
	v_add3_u32 v14, 0, v14, v106
	s_waitcnt lgkmcnt(1)
	v_mfma_f32_16x16x32_bf16 v[64:67], v[26:29], v[64:67], v[68:71]
	v_or_b32_e32 v13, 0x60, v13
	s_waitcnt lgkmcnt(0)
	v_mfma_f32_16x16x32_bf16 v[68:71], v[26:29], v[84:87], v[72:75]
	ds_read_b128 v[84:87], v14
	v_add_u32_e32 v14, v13, v17
	v_and_b32_e32 v14, 0x78, v14
	ds_read_b128 v[72:75], v35
	v_lshlrev_b32_e32 v14, 1, v14
	v_add3_u32 v14, 0, v14, v15
	v_mfma_f32_16x16x32_bf16 v[38:41], v[26:29], v[92:95], v[38:41]
	v_and_b32_e32 v35, 0xffff0000, v7
	s_waitcnt lgkmcnt(0)
	v_mfma_f32_16x16x32_bf16 v[72:75], v[26:29], v[72:75], v[76:79]
	v_mfma_f32_16x16x32_bf16 v[18:21], v[26:29], v[84:87], v[18:21]
	ds_read_b128 v[26:29], v14
	v_add_u32_e32 v14, v13, v32
	v_and_b32_e32 v14, 0x78, v14
	v_lshlrev_b32_e32 v14, 1, v14
	v_add3_u32 v14, 0, v14, v63
	ds_read_b128 v[76:79], v14
	v_add_u32_e32 v14, v13, v31
	v_and_b32_e32 v14, 56, v14
	v_lshlrev_b32_e32 v14, 1, v14
	v_add3_u32 v14, 0, v14, v96
	s_waitcnt lgkmcnt(1)
	v_mfma_f32_16x16x32_bf16 v[22:25], v[80:83], v[26:29], v[22:25]
	v_lshlrev_b32_e32 v32, 16, v7
	s_waitcnt lgkmcnt(0)
	v_mfma_f32_16x16x32_bf16 v[26:29], v[80:83], v[76:79], v[38:41]
	s_nop 2
	ds_read_b128 v[38:41], v14
	v_add_u32_e32 v14, v13, v97
	v_and_b32_e32 v14, 56, v14
	v_lshlrev_b32_e32 v14, 1, v14
	v_add3_u32 v14, 0, v14, v98
	ds_read_b128 v[76:79], v14
	v_add_u32_e32 v14, v13, v99
	v_and_b32_e32 v14, 0x78, v14
	v_lshlrev_b32_e32 v14, 1, v14
	v_add3_u32 v14, 0, v14, v100
	s_waitcnt lgkmcnt(1)
	v_mfma_f32_16x16x32_bf16 v[38:41], v[80:83], v[38:41], v[42:45]
	s_waitcnt lgkmcnt(0)
	v_mfma_f32_16x16x32_bf16 v[42:45], v[80:83], v[76:79], v[46:49]
	s_nop 2
	ds_read_b128 v[46:49], v14
	v_add_u32_e32 v14, v13, v101
	v_and_b32_e32 v14, 0x78, v14
	v_lshlrev_b32_e32 v14, 1, v14
	v_add3_u32 v14, 0, v14, v102
	ds_read_b128 v[76:79], v14
	v_add_u32_e32 v14, v13, v103
	v_add_u32_e32 v13, v13, v105
	v_and_b32_e32 v14, 0x78, v14
	v_and_b32_e32 v13, 0x78, v13
	v_lshlrev_b32_e32 v14, 1, v14
	v_lshlrev_b32_e32 v13, 1, v13
	v_add3_u32 v14, 0, v14, v104
	v_add3_u32 v13, 0, v13, v106
	s_waitcnt lgkmcnt(1)
	v_mfma_f32_16x16x32_bf16 v[46:49], v[80:83], v[46:49], v[64:67]
	s_waitcnt lgkmcnt(0)
	v_mfma_f32_16x16x32_bf16 v[64:67], v[80:83], v[76:79], v[68:71]
	ds_read_b128 v[76:79], v13
	v_fma_f32 v13, v10, s54, -v12
	v_fmac_f32_e32 v13, 0x32a5705f, v10
	ds_read_b128 v[68:71], v14
	v_rndne_f32_e32 v14, v12
	v_sub_f32_e32 v12, v12, v14
	v_add_f32_e32 v12, v12, v13
	v_exp_f32_e32 v17, v12
	v_cvt_i32_f32_e32 v31, v14
	s_waitcnt lgkmcnt(1)
	v_mfma_f32_16x16x32_bf16 v[12:15], v[80:83], v[76:79], v[18:21]
	v_ldexp_f32 v17, v17, v31
	s_nop 1
	v_fma_f32 v18, v8, s54, -v11
	v_rndne_f32_e32 v19, v11
	v_fmac_f32_e32 v18, 0x32a5705f, v8
	v_sub_f32_e32 v11, v11, v19
	v_add_f32_e32 v11, v11, v18
	v_exp_f32_e32 v11, v11
	v_cvt_i32_f32_e32 v18, v19
	v_cndmask_b32_e32 v17, 0, v17, vcc
	v_cmp_nlt_f32_e32 vcc, s56, v10
	v_and_b32_e32 v19, 0xffff0000, v5
	v_ldexp_f32 v10, v11, v18
	v_cndmask_b32_e32 v17, v51, v17, vcc
	v_cmp_ngt_f32_e32 vcc, s55, v8
	v_and_b32_e32 v11, 0xffff0000, v4
	v_and_b32_e32 v21, 0xffff0000, v6
	v_cndmask_b32_e32 v10, 0, v10, vcc
	v_cmp_nlt_f32_e32 vcc, s56, v8
	v_lshlrev_b32_e32 v8, 16, v4
	v_mul_f32_e32 v4, v17, v11
	v_cndmask_b32_e32 v31, v51, v10, vcc
	v_mul_u32_u24_e32 v10, 0x48, v9
	v_mul_f32_e32 v9, v17, v8
	v_cvt_pk_bf16_f32 v4, v9, v4
	v_lshlrev_b32_e32 v9, 16, v5
	v_mul_f32_e32 v18, v17, v9
	v_mul_f32_e32 v5, v17, v19
	v_cvt_pk_bf16_f32 v5, v18, v5
	v_lshlrev_b32_e32 v18, 16, v6
	v_mul_f32_e32 v20, v17, v18
	v_mul_f32_e32 v6, v17, v21
	v_mul_f32_e32 v8, v31, v8
	v_mul_f32_e32 v11, v31, v11
	v_cvt_pk_bf16_f32 v6, v20, v6
	v_mul_f32_e32 v20, v17, v32
	v_mul_f32_e32 v7, v17, v35
	v_cvt_pk_bf16_f32 v8, v8, v11
	v_mul_f32_e32 v9, v31, v9
	v_mul_f32_e32 v11, v31, v19
	v_lshl_add_u32 v30, v10, 1, v30
	v_cvt_pk_bf16_f32 v7, v20, v7
	v_cvt_pk_bf16_f32 v9, v9, v11
	v_mul_f32_e32 v11, v31, v18
	v_mul_f32_e32 v63, v31, v21
	ds_read_b128 v[18:21], v30 offset:34816
	s_waitcnt lgkmcnt(1)
; __device__ __forceinline__ float bf2f(unsigned short b) { return __uint_as_float(((unsigned)b) << 16); }
; __device__ __forceinline__ void retout_item(PRef p, int layer, int item, unsigned char* shm) {
;     ...
;       for (int kk = 0; kk < 2; ++kk) { const bf16x8 af = scale8(qa[kk], sf), ab = scale8(qa[kk], sb);
; #pragma unroll
;           for (int et = 0; et < 8; ++et) { const bf16x8 b1 = *(const bf16x8*)(sTf + (16 * et + fr) * 72 + kk * 32 + fq * 8);
;               acc[et] = __builtin_amdgcn_mfma_f32_16x16x32_bf16(af, b1, acc[et], 0, 0, 0);
;               const bf16x8 b2 = *(const bf16x8*)(sTb + (16 * et + fr) * 72 + kk * 32 + fq * 8);
;               acc[et] = __builtin_amdgcn_mfma_f32_16x16x32_bf16(ab, b2, acc[et], 0, 0, 0); } } }
; #pragma unroll
;     for (int r = 0; r < 4; ++r) { float ss = 0.f;
; #pragma unroll
;         for (int et = 0; et < 8; ++et) ss += acc[et][r] * acc[et][r];
;         ss += __shfl_xor(ss, 1); ss += __shfl_xor(ss, 2); ss += __shfl_xor(ss, 4); ss += __shfl_xor(ss, 8);
;         const float rinv = rsqrtf(ss * (1.f / 128.f) + 1e-6f);
;         const size_t row = (size_t)(row0 + 16 * wave + fq * 4 + r);
; #pragma unroll
;         for (int et = 0; et < 8; ++et) { const int e = 16 * et + fr; const float gg = bf2f(A[row * NIN + C_G + h * 128 + e]);
	v_mfma_f32_16x16x32_bf16 v[68:71], v[80:83], v[68:71], v[72:75]
	s_nop 2
	ds_read_b128 v[72:75], v30 offset:53248
	ds_read_b128 v[76:79], v30 offset:34880
	v_cvt_pk_bf16_f32 v10, v11, v63
	v_mul_f32_e32 v11, v31, v32
	s_waitcnt lgkmcnt(2)
	v_mfma_f32_16x16x32_bf16 v[18:21], v[4:7], v[18:21], v[22:25]
	v_add_u32_e32 v32, 0x900, v30
	s_nop 1
	v_mul_f32_e32 v22, v31, v35
	v_cvt_pk_bf16_f32 v11, v11, v22
	ds_read_b128 v[22:25], v30 offset:53312
	s_waitcnt lgkmcnt(2)
	v_mfma_f32_16x16x32_bf16 v[18:21], v[8:11], v[72:75], v[18:21]
	ds_read_b128 v[72:75], v30 offset:37120
	ds_read_b128 v[80:83], v30 offset:37184
	v_mov_b32_e32 v35, v33
	s_waitcnt lgkmcnt(1)
	v_mfma_f32_16x16x32_bf16 v[26:29], v[4:7], v[72:75], v[26:29]
	ds_read_b128 v[72:75], v30 offset:55552
	ds_read_b128 v[84:87], v30 offset:55616
	s_waitcnt lgkmcnt(1)
	v_mfma_f32_16x16x32_bf16 v[72:75], v[8:11], v[72:75], v[26:29]
	s_nop 3
	ds_read_b128 v[26:29], v30 offset:39424
	ds_read_b128 v[88:91], v30 offset:39488
	s_waitcnt lgkmcnt(1)
	v_mfma_f32_16x16x32_bf16 v[26:29], v[4:7], v[26:29], v[38:41]
	s_nop 2
	ds_read_b128 v[38:41], v30 offset:57856
	ds_read_b128 v[92:95], v30 offset:57920
	s_waitcnt lgkmcnt(1)
	v_mfma_f32_16x16x32_bf16 v[38:41], v[8:11], v[38:41], v[26:29]
	s_nop 2
	ds_read_b128 v[26:29], v30 offset:41728
	ds_read_b128 v[96:99], v30 offset:41792
	s_waitcnt lgkmcnt(1)
	v_mfma_f32_16x16x32_bf16 v[26:29], v[4:7], v[26:29], v[42:45]
	s_nop 2
	ds_read_b128 v[42:45], v30 offset:60160
	ds_read_b128 v[100:103], v30 offset:60224
	s_waitcnt lgkmcnt(1)
	v_mfma_f32_16x16x32_bf16 v[42:45], v[8:11], v[42:45], v[26:29]
	s_nop 2
	ds_read_b128 v[26:29], v30 offset:44032
	ds_read_b128 v[104:107], v30 offset:44096
	s_waitcnt lgkmcnt(1)
	v_mfma_f32_16x16x32_bf16 v[26:29], v[4:7], v[26:29], v[46:49]
	s_nop 2
	ds_read_b128 v[46:49], v30 offset:62464
	ds_read_b128 v[108:111], v30 offset:62528
	s_waitcnt lgkmcnt(1)
	v_mfma_f32_16x16x32_bf16 v[46:49], v[8:11], v[46:49], v[26:29]
	s_nop 2
	ds_read_b128 v[26:29], v30 offset:46336
	ds_read_b128 v[112:115], v30 offset:46400
	s_waitcnt lgkmcnt(1)
	v_mfma_f32_16x16x32_bf16 v[26:29], v[4:7], v[26:29], v[64:67]
	s_nop 2
	ds_read_b128 v[64:67], v30 offset:64768
	ds_read_b128 v[116:119], v30 offset:64832
	ds_read_b128 v[120:123], v30 offset:48704
	s_waitcnt lgkmcnt(2)
	v_mfma_f32_16x16x32_bf16 v[64:67], v[8:11], v[64:67], v[26:29]
	s_nop 2
	ds_read_b128 v[26:29], v30 offset:48640
	s_waitcnt lgkmcnt(0)
	v_mfma_f32_16x16x32_bf16 v[26:29], v[4:7], v[26:29], v[68:71]
	s_nop 2
	ds_read_b128 v[68:71], v32 offset:64768
	ds_read_b128 v[124:127], v32 offset:64832
	v_add_u32_e32 v32, 0x1200, v30
	ds_read_b128 v[128:131], v30 offset:51008
	s_waitcnt lgkmcnt(2)
	v_mfma_f32_16x16x32_bf16 v[68:71], v[8:11], v[68:71], v[26:29]
	s_nop 2
	ds_read_b128 v[26:29], v30 offset:50944
	s_waitcnt lgkmcnt(0)
	v_mfma_f32_16x16x32_bf16 v[4:7], v[4:7], v[26:29], v[12:15]
	s_nop 2
	ds_read_b128 v[12:15], v32 offset:64768
	ds_read_b128 v[132:135], v32 offset:64832
	v_xor_b32_e32 v32, 1, v62
	s_waitcnt lgkmcnt(1)
	v_mfma_f32_16x16x32_bf16 v[136:139], v[8:11], v[12:15], v[4:7]
	v_and_b32_e32 v9, 0xffff0000, v3
	s_nop 1
	v_lshlrev_b32_e32 v4, 16, v0
	v_mul_f32_e32 v5, v17, v4
	v_and_b32_e32 v0, 0xffff0000, v0
	v_mul_f32_e32 v6, v17, v0
	v_cvt_pk_bf16_f32 v140, v5, v6
	v_lshlrev_b32_e32 v5, 16, v1
	v_mul_f32_e32 v6, v17, v5
	v_and_b32_e32 v1, 0xffff0000, v1
	v_mul_f32_e32 v7, v17, v1
	v_cvt_pk_bf16_f32 v141, v6, v7
	v_lshlrev_b32_e32 v6, 16, v2
	v_mul_f32_e32 v7, v17, v6
	v_and_b32_e32 v2, 0xffff0000, v2
	v_mul_f32_e32 v8, v17, v2
	v_cvt_pk_bf16_f32 v142, v7, v8
	v_lshlrev_b32_e32 v7, 16, v3
	v_mul_f32_e32 v3, v17, v9
	v_mul_f32_e32 v0, v31, v0
	v_mul_f32_e32 v8, v17, v7
	v_cvt_pk_bf16_f32 v143, v8, v3
	v_mul_f32_e32 v3, v31, v4
	v_cvt_pk_bf16_f32 v144, v3, v0
	v_mul_f32_e32 v0, v31, v5
	v_mul_f32_e32 v1, v31, v1
	v_cvt_pk_bf16_f32 v145, v0, v1
	v_mul_f32_e32 v0, v31, v6
	v_mul_f32_e32 v1, v31, v2
	v_cvt_pk_bf16_f32 v146, v0, v1
	v_mfma_f32_16x16x32_bf16 v[0:3], v[140:143], v[76:79], v[18:21]
	v_mul_f32_e32 v4, v31, v7
	v_mul_f32_e32 v5, v31, v9
	v_cvt_pk_bf16_f32 v147, v4, v5
	s_nop 0
	v_mfma_f32_16x16x32_bf16 v[28:31], v[144:147], v[22:25], v[0:3]
	v_mfma_f32_16x16x32_bf16 v[0:3], v[140:143], v[80:83], v[72:75]
	v_mfma_f32_16x16x32_bf16 v[24:27], v[144:147], v[84:87], v[0:3]
	v_mfma_f32_16x16x32_bf16 v[0:3], v[140:143], v[88:91], v[38:41]
	s_nop 2
	v_add_u32_e32 v38, s46, v16
	v_mad_i64_i32 v[16:17], s[2:3], v38, s37, v[36:37]
	v_lshl_add_u64 v[16:17], v[16:17], 0, s[22:23]
	v_mfma_f32_16x16x32_bf16 v[20:23], v[144:147], v[92:95], v[0:3]
	s_add_u32 s2, s29, s22
	s_addc_u32 s3, s30, 0
	v_mfma_f32_16x16x32_bf16 v[0:3], v[140:143], v[96:99], v[42:45]
	s_nop 2
	v_lshl_add_u64 v[44:45], v[16:17], 0, v[34:35]
	v_add_co_u32_e32 v16, vcc, s39, v44
	v_mfma_f32_16x16x32_bf16 v[12:15], v[144:147], v[100:103], v[0:3]
	s_nop 0
	v_addc_co_u32_e32 v17, vcc, 0, v45, vcc
	global_load_ushort v39, v[16:17], off offset:3072
	v_mfma_f32_16x16x32_bf16 v[0:3], v[140:143], v[104:107], v[46:49]
	v_mfma_f32_16x16x32_bf16 v[8:11], v[144:147], v[108:111], v[0:3]
	s_nop 1
	v_mul_f32_e32 v47, v24, v24
	v_fmac_f32_e32 v47, v28, v28
	v_xor_b32_e32 v49, 8, v62
	v_mfma_f32_16x16x32_bf16 v[0:3], v[140:143], v[112:115], v[64:67]
	v_mfma_f32_16x16x32_bf16 v[40:43], v[140:143], v[128:131], v[136:139]
	s_waitcnt vmcnt(0)
	s_nop 0
	v_lshlrev_b32_e32 v67, 16, v39
	v_mfma_f32_16x16x32_bf16 v[4:7], v[144:147], v[116:119], v[0:3]
	v_mul_f32_e32 v39, 0xbfb8aa3b, v67
	v_mfma_f32_16x16x32_bf16 v[0:3], v[140:143], v[120:123], v[68:71]
	s_waitcnt lgkmcnt(0)
; __device__ __forceinline__ float bf2f(unsigned short b) { return __uint_as_float(((unsigned)b) << 16); }
; __device__ __forceinline__ unsigned short f2bf(float f) { return (unsigned short)(cvt_pk_bf16(f, 0.f) & 0xffffu); }
; __device__ __forceinline__ float sigmoidf_(float x) { return 1.f / (1.f + __expf(-x)); }
; __device__ __forceinline__ void retout_item(PRef p, int layer, int item, unsigned char* shm) {
;     ...
; #pragma unroll
;     for (int r = 0; r < 4; ++r) { float ss = 0.f;
; #pragma unroll
;         for (int et = 0; et < 8; ++et) ss += acc[et][r] * acc[et][r];
;         ss += __shfl_xor(ss, 1); ss += __shfl_xor(ss, 2); ss += __shfl_xor(ss, 4); ss += __shfl_xor(ss, 8);
;         const float rinv = rsqrtf(ss * (1.f / 128.f) + 1e-6f);
;         const size_t row = (size_t)(row0 + 16 * wave + fq * 4 + r);
; #pragma unroll
;         for (int et = 0; et < 8; ++et) { const int e = 16 * et + fr; const float gg = bf2f(A[row * NIN + C_G + h * 128 + e]);
;             MIX[row * 2048 + 512 + h * 128 + e] = f2bf(acc[et][r] * rinv * gg * sigmoidf_(gg)); } }
	v_mfma_f32_16x16x32_bf16 v[16:19], v[144:147], v[132:135], v[40:43]
	s_nop 0
	v_exp_f32_e32 v68, v39
	v_ashrrev_i32_e32 v39, 31, v38
	v_and_b32_e32 v40, 64, v62
	v_add_u32_e32 v46, 64, v40
	v_lshl_add_u64 v[40:41], v[44:45], 0, s[40:41]
	v_mov_b32_e32 v42, v20
	v_mov_b32_e32 v43, v12
	global_load_ushort v48, v[40:41], off offset:32
	v_pk_mul_f32 v[42:43], v[42:43], v[42:43]
	v_mfma_f32_16x16x32_bf16 v[0:3], v[144:147], v[124:127], v[0:3]
	v_add_f32_e32 v42, v47, v42
	v_add_f32_e32 v44, v42, v43
	v_mov_b32_e32 v42, v8
	v_mov_b32_e32 v43, v4
	v_pk_mul_f32 v[42:43], v[42:43], v[42:43]
	v_cmp_lt_i32_e32 vcc, v32, v46
	v_add_f32_e32 v42, v44, v42
	v_add_f32_e32 v44, v42, v43
	v_mov_b32_e32 v42, v0
	v_mov_b32_e32 v43, v16
	v_pk_mul_f32 v[42:43], v[42:43], v[42:43]
	v_cndmask_b32_e32 v32, v62, v32, vcc
	v_add_f32_e32 v42, v44, v42
	v_lshlrev_b32_e32 v32, 2, v32
	v_add_f32_e32 v42, v42, v43
	ds_bpermute_b32 v43, v32, v42
	v_xor_b32_e32 v44, 2, v62
	v_cmp_lt_i32_e32 vcc, v44, v46
	v_xor_b32_e32 v45, 4, v62
	s_waitcnt lgkmcnt(0)
	v_add_f32_e32 v42, v42, v43
	v_cndmask_b32_e32 v44, v62, v44, vcc
	v_lshlrev_b32_e32 v44, 2, v44
	ds_bpermute_b32 v47, v44, v42
	global_load_ushort v43, v[40:41], off offset:64
	v_cmp_lt_i32_e32 vcc, v45, v46
	s_waitcnt lgkmcnt(0)
	v_add_f32_e32 v42, v42, v47
	v_cndmask_b32_e32 v45, v62, v45, vcc
	v_lshlrev_b32_e32 v45, 2, v45
	ds_bpermute_b32 v47, v45, v42
	v_cmp_lt_i32_e32 vcc, v49, v46
	s_waitcnt lgkmcnt(0)
	v_add_f32_e32 v42, v42, v47
	v_cndmask_b32_e32 v46, v62, v49, vcc
	v_lshlrev_b32_e32 v46, 2, v46
	ds_bpermute_b32 v47, v46, v42
	s_waitcnt lgkmcnt(0)
	v_add_f32_e32 v42, v42, v47
	v_fmamk_f32 v42, v42, 0x3c000000, v50
	v_mul_f32_e32 v47, 0x4b800000, v42
	v_cmp_gt_f32_e32 vcc, s60, v42
	s_nop 1
	v_cndmask_b32_e32 v42, v42, v47, vcc
	global_load_ushort v47, v[40:41], off offset:96
	global_load_ushort v63, v[40:41], off offset:128
	global_load_ushort v64, v[40:41], off offset:160
	global_load_ushort v65, v[40:41], off offset:192
	global_load_ushort v66, v[40:41], off offset:224
	v_rsq_f32_e32 v42, v42
	v_lshlrev_b64 v[40:41], 12, v[38:39]
	v_add_f32_e32 v39, 1.0, v68
	v_lshl_add_u64 v[40:41], s[2:3], 0, v[40:41]
	v_mul_f32_e32 v49, 0x45800000, v42
	v_cndmask_b32_e32 v69, v42, v49, vcc
	v_rcp_f32_e32 v39, v39
	v_mul_f32_e32 v28, v28, v69
	v_mul_f32_e32 v28, v28, v67
	v_lshl_add_u64 v[40:41], v[40:41], 0, v[34:35]
	v_mul_f32_e32 v28, v39, v28
	v_cvt_pk_bf16_f32 v28, v28, v33
	s_waitcnt vmcnt(6)
	v_lshlrev_b32_e32 v42, 16, v48
	v_mul_f32_e32 v48, 0xbfb8aa3b, v42
	v_exp_f32_e32 v48, v48
	global_store_short v[40:41], v28, off
	v_mul_f32_e32 v24, v24, v69
	v_mul_f32_e32 v24, v24, v42
	v_add_f32_e32 v39, 1.0, v48
	v_rcp_f32_e32 v28, v39
	v_mul_f32_e32 v20, v20, v69
	v_mul_f32_e32 v12, v12, v69
	v_mul_f32_e32 v8, v8, v69
	v_mul_f32_e32 v24, v24, v28
	v_cvt_pk_bf16_f32 v24, v24, v33
	global_store_short v[40:41], v24, off offset:32
	v_mul_f32_e32 v4, v4, v69
	s_waitcnt vmcnt(7)
	v_lshlrev_b32_e32 v42, 16, v43
	v_mul_f32_e32 v43, 0xbfb8aa3b, v42
	v_exp_f32_e32 v43, v43
	v_mul_f32_e32 v20, v20, v42
	v_mul_f32_e32 v0, v0, v69
	v_add_f32_e32 v28, 1.0, v43
	v_rcp_f32_e32 v24, v28
	s_nop 0
	v_mul_f32_e32 v20, v20, v24
	v_cvt_pk_bf16_f32 v20, v20, v33
	global_store_short v[40:41], v20, off offset:64
	s_waitcnt vmcnt(7)
	v_lshlrev_b32_e32 v39, 16, v47
	v_mul_f32_e32 v42, 0xbfb8aa3b, v39
	v_exp_f32_e32 v42, v42
	v_mul_f32_e32 v12, v12, v39
	v_add_f32_e32 v24, 1.0, v42
	v_rcp_f32_e32 v20, v24
	s_nop 0
	s_waitcnt vmcnt(6)
	v_lshlrev_b32_e32 v28, 16, v63
	v_mul_f32_e32 v39, 0xbfb8aa3b, v28
	v_exp_f32_e32 v39, v39
	v_mul_f32_e32 v12, v12, v20
	v_cvt_pk_bf16_f32 v12, v12, v33
	v_add_f32_e32 v20, 1.0, v39
	v_rcp_f32_e32 v39, v20
	global_store_short v[40:41], v12, off offset:96
	v_mul_f32_e32 v8, v8, v28
	s_waitcnt vmcnt(6)
	v_lshlrev_b32_e32 v24, 16, v64
	v_mul_f32_e32 v28, 0xbfb8aa3b, v24
	v_exp_f32_e32 v28, v28
	v_mov_b32_e32 v12, v39
	v_mul_f32_e32 v8, v8, v12
	v_cvt_pk_bf16_f32 v8, v8, v33
	v_add_f32_e32 v12, 1.0, v28
	v_rcp_f32_e32 v28, v12
	global_store_short v[40:41], v8, off offset:128
	v_mul_f32_e32 v4, v4, v24
	v_add_u32_e32 v42, 1, v38
	s_waitcnt vmcnt(6)
	v_lshlrev_b32_e32 v20, 16, v65
	v_mul_f32_e32 v24, 0xbfb8aa3b, v20
	v_mad_i64_i32 v[48:49], s[4:5], v42, s37, v[36:37]
	v_exp_f32_e32 v24, v24
	v_lshl_add_u64 v[48:49], v[48:49], 0, s[22:23]
	v_lshl_add_u64 v[48:49], v[48:49], 0, v[34:35]
	v_add_co_u32_e32 v64, vcc, s39, v48
	v_mov_b32_e32 v8, v28
	s_nop 0
	v_addc_co_u32_e32 v65, vcc, 0, v49, vcc
	v_mul_f32_e32 v4, v4, v8
	v_add_f32_e32 v8, 1.0, v24
	global_load_ushort v24, v[64:65], off offset:3072
	v_rcp_f32_e32 v28, v8
	v_cvt_pk_bf16_f32 v4, v4, v33
	global_store_short v[40:41], v4, off offset:160
	v_mul_f32_e32 v0, v0, v20
	v_mov_b32_e32 v4, v28
	s_waitcnt vmcnt(7)
	v_lshlrev_b32_e32 v8, 16, v66
	v_mul_f32_e32 v0, v0, v4
	v_mul_f32_e32 v4, 0xbfb8aa3b, v8
	v_lshl_add_u64 v[48:49], v[48:49], 0, s[40:41]
	v_exp_f32_e32 v39, v4
	v_mul_f32_e32 v4, v25, v25
	v_mov_b32_e32 v12, v21
	global_load_ushort v28, v[48:49], off offset:32
	global_load_ushort v47, v[48:49], off offset:64
	v_fmac_f32_e32 v4, v29, v29
	v_mul_f32_e32 v20, v16, v69
	v_fma_f32 v4, v12, v12, v4
	v_fma_f32 v12, v13, v13, v4
	v_mov_b32_e32 v4, v9
	v_mov_b32_e32 v16, v1
	v_fma_f32 v4, v4, v4, v12
	v_fma_f32 v4, v5, v5, v4
	v_pk_mul_f32 v[64:65], v[16:17], v[16:17]
	v_add_f32_e32 v16, 1.0, v39
	v_add_f32_e32 v4, v4, v64
	v_add_f32_e32 v4, v4, v65
	ds_bpermute_b32 v12, v32, v4
	v_rcp_f32_e32 v43, v16
	v_cvt_pk_bf16_f32 v0, v0, v33
	s_waitcnt lgkmcnt(0)
	v_add_f32_e32 v4, v4, v12
	ds_bpermute_b32 v12, v44, v4
	global_store_short v[40:41], v0, off offset:192
	v_mul_f32_e32 v0, v20, v8
	s_waitcnt lgkmcnt(0)
; __device__ __forceinline__ float bf2f(unsigned short b) { return __uint_as_float(((unsigned)b) << 16); }
; __device__ __forceinline__ unsigned short f2bf(float f) { return (unsigned short)(cvt_pk_bf16(f, 0.f) & 0xffffu); }
; __device__ __forceinline__ float sigmoidf_(float x) { return 1.f / (1.f + __expf(-x)); }
; __device__ __forceinline__ void retout_item(PRef p, int layer, int item, unsigned char* shm) {
;     ...
; #pragma unroll
;     for (int r = 0; r < 4; ++r) { float ss = 0.f;
; #pragma unroll
;         for (int et = 0; et < 8; ++et) ss += acc[et][r] * acc[et][r];
;         ss += __shfl_xor(ss, 1); ss += __shfl_xor(ss, 2); ss += __shfl_xor(ss, 4); ss += __shfl_xor(ss, 8);
;         const float rinv = rsqrtf(ss * (1.f / 128.f) + 1e-6f);
;         const size_t row = (size_t)(row0 + 16 * wave + fq * 4 + r);
; #pragma unroll
;         for (int et = 0; et < 8; ++et) { const int e = 16 * et + fr; const float gg = bf2f(A[row * NIN + C_G + h * 128 + e]);
;             MIX[row * 2048 + 512 + h * 128 + e] = f2bf(acc[et][r] * rinv * gg * sigmoidf_(gg)); } }
	v_add_f32_e32 v4, v4, v12
	ds_bpermute_b32 v8, v45, v4
	s_waitcnt lgkmcnt(0)
	v_add_f32_e32 v4, v4, v8
	ds_bpermute_b32 v8, v46, v4
	v_mov_b32_e32 v12, v43
	s_waitcnt lgkmcnt(0)
	v_add_f32_e32 v4, v4, v8
	v_fmamk_f32 v4, v4, 0x3c000000, v50
	v_mul_f32_e32 v8, 0x4b800000, v4
	v_cmp_gt_f32_e32 vcc, s60, v4
	v_mul_f32_e32 v0, v0, v12
	v_cvt_pk_bf16_f32 v0, v0, v33
	global_store_short v[40:41], v0, off offset:224
	v_cndmask_b32_e32 v4, v4, v8, vcc
	global_load_ushort v8, v[48:49], off offset:96
	global_load_ushort v12, v[48:49], off offset:128
	global_load_ushort v16, v[48:49], off offset:160
	global_load_ushort v20, v[48:49], off offset:192
	global_load_ushort v39, v[48:49], off offset:224
	v_rsq_f32_e32 v4, v4
	v_ashrrev_i32_e32 v43, 31, v42
	v_mul_f32_e32 v0, 0x45800000, v4
	v_cndmask_b32_e32 v49, v4, v0, vcc
	v_mul_f32_e32 v29, v29, v49
	s_waitcnt vmcnt(10)
	v_lshlrev_b32_e32 v24, 16, v24
	v_mul_f32_e32 v40, 0xbfb8aa3b, v24
	v_exp_f32_e32 v48, v40
	v_lshlrev_b64 v[40:41], 12, v[42:43]
	v_mul_f32_e32 v24, v29, v24
	v_lshl_add_u64 v[40:41], s[2:3], 0, v[40:41]
	v_add_f32_e32 v0, 1.0, v48
	v_rcp_f32_e32 v0, v0
	v_mul_f32_e32 v1, v1, v49
	v_mul_f32_e32 v17, v17, v49
	v_mul_f32_e32 v0, v0, v24
	s_waitcnt vmcnt(8)
	v_lshlrev_b32_e32 v4, 16, v28
	v_mul_f32_e32 v28, 0xbfb8aa3b, v4
	v_exp_f32_e32 v42, v28
	v_lshl_add_u64 v[28:29], v[40:41], 0, v[34:35]
	v_cvt_pk_bf16_f32 v0, v0, v33
	global_store_short v[28:29], v0, off
	v_add_f32_e32 v24, 1.0, v42
	v_rcp_f32_e32 v41, v24
	v_mul_f32_e32 v0, v25, v49
	v_mul_f32_e32 v0, v0, v4
	s_waitcnt vmcnt(8)
	v_lshlrev_b32_e32 v25, 16, v47
	v_mul_f32_e32 v40, 0xbfb8aa3b, v25
	v_exp_f32_e32 v40, v40
	v_mov_b32_e32 v4, v41
	v_mul_f32_e32 v0, v0, v4
	v_cvt_pk_bf16_f32 v0, v0, v33
	v_add_f32_e32 v4, 1.0, v40
	v_rcp_f32_e32 v4, v4
	global_store_short v[28:29], v0, off offset:32
	v_mul_f32_e32 v0, v21, v49
	v_mul_f32_e32 v0, v0, v25
	v_mul_f32_e32 v0, v0, v4
	v_cvt_pk_bf16_f32 v0, v0, v33
	s_waitcnt vmcnt(6)
	v_lshlrev_b32_e32 v8, 16, v8
	v_mul_f32_e32 v24, 0xbfb8aa3b, v8
	v_exp_f32_e32 v24, v24
	global_store_short v[28:29], v0, off offset:64
	v_mul_f32_e32 v0, v13, v49
	v_mul_f32_e32 v0, v0, v8
	v_add_f32_e32 v4, 1.0, v24
	v_rcp_f32_e32 v4, v4
	s_waitcnt vmcnt(6)
	v_lshlrev_b32_e32 v12, 16, v12
	v_mul_f32_e32 v13, 0xbfb8aa3b, v12
	v_exp_f32_e32 v13, v13
	v_mul_f32_e32 v0, v0, v4
	v_cvt_pk_bf16_f32 v0, v0, v33
	v_add_f32_e32 v4, 1.0, v13
	v_rcp_f32_e32 v4, v4
	global_store_short v[28:29], v0, off offset:96
	v_mul_f32_e32 v0, v9, v49
	v_mul_f32_e32 v0, v0, v12
	s_waitcnt vmcnt(6)
	v_lshlrev_b32_e32 v9, 16, v16
	v_mul_f32_e32 v12, 0xbfb8aa3b, v9
	v_exp_f32_e32 v12, v12
	v_mul_f32_e32 v0, v0, v4
	v_cvt_pk_bf16_f32 v0, v0, v33
	v_add_f32_e32 v4, 1.0, v12
	v_rcp_f32_e32 v4, v4
	global_store_short v[28:29], v0, off offset:128
	v_mul_f32_e32 v0, v5, v49
	v_mul_f32_e32 v0, v0, v9
	s_waitcnt vmcnt(6)
	v_lshlrev_b32_e32 v12, 16, v20
	v_mul_f32_e32 v8, 0xbfb8aa3b, v12
	v_exp_f32_e32 v8, v8
	v_mul_f32_e32 v0, v0, v4
	v_cvt_pk_bf16_f32 v13, v0, v33
	v_add_u32_e32 v0, 2, v38
	v_mad_i64_i32 v[4:5], s[4:5], v0, s37, v[36:37]
	v_lshl_add_u64 v[4:5], v[4:5], 0, s[22:23]
	v_add_f32_e32 v16, 1.0, v8
	v_lshl_add_u64 v[4:5], v[4:5], 0, v[34:35]
	v_add_co_u32_e32 v8, vcc, s39, v4
	v_rcp_f32_e32 v21, v16
	s_nop 0
	v_addc_co_u32_e32 v9, vcc, 0, v5, vcc
	global_load_ushort v24, v[8:9], off offset:3072
	v_mul_f32_e32 v1, v1, v12
	v_mov_b32_e32 v8, v21
	v_mul_f32_e32 v1, v1, v8
	v_cvt_pk_bf16_f32 v1, v1, v33
	global_store_short v[28:29], v1, off offset:192
	s_waitcnt vmcnt(7)
	v_lshlrev_b32_e32 v1, 16, v39
	v_mul_f32_e32 v8, 0xbfb8aa3b, v1
	global_store_short v[28:29], v13, off offset:160
	v_exp_f32_e32 v12, v8
	v_mul_f32_e32 v13, v26, v26
	v_mov_b32_e32 v8, v22
	v_mov_b32_e32 v9, v14
	v_fmac_f32_e32 v13, v30, v30
	v_pk_mul_f32 v[8:9], v[8:9], v[8:9]
	v_lshl_add_u64 v[4:5], v[4:5], 0, s[40:41]
	v_add_f32_e32 v8, v13, v8
	global_load_ushort v16, v[4:5], off offset:32
	global_load_ushort v21, v[4:5], off offset:64
	v_add_f32_e32 v13, v8, v9
	v_mov_b32_e32 v8, v10
	v_mov_b32_e32 v9, v6
	v_pk_mul_f32 v[8:9], v[8:9], v[8:9]
	v_add_f32_e32 v12, 1.0, v12
	v_add_f32_e32 v8, v13, v8
	v_add_f32_e32 v13, v8, v9
	v_mov_b32_e32 v8, v2
	v_mov_b32_e32 v9, v18
	v_pk_mul_f32 v[8:9], v[8:9], v[8:9]
	v_mul_f32_e32 v1, v17, v1
	v_add_f32_e32 v8, v13, v8
	v_add_f32_e32 v8, v8, v9
	ds_bpermute_b32 v9, v32, v8
	v_rcp_f32_e32 v12, v12
	s_waitcnt lgkmcnt(0)
	v_add_f32_e32 v8, v8, v9
	ds_bpermute_b32 v9, v44, v8
	s_waitcnt lgkmcnt(0)
	v_add_f32_e32 v8, v8, v9
	ds_bpermute_b32 v9, v45, v8
	s_waitcnt lgkmcnt(0)
	v_add_f32_e32 v8, v8, v9
	ds_bpermute_b32 v9, v46, v8
	v_mul_f32_e32 v1, v1, v12
	v_cvt_pk_bf16_f32 v1, v1, v33
	s_waitcnt lgkmcnt(0)
	v_add_f32_e32 v8, v8, v9
	v_fmamk_f32 v8, v8, 0x3c000000, v50
	v_mul_f32_e32 v9, 0x4b800000, v8
	v_cmp_gt_f32_e32 vcc, s60, v8
	global_store_short v[28:29], v1, off offset:224
	s_nop 0
	v_cndmask_b32_e32 v8, v8, v9, vcc
	global_load_ushort v9, v[4:5], off offset:96
	global_load_ushort v12, v[4:5], off offset:128
	global_load_ushort v13, v[4:5], off offset:160
	global_load_ushort v17, v[4:5], off offset:192
	s_nop 0
	global_load_ushort v5, v[4:5], off offset:224
	v_rsq_f32_e32 v8, v8
	s_waitcnt vmcnt(10)
	v_lshlrev_b32_e32 v4, 16, v24
	v_mul_f32_e32 v20, 0xbfb8aa3b, v4
	v_exp_f32_e32 v20, v20
	v_mul_f32_e32 v1, 0x45800000, v8
	v_cndmask_b32_e32 v24, v8, v1, vcc
	v_mul_f32_e32 v28, v30, v24
	v_add_f32_e32 v8, 1.0, v20
	v_rcp_f32_e32 v8, v8
	v_mul_f32_e32 v4, v28, v4
	v_ashrrev_i32_e32 v1, 31, v0
	v_lshlrev_b64 v[0:1], 12, v[0:1]
	v_mul_f32_e32 v4, v8, v4
	v_lshl_add_u64 v[0:1], s[2:3], 0, v[0:1]
	v_cvt_pk_bf16_f32 v4, v4, v33
	s_waitcnt vmcnt(7)
; __device__ __forceinline__ float bf2f(unsigned short b) { return __uint_as_float(((unsigned)b) << 16); }
; __device__ __forceinline__ unsigned short f2bf(float f) { return (unsigned short)(cvt_pk_bf16(f, 0.f) & 0xffffu); }
; __device__ __forceinline__ float sigmoidf_(float x) { return 1.f / (1.f + __expf(-x)); }
; __device__ __forceinline__ void retout_item(PRef p, int layer, int item, unsigned char* shm) {
;     ...
; #pragma unroll
;     for (int r = 0; r < 4; ++r) { float ss = 0.f;
; #pragma unroll
;         for (int et = 0; et < 8; ++et) ss += acc[et][r] * acc[et][r];
;         ss += __shfl_xor(ss, 1); ss += __shfl_xor(ss, 2); ss += __shfl_xor(ss, 4); ss += __shfl_xor(ss, 8);
;         const float rinv = rsqrtf(ss * (1.f / 128.f) + 1e-6f);
;         const size_t row = (size_t)(row0 + 16 * wave + fq * 4 + r);
; #pragma unroll
;         for (int et = 0; et < 8; ++et) { const int e = 16 * et + fr; const float gg = bf2f(A[row * NIN + C_G + h * 128 + e]);
;             MIX[row * 2048 + 512 + h * 128 + e] = f2bf(acc[et][r] * rinv * gg * sigmoidf_(gg)); } }
	v_lshlrev_b32_e32 v16, 16, v16
	v_mul_f32_e32 v20, 0xbfb8aa3b, v16
	v_exp_f32_e32 v20, v20
	v_lshl_add_u64 v[0:1], v[0:1], 0, v[34:35]
	global_store_short v[0:1], v4, off
	v_mul_f32_e32 v4, v26, v24
	v_add_f32_e32 v8, 1.0, v20
	v_rcp_f32_e32 v8, v8
	v_mul_f32_e32 v4, v4, v16
	v_mul_f32_e32 v2, v2, v24
	s_waitcnt vmcnt(7)
	v_lshlrev_b32_e32 v20, 16, v21
	v_mul_f32_e32 v21, 0xbfb8aa3b, v20
	v_exp_f32_e32 v21, v21
	v_mul_f32_e32 v4, v4, v8
	v_add_f32_e32 v8, 1.0, v21
	v_rcp_f32_e32 v8, v8
	v_cvt_pk_bf16_f32 v4, v4, v33
	global_store_short v[0:1], v4, off offset:32
	v_mul_f32_e32 v4, v22, v24
	v_mul_f32_e32 v4, v4, v20
	s_waitcnt vmcnt(6)
	v_lshlrev_b32_e32 v9, 16, v9
	v_mul_f32_e32 v20, 0xbfb8aa3b, v9
	v_exp_f32_e32 v20, v20
	v_mul_f32_e32 v4, v4, v8
	v_cvt_pk_bf16_f32 v4, v4, v33
	global_store_short v[0:1], v4, off offset:64
	v_add_f32_e32 v8, 1.0, v20
	v_rcp_f32_e32 v8, v8
	v_mul_f32_e32 v4, v14, v24
	v_mul_f32_e32 v4, v4, v9
	s_waitcnt vmcnt(6)
	v_lshlrev_b32_e32 v12, 16, v12
	v_mul_f32_e32 v14, 0xbfb8aa3b, v12
	v_exp_f32_e32 v14, v14
	v_mul_f32_e32 v4, v4, v8
	v_cvt_pk_bf16_f32 v4, v4, v33
	v_add_f32_e32 v8, 1.0, v14
	v_rcp_f32_e32 v8, v8
	global_store_short v[0:1], v4, off offset:96
	v_mul_f32_e32 v4, v10, v24
	v_mul_f32_e32 v4, v4, v12
	s_waitcnt vmcnt(6)
	v_lshlrev_b32_e32 v10, 16, v13
	v_mul_f32_e32 v12, 0xbfb8aa3b, v10
	v_exp_f32_e32 v12, v12
	v_mul_f32_e32 v4, v4, v8
	v_cvt_pk_bf16_f32 v4, v4, v33
	v_add_f32_e32 v8, 1.0, v12
	v_rcp_f32_e32 v12, v8
	global_store_short v[0:1], v4, off offset:128
	v_mul_f32_e32 v4, v6, v24
	v_mul_f32_e32 v4, v4, v10
	s_waitcnt vmcnt(6)
	v_lshlrev_b32_e32 v10, 16, v17
	v_mul_f32_e32 v9, 0xbfb8aa3b, v10
	v_exp_f32_e32 v9, v9
	v_mov_b32_e32 v6, v12
	v_mul_f32_e32 v4, v4, v6
	v_cvt_pk_bf16_f32 v6, v4, v33
	v_add_u32_e32 v4, 3, v38
	v_add_f32_e32 v14, 1.0, v9
	v_mad_i64_i32 v[8:9], s[4:5], v4, s37, v[36:37]
	v_lshl_add_u64 v[8:9], v[8:9], 0, s[22:23]
	v_lshl_add_u64 v[8:9], v[8:9], 0, v[34:35]
	v_add_co_u32_e32 v12, vcc, s39, v8
	global_store_short v[0:1], v6, off offset:160
	s_nop 0
	v_addc_co_u32_e32 v13, vcc, 0, v9, vcc
	global_load_ushort v16, v[12:13], off offset:3072
	v_rcp_f32_e32 v6, v14
	v_mul_f32_e32 v2, v2, v10
	s_waitcnt vmcnt(7)
	v_lshlrev_b32_e32 v5, 16, v5
	v_lshl_add_u64 v[8:9], v[8:9], 0, s[40:41]
	v_mul_f32_e32 v2, v2, v6
	v_mul_f32_e32 v6, 0xbfb8aa3b, v5
	v_exp_f32_e32 v20, v6
	v_mul_f32_e32 v6, v27, v27
	v_mov_b32_e32 v14, v23
	v_fmac_f32_e32 v6, v31, v31
	global_load_ushort v17, v[8:9], off offset:32
	v_fma_f32 v6, v14, v14, v6
	v_fma_f32 v14, v15, v15, v6
	v_mov_b32_e32 v6, v11
	v_mul_f32_e32 v10, v18, v24
	v_fma_f32 v6, v6, v6, v14
	v_mov_b32_e32 v18, v3
	v_fma_f32 v6, v7, v7, v6
	v_cvt_pk_bf16_f32 v2, v2, v33
	global_store_short v[0:1], v2, off offset:192
	v_fma_f32 v6, v18, v18, v6
	v_fma_f32 v6, v19, v19, v6
	ds_bpermute_b32 v12, v32, v6
	v_add_f32_e32 v13, 1.0, v20
	v_rcp_f32_e32 v18, v13
	s_waitcnt lgkmcnt(0)
	v_add_f32_e32 v6, v6, v12
	ds_bpermute_b32 v12, v44, v6
	global_load_ushort v20, v[8:9], off offset:64
	v_mul_f32_e32 v2, v10, v5
	s_waitcnt lgkmcnt(0)
	v_add_f32_e32 v5, v6, v12
	ds_bpermute_b32 v6, v45, v5
	s_waitcnt lgkmcnt(0)
	v_add_f32_e32 v5, v5, v6
	ds_bpermute_b32 v6, v46, v5
	v_mov_b32_e32 v10, v18
	s_waitcnt lgkmcnt(0)
	v_add_f32_e32 v5, v5, v6
	v_fmamk_f32 v5, v5, 0x3c000000, v50
	v_mul_f32_e32 v6, 0x4b800000, v5
	v_cmp_gt_f32_e32 vcc, s60, v5
	v_mul_f32_e32 v2, v2, v10
	v_cvt_pk_bf16_f32 v2, v2, v33
	global_store_short v[0:1], v2, off offset:224
	v_cndmask_b32_e32 v5, v5, v6, vcc
	global_load_ushort v6, v[8:9], off offset:96
	global_load_ushort v2, v[8:9], off offset:128
	global_load_ushort v10, v[8:9], off offset:160
	global_load_ushort v12, v[8:9], off offset:192
	s_nop 0
	global_load_ushort v8, v[8:9], off offset:224
	v_rsq_f32_e32 v5, v5
	s_waitcnt vmcnt(9)
	v_lshlrev_b32_e32 v9, 16, v16
	v_mul_f32_e32 v1, 0xbfb8aa3b, v9
	v_exp_f32_e32 v13, v1
	v_mul_f32_e32 v0, 0x45800000, v5
	v_cndmask_b32_e32 v14, v5, v0, vcc
	v_ashrrev_i32_e32 v5, 31, v4
	v_lshlrev_b64 v[0:1], 12, v[4:5]
	v_add_f32_e32 v4, 1.0, v13
	v_rcp_f32_e32 v4, v4
	v_mul_f32_e32 v16, v31, v14
	v_mul_f32_e32 v9, v16, v9
	v_lshl_add_u64 v[0:1], s[2:3], 0, v[0:1]
	s_waitcnt vmcnt(8)
	v_lshlrev_b32_e32 v5, 16, v17
	v_mul_f32_e32 v13, 0xbfb8aa3b, v5
	v_exp_f32_e32 v13, v13
	v_mul_f32_e32 v4, v4, v9
	v_cvt_pk_bf16_f32 v4, v4, v33
	v_lshl_add_u64 v[0:1], v[0:1], 0, v[34:35]
	v_add_f32_e32 v9, 1.0, v13
	global_store_short v[0:1], v4, off
	v_mul_f32_e32 v4, v27, v14
	v_mul_f32_e32 v4, v4, v5
	s_waitcnt vmcnt(7)
	v_lshlrev_b32_e32 v13, 16, v20
	v_mul_f32_e32 v16, 0xbfb8aa3b, v13
	v_exp_f32_e32 v16, v16
	v_rcp_f32_e32 v5, v9
	s_nop 0
	v_mul_f32_e32 v4, v4, v5
	v_cvt_pk_bf16_f32 v4, v4, v33
	v_add_f32_e32 v5, 1.0, v16
	v_rcp_f32_e32 v5, v5
	global_store_short v[0:1], v4, off offset:32
	v_mul_f32_e32 v4, v23, v14
	v_mul_f32_e32 v4, v4, v13
	s_waitcnt vmcnt(6)
	v_lshlrev_b32_e32 v6, 16, v6
	v_mul_f32_e32 v13, 0xbfb8aa3b, v6
	v_exp_f32_e32 v13, v13
	v_mul_f32_e32 v4, v4, v5
	v_cvt_pk_bf16_f32 v4, v4, v33
	global_store_short v[0:1], v4, off offset:64
	v_add_f32_e32 v5, 1.0, v13
	v_rcp_f32_e32 v5, v5
	v_mul_f32_e32 v4, v15, v14
	v_mul_f32_e32 v4, v4, v6
	s_waitcnt vmcnt(6)
	v_lshlrev_b32_e32 v2, 16, v2
	v_mul_f32_e32 v9, 0xbfb8aa3b, v2
	v_exp_f32_e32 v9, v9
	v_mul_f32_e32 v4, v4, v5
	v_add_f32_e32 v5, 1.0, v9
	v_cvt_pk_bf16_f32 v4, v4, v33
	global_store_short v[0:1], v4, off offset:96
	v_mul_f32_e32 v4, v11, v14
	v_mul_f32_e32 v2, v4, v2
	s_waitcnt vmcnt(6)
	v_lshlrev_b32_e32 v6, 16, v10
	v_mul_f32_e32 v9, 0xbfb8aa3b, v6
	v_exp_f32_e32 v9, v9
	v_rcp_f32_e32 v4, v5
	s_nop 0
	v_mul_f32_e32 v2, v2, v4
	v_cvt_pk_bf16_f32 v2, v2, v33
	v_add_f32_e32 v4, 1.0, v9
	v_rcp_f32_e32 v4, v4
	global_store_short v[0:1], v2, off offset:128
	v_mul_f32_e32 v2, v7, v14
	v_mul_f32_e32 v2, v2, v6
	s_waitcnt vmcnt(6)
	v_lshlrev_b32_e32 v6, 16, v12
	v_mul_f32_e32 v7, 0xbfb8aa3b, v6
	v_exp_f32_e32 v7, v7
	v_mul_f32_e32 v2, v2, v4
	v_cvt_pk_bf16_f32 v2, v2, v33
	v_add_f32_e32 v4, 1.0, v7
	v_rcp_f32_e32 v7, v4
	global_store_short v[0:1], v2, off offset:160
	v_mul_f32_e32 v2, v3, v14
	v_mul_f32_e32 v2, v2, v6
	s_waitcnt vmcnt(6)
	v_lshlrev_b32_e32 v5, 16, v8
	v_mul_f32_e32 v6, 0xbfb8aa3b, v5
	v_exp_f32_e32 v6, v6
	v_mov_b32_e32 v3, v7
	v_mul_f32_e32 v2, v2, v3
	v_cvt_pk_bf16_f32 v2, v2, v33
	v_add_f32_e32 v3, 1.0, v6
	v_rcp_f32_e32 v3, v3
	global_store_short v[0:1], v2, off offset:192
	v_mul_f32_e32 v2, v19, v14
	v_mul_f32_e32 v2, v2, v5
	v_mul_f32_e32 v2, v2, v3
	s_mov_b64 s[2:3], 0
	v_cvt_pk_bf16_f32 v2, v2, v33
	global_store_short v[0:1], v2, off offset:224
	s_barrier

; __device__ __forceinline__ unsigned cvt_pk_bf16(float lo, float hi) { unsigned r; asm("v_cvt_pk_bf16_f32 %0, %1, %2" : "=v"(r) : "v"(lo), "v"(hi)); return r; }
; __device__ __forceinline__ void s5out_item(PRef p, int layer, int item, unsigned char* shm) {
;     ...
; #pragma unroll 4
;         for (int kk = 0; kk < 32; ++kk) {
;             const bf16x8 bfr = *(const bf16x8*)(ul + fr * S5_UP + kk * 64 + fq * 16);
;             const int sq = 2 * kk + (fq >> 1);
; #pragma unroll
;             for (int mi = 0; mi < 4; ++mi) { const bf16x8 af = *(const bf16x8*)(KT + (tb + mi - sq + 63) * 256 + fr * 16 + (fq & 1) * 8);
;                 acc[mi] = __builtin_amdgcn_mfma_f32_16x16x32_bf16(af, bfr, acc[mi], 0, 0, 0); } }
;         const int cidx = nt < 4 ? 4 + 16 * nt + fr : (fr & 3);
; #pragma unroll
;         for (int dir = 0; dir < 2; ++dir) {
;             const bf16_t* G = (const bf16_t*)(p.ws + O_S5G) + (size_t)(dir * 32 + g) * 1024 * 128;
;             const float* ST = (const float*)(p.ws + O_S5ST) + (size_t)((g * 2 + dir) * 4 + b) * 68 * 128 + (size_t)cidx * 128;
; #pragma unroll
;             for (int kk = 0; kk < 4; ++kk) {
;                 const f32x4 x0 = *(const f32x4*)(ST + kk * 32 + fq * 8), x1 = *(const f32x4*)(ST + kk * 32 + fq * 8 + 4);
;                 u32x4 w; w.x = cvt_pk_bf16(x0[0], x0[1]); w.y = cvt_pk_bf16(x0[2], x0[3]); w.z = cvt_pk_bf16(x1[0], x1[1]); w.w = cvt_pk_bf16(x1[2], x1[3]);
;                 const bf16x8 bfr = mk8(w);
; #pragma unroll
;                 for (int mi = 0; mi < 4; ++mi) { const bf16x8 af = *(const bf16x8*)(G + (size_t)((tb + mi) * 16 + fr) * 128 + kk * 32 + fq * 8);
;                     acc[mi] = __builtin_amdgcn_mfma_f32_16x16x32_bf16(af, bfr, acc[mi], 0, 0, 0); } } }
.LBB0_417:
	v_add_u32_e32 v43, s50, v81
	ds_read_b128 v[44:47], v42
	ds_read_b128 v[90:93], v42 offset:64
	ds_read_b128 v[94:97], v43 offset:32256
	ds_read_b128 v[98:101], v43 offset:32768
	ds_read_b128 v[102:105], v43 offset:31744
	ds_read_b128 v[106:109], v43 offset:33280
	s_waitcnt lgkmcnt(3)
	v_mfma_f32_16x16x32_bf16 v[16:19], v[94:97], v[44:47], v[16:19]
	s_addk_i32 s50, 0xf000
	s_cmpk_eq_i32 s50, 0x8000
	s_waitcnt lgkmcnt(2)
	v_mfma_f32_16x16x32_bf16 v[12:15], v[98:101], v[44:47], v[12:15]
	s_waitcnt lgkmcnt(0)
	v_mfma_f32_16x16x32_bf16 v[8:11], v[106:109], v[44:47], v[8:11]
	ds_read_b128 v[106:109], v43 offset:33792
	ds_read_b128 v[110:113], v43 offset:29184
	s_waitcnt lgkmcnt(1)
	v_mfma_f32_16x16x32_bf16 v[4:7], v[106:109], v[44:47], v[4:7]
	ds_read_b128 v[44:47], v43 offset:31232
	ds_read_b128 v[106:109], v43 offset:30720
	s_waitcnt lgkmcnt(1)
	v_mfma_f32_16x16x32_bf16 v[16:19], v[44:47], v[90:93], v[16:19]
	v_mfma_f32_16x16x32_bf16 v[12:15], v[102:105], v[90:93], v[12:15]
	v_mfma_f32_16x16x32_bf16 v[8:11], v[94:97], v[90:93], v[8:11]
	ds_read_b128 v[94:97], v42 offset:128
	ds_read_b128 v[114:117], v42 offset:192
	v_add_u32_e32 v42, 0x100, v42
	v_mfma_f32_16x16x32_bf16 v[4:7], v[98:101], v[90:93], v[4:7]
	ds_read_b128 v[90:93], v43 offset:30208
	ds_read_b128 v[98:101], v43 offset:29696
	s_waitcnt lgkmcnt(1)
	v_mfma_f32_16x16x32_bf16 v[16:19], v[90:93], v[94:97], v[16:19]
	v_mfma_f32_16x16x32_bf16 v[12:15], v[106:109], v[94:97], v[12:15]
	v_mfma_f32_16x16x32_bf16 v[8:11], v[44:47], v[94:97], v[8:11]
	v_mfma_f32_16x16x32_bf16 v[4:7], v[102:105], v[94:97], v[4:7]
	v_mfma_f32_16x16x32_bf16 v[16:19], v[110:113], v[114:117], v[16:19]
	s_waitcnt lgkmcnt(0)
	v_mfma_f32_16x16x32_bf16 v[12:15], v[98:101], v[114:117], v[12:15]
	v_mfma_f32_16x16x32_bf16 v[8:11], v[90:93], v[114:117], v[8:11]
	v_mfma_f32_16x16x32_bf16 v[4:7], v[106:109], v[114:117], v[4:7]
	s_cbranch_scc0 .LBB0_417
	v_lshl_add_u32 v42, s22, 4, v73
	v_cndmask_b32_e64 v42, v74, v42, s[4:5]
	v_mov_b32_e32 v43, v33
	v_lshlrev_b64 v[42:43], 9, v[42:43]
	v_lshl_add_u64 v[130:131], v[20:21], 0, v[42:43]
	v_lshl_add_u64 v[132:133], v[130:131], 0, s[46:47]
	global_load_dwordx4 v[42:45], v[24:25], off
	global_load_dwordx4 v[46:49], v[132:133], off
	global_load_dwordx4 v[90:93], v[132:133], off offset:16
	global_load_dwordx4 v[94:97], v[26:27], off
	global_load_dwordx4 v[98:101], v[28:29], off
	global_load_dwordx4 v[102:105], v[30:31], off
	global_load_dwordx4 v[106:109], v[132:133], off offset:128
	global_load_dwordx4 v[110:113], v[24:25], off offset:64
	global_load_dwordx4 v[114:117], v[132:133], off offset:144
	global_load_dwordx4 v[118:121], v[26:27], off offset:64
	s_or_b64 s[68:69], s[4:5], s[2:3]
	s_waitcnt vmcnt(8)
	v_cvt_pk_bf16_f32 v46, v46, v47
	v_cvt_pk_bf16_f32 v47, v48, v49
	s_waitcnt vmcnt(7)
	v_cvt_pk_bf16_f32 v48, v90, v91
	v_cvt_pk_bf16_f32 v49, v92, v93
	s_waitcnt vmcnt(3)
	v_cvt_pk_bf16_f32 v106, v106, v107
	v_mfma_f32_16x16x32_bf16 v[16:19], v[42:45], v[46:49], v[16:19]
	global_load_dwordx4 v[42:45], v[28:29], off offset:64
	v_cvt_pk_bf16_f32 v107, v108, v109
	s_waitcnt vmcnt(2)
	v_cvt_pk_bf16_f32 v108, v114, v115
	v_mfma_f32_16x16x32_bf16 v[12:15], v[94:97], v[46:49], v[12:15]
	global_load_dwordx4 v[90:93], v[30:31], off offset:64
	global_load_dwordx4 v[94:97], v[132:133], off offset:256
	global_load_dwordx4 v[122:125], v[24:25], off offset:128
	v_cvt_pk_bf16_f32 v109, v116, v117
	s_waitcnt vmcnt(1)
	v_cvt_pk_bf16_f32 v94, v94, v95
	v_mfma_f32_16x16x32_bf16 v[8:11], v[98:101], v[46:49], v[8:11]
	global_load_dwordx4 v[98:101], v[132:133], off offset:272
	global_load_dwordx4 v[126:129], v[26:27], off offset:128
	v_cvt_pk_bf16_f32 v95, v96, v97
	s_waitcnt vmcnt(1)
	v_cvt_pk_bf16_f32 v96, v98, v99
	v_mfma_f32_16x16x32_bf16 v[4:7], v[102:105], v[46:49], v[4:7]
	global_load_dwordx4 v[46:49], v[28:29], off offset:128
	v_cvt_pk_bf16_f32 v97, v100, v101
	v_mfma_f32_16x16x32_bf16 v[16:19], v[110:113], v[106:109], v[16:19]
	global_load_dwordx4 v[102:105], v[30:31], off offset:128
	global_load_dwordx4 v[110:113], v[132:133], off offset:400
	global_load_dwordx4 v[114:117], v[132:133], off offset:384
	s_waitcnt vmcnt(0)
	v_cvt_pk_bf16_f32 v114, v114, v115
	v_mfma_f32_16x16x32_bf16 v[12:15], v[118:121], v[106:109], v[12:15]
	v_cvt_pk_bf16_f32 v115, v116, v117
	v_cvt_pk_bf16_f32 v116, v110, v111
	v_cvt_pk_bf16_f32 v117, v112, v113
	v_mfma_f32_16x16x32_bf16 v[8:11], v[42:45], v[106:109], v[8:11]
	global_load_dwordx4 v[42:45], v[24:25], off offset:192
	global_load_dwordx4 v[118:121], v[26:27], off offset:192
	v_mfma_f32_16x16x32_bf16 v[4:7], v[90:93], v[106:109], v[4:7]
	global_load_dwordx4 v[90:93], v[28:29], off offset:192
	global_load_dwordx4 v[98:101], v[30:31], off offset:192
	v_mfma_f32_16x16x32_bf16 v[12:15], v[126:129], v[94:97], v[12:15]
	v_lshl_add_u64 v[126:127], v[130:131], 0, s[48:49]
	v_mfma_f32_16x16x32_bf16 v[16:19], v[122:125], v[94:97], v[16:19]
	global_load_dwordx4 v[106:109], v[126:127], off
	global_load_dwordx4 v[122:125], v[34:35], off
	s_waitcnt vmcnt(1)
	v_cvt_pk_bf16_f32 v106, v106, v107
	v_mfma_f32_16x16x32_bf16 v[8:11], v[46:49], v[94:97], v[8:11]
	global_load_dwordx4 v[46:49], v[126:127], off offset:16
	v_cvt_pk_bf16_f32 v107, v108, v109
	v_mfma_f32_16x16x32_bf16 v[16:19], v[42:45], v[114:117], v[16:19]
	global_load_dwordx4 v[42:45], v[36:37], off
	s_waitcnt vmcnt(1)
; __device__ __forceinline__ unsigned cvt_pk_bf16(float lo, float hi) { unsigned r; asm("v_cvt_pk_bf16_f32 %0, %1, %2" : "=v"(r) : "v"(lo), "v"(hi)); return r; }
; __device__ __forceinline__ float bflo(unsigned w) { return __uint_as_float(w << 16); }
; __device__ __forceinline__ float bfhi(unsigned w) { return __uint_as_float(w & 0xffff0000u); }
; __device__ __forceinline__ float gelu_tanh(float x) { const float u = 0.7978845608028654f * (x + 0.044715f * x * x * x); return x / (1.f + __expf(-2.f * u)); }
; __device__ __forceinline__ void s5out_item(PRef p, int layer, int item, unsigned char* shm) {
;     ...
;         if (nt < 4 || fr < 4) {
; #pragma unroll
;             for (int mi = 0; mi < 4; ++mi) { const int t = tb + mi; const size_t row = nt < 4 ? (size_t)(b * 4096 + (16 * nt + fr) * 64 + t) : (size_t)(RL + b * 256 + fr * 64 + t);
;                 const u32x2 uu = *(const u32x2*)(ul + fr * S5_UP + t * 32 + fq * 8);
;                 const f32x4 y = acc[mi];
;                 u32x2 w; w.x = cvt_pk_bf16(gelu_tanh(y[0] + dv[0] * bflo(uu.x)), gelu_tanh(y[1] + dv[1] * bfhi(uu.x)));
;                 w.y = cvt_pk_bf16(gelu_tanh(y[2] + dv[2] * bflo(uu.y)), gelu_tanh(y[3] + dv[3] * bfhi(uu.y)));
;                 *(u32x2*)(Z + row * 512 + g * 16 + fq * 4) = w; } }
	v_cvt_pk_bf16_f32 v108, v46, v47
	v_cvt_pk_bf16_f32 v109, v48, v49
	v_mfma_f32_16x16x32_bf16 v[4:7], v[102:105], v[94:97], v[4:7]
	global_load_dwordx4 v[94:97], v[38:39], off
	global_load_dwordx4 v[102:105], v[40:41], off
	global_load_dwordx4 v[110:113], v[34:35], off offset:64
	v_mfma_f32_16x16x32_bf16 v[12:15], v[118:121], v[114:117], v[12:15]
	v_mfma_f32_16x16x32_bf16 v[8:11], v[90:93], v[114:117], v[8:11]
	global_load_dwordx4 v[90:93], v[126:127], off offset:144
	global_load_dwordx4 v[118:121], v[126:127], off offset:128
	global_load_dwordx4 v[46:49], v[36:37], off offset:64
	s_waitcnt vmcnt(1)
	v_cvt_pk_bf16_f32 v118, v118, v119
	v_mfma_f32_16x16x32_bf16 v[4:7], v[98:101], v[114:117], v[4:7]
	v_cvt_pk_bf16_f32 v119, v120, v121
	v_cvt_pk_bf16_f32 v120, v90, v91
	v_cvt_pk_bf16_f32 v121, v92, v93
	v_mfma_f32_16x16x32_bf16 v[16:19], v[122:125], v[106:109], v[16:19]
	v_mfma_f32_16x16x32_bf16 v[12:15], v[42:45], v[106:109], v[12:15]
	global_load_dwordx4 v[42:45], v[38:39], off offset:64
	global_load_dwordx4 v[98:101], v[40:41], off offset:64
	global_load_dwordx4 v[114:117], v[34:35], off offset:128
	v_mfma_f32_16x16x32_bf16 v[8:11], v[94:97], v[106:109], v[8:11]
	global_load_dwordx4 v[94:97], v[126:127], off offset:272
	global_load_dwordx4 v[122:125], v[126:127], off offset:256
	global_load_dwordx4 v[90:93], v[36:37], off offset:128
	s_waitcnt vmcnt(1)
	v_cvt_pk_bf16_f32 v122, v122, v123
	v_mfma_f32_16x16x32_bf16 v[4:7], v[102:105], v[106:109], v[4:7]
	v_cvt_pk_bf16_f32 v123, v124, v125
	v_cvt_pk_bf16_f32 v124, v94, v95
	v_cvt_pk_bf16_f32 v125, v96, v97
	v_mfma_f32_16x16x32_bf16 v[12:15], v[46:49], v[118:121], v[12:15]
	global_load_dwordx4 v[46:49], v[38:39], off offset:128
	global_load_dwordx4 v[102:105], v[40:41], off offset:128
	global_load_dwordx4 v[106:109], v[34:35], off offset:192
	v_mfma_f32_16x16x32_bf16 v[8:11], v[42:45], v[118:121], v[8:11]
	v_mfma_f32_16x16x32_bf16 v[16:19], v[110:113], v[118:121], v[16:19]
	global_load_dwordx4 v[42:45], v[126:127], off offset:400
	global_load_dwordx4 v[110:113], v[126:127], off offset:384
	global_load_dwordx4 v[94:97], v[36:37], off offset:192
	s_waitcnt vmcnt(6)
	v_mfma_f32_16x16x32_bf16 v[12:15], v[90:93], v[122:125], v[12:15]
	global_load_dwordx4 v[90:93], v[38:39], off offset:192
	s_waitcnt vmcnt(6)
	v_mfma_f32_16x16x32_bf16 v[8:11], v[46:49], v[122:125], v[8:11]
	global_load_dwordx4 v[46:49], v[40:41], off offset:192
	v_mfma_f32_16x16x32_bf16 v[4:7], v[98:101], v[118:121], v[4:7]
	s_waitcnt vmcnt(3)
	v_cvt_pk_bf16_f32 v98, v110, v111
	v_mfma_f32_16x16x32_bf16 v[16:19], v[114:117], v[122:125], v[16:19]
	v_cvt_pk_bf16_f32 v99, v112, v113
	v_cvt_pk_bf16_f32 v100, v42, v43
	v_cvt_pk_bf16_f32 v101, v44, v45
	v_mfma_f32_16x16x32_bf16 v[4:7], v[102:105], v[122:125], v[4:7]
	v_mfma_f32_16x16x32_bf16 v[16:19], v[106:109], v[98:101], v[16:19]
	s_waitcnt vmcnt(2)
	v_mfma_f32_16x16x32_bf16 v[12:15], v[94:97], v[98:101], v[12:15]
	s_waitcnt vmcnt(1)
	v_mfma_f32_16x16x32_bf16 v[8:11], v[90:93], v[98:101], v[8:11]
	s_waitcnt vmcnt(0)
	v_mfma_f32_16x16x32_bf16 v[4:7], v[46:49], v[98:101], v[4:7]
	s_and_saveexec_b64 s[50:51], s[68:69]
	s_cbranch_execz .LBB0_415
	ds_read_b64 v[42:43], v86 offset:65024
	ds_read_b64 v[44:45], v87 offset:65024
	ds_read_b64 v[48:49], v88 offset:65024
	ds_read_b64 v[46:47], v89 offset:65024
	s_waitcnt lgkmcnt(3)
	v_lshlrev_b32_e32 v90, 16, v42
	v_fma_f32 v16, v0, v90, v16
	v_mul_f32_e32 v90, 0x3d372713, v16
	v_mul_f32_e32 v90, v16, v90
	v_fma_f32 v90, v16, v90, v16
	v_mul_f32_e32 v90, 0x3f4c422a, v90
	v_mul_f32_e32 v90, -2.0, v90
	v_mul_f32_e32 v90, 0x3fb8aa3b, v90
	v_exp_f32_e32 v91, v90
	v_add_u32_e32 v90, s12, v76
	v_cndmask_b32_e64 v92, v75, v90, s[4:5]
	v_and_b32_e32 v42, 0xffff0000, v42
	v_add_f32_e32 v93, 1.0, v91
	v_rcp_f32_e32 v95, v93
	v_fma_f32 v17, v1, v42, v17
	v_mul_f32_e32 v42, 0x3d372713, v17
	v_mul_f32_e32 v42, v17, v42
	v_fma_f32 v42, v17, v42, v17
	v_mul_f32_e32 v42, 0x3f4c422a, v42
	v_mul_f32_e32 v42, -2.0, v42
	v_mul_f32_e32 v42, 0x3fb8aa3b, v42
	v_exp_f32_e32 v42, v42
	v_mul_f32_e32 v94, v16, v95
	v_lshlrev_b32_e32 v95, 16, v43
	v_fma_f32 v18, v2, v95, v18
	v_add_f32_e32 v42, 1.0, v42
	v_mul_f32_e32 v95, 0x3d372713, v18
	v_mul_f32_e32 v95, v18, v95
	v_rcp_f32_e32 v98, v42
	v_fma_f32 v95, v18, v95, v18
	v_mul_f32_e32 v95, 0x3f4c422a, v95
	v_mul_f32_e32 v95, -2.0, v95
	v_mul_f32_e32 v95, 0x3fb8aa3b, v95
	v_mov_b32_e32 v16, v94
	v_exp_f32_e32 v95, v95
	v_and_b32_e32 v43, 0xffff0000, v43
	v_fmac_f32_e32 v19, v3, v43
	v_mul_f32_e32 v43, 0x3d372713, v19
	v_add_f32_e32 v95, 1.0, v95
	v_mul_f32_e32 v43, v19, v43
	v_fma_f32 v43, v19, v43, v19
	v_rcp_f32_e32 v97, v95
	v_mul_f32_e32 v43, 0x3f4c422a, v43
	v_mul_f32_e32 v43, -2.0, v43
	v_mul_f32_e32 v43, 0x3fb8aa3b, v43
	v_mul_f32_e32 v17, v17, v98
	v_exp_f32_e32 v43, v43
	v_cvt_pk_bf16_f32 v16, v16, v17
	v_add_f32_e32 v43, 1.0, v43
	v_rcp_f32_e32 v94, v43
	v_mul_f32_e32 v17, v18, v97
	v_mul_f32_e32 v18, v19, v94
	s_waitcnt lgkmcnt(2)
; __device__ __forceinline__ unsigned cvt_pk_bf16(float lo, float hi) { unsigned r; asm("v_cvt_pk_bf16_f32 %0, %1, %2" : "=v"(r) : "v"(lo), "v"(hi)); return r; }
; __device__ __forceinline__ float bflo(unsigned w) { return __uint_as_float(w << 16); }
; __device__ __forceinline__ float bfhi(unsigned w) { return __uint_as_float(w & 0xffff0000u); }
; __device__ __forceinline__ float gelu_tanh(float x) { const float u = 0.7978845608028654f * (x + 0.044715f * x * x * x); return x / (1.f + __expf(-2.f * u)); }
; __device__ __forceinline__ void s5out_item(PRef p, int layer, int item, unsigned char* shm) {
;     ...
;         if (nt < 4 || fr < 4) {
; #pragma unroll
;             for (int mi = 0; mi < 4; ++mi) { const int t = tb + mi; const size_t row = nt < 4 ? (size_t)(b * 4096 + (16 * nt + fr) * 64 + t) : (size_t)(RL + b * 256 + fr * 64 + t);
;                 const u32x2 uu = *(const u32x2*)(ul + fr * S5_UP + t * 32 + fq * 8);
;                 const f32x4 y = acc[mi];
;                 u32x2 w; w.x = cvt_pk_bf16(gelu_tanh(y[0] + dv[0] * bflo(uu.x)), gelu_tanh(y[1] + dv[1] * bfhi(uu.x)));
;                 w.y = cvt_pk_bf16(gelu_tanh(y[2] + dv[2] * bflo(uu.y)), gelu_tanh(y[3] + dv[3] * bfhi(uu.y)));
;                 *(u32x2*)(Z + row * 512 + g * 16 + fq * 4) = w; } }
	v_lshlrev_b32_e32 v19, 16, v44
	v_fma_f32 v12, v0, v19, v12
	v_mul_f32_e32 v19, 0x3d372713, v12
	v_mul_f32_e32 v19, v12, v19
	v_fma_f32 v19, v12, v19, v12
	v_mul_f32_e32 v19, 0x3f4c422a, v19
	v_mul_f32_e32 v19, -2.0, v19
	v_mul_f32_e32 v19, 0x3fb8aa3b, v19
	v_exp_f32_e32 v42, v19
	v_and_b32_e32 v44, 0xffff0000, v44
	v_add_u32_e32 v90, v92, v63
	v_fma_f32 v13, v1, v44, v13
	v_add_f32_e32 v42, 1.0, v42
	v_ashrrev_i32_e32 v91, 31, v90
	v_mul_f32_e32 v44, 0x3d372713, v13
	v_cvt_pk_bf16_f32 v17, v17, v18
	v_lshlrev_b64 v[18:19], 10, v[90:91]
	v_rcp_f32_e32 v90, v42
	v_mul_f32_e32 v44, v13, v44
	v_fma_f32 v44, v13, v44, v13
	v_mul_f32_e32 v44, 0x3f4c422a, v44
	v_lshl_add_u64 v[18:19], v[22:23], 0, v[18:19]
	v_mul_f32_e32 v44, -2.0, v44
	global_store_dwordx2 v[18:19], v[16:17], off
	v_mul_f32_e32 v44, 0x3fb8aa3b, v44
	v_exp_f32_e32 v44, v44
	s_nop 0
	v_add_f32_e32 v43, 1.0, v44
	v_rcp_f32_e32 v91, v43
	v_mul_f32_e32 v12, v12, v90
	v_lshlrev_b32_e32 v42, 16, v45
	v_fma_f32 v14, v2, v42, v14
	v_mul_f32_e32 v42, 0x3d372713, v14
	v_mul_f32_e32 v42, v14, v42
	v_fma_f32 v42, v14, v42, v14
	v_mul_f32_e32 v42, 0x3f4c422a, v42
	v_mul_f32_e32 v42, -2.0, v42
	v_mul_f32_e32 v42, 0x3fb8aa3b, v42
	v_exp_f32_e32 v42, v42
	v_and_b32_e32 v19, 0xffff0000, v45
	v_fmac_f32_e32 v15, v3, v19
	v_mul_f32_e32 v19, 0x3d372713, v15
	v_add_f32_e32 v42, 1.0, v42
	v_mul_f32_e32 v19, v15, v19
	v_fma_f32 v19, v15, v19, v15
	v_rcp_f32_e32 v90, v42
	v_mul_f32_e32 v19, 0x3f4c422a, v19
	v_mul_f32_e32 v19, -2.0, v19
	v_mul_f32_e32 v19, 0x3fb8aa3b, v19
	v_mul_f32_e32 v13, v13, v91
	v_exp_f32_e32 v19, v19
	v_cvt_pk_bf16_f32 v12, v12, v13
	v_add_f32_e32 v19, 1.0, v19
	v_rcp_f32_e32 v44, v19
	v_mul_f32_e32 v13, v14, v90
	v_add_u32_e32 v16, v92, v77
	v_mul_f32_e32 v14, v15, v44
	s_waitcnt lgkmcnt(1)
	v_lshlrev_b32_e32 v15, 16, v48
	v_fma_f32 v8, v0, v15, v8
	v_mul_f32_e32 v15, 0x3d372713, v8
	v_mul_f32_e32 v15, v8, v15
	v_fma_f32 v15, v8, v15, v8
	v_mul_f32_e32 v15, 0x3f4c422a, v15
	v_mul_f32_e32 v15, -2.0, v15
	v_mul_f32_e32 v15, 0x3fb8aa3b, v15
	v_exp_f32_e32 v18, v15
	v_ashrrev_i32_e32 v17, 31, v16
	v_and_b32_e32 v19, 0xffff0000, v48
	v_cvt_pk_bf16_f32 v13, v13, v14
	v_lshlrev_b64 v[14:15], 10, v[16:17]
	v_add_f32_e32 v16, 1.0, v18
	v_fma_f32 v9, v1, v19, v9
	v_mul_f32_e32 v19, 0x3d372713, v9
	v_rcp_f32_e32 v18, v16
	v_mul_f32_e32 v19, v9, v19
	v_fma_f32 v19, v9, v19, v9
	v_mul_f32_e32 v19, 0x3f4c422a, v19
	v_lshl_add_u64 v[14:15], v[22:23], 0, v[14:15]
	v_mul_f32_e32 v19, -2.0, v19
	global_store_dwordx2 v[14:15], v[12:13], off
	v_mul_f32_e32 v19, 0x3fb8aa3b, v19
	v_exp_f32_e32 v19, v19
	s_nop 0
	v_add_f32_e32 v17, 1.0, v19
	v_rcp_f32_e32 v42, v17
	v_mul_f32_e32 v8, v8, v18
	v_lshlrev_b32_e32 v16, 16, v49
	v_fma_f32 v10, v2, v16, v10
	v_mul_f32_e32 v16, 0x3d372713, v10
	v_mul_f32_e32 v16, v10, v16
	v_fma_f32 v16, v10, v16, v10
	v_mul_f32_e32 v16, 0x3f4c422a, v16
	v_mul_f32_e32 v16, -2.0, v16
	v_mul_f32_e32 v16, 0x3fb8aa3b, v16
	v_exp_f32_e32 v16, v16
	v_and_b32_e32 v15, 0xffff0000, v49
	v_fmac_f32_e32 v11, v3, v15
	v_mul_f32_e32 v15, 0x3d372713, v11
	v_add_f32_e32 v16, 1.0, v16
	v_mul_f32_e32 v15, v11, v15
	v_fma_f32 v15, v11, v15, v11
	v_rcp_f32_e32 v19, v16
	v_mul_f32_e32 v15, 0x3f4c422a, v15
	v_mul_f32_e32 v15, -2.0, v15
	v_mul_f32_e32 v15, 0x3fb8aa3b, v15
	v_mul_f32_e32 v9, v9, v42
	v_exp_f32_e32 v15, v15
	v_cvt_pk_bf16_f32 v8, v8, v9
	v_add_f32_e32 v15, 1.0, v15
	v_rcp_f32_e32 v18, v15
	v_mul_f32_e32 v9, v10, v19
	v_add_u32_e32 v12, v92, v78
	v_mul_f32_e32 v10, v11, v18
	s_waitcnt lgkmcnt(0)
	v_lshlrev_b32_e32 v11, 16, v46
	v_fma_f32 v4, v0, v11, v4
	v_mul_f32_e32 v11, 0x3d372713, v4
	v_mul_f32_e32 v11, v4, v11
	v_fma_f32 v11, v4, v11, v4
	v_mul_f32_e32 v11, 0x3f4c422a, v11
	v_mul_f32_e32 v11, -2.0, v11
	v_mul_f32_e32 v11, 0x3fb8aa3b, v11
	v_exp_f32_e32 v14, v11
	v_ashrrev_i32_e32 v13, 31, v12
	v_and_b32_e32 v15, 0xffff0000, v46
	v_cvt_pk_bf16_f32 v9, v9, v10
	v_lshlrev_b64 v[10:11], 10, v[12:13]
	v_add_f32_e32 v12, 1.0, v14
	v_fma_f32 v5, v1, v15, v5
	v_mul_f32_e32 v15, 0x3d372713, v5
	v_rcp_f32_e32 v14, v12
	v_mul_f32_e32 v15, v5, v15
	v_fma_f32 v15, v5, v15, v5
	v_mul_f32_e32 v15, 0x3f4c422a, v15
	v_lshl_add_u64 v[10:11], v[22:23], 0, v[10:11]
	v_mul_f32_e32 v15, -2.0, v15
	global_store_dwordx2 v[10:11], v[8:9], off
	v_mul_f32_e32 v15, 0x3fb8aa3b, v15
	v_exp_f32_e32 v15, v15
	s_nop 0
	v_add_f32_e32 v13, 1.0, v15
	v_rcp_f32_e32 v16, v13
	v_mul_f32_e32 v4, v4, v14
	v_lshlrev_b32_e32 v12, 16, v47
	v_fma_f32 v6, v2, v12, v6
	v_mul_f32_e32 v12, 0x3d372713, v6
	v_mul_f32_e32 v12, v6, v12
	v_fma_f32 v12, v6, v12, v6
	v_mul_f32_e32 v12, 0x3f4c422a, v12
	v_mul_f32_e32 v12, -2.0, v12
	v_mul_f32_e32 v12, 0x3fb8aa3b, v12
	v_exp_f32_e32 v12, v12
	v_and_b32_e32 v11, 0xffff0000, v47
	v_fmac_f32_e32 v7, v3, v11
	v_mul_f32_e32 v11, 0x3d372713, v7
	v_add_f32_e32 v12, 1.0, v12
	v_mul_f32_e32 v11, v7, v11
	v_fma_f32 v11, v7, v11, v7
	v_rcp_f32_e32 v15, v12
	v_mul_f32_e32 v11, 0x3f4c422a, v11
	v_mul_f32_e32 v11, -2.0, v11
	v_mul_f32_e32 v11, 0x3fb8aa3b, v11
	v_mul_f32_e32 v5, v5, v16
	v_exp_f32_e32 v11, v11
	v_cvt_pk_bf16_f32 v4, v4, v5
	v_add_f32_e32 v11, 1.0, v11
	v_rcp_f32_e32 v14, v11
	v_mul_f32_e32 v5, v6, v15
	v_add_u32_e32 v8, v92, v79
	v_ashrrev_i32_e32 v9, 31, v8
	v_mul_f32_e32 v6, v7, v14
	v_cvt_pk_bf16_f32 v5, v5, v6
	v_lshlrev_b64 v[6:7], 10, v[8:9]
	v_lshl_add_u64 v[6:7], v[22:23], 0, v[6:7]
	global_store_dwordx2 v[6:7], v[4:5], off
	s_branch .LBB0_415

; #define PG8_STAGE(bufoff, gbase, voff) do { _Pragma("unroll") for (int _i = 0; _i < 2; ++_i) \
;         __builtin_amdgcn_global_load_lds((const unsigned*)((const char*)(gbase) + (size_t)_i * r64##voff + (voff)), (LAS unsigned*)(lds + (bufoff) + ldsw + _i * 8192), 16, 0, 0); } while (0)
; #define PG8_LDA(dst, b, h) do { _Pragma("unroll") for (int m = 0; m < 4; ++m) _Pragma("unroll") for (int k = 0; k < 2; ++k) dst[m][k] = *(const LAS bf16x8*)(lds + PG8_SA(b, h) + aoff + m * 2048 + k * 1024); } while (0)
; #define PG8_LDB(dst, b, h) do { _Pragma("unroll") for (int n = 0; n < 2; ++n) _Pragma("unroll") for (int k = 0; k < 2; ++k) dst[n][k] = *(const LAS bf16x8*)(lds + PG8_SB(b, h) + boff + n * 2048 + k * 1024); } while (0)
; #define PG8_MMA(ai, bj, At, Bt) do { __builtin_amdgcn_s_setprio(1); _Pragma("unroll") for (int m = 0; m < 4; ++m) _Pragma("unroll") for (int n = 0; n < 2; ++n) _Pragma("unroll") for (int k = 0; k < 2; ++k) \
;         acc[ai][bj][m][n] = __builtin_amdgcn_mfma_f32_16x16x32_bf16(Bt[n][k], At[m][k], acc[ai][bj][m][n], 0, 0, 0); __builtin_amdgcn_s_setprio(0); } while (0)
; #define PG8_WAIT_L(n) asm volatile("s_waitcnt lgkmcnt(" #n ")" ::: "memory")
; #define PG8_BAR __builtin_amdgcn_s_barrier()
; #define PG8_SCHED __builtin_amdgcn_sched_barrier(0)
; template <class Epi, class Sched>
; __device__ __forceinline__ void gemm_phase(LAS unsigned char* lds, const Gemm g, const Sched& S, const Epi& E) {
;     ...
;             PG8_LDB(B0, 0, 0); PG8_SCHED; PG8_LDA(At, 0, 0); PG8_STAGE(PG8_SA(1, 1), a1 + hstepA, voffA);
;             PG8_WAIT_L(8); PG8_BAR; PG8_WAIT_L(0); PG8_MMA(0, 0, At, B0); PG8_BAR; PG8_SCHED;
;             PG8_LDB(B1, 0, 1); PG8_STAGE(PG8_SB(0, 0), b2, voffB);
;             PG8_BAR; PG8_WAIT_L(0); PG8_MMA(0, 1, At, B1); PG8_BAR;
;             PG8_LDA(At, 0, 1); PG8_STAGE(PG8_SA(0, 0), a2, voffA);
;             PG8_BAR; PG8_WAIT_L(0); PG8_MMA(1, 0, At, B0); PG8_BAR; PG8_SCHED;
.LBB0_446:
	ds_read_b128 v[138:141], v147
	ds_read_b128 v[142:145], v147 offset:1024
	ds_read_b128 v[150:153], v147 offset:2048
	ds_read_b128 v[154:157], v147 offset:3072
	s_add_u32 s58, s6, 0xfffe0080
	s_addc_u32 s59, s7, -1
	s_cmp_eq_u32 s57, 4
	s_cselect_b32 s59, s12, s59
	s_cselect_b32 s58, s51, s58
	s_cselect_b32 s61, s49, s9
	s_cselect_b32 s60, s56, s8
	v_lshl_add_u64 v[190:191], s[6:7], 0, v[132:133]
	s_add_i32 m0, s33, 0xc000
	ds_read_b128 v[158:161], v148
	ds_read_b128 v[162:165], v148 offset:1024
	ds_read_b128 v[166:169], v148 offset:2048
	ds_read_b128 v[170:173], v148 offset:3072
	ds_read_b128 v[174:177], v148 offset:4096
	ds_read_b128 v[178:181], v148 offset:5120
	ds_read_b128 v[182:185], v148 offset:6144
	ds_read_b128 v[186:189], v148 offset:7168
	global_load_lds_dwordx4 v[190:191], off
	v_lshl_add_u64 v[190:191], v[190:191], 0, s[10:11]
	s_add_i32 m0, s33, 0xe000
	s_nop 0
	global_load_lds_dwordx4 v[190:191], off
	s_waitcnt lgkmcnt(8)
	s_barrier
	s_waitcnt lgkmcnt(0)
	s_setprio 1
	s_waitcnt lgkmcnt(0)
	v_mfma_f32_16x16x32_bf16 v[124:127], v[138:141], v[158:161], v[124:127]
	v_mfma_f32_16x16x32_bf16 v[120:123], v[150:153], v[158:161], v[120:123]
	v_mfma_f32_16x16x32_bf16 v[108:111], v[138:141], v[166:169], v[108:111]
	v_mfma_f32_16x16x32_bf16 v[104:107], v[150:153], v[166:169], v[104:107]
	v_mfma_f32_16x16x32_bf16 v[92:95], v[138:141], v[174:177], v[92:95]
	v_mfma_f32_16x16x32_bf16 v[88:91], v[150:153], v[174:177], v[88:91]
	v_mfma_f32_16x16x32_bf16 v[76:79], v[138:141], v[182:185], v[76:79]
	v_mfma_f32_16x16x32_bf16 v[72:75], v[150:153], v[182:185], v[72:75]
	v_mfma_f32_16x16x32_bf16 v[124:127], v[142:145], v[162:165], v[124:127]
	v_mfma_f32_16x16x32_bf16 v[120:123], v[154:157], v[162:165], v[120:123]
	v_mfma_f32_16x16x32_bf16 v[108:111], v[142:145], v[170:173], v[108:111]
	v_mfma_f32_16x16x32_bf16 v[104:107], v[154:157], v[170:173], v[104:107]
	v_mfma_f32_16x16x32_bf16 v[92:95], v[142:145], v[178:181], v[92:95]
	v_mfma_f32_16x16x32_bf16 v[88:91], v[154:157], v[178:181], v[88:91]
	v_mfma_f32_16x16x32_bf16 v[76:79], v[142:145], v[186:189], v[76:79]
	v_mfma_f32_16x16x32_bf16 v[72:75], v[154:157], v[186:189], v[72:75]
	s_setprio 0
	s_barrier
	v_lshl_add_u64 v[206:207], s[60:61], 0, v[128:129]
	s_add_i32 s60, s40, s31
	s_mov_b32 m0, s60
	ds_read_b128 v[190:193], v149
	ds_read_b128 v[194:197], v149 offset:1024
	ds_read_b128 v[198:201], v149 offset:2048
	ds_read_b128 v[202:205], v149 offset:3072
	global_load_lds_dwordx4 v[206:207], off
	v_lshl_add_u64 v[208:209], v[206:207], 0, s[10:11]
	s_add_i32 m0, s60, 0x2000
	s_nop 0
	global_load_lds_dwordx4 v[208:209], off
	s_barrier
	s_waitcnt lgkmcnt(0)
	s_setprio 1
	s_waitcnt lgkmcnt(0)
	v_mfma_f32_16x16x32_bf16 v[116:119], v[190:193], v[158:161], v[116:119]
	v_mfma_f32_16x16x32_bf16 v[112:115], v[198:201], v[158:161], v[112:115]
	v_mfma_f32_16x16x32_bf16 v[100:103], v[190:193], v[166:169], v[100:103]
	v_mfma_f32_16x16x32_bf16 v[96:99], v[198:201], v[166:169], v[96:99]
	v_mfma_f32_16x16x32_bf16 v[84:87], v[190:193], v[174:177], v[84:87]
	v_mfma_f32_16x16x32_bf16 v[80:83], v[198:201], v[174:177], v[80:83]
	v_mfma_f32_16x16x32_bf16 v[68:71], v[190:193], v[182:185], v[68:71]
	v_mfma_f32_16x16x32_bf16 v[64:67], v[198:201], v[182:185], v[64:67]
	v_mfma_f32_16x16x32_bf16 v[116:119], v[194:197], v[162:165], v[116:119]
	v_mfma_f32_16x16x32_bf16 v[112:115], v[202:205], v[162:165], v[112:115]
	v_mfma_f32_16x16x32_bf16 v[100:103], v[194:197], v[170:173], v[100:103]
	v_mfma_f32_16x16x32_bf16 v[96:99], v[202:205], v[170:173], v[96:99]
	v_mfma_f32_16x16x32_bf16 v[84:87], v[194:197], v[178:181], v[84:87]
	v_mfma_f32_16x16x32_bf16 v[80:83], v[202:205], v[178:181], v[80:83]
	v_mfma_f32_16x16x32_bf16 v[68:71], v[194:197], v[186:189], v[68:71]
	v_mfma_f32_16x16x32_bf16 v[64:67], v[202:205], v[186:189], v[64:67]
	s_setprio 0
	s_mov_b32 m0, s33
	v_lshl_add_u64 v[208:209], s[58:59], 0, v[130:131]
	s_barrier
	ds_read_b128 v[158:161], v148 offset:16384
	ds_read_b128 v[162:165], v148 offset:17408
	ds_read_b128 v[166:169], v148 offset:18432
	ds_read_b128 v[170:173], v148 offset:19456
	ds_read_b128 v[174:177], v148 offset:20480
	ds_read_b128 v[178:181], v148 offset:21504
	ds_read_b128 v[182:185], v148 offset:22528
	ds_read_b128 v[186:189], v148 offset:23552
	global_load_lds_dwordx4 v[208:209], off
	v_lshl_add_u64 v[210:211], v[208:209], 0, s[10:11]
	s_mov_b32 m0, s34
	s_nop 0
	global_load_lds_dwordx4 v[210:211], off
	s_barrier
	s_waitcnt lgkmcnt(0)
	s_setprio 1
	s_waitcnt lgkmcnt(0)
	v_mfma_f32_16x16x32_bf16 v[60:63], v[138:141], v[158:161], v[60:63]
	v_mfma_f32_16x16x32_bf16 v[56:59], v[150:153], v[158:161], v[56:59]
	v_mfma_f32_16x16x32_bf16 v[44:47], v[138:141], v[166:169], v[44:47]
	v_mfma_f32_16x16x32_bf16 v[40:43], v[150:153], v[166:169], v[40:43]
	v_mfma_f32_16x16x32_bf16 v[28:31], v[138:141], v[174:177], v[28:31]
	v_mfma_f32_16x16x32_bf16 v[24:27], v[150:153], v[174:177], v[24:27]
	v_mfma_f32_16x16x32_bf16 v[12:15], v[138:141], v[182:185], v[12:15]
	v_mfma_f32_16x16x32_bf16 v[8:11], v[150:153], v[182:185], v[8:11]
	v_mfma_f32_16x16x32_bf16 v[60:63], v[142:145], v[162:165], v[60:63]
	v_mfma_f32_16x16x32_bf16 v[56:59], v[154:157], v[162:165], v[56:59]
	v_mfma_f32_16x16x32_bf16 v[44:47], v[142:145], v[170:173], v[44:47]
	v_mfma_f32_16x16x32_bf16 v[40:43], v[154:157], v[170:173], v[40:43]
	v_mfma_f32_16x16x32_bf16 v[28:31], v[142:145], v[178:181], v[28:31]
	v_mfma_f32_16x16x32_bf16 v[24:27], v[154:157], v[178:181], v[24:27]
	v_mfma_f32_16x16x32_bf16 v[12:15], v[142:145], v[186:189], v[12:15]
	v_mfma_f32_16x16x32_bf16 v[8:11], v[154:157], v[186:189], v[8:11]
	s_setprio 0
	s_barrier
; #define PG8_STAGE(bufoff, gbase, voff) do { _Pragma("unroll") for (int _i = 0; _i < 2; ++_i) \
;         __builtin_amdgcn_global_load_lds((const unsigned*)((const char*)(gbase) + (size_t)_i * r64##voff + (voff)), (LAS unsigned*)(lds + (bufoff) + ldsw + _i * 8192), 16, 0, 0); } while (0)
; #define PG8_LDA(dst, b, h) do { _Pragma("unroll") for (int m = 0; m < 4; ++m) _Pragma("unroll") for (int k = 0; k < 2; ++k) dst[m][k] = *(const LAS bf16x8*)(lds + PG8_SA(b, h) + aoff + m * 2048 + k * 1024); } while (0)
; #define PG8_LDB(dst, b, h) do { _Pragma("unroll") for (int n = 0; n < 2; ++n) _Pragma("unroll") for (int k = 0; k < 2; ++k) dst[n][k] = *(const LAS bf16x8*)(lds + PG8_SB(b, h) + boff + n * 2048 + k * 1024); } while (0)
; #define PG8_MMA(ai, bj, At, Bt) do { __builtin_amdgcn_s_setprio(1); _Pragma("unroll") for (int m = 0; m < 4; ++m) _Pragma("unroll") for (int n = 0; n < 2; ++n) _Pragma("unroll") for (int k = 0; k < 2; ++k) \
;         acc[ai][bj][m][n] = __builtin_amdgcn_mfma_f32_16x16x32_bf16(Bt[n][k], At[m][k], acc[ai][bj][m][n], 0, 0, 0); __builtin_amdgcn_s_setprio(0); } while (0)
; #define PG8_WAIT_V(n) asm volatile("s_waitcnt vmcnt(" #n ")" ::: "memory")
; #define PG8_WAIT_L(n) asm volatile("s_waitcnt lgkmcnt(" #n ")" ::: "memory")
; #define PG8_BAR __builtin_amdgcn_s_barrier()
; #define PG8_SCHED __builtin_amdgcn_sched_barrier(0)
; template <class Epi, class Sched>
; __device__ __forceinline__ void gemm_phase(LAS unsigned char* lds, const Gemm g, const Sched& S, const Epi& E) {
;     ...
;             PG8_STAGE(PG8_SB(0, 1), b2 + hstepB, voffB);
;             PG8_WAIT_V(6); PG8_BAR; PG8_MMA(1, 1, At, B1); PG8_BAR;
;             PG8_LDB(B0, 1, 0); PG8_SCHED; PG8_LDA(At, 1, 0); PG8_STAGE(PG8_SA(0, 1), a2 + hstepA, voffA);
;             PG8_WAIT_L(8); PG8_BAR; PG8_WAIT_L(0); PG8_MMA(0, 0, At, B0); PG8_BAR; PG8_SCHED;
;             PG8_LDB(B1, 1, 1); PG8_STAGE(PG8_SB(1, 0), b3, voffB);
;             PG8_BAR; PG8_WAIT_L(0); PG8_MMA(0, 1, At, B1); PG8_BAR;
;             PG8_LDA(At, 1, 1); PG8_STAGE(PG8_SA(1, 0), a3, voffA);
	s_add_i32 s58, s41, s31
	v_lshl_add_u64 v[138:139], v[206:207], 0, s[16:17]
	s_mov_b32 m0, s58
	s_nop 0
	global_load_lds_dwordx4 v[138:139], off
	v_lshl_add_u64 v[138:139], v[206:207], 0, s[18:19]
	s_add_i32 m0, s58, 0x2000
	s_nop 0
	global_load_lds_dwordx4 v[138:139], off
	s_waitcnt vmcnt(6)
	s_barrier
	s_setprio 1
	v_mfma_f32_16x16x32_bf16 v[52:55], v[190:193], v[158:161], v[52:55]
	v_mfma_f32_16x16x32_bf16 v[48:51], v[198:201], v[158:161], v[48:51]
	v_mfma_f32_16x16x32_bf16 v[36:39], v[190:193], v[166:169], v[36:39]
	v_mfma_f32_16x16x32_bf16 v[32:35], v[198:201], v[166:169], v[32:35]
	v_mfma_f32_16x16x32_bf16 v[20:23], v[190:193], v[174:177], v[20:23]
	v_mfma_f32_16x16x32_bf16 v[16:19], v[198:201], v[174:177], v[16:19]
	v_mfma_f32_16x16x32_bf16 v[4:7], v[190:193], v[182:185], v[4:7]
	v_mfma_f32_16x16x32_bf16 v[0:3], v[198:201], v[182:185], v[0:3]
	v_mfma_f32_16x16x32_bf16 v[52:55], v[194:197], v[162:165], v[52:55]
	v_mfma_f32_16x16x32_bf16 v[48:51], v[202:205], v[162:165], v[48:51]
	v_mfma_f32_16x16x32_bf16 v[36:39], v[194:197], v[170:173], v[36:39]
	v_mfma_f32_16x16x32_bf16 v[32:35], v[202:205], v[170:173], v[32:35]
	v_mfma_f32_16x16x32_bf16 v[20:23], v[194:197], v[178:181], v[20:23]
	v_mfma_f32_16x16x32_bf16 v[16:19], v[202:205], v[178:181], v[16:19]
	v_mfma_f32_16x16x32_bf16 v[4:7], v[194:197], v[186:189], v[4:7]
	v_mfma_f32_16x16x32_bf16 v[0:3], v[202:205], v[186:189], v[0:3]
	s_setprio 0
	s_add_i32 s58, 0, 0x18000
	v_add_u32_e32 v154, s58, v146
	s_barrier
	ds_read_b128 v[138:141], v154
	ds_read_b128 v[142:145], v154 offset:1024
	ds_read_b128 v[150:153], v154 offset:2048
	ds_read_b128 v[154:157], v154 offset:3072
	s_mov_b32 m0, s35
	v_lshl_add_u64 v[190:191], v[208:209], 0, s[16:17]
	ds_read_b128 v[158:161], v148 offset:32768
	ds_read_b128 v[162:165], v148 offset:33792
	ds_read_b128 v[166:169], v148 offset:34816
	ds_read_b128 v[170:173], v148 offset:35840
	ds_read_b128 v[174:177], v148 offset:36864
	ds_read_b128 v[178:181], v148 offset:37888
	ds_read_b128 v[182:185], v148 offset:38912
	ds_read_b128 v[186:189], v148 offset:39936
	global_load_lds_dwordx4 v[190:191], off
	v_lshl_add_u64 v[190:191], v[208:209], 0, s[18:19]
	s_mov_b32 m0, s36
	s_nop 0
	global_load_lds_dwordx4 v[190:191], off
	s_waitcnt lgkmcnt(8)
	s_barrier
	s_waitcnt lgkmcnt(0)
	s_setprio 1
	s_waitcnt lgkmcnt(0)
	v_mfma_f32_16x16x32_bf16 v[124:127], v[138:141], v[158:161], v[124:127]
	v_mfma_f32_16x16x32_bf16 v[120:123], v[150:153], v[158:161], v[120:123]
	v_mfma_f32_16x16x32_bf16 v[108:111], v[138:141], v[166:169], v[108:111]
	v_mfma_f32_16x16x32_bf16 v[104:107], v[150:153], v[166:169], v[104:107]
	v_mfma_f32_16x16x32_bf16 v[92:95], v[138:141], v[174:177], v[92:95]
	v_mfma_f32_16x16x32_bf16 v[88:91], v[150:153], v[174:177], v[88:91]
	v_mfma_f32_16x16x32_bf16 v[76:79], v[138:141], v[182:185], v[76:79]
	v_mfma_f32_16x16x32_bf16 v[72:75], v[150:153], v[182:185], v[72:75]
	v_mfma_f32_16x16x32_bf16 v[124:127], v[142:145], v[162:165], v[124:127]
	v_mfma_f32_16x16x32_bf16 v[120:123], v[154:157], v[162:165], v[120:123]
	v_mfma_f32_16x16x32_bf16 v[108:111], v[142:145], v[170:173], v[108:111]
	v_mfma_f32_16x16x32_bf16 v[104:107], v[154:157], v[170:173], v[104:107]
	v_mfma_f32_16x16x32_bf16 v[92:95], v[142:145], v[178:181], v[92:95]
	v_mfma_f32_16x16x32_bf16 v[88:91], v[154:157], v[178:181], v[88:91]
	v_mfma_f32_16x16x32_bf16 v[76:79], v[142:145], v[186:189], v[76:79]
	v_mfma_f32_16x16x32_bf16 v[72:75], v[154:157], v[186:189], v[72:75]
	s_setprio 0
	s_barrier
	s_add_i32 s59, 0, 0x1c000
	s_add_i32 s58, s58, s31
	v_add_u32_e32 v202, s59, v146
	v_lshl_add_u64 v[210:211], v[206:207], 0, s[26:27]
	s_mov_b32 m0, s58
	ds_read_b128 v[190:193], v202
	ds_read_b128 v[194:197], v202 offset:1024
	ds_read_b128 v[198:201], v202 offset:2048
	ds_read_b128 v[202:205], v202 offset:3072
	global_load_lds_dwordx4 v[210:211], off
	v_lshl_add_u64 v[210:211], v[206:207], 0, s[42:43]
	s_add_i32 m0, s58, 0x2000
	s_nop 0
	global_load_lds_dwordx4 v[210:211], off
	s_barrier
	s_waitcnt lgkmcnt(0)
	s_setprio 1
	s_waitcnt lgkmcnt(0)
	v_mfma_f32_16x16x32_bf16 v[116:119], v[190:193], v[158:161], v[116:119]
	v_mfma_f32_16x16x32_bf16 v[112:115], v[198:201], v[158:161], v[112:115]
	v_mfma_f32_16x16x32_bf16 v[100:103], v[190:193], v[166:169], v[100:103]
	v_mfma_f32_16x16x32_bf16 v[96:99], v[198:201], v[166:169], v[96:99]
	v_mfma_f32_16x16x32_bf16 v[84:87], v[190:193], v[174:177], v[84:87]
	v_mfma_f32_16x16x32_bf16 v[80:83], v[198:201], v[174:177], v[80:83]
	v_mfma_f32_16x16x32_bf16 v[68:71], v[190:193], v[182:185], v[68:71]
	v_mfma_f32_16x16x32_bf16 v[64:67], v[198:201], v[182:185], v[64:67]
	v_mfma_f32_16x16x32_bf16 v[116:119], v[194:197], v[162:165], v[116:119]
	v_mfma_f32_16x16x32_bf16 v[112:115], v[202:205], v[162:165], v[112:115]
	v_mfma_f32_16x16x32_bf16 v[100:103], v[194:197], v[170:173], v[100:103]
	v_mfma_f32_16x16x32_bf16 v[96:99], v[202:205], v[170:173], v[96:99]
	v_mfma_f32_16x16x32_bf16 v[84:87], v[194:197], v[178:181], v[84:87]
	v_mfma_f32_16x16x32_bf16 v[80:83], v[202:205], v[178:181], v[80:83]
	v_mfma_f32_16x16x32_bf16 v[68:71], v[194:197], v[186:189], v[68:71]
	v_mfma_f32_16x16x32_bf16 v[64:67], v[202:205], v[186:189], v[64:67]
	s_setprio 0
	s_mov_b32 m0, s38
	v_lshl_add_u64 v[210:211], v[208:209], 0, s[26:27]
	s_barrier
	ds_read_b128 v[158:161], v148 offset:49152
	ds_read_b128 v[162:165], v148 offset:50176
	ds_read_b128 v[166:169], v148 offset:51200
	ds_read_b128 v[170:173], v148 offset:52224
	ds_read_b128 v[174:177], v148 offset:53248
	ds_read_b128 v[178:181], v148 offset:54272
	ds_read_b128 v[182:185], v148 offset:55296
	ds_read_b128 v[186:189], v148 offset:56320
	global_load_lds_dwordx4 v[210:211], off
	v_lshl_add_u64 v[208:209], v[208:209], 0, s[42:43]
	s_mov_b32 m0, s39
	s_nop 0
	global_load_lds_dwordx4 v[208:209], off
	s_barrier
; __device__ __forceinline__ int otid() { int t = (int)__builtin_amdgcn_workitem_id_x(); asm volatile("" : "+v"(t)); return t; }
; __device__ __forceinline__ unsigned cvt_pk_bf16(float lo, float hi) { unsigned r; asm("v_cvt_pk_bf16_f32 %0, %1, %2" : "=v"(r) : "v"(lo), "v"(hi)); return r; }
; __device__ __forceinline__ float bflo(unsigned w) { return __uint_as_float(w << 16); }
; #define PG8_BAR __builtin_amdgcn_s_barrier()
; template <class Epi, class Sched>
; __device__ __forceinline__ void gemm_phase(LAS unsigned char* lds, const Gemm g, const Sched& S, const Epi& E) {
;     ...
;             PG8_BAR; PG8_WAIT_L(0); PG8_MMA(0, 1, At, B1); PG8_BAR;
;             PG8_LDA(At, 1, 1); PG8_STAGE(PG8_SA(1, 0), a3, voffA);
;             PG8_BAR; PG8_WAIT_L(0); PG8_MMA(1, 0, At, B0); PG8_BAR; PG8_SCHED;
;             PG8_STAGE(PG8_SB(1, 1), b3 + hstepB, voffB);
;             PG8_WAIT_V(6); PG8_BAR; PG8_MMA(1, 1, At, B1); PG8_BAR;
;     __device__ __forceinline__ void operator()(const f32x4 (&acc)[2][2][4][2], const pg8::Unit& u, int wr_, int wc_, int fr_, int fq_) const {
;         const int t2_ = otid(), wr = t2_ >> 8, wc = (t2_ >> 6) & 3, fr = t2_ & 15, fq = (t2_ >> 4) & 3; (void)wr_; (void)wc_; (void)fr_; (void)fq_;
;         const int row0 = u.pm * 256 + wr * 64 + fr, col0 = u.pn * 256 + wc * 32 + 8 * fq;
; #pragma unroll
;         for (int ai = 0; ai < 2; ++ai)
; #pragma unroll
;             for (int m = 0; m < 4; ++m) { const int row = row0 + ai * 128 + m * 16;
; #pragma unroll
;                 for (int bj = 0; bj < 2; ++bj) { const int col = col0 + bj * 128;
;                     const f32x4 b0 = *(const f32x4*)(bias + col), b1 = *(const f32x4*)(bias + col + 4);
;                     const f32x4 v0 = acc[ai][bj][m][0] + b0, v1 = acc[ai][bj][m][1] + b1;
;                     const u32x4 z = *(const u32x4*)(Z + (size_t)row * 512 + col);
;                     u32x4 w;
;                     w.x = cvt_pk_bf16(bflo(z.x) * sigmoidf_(v0[0]), bfhi(z.x) * sigmoidf_(v0[1]));
;                     w.y = cvt_pk_bf16(bflo(z.y) * sigmoidf_(v0[2]), bfhi(z.y) * sigmoidf_(v0[3]));
;                     w.z = cvt_pk_bf16(bflo(z.z) * sigmoidf_(v1[0]), bfhi(z.z) * sigmoidf_(v1[1]));
;                     w.w = cvt_pk_bf16(bflo(z.w) * sigmoidf_(v1[2]), bfhi(z.w) * sigmoidf_(v1[3]));
;                     *(u32x4*)(MIX + (size_t)row * 2048 + 1536 + col) = w; } }
	s_waitcnt lgkmcnt(0)
	s_setprio 1
	s_waitcnt lgkmcnt(0)
	v_mfma_f32_16x16x32_bf16 v[60:63], v[138:141], v[158:161], v[60:63]
	v_mfma_f32_16x16x32_bf16 v[56:59], v[150:153], v[158:161], v[56:59]
	v_mfma_f32_16x16x32_bf16 v[44:47], v[138:141], v[166:169], v[44:47]
	v_mfma_f32_16x16x32_bf16 v[40:43], v[150:153], v[166:169], v[40:43]
	v_mfma_f32_16x16x32_bf16 v[28:31], v[138:141], v[174:177], v[28:31]
	v_mfma_f32_16x16x32_bf16 v[24:27], v[150:153], v[174:177], v[24:27]
	v_mfma_f32_16x16x32_bf16 v[12:15], v[138:141], v[182:185], v[12:15]
	v_mfma_f32_16x16x32_bf16 v[8:11], v[150:153], v[182:185], v[8:11]
	v_mfma_f32_16x16x32_bf16 v[60:63], v[142:145], v[162:165], v[60:63]
	v_mfma_f32_16x16x32_bf16 v[56:59], v[154:157], v[162:165], v[56:59]
	v_mfma_f32_16x16x32_bf16 v[44:47], v[142:145], v[170:173], v[44:47]
	v_mfma_f32_16x16x32_bf16 v[40:43], v[154:157], v[170:173], v[40:43]
	v_mfma_f32_16x16x32_bf16 v[28:31], v[142:145], v[178:181], v[28:31]
	v_mfma_f32_16x16x32_bf16 v[24:27], v[154:157], v[178:181], v[24:27]
	v_mfma_f32_16x16x32_bf16 v[12:15], v[142:145], v[186:189], v[12:15]
	v_mfma_f32_16x16x32_bf16 v[8:11], v[154:157], v[186:189], v[8:11]
	s_setprio 0
	s_barrier
	s_add_i32 s58, s59, s31
	v_lshl_add_u64 v[138:139], v[206:207], 0, s[44:45]
	s_mov_b32 m0, s58
	s_nop 0
	global_load_lds_dwordx4 v[138:139], off
	v_lshl_add_u64 v[138:139], v[206:207], 0, s[46:47]
	s_add_i32 m0, s58, 0x2000
	s_nop 0
	global_load_lds_dwordx4 v[138:139], off
	s_waitcnt vmcnt(6)
	s_barrier
	s_setprio 1
	v_mfma_f32_16x16x32_bf16 v[52:55], v[190:193], v[158:161], v[52:55]
	v_mfma_f32_16x16x32_bf16 v[48:51], v[198:201], v[158:161], v[48:51]
	v_mfma_f32_16x16x32_bf16 v[36:39], v[190:193], v[166:169], v[36:39]
	v_mfma_f32_16x16x32_bf16 v[32:35], v[198:201], v[166:169], v[32:35]
	v_mfma_f32_16x16x32_bf16 v[20:23], v[190:193], v[174:177], v[20:23]
	v_mfma_f32_16x16x32_bf16 v[16:19], v[198:201], v[174:177], v[16:19]
	v_mfma_f32_16x16x32_bf16 v[4:7], v[190:193], v[182:185], v[4:7]
	v_mfma_f32_16x16x32_bf16 v[0:3], v[198:201], v[182:185], v[0:3]
	v_mfma_f32_16x16x32_bf16 v[52:55], v[194:197], v[162:165], v[52:55]
	v_mfma_f32_16x16x32_bf16 v[48:51], v[202:205], v[162:165], v[48:51]
	v_mfma_f32_16x16x32_bf16 v[36:39], v[194:197], v[170:173], v[36:39]
	v_mfma_f32_16x16x32_bf16 v[32:35], v[202:205], v[170:173], v[32:35]
	v_mfma_f32_16x16x32_bf16 v[20:23], v[194:197], v[178:181], v[20:23]
	v_mfma_f32_16x16x32_bf16 v[16:19], v[202:205], v[178:181], v[16:19]
	v_mfma_f32_16x16x32_bf16 v[4:7], v[194:197], v[186:189], v[4:7]
	v_mfma_f32_16x16x32_bf16 v[0:3], v[202:205], v[186:189], v[0:3]
	s_setprio 0
	s_add_i32 s57, s57, 2
	s_add_u32 s6, s6, 0x100
	s_addc_u32 s7, s7, 0
	s_add_u32 s8, s8, 0x100
	s_addc_u32 s9, s9, 0
	s_cmp_gt_u32 s57, 5
	s_barrier
	s_cbranch_scc0 .LBB0_446
	v_mov_b32_e32 v142, v222
	s_lshl_b32 s4, s4, 8
	v_lshrrev_b32_e32 v138, 1, v142
	v_and_b32_e32 v138, 0x78, v138
	v_lshl_or_b32 v140, s5, 8, v138
	v_ashrrev_i32_e32 v141, 31, v140
	v_lshl_add_u64 v[138:139], v[140:141], 2, s[20:21]
	global_load_dwordx4 v[150:153], v[138:139], off offset:16
	global_load_dwordx4 v[154:157], v[138:139], off
	v_ashrrev_i32_e32 v143, 2, v142
	v_and_b32_e32 v143, 0xffffffc0, v143
	v_and_or_b32 v142, v142, 15, s4
	v_add_u32_e32 v142, v142, v143
	v_ashrrev_i32_e32 v143, 31, v142
	v_lshlrev_b64 v[144:145], 10, v[142:143]
	v_lshl_add_u64 v[144:145], s[22:23], 0, v[144:145]
	v_lshlrev_b64 v[140:141], 1, v[140:141]
	v_lshl_add_u64 v[144:145], v[144:145], 0, v[140:141]
	global_load_dwordx4 v[158:161], v[144:145], off
	v_lshlrev_b64 v[162:163], 12, v[142:143]
	s_waitcnt vmcnt(0)
	v_pk_add_f32 v[150:151], v[120:121], v[150:151]
	v_pk_add_f32 v[124:125], v[124:125], v[154:155]
	v_pk_add_f32 v[126:127], v[126:127], v[156:157]
	v_mul_f32_e32 v120, 0xbfb8aa3b, v124
	v_mul_f32_e32 v121, 0xbfb8aa3b, v125
	v_exp_f32_e32 v120, v120
	v_mul_f32_e32 v124, 0xbfb8aa3b, v126
	v_mul_f32_e32 v126, 0xbfb8aa3b, v150
	v_exp_f32_e32 v121, v121
	v_mul_f32_e32 v125, 0xbfb8aa3b, v127
	v_exp_f32_e32 v124, v124
	v_exp_f32_e32 v126, v126
	v_exp_f32_e32 v125, v125
	v_add_f32_e32 v120, 1.0, v120
	v_add_f32_e32 v121, 1.0, v121
	v_add_f32_e32 v124, 1.0, v124
	v_add_f32_e32 v126, 1.0, v126
	v_rcp_f32_e32 v120, v120
	v_lshlrev_b32_e32 v127, 16, v158
	v_and_b32_e32 v143, 0xffff0000, v158
	v_add_f32_e32 v125, 1.0, v125
	v_rcp_f32_e32 v121, v121
	v_rcp_f32_e32 v124, v124
	v_rcp_f32_e32 v171, v126
	v_rcp_f32_e32 v170, v125
	v_pk_add_f32 v[122:123], v[122:123], v[152:153]
	v_lshlrev_b32_e32 v150, 16, v159
	v_and_b32_e32 v152, 0xffff0000, v159
	v_mul_f32_e32 v120, v120, v127
	v_mul_f32_e32 v121, v121, v143
	v_cvt_pk_bf16_f32 v120, v120, v121
	v_mul_f32_e32 v121, v124, v150
	v_mov_b32_e32 v124, v170
	v_mul_f32_e32 v124, v124, v152
	v_cvt_pk_bf16_f32 v121, v121, v124
	v_mul_f32_e32 v127, 0xbfb8aa3b, v151
	v_exp_f32_e32 v127, v127
	v_mul_f32_e32 v122, 0xbfb8aa3b, v122
	v_add_f32_e32 v125, 1.0, v127
	v_rcp_f32_e32 v125, v125
	v_exp_f32_e32 v122, v122
	v_mov_b32_e32 v124, v171
	v_and_b32_e32 v126, 0xffff0000, v160
	v_add_f32_e32 v127, 1.0, v122
	v_rcp_f32_e32 v150, v127
	v_mul_f32_e32 v122, v125, v126
	v_mul_f32_e32 v123, 0xbfb8aa3b, v123
	v_exp_f32_e32 v123, v123
	s_nop 0
	v_add_f32_e32 v123, 1.0, v123
	v_rcp_f32_e32 v123, v123
	v_mov_b32_e32 v125, v150
	v_lshlrev_b32_e32 v153, 16, v160
	v_mul_f32_e32 v124, v124, v153
	v_cvt_pk_bf16_f32 v122, v124, v122
	v_lshlrev_b32_e32 v124, 16, v161
	v_mul_f32_e32 v124, v125, v124
	v_and_b32_e32 v125, 0xffff0000, v161
	v_mul_f32_e32 v123, v123, v125
	v_cvt_pk_bf16_f32 v123, v124, v123
	v_lshl_add_u64 v[124:125], s[24:25], 0, v[162:163]
	v_lshl_add_u64 v[154:155], v[124:125], 0, v[140:141]
	global_store_dwordx4 v[154:155], v[120:123], off offset:3072
	global_load_dwordx4 v[120:123], v[138:139], off offset:512
	s_nop 0
	global_load_dwordx4 v[124:127], v[138:139], off offset:528
	global_load_dwordx4 v[150:153], v[144:145], off offset:256
	s_mov_b64 s[8:9], s[54:55]
	s_mov_b64 s[6:7], s[52:53]
	s_waitcnt vmcnt(0)
; __device__ __forceinline__ unsigned cvt_pk_bf16(float lo, float hi) { unsigned r; asm("v_cvt_pk_bf16_f32 %0, %1, %2" : "=v"(r) : "v"(lo), "v"(hi)); return r; }
; __device__ __forceinline__ float bflo(unsigned w) { return __uint_as_float(w << 16); }
; __device__ __forceinline__ float bfhi(unsigned w) { return __uint_as_float(w & 0xffff0000u); }
; __device__ __forceinline__ float sigmoidf_(float x) { return 1.f / (1.f + __expf(-x)); }
;     __device__ __forceinline__ void operator()(const f32x4 (&acc)[2][2][4][2], const pg8::Unit& u, int wr_, int wc_, int fr_, int fq_) const {
;     ...
;             for (int m = 0; m < 4; ++m) { const int row = row0 + ai * 128 + m * 16;
; #pragma unroll
;                 for (int bj = 0; bj < 2; ++bj) { const int col = col0 + bj * 128;
;                     const f32x4 b0 = *(const f32x4*)(bias + col), b1 = *(const f32x4*)(bias + col + 4);
;                     const f32x4 v0 = acc[ai][bj][m][0] + b0, v1 = acc[ai][bj][m][1] + b1;
;                     const u32x4 z = *(const u32x4*)(Z + (size_t)row * 512 + col);
;                     u32x4 w;
;                     w.x = cvt_pk_bf16(bflo(z.x) * sigmoidf_(v0[0]), bfhi(z.x) * sigmoidf_(v0[1]));
;                     w.y = cvt_pk_bf16(bflo(z.y) * sigmoidf_(v0[2]), bfhi(z.y) * sigmoidf_(v0[3]));
;                     w.z = cvt_pk_bf16(bflo(z.z) * sigmoidf_(v1[0]), bfhi(z.z) * sigmoidf_(v1[1]));
;                     w.w = cvt_pk_bf16(bflo(z.w) * sigmoidf_(v1[2]), bfhi(z.w) * sigmoidf_(v1[3]));
;                     *(u32x4*)(MIX + (size_t)row * 2048 + 1536 + col) = w; } }
	v_pk_add_f32 v[116:117], v[116:117], v[120:121]
	v_pk_add_f32 v[120:121], v[112:113], v[124:125]
	v_mul_f32_e32 v112, 0xbfb8aa3b, v116
	v_exp_f32_e32 v112, v112
	v_pk_add_f32 v[118:119], v[118:119], v[122:123]
	v_mul_f32_e32 v113, 0xbfb8aa3b, v117
	v_exp_f32_e32 v113, v113
	v_add_f32_e32 v112, 1.0, v112
	v_rcp_f32_e32 v112, v112
	v_pk_add_f32 v[114:115], v[114:115], v[126:127]
	v_add_f32_e32 v113, 1.0, v113
	v_rcp_f32_e32 v113, v113
	v_lshlrev_b32_e32 v116, 16, v150
	v_mul_f32_e32 v112, v112, v116
	v_mul_f32_e32 v118, 0xbfb8aa3b, v118
	v_exp_f32_e32 v118, v118
	s_nop 0
	v_add_f32_e32 v116, 1.0, v118
	v_rcp_f32_e32 v116, v116
	v_and_b32_e32 v117, 0xffff0000, v150
	v_mul_f32_e32 v113, v113, v117
	v_mul_f32_e32 v119, 0xbfb8aa3b, v119
	v_exp_f32_e32 v119, v119
	s_nop 0
	v_add_f32_e32 v118, 1.0, v119
	v_rcp_f32_e32 v122, v118
	v_cvt_pk_bf16_f32 v112, v112, v113
	v_lshlrev_b32_e32 v113, 16, v151
	v_mul_f32_e32 v119, 0xbfb8aa3b, v120
	v_exp_f32_e32 v119, v119
	v_mov_b32_e32 v117, v122
	v_mul_f32_e32 v113, v116, v113
	v_add_f32_e32 v118, 1.0, v119
	v_and_b32_e32 v116, 0xffff0000, v151
	v_mul_f32_e32 v116, v117, v116
	v_mul_f32_e32 v121, 0xbfb8aa3b, v121
	v_exp_f32_e32 v121, v121
	s_nop 0
	v_add_f32_e32 v119, 1.0, v121
	v_rcp_f32_e32 v121, v119
	v_rcp_f32_e32 v117, v118
	v_mul_f32_e32 v114, 0xbfb8aa3b, v114
	v_exp_f32_e32 v114, v114
	v_mov_b32_e32 v118, v121
	v_add_f32_e32 v119, 1.0, v114
	v_rcp_f32_e32 v121, v119
	v_cvt_pk_bf16_f32 v113, v113, v116
	v_lshlrev_b32_e32 v116, 16, v152
	v_mul_f32_e32 v116, v117, v116
	v_and_b32_e32 v117, 0xffff0000, v152
	v_mul_f32_e32 v114, v118, v117
	v_mul_f32_e32 v115, 0xbfb8aa3b, v115
	v_exp_f32_e32 v115, v115
	s_nop 0
	v_add_f32_e32 v115, 1.0, v115
	v_rcp_f32_e32 v115, v115
	v_mov_b32_e32 v117, v121
	v_cvt_pk_bf16_f32 v114, v116, v114
	v_lshlrev_b32_e32 v116, 16, v153
	v_mul_f32_e32 v116, v117, v116
	v_and_b32_e32 v117, 0xffff0000, v153
	v_mul_f32_e32 v115, v115, v117
	v_cvt_pk_bf16_f32 v115, v116, v115
	global_store_dwordx4 v[154:155], v[112:115], off offset:3328
	global_load_dwordx4 v[112:115], v[138:139], off
	s_nop 0
	global_load_dwordx4 v[116:119], v[138:139], off offset:16
	v_or_b32_e32 v124, 16, v142
	v_ashrrev_i32_e32 v125, 31, v124
	v_lshlrev_b64 v[120:121], 10, v[124:125]
	v_lshl_add_u64 v[120:121], s[22:23], 0, v[120:121]
	v_lshl_add_u64 v[126:127], v[120:121], 0, v[140:141]
	global_load_dwordx4 v[120:123], v[126:127], off
	s_waitcnt vmcnt(0)
	v_pk_add_f32 v[108:109], v[108:109], v[112:113]
	s_nop 0
	v_mul_f32_e32 v108, 0xbfb8aa3b, v108
	v_exp_f32_e32 v108, v108
	v_lshlrev_b64 v[112:113], 12, v[124:125]
	v_pk_add_f32 v[110:111], v[110:111], v[114:115]
	v_pk_add_f32 v[114:115], v[104:105], v[116:117]
	v_add_f32_e32 v108, 1.0, v108
	v_rcp_f32_e32 v105, v108
	v_mul_f32_e32 v109, 0xbfb8aa3b, v109
	v_exp_f32_e32 v109, v109
	v_pk_add_f32 v[106:107], v[106:107], v[118:119]
	v_add_f32_e32 v109, 1.0, v109
	v_rcp_f32_e32 v117, v109
	v_mul_f32_e32 v110, 0xbfb8aa3b, v110
	v_exp_f32_e32 v110, v110
	v_mov_b32_e32 v108, v117
	v_add_f32_e32 v109, 1.0, v110
	v_lshlrev_b32_e32 v104, 16, v120
	v_mul_f32_e32 v104, v105, v104
	v_and_b32_e32 v105, 0xffff0000, v120
	v_mul_f32_e32 v105, v108, v105
	v_mul_f32_e32 v111, 0xbfb8aa3b, v111
	v_exp_f32_e32 v111, v111
	s_nop 0
	v_add_f32_e32 v110, 1.0, v111
	v_rcp_f32_e32 v116, v110
	v_rcp_f32_e32 v108, v109
	v_cvt_pk_bf16_f32 v104, v104, v105
	v_lshlrev_b32_e32 v105, 16, v121
	v_mul_f32_e32 v111, 0xbfb8aa3b, v114
	v_exp_f32_e32 v111, v111
	v_mov_b32_e32 v109, v116
	v_mul_f32_e32 v105, v108, v105
	v_add_f32_e32 v110, 1.0, v111
	v_and_b32_e32 v108, 0xffff0000, v121
	v_mul_f32_e32 v108, v109, v108
	v_mul_f32_e32 v115, 0xbfb8aa3b, v115
	v_exp_f32_e32 v115, v115
	s_nop 0
	v_add_f32_e32 v111, 1.0, v115
	v_rcp_f32_e32 v115, v111
	v_rcp_f32_e32 v109, v110
	v_mul_f32_e32 v106, 0xbfb8aa3b, v106
	v_exp_f32_e32 v106, v106
	v_mov_b32_e32 v110, v115
	v_add_f32_e32 v111, 1.0, v106
	v_rcp_f32_e32 v115, v111
	v_cvt_pk_bf16_f32 v105, v105, v108
	v_lshlrev_b32_e32 v108, 16, v122
	v_mul_f32_e32 v108, v109, v108
	v_and_b32_e32 v109, 0xffff0000, v122
	v_mul_f32_e32 v106, v110, v109
	v_mul_f32_e32 v107, 0xbfb8aa3b, v107
	v_exp_f32_e32 v107, v107
	s_nop 0
	v_add_f32_e32 v107, 1.0, v107
	v_rcp_f32_e32 v107, v107
	v_mov_b32_e32 v109, v115
	v_cvt_pk_bf16_f32 v106, v108, v106
	v_lshlrev_b32_e32 v108, 16, v123
	v_mul_f32_e32 v108, v109, v108
	v_and_b32_e32 v109, 0xffff0000, v123
	v_mul_f32_e32 v107, v107, v109
	v_cvt_pk_bf16_f32 v107, v108, v107
	v_lshl_add_u64 v[108:109], s[24:25], 0, v[112:113]
	v_lshl_add_u64 v[116:117], v[108:109], 0, v[140:141]
	global_store_dwordx4 v[116:117], v[104:107], off offset:3072
	global_load_dwordx4 v[104:107], v[138:139], off offset:512
	s_nop 0
	global_load_dwordx4 v[108:111], v[138:139], off offset:528
	global_load_dwordx4 v[112:115], v[126:127], off offset:256
	s_waitcnt vmcnt(0)
; __device__ __forceinline__ unsigned cvt_pk_bf16(float lo, float hi) { unsigned r; asm("v_cvt_pk_bf16_f32 %0, %1, %2" : "=v"(r) : "v"(lo), "v"(hi)); return r; }
; __device__ __forceinline__ float bflo(unsigned w) { return __uint_as_float(w << 16); }
; __device__ __forceinline__ float bfhi(unsigned w) { return __uint_as_float(w & 0xffff0000u); }
; __device__ __forceinline__ float sigmoidf_(float x) { return 1.f / (1.f + __expf(-x)); }
;     __device__ __forceinline__ void operator()(const f32x4 (&acc)[2][2][4][2], const pg8::Unit& u, int wr_, int wc_, int fr_, int fq_) const {
;     ...
;             for (int m = 0; m < 4; ++m) { const int row = row0 + ai * 128 + m * 16;
; #pragma unroll
;                 for (int bj = 0; bj < 2; ++bj) { const int col = col0 + bj * 128;
;                     const f32x4 b0 = *(const f32x4*)(bias + col), b1 = *(const f32x4*)(bias + col + 4);
;                     const f32x4 v0 = acc[ai][bj][m][0] + b0, v1 = acc[ai][bj][m][1] + b1;
;                     const u32x4 z = *(const u32x4*)(Z + (size_t)row * 512 + col);
;                     u32x4 w;
;                     w.x = cvt_pk_bf16(bflo(z.x) * sigmoidf_(v0[0]), bfhi(z.x) * sigmoidf_(v0[1]));
;                     w.y = cvt_pk_bf16(bflo(z.y) * sigmoidf_(v0[2]), bfhi(z.y) * sigmoidf_(v0[3]));
;                     w.z = cvt_pk_bf16(bflo(z.z) * sigmoidf_(v1[0]), bfhi(z.z) * sigmoidf_(v1[1]));
;                     w.w = cvt_pk_bf16(bflo(z.w) * sigmoidf_(v1[2]), bfhi(z.w) * sigmoidf_(v1[3]));
;                     *(u32x4*)(MIX + (size_t)row * 2048 + 1536 + col) = w; } }
	v_pk_add_f32 v[100:101], v[100:101], v[104:105]
	s_nop 0
	v_mul_f32_e32 v100, 0xbfb8aa3b, v100
	v_exp_f32_e32 v100, v100
	v_pk_add_f32 v[102:103], v[102:103], v[106:107]
	v_mul_f32_e32 v101, 0xbfb8aa3b, v101
	v_pk_add_f32 v[104:105], v[96:97], v[108:109]
	v_add_f32_e32 v100, 1.0, v100
	v_rcp_f32_e32 v97, v100
	v_exp_f32_e32 v101, v101
	v_mul_f32_e32 v102, 0xbfb8aa3b, v102
	v_exp_f32_e32 v102, v102
	v_add_f32_e32 v101, 1.0, v101
	v_rcp_f32_e32 v107, v101
	v_lshlrev_b32_e32 v96, 16, v112
	v_mul_f32_e32 v96, v97, v96
	v_mov_b32_e32 v100, v107
	v_add_f32_e32 v101, 1.0, v102
	v_and_b32_e32 v97, 0xffff0000, v112
	v_mul_f32_e32 v97, v100, v97
	v_mul_f32_e32 v103, 0xbfb8aa3b, v103
	v_exp_f32_e32 v103, v103
	s_nop 0
	v_add_f32_e32 v102, 1.0, v103
	v_rcp_f32_e32 v106, v102
	v_rcp_f32_e32 v100, v101
	v_cvt_pk_bf16_f32 v96, v96, v97
	v_lshlrev_b32_e32 v97, 16, v113
	v_mul_f32_e32 v103, 0xbfb8aa3b, v104
	v_exp_f32_e32 v103, v103
	v_mov_b32_e32 v101, v106
	v_mul_f32_e32 v97, v100, v97
	v_add_f32_e32 v102, 1.0, v103
	v_and_b32_e32 v100, 0xffff0000, v113
	v_mul_f32_e32 v100, v101, v100
	v_mul_f32_e32 v105, 0xbfb8aa3b, v105
	v_exp_f32_e32 v105, v105
	s_nop 0
	v_add_f32_e32 v103, 1.0, v105
	v_rcp_f32_e32 v105, v103
	v_rcp_f32_e32 v101, v102
	v_pk_add_f32 v[98:99], v[98:99], v[110:111]
	v_cvt_pk_bf16_f32 v97, v97, v100
	v_mul_f32_e32 v98, 0xbfb8aa3b, v98
	v_exp_f32_e32 v98, v98
	v_mov_b32_e32 v102, v105
	v_add_f32_e32 v103, 1.0, v98
	v_rcp_f32_e32 v105, v103
	v_lshlrev_b32_e32 v100, 16, v114
	v_mul_f32_e32 v100, v101, v100
	v_and_b32_e32 v101, 0xffff0000, v114
	v_mul_f32_e32 v98, v102, v101
	v_mul_f32_e32 v99, 0xbfb8aa3b, v99
	v_exp_f32_e32 v99, v99
	s_nop 0
	v_add_f32_e32 v99, 1.0, v99
	v_rcp_f32_e32 v99, v99
	v_mov_b32_e32 v101, v105
	v_cvt_pk_bf16_f32 v98, v100, v98
	v_lshlrev_b32_e32 v100, 16, v115
	v_mul_f32_e32 v100, v101, v100
	v_and_b32_e32 v101, 0xffff0000, v115
	v_mul_f32_e32 v99, v99, v101
	v_cvt_pk_bf16_f32 v99, v100, v99
	global_store_dwordx4 v[116:117], v[96:99], off offset:3328
	global_load_dwordx4 v[96:99], v[138:139], off
	s_nop 0
	global_load_dwordx4 v[100:103], v[138:139], off offset:16
	v_or_b32_e32 v108, 32, v142
	v_ashrrev_i32_e32 v109, 31, v108
	v_lshlrev_b64 v[104:105], 10, v[108:109]
	v_lshl_add_u64 v[104:105], s[22:23], 0, v[104:105]
	v_lshl_add_u64 v[110:111], v[104:105], 0, v[140:141]
	global_load_dwordx4 v[104:107], v[110:111], off
	s_waitcnt vmcnt(0)
	v_pk_add_f32 v[92:93], v[92:93], v[96:97]
	s_nop 0
	v_mul_f32_e32 v92, 0xbfb8aa3b, v92
	v_exp_f32_e32 v92, v92
	v_lshlrev_b64 v[96:97], 12, v[108:109]
	v_pk_add_f32 v[94:95], v[94:95], v[98:99]
	v_pk_add_f32 v[98:99], v[88:89], v[100:101]
	v_add_f32_e32 v92, 1.0, v92
	v_rcp_f32_e32 v89, v92
	v_mul_f32_e32 v93, 0xbfb8aa3b, v93
	v_exp_f32_e32 v93, v93
	v_pk_add_f32 v[90:91], v[90:91], v[102:103]
	v_add_f32_e32 v93, 1.0, v93
	v_rcp_f32_e32 v101, v93
	v_mul_f32_e32 v94, 0xbfb8aa3b, v94
	v_exp_f32_e32 v94, v94
	v_mov_b32_e32 v92, v101
	v_add_f32_e32 v93, 1.0, v94
	v_lshlrev_b32_e32 v88, 16, v104
	v_mul_f32_e32 v88, v89, v88
	v_and_b32_e32 v89, 0xffff0000, v104
	v_mul_f32_e32 v89, v92, v89
	v_mul_f32_e32 v95, 0xbfb8aa3b, v95
	v_exp_f32_e32 v95, v95
	s_nop 0
	v_add_f32_e32 v94, 1.0, v95
	v_rcp_f32_e32 v100, v94
	v_rcp_f32_e32 v92, v93
	v_cvt_pk_bf16_f32 v88, v88, v89
	v_lshlrev_b32_e32 v89, 16, v105
	v_mul_f32_e32 v95, 0xbfb8aa3b, v98
	v_exp_f32_e32 v95, v95
	v_mov_b32_e32 v93, v100
	v_mul_f32_e32 v89, v92, v89
	v_add_f32_e32 v94, 1.0, v95
	v_and_b32_e32 v92, 0xffff0000, v105
	v_mul_f32_e32 v92, v93, v92
	v_mul_f32_e32 v99, 0xbfb8aa3b, v99
	v_exp_f32_e32 v99, v99
	s_nop 0
	v_add_f32_e32 v95, 1.0, v99
	v_rcp_f32_e32 v99, v95
	v_rcp_f32_e32 v93, v94
	v_mul_f32_e32 v90, 0xbfb8aa3b, v90
	v_exp_f32_e32 v90, v90
	v_mov_b32_e32 v94, v99
	v_add_f32_e32 v95, 1.0, v90
	v_rcp_f32_e32 v99, v95
	v_cvt_pk_bf16_f32 v89, v89, v92
	v_lshlrev_b32_e32 v92, 16, v106
	v_mul_f32_e32 v92, v93, v92
	v_and_b32_e32 v93, 0xffff0000, v106
	v_mul_f32_e32 v90, v94, v93
	v_mul_f32_e32 v91, 0xbfb8aa3b, v91
	v_exp_f32_e32 v91, v91
	s_nop 0
	v_add_f32_e32 v91, 1.0, v91
	v_rcp_f32_e32 v91, v91
	v_mov_b32_e32 v93, v99
	v_cvt_pk_bf16_f32 v90, v92, v90
	v_lshlrev_b32_e32 v92, 16, v107
	v_mul_f32_e32 v92, v93, v92
	v_and_b32_e32 v93, 0xffff0000, v107
	v_mul_f32_e32 v91, v91, v93
	v_cvt_pk_bf16_f32 v91, v92, v91
	v_lshl_add_u64 v[92:93], s[24:25], 0, v[96:97]
	v_lshl_add_u64 v[100:101], v[92:93], 0, v[140:141]
	global_store_dwordx4 v[100:101], v[88:91], off offset:3072
	global_load_dwordx4 v[88:91], v[138:139], off offset:512
	s_nop 0
	global_load_dwordx4 v[92:95], v[138:139], off offset:528
	global_load_dwordx4 v[96:99], v[110:111], off offset:256
	s_waitcnt vmcnt(0)
; __device__ __forceinline__ unsigned cvt_pk_bf16(float lo, float hi) { unsigned r; asm("v_cvt_pk_bf16_f32 %0, %1, %2" : "=v"(r) : "v"(lo), "v"(hi)); return r; }
; __device__ __forceinline__ float bflo(unsigned w) { return __uint_as_float(w << 16); }
; __device__ __forceinline__ float bfhi(unsigned w) { return __uint_as_float(w & 0xffff0000u); }
; __device__ __forceinline__ float sigmoidf_(float x) { return 1.f / (1.f + __expf(-x)); }
;     __device__ __forceinline__ void operator()(const f32x4 (&acc)[2][2][4][2], const pg8::Unit& u, int wr_, int wc_, int fr_, int fq_) const {
;     ...
;             for (int m = 0; m < 4; ++m) { const int row = row0 + ai * 128 + m * 16;
; #pragma unroll
;                 for (int bj = 0; bj < 2; ++bj) { const int col = col0 + bj * 128;
;                     const f32x4 b0 = *(const f32x4*)(bias + col), b1 = *(const f32x4*)(bias + col + 4);
;                     const f32x4 v0 = acc[ai][bj][m][0] + b0, v1 = acc[ai][bj][m][1] + b1;
;                     const u32x4 z = *(const u32x4*)(Z + (size_t)row * 512 + col);
;                     u32x4 w;
;                     w.x = cvt_pk_bf16(bflo(z.x) * sigmoidf_(v0[0]), bfhi(z.x) * sigmoidf_(v0[1]));
;                     w.y = cvt_pk_bf16(bflo(z.y) * sigmoidf_(v0[2]), bfhi(z.y) * sigmoidf_(v0[3]));
;                     w.z = cvt_pk_bf16(bflo(z.z) * sigmoidf_(v1[0]), bfhi(z.z) * sigmoidf_(v1[1]));
;                     w.w = cvt_pk_bf16(bflo(z.w) * sigmoidf_(v1[2]), bfhi(z.w) * sigmoidf_(v1[3]));
;                     *(u32x4*)(MIX + (size_t)row * 2048 + 1536 + col) = w; } }
	v_pk_add_f32 v[84:85], v[84:85], v[88:89]
	s_nop 0
	v_mul_f32_e32 v84, 0xbfb8aa3b, v84
	v_exp_f32_e32 v84, v84
	v_pk_add_f32 v[86:87], v[86:87], v[90:91]
	v_mul_f32_e32 v85, 0xbfb8aa3b, v85
	v_pk_add_f32 v[88:89], v[80:81], v[92:93]
	v_add_f32_e32 v84, 1.0, v84
	v_rcp_f32_e32 v81, v84
	v_exp_f32_e32 v85, v85
	v_mul_f32_e32 v86, 0xbfb8aa3b, v86
	v_exp_f32_e32 v86, v86
	v_add_f32_e32 v85, 1.0, v85
	v_rcp_f32_e32 v91, v85
	v_lshlrev_b32_e32 v80, 16, v96
	v_mul_f32_e32 v80, v81, v80
	v_mov_b32_e32 v84, v91
	v_add_f32_e32 v85, 1.0, v86
	v_and_b32_e32 v81, 0xffff0000, v96
	v_mul_f32_e32 v81, v84, v81
	v_mul_f32_e32 v87, 0xbfb8aa3b, v87
	v_exp_f32_e32 v87, v87
	s_nop 0
	v_add_f32_e32 v86, 1.0, v87
	v_rcp_f32_e32 v90, v86
	v_rcp_f32_e32 v84, v85
	v_cvt_pk_bf16_f32 v80, v80, v81
	v_lshlrev_b32_e32 v81, 16, v97
	v_mul_f32_e32 v87, 0xbfb8aa3b, v88
	v_exp_f32_e32 v87, v87
	v_mov_b32_e32 v85, v90
	v_mul_f32_e32 v81, v84, v81
	v_add_f32_e32 v86, 1.0, v87
	v_and_b32_e32 v84, 0xffff0000, v97
	v_mul_f32_e32 v84, v85, v84
	v_mul_f32_e32 v89, 0xbfb8aa3b, v89
	v_exp_f32_e32 v89, v89
	s_nop 0
	v_add_f32_e32 v87, 1.0, v89
	v_rcp_f32_e32 v89, v87
	v_rcp_f32_e32 v85, v86
	v_pk_add_f32 v[82:83], v[82:83], v[94:95]
	v_cvt_pk_bf16_f32 v81, v81, v84
	v_mul_f32_e32 v82, 0xbfb8aa3b, v82
	v_exp_f32_e32 v82, v82
	v_mov_b32_e32 v86, v89
	v_add_f32_e32 v87, 1.0, v82
	v_rcp_f32_e32 v89, v87
	v_lshlrev_b32_e32 v84, 16, v98
	v_mul_f32_e32 v84, v85, v84
	v_and_b32_e32 v85, 0xffff0000, v98
	v_mul_f32_e32 v82, v86, v85
	v_mul_f32_e32 v83, 0xbfb8aa3b, v83
	v_exp_f32_e32 v83, v83
	s_nop 0
	v_add_f32_e32 v83, 1.0, v83
	v_rcp_f32_e32 v83, v83
	v_mov_b32_e32 v85, v89
	v_cvt_pk_bf16_f32 v82, v84, v82
	v_lshlrev_b32_e32 v84, 16, v99
	v_mul_f32_e32 v84, v85, v84
	v_and_b32_e32 v85, 0xffff0000, v99
	v_mul_f32_e32 v83, v83, v85
	v_cvt_pk_bf16_f32 v83, v84, v83
	global_store_dwordx4 v[100:101], v[80:83], off offset:3328
	global_load_dwordx4 v[80:83], v[138:139], off
	s_nop 0
	global_load_dwordx4 v[84:87], v[138:139], off offset:16
	v_or_b32_e32 v92, 48, v142
	v_ashrrev_i32_e32 v93, 31, v92
	v_lshlrev_b64 v[88:89], 10, v[92:93]
	v_lshl_add_u64 v[88:89], s[22:23], 0, v[88:89]
	v_lshl_add_u64 v[94:95], v[88:89], 0, v[140:141]
	global_load_dwordx4 v[88:91], v[94:95], off
	s_waitcnt vmcnt(0)
	v_pk_add_f32 v[76:77], v[76:77], v[80:81]
	s_nop 0
	v_mul_f32_e32 v76, 0xbfb8aa3b, v76
	v_exp_f32_e32 v76, v76
	v_lshlrev_b64 v[80:81], 12, v[92:93]
	v_pk_add_f32 v[78:79], v[78:79], v[82:83]
	v_pk_add_f32 v[82:83], v[72:73], v[84:85]
	v_add_f32_e32 v76, 1.0, v76
	v_rcp_f32_e32 v73, v76
	v_mul_f32_e32 v77, 0xbfb8aa3b, v77
	v_exp_f32_e32 v77, v77
	v_pk_add_f32 v[74:75], v[74:75], v[86:87]
	v_add_f32_e32 v77, 1.0, v77
	v_rcp_f32_e32 v85, v77
	v_mul_f32_e32 v78, 0xbfb8aa3b, v78
	v_exp_f32_e32 v78, v78
	v_mov_b32_e32 v76, v85
	v_add_f32_e32 v77, 1.0, v78
	v_lshlrev_b32_e32 v72, 16, v88
	v_mul_f32_e32 v72, v73, v72
	v_and_b32_e32 v73, 0xffff0000, v88
	v_mul_f32_e32 v73, v76, v73
	v_mul_f32_e32 v79, 0xbfb8aa3b, v79
	v_exp_f32_e32 v79, v79
	s_nop 0
	v_add_f32_e32 v78, 1.0, v79
	v_rcp_f32_e32 v84, v78
	v_rcp_f32_e32 v76, v77
	v_cvt_pk_bf16_f32 v72, v72, v73
	v_lshlrev_b32_e32 v73, 16, v89
	v_mul_f32_e32 v79, 0xbfb8aa3b, v82
	v_exp_f32_e32 v79, v79
	v_mov_b32_e32 v77, v84
	v_mul_f32_e32 v73, v76, v73
	v_add_f32_e32 v78, 1.0, v79
	v_and_b32_e32 v76, 0xffff0000, v89
	v_mul_f32_e32 v76, v77, v76
	v_mul_f32_e32 v83, 0xbfb8aa3b, v83
	v_exp_f32_e32 v83, v83
	s_nop 0
	v_add_f32_e32 v79, 1.0, v83
	v_rcp_f32_e32 v83, v79
	v_rcp_f32_e32 v77, v78
	v_mul_f32_e32 v74, 0xbfb8aa3b, v74
	v_exp_f32_e32 v74, v74
	v_mov_b32_e32 v78, v83
	v_add_f32_e32 v79, 1.0, v74
	v_rcp_f32_e32 v83, v79
	v_cvt_pk_bf16_f32 v73, v73, v76
	v_lshlrev_b32_e32 v76, 16, v90
	v_mul_f32_e32 v76, v77, v76
	v_and_b32_e32 v77, 0xffff0000, v90
	v_mul_f32_e32 v74, v78, v77
	v_mul_f32_e32 v75, 0xbfb8aa3b, v75
	v_exp_f32_e32 v75, v75
	s_nop 0
	v_add_f32_e32 v75, 1.0, v75
	v_rcp_f32_e32 v75, v75
	v_mov_b32_e32 v77, v83
	v_cvt_pk_bf16_f32 v74, v76, v74
	v_lshlrev_b32_e32 v76, 16, v91
	v_mul_f32_e32 v76, v77, v76
	v_and_b32_e32 v77, 0xffff0000, v91
	v_mul_f32_e32 v75, v75, v77
	v_cvt_pk_bf16_f32 v75, v76, v75
	v_lshl_add_u64 v[76:77], s[24:25], 0, v[80:81]
	v_lshl_add_u64 v[84:85], v[76:77], 0, v[140:141]
	global_store_dwordx4 v[84:85], v[72:75], off offset:3072
	global_load_dwordx4 v[72:75], v[138:139], off offset:512
	s_nop 0
	global_load_dwordx4 v[76:79], v[138:139], off offset:528
	global_load_dwordx4 v[80:83], v[94:95], off offset:256
	s_waitcnt vmcnt(0)
; __device__ __forceinline__ unsigned cvt_pk_bf16(float lo, float hi) { unsigned r; asm("v_cvt_pk_bf16_f32 %0, %1, %2" : "=v"(r) : "v"(lo), "v"(hi)); return r; }
; __device__ __forceinline__ float bflo(unsigned w) { return __uint_as_float(w << 16); }
; __device__ __forceinline__ float bfhi(unsigned w) { return __uint_as_float(w & 0xffff0000u); }
; __device__ __forceinline__ float sigmoidf_(float x) { return 1.f / (1.f + __expf(-x)); }
;     __device__ __forceinline__ void operator()(const f32x4 (&acc)[2][2][4][2], const pg8::Unit& u, int wr_, int wc_, int fr_, int fq_) const {
;     ...
;             for (int m = 0; m < 4; ++m) { const int row = row0 + ai * 128 + m * 16;
; #pragma unroll
;                 for (int bj = 0; bj < 2; ++bj) { const int col = col0 + bj * 128;
;                     const f32x4 b0 = *(const f32x4*)(bias + col), b1 = *(const f32x4*)(bias + col + 4);
;                     const f32x4 v0 = acc[ai][bj][m][0] + b0, v1 = acc[ai][bj][m][1] + b1;
;                     const u32x4 z = *(const u32x4*)(Z + (size_t)row * 512 + col);
;                     u32x4 w;
;                     w.x = cvt_pk_bf16(bflo(z.x) * sigmoidf_(v0[0]), bfhi(z.x) * sigmoidf_(v0[1]));
;                     w.y = cvt_pk_bf16(bflo(z.y) * sigmoidf_(v0[2]), bfhi(z.y) * sigmoidf_(v0[3]));
;                     w.z = cvt_pk_bf16(bflo(z.z) * sigmoidf_(v1[0]), bfhi(z.z) * sigmoidf_(v1[1]));
;                     w.w = cvt_pk_bf16(bflo(z.w) * sigmoidf_(v1[2]), bfhi(z.w) * sigmoidf_(v1[3]));
;                     *(u32x4*)(MIX + (size_t)row * 2048 + 1536 + col) = w; } }
	v_pk_add_f32 v[68:69], v[68:69], v[72:73]
	s_nop 0
	v_mul_f32_e32 v68, 0xbfb8aa3b, v68
	v_exp_f32_e32 v68, v68
	v_pk_add_f32 v[70:71], v[70:71], v[74:75]
	v_mul_f32_e32 v69, 0xbfb8aa3b, v69
	v_pk_add_f32 v[72:73], v[64:65], v[76:77]
	v_add_f32_e32 v68, 1.0, v68
	v_rcp_f32_e32 v65, v68
	v_exp_f32_e32 v69, v69
	v_mul_f32_e32 v70, 0xbfb8aa3b, v70
	v_exp_f32_e32 v70, v70
	v_add_f32_e32 v69, 1.0, v69
	v_rcp_f32_e32 v75, v69
	v_lshlrev_b32_e32 v64, 16, v80
	v_mul_f32_e32 v64, v65, v64
	v_mov_b32_e32 v68, v75
	v_add_f32_e32 v69, 1.0, v70
	v_and_b32_e32 v65, 0xffff0000, v80
	v_mul_f32_e32 v65, v68, v65
	v_mul_f32_e32 v71, 0xbfb8aa3b, v71
	v_exp_f32_e32 v71, v71
	s_nop 0
	v_add_f32_e32 v70, 1.0, v71
	v_rcp_f32_e32 v74, v70
	v_rcp_f32_e32 v68, v69
	v_cvt_pk_bf16_f32 v64, v64, v65
	v_lshlrev_b32_e32 v65, 16, v81
	v_mul_f32_e32 v71, 0xbfb8aa3b, v72
	v_exp_f32_e32 v71, v71
	v_mov_b32_e32 v69, v74
	v_mul_f32_e32 v65, v68, v65
	v_add_f32_e32 v70, 1.0, v71
	v_and_b32_e32 v68, 0xffff0000, v81
	v_mul_f32_e32 v68, v69, v68
	v_mul_f32_e32 v73, 0xbfb8aa3b, v73
	v_exp_f32_e32 v73, v73
	s_nop 0
	v_add_f32_e32 v71, 1.0, v73
	v_rcp_f32_e32 v73, v71
	v_rcp_f32_e32 v69, v70
	v_pk_add_f32 v[66:67], v[66:67], v[78:79]
	v_cvt_pk_bf16_f32 v65, v65, v68
	v_mul_f32_e32 v66, 0xbfb8aa3b, v66
	v_exp_f32_e32 v66, v66
	v_mov_b32_e32 v70, v73
	v_add_f32_e32 v71, 1.0, v66
	v_rcp_f32_e32 v73, v71
	v_lshlrev_b32_e32 v68, 16, v82
	v_mul_f32_e32 v68, v69, v68
	v_and_b32_e32 v69, 0xffff0000, v82
	v_mul_f32_e32 v66, v70, v69
	v_mul_f32_e32 v67, 0xbfb8aa3b, v67
	v_exp_f32_e32 v67, v67
	s_nop 0
	v_add_f32_e32 v67, 1.0, v67
	v_rcp_f32_e32 v67, v67
	v_mov_b32_e32 v69, v73
	v_cvt_pk_bf16_f32 v66, v68, v66
	v_lshlrev_b32_e32 v68, 16, v83
	v_mul_f32_e32 v68, v69, v68
	v_and_b32_e32 v69, 0xffff0000, v83
	v_mul_f32_e32 v67, v67, v69
	v_cvt_pk_bf16_f32 v67, v68, v67
	global_store_dwordx4 v[84:85], v[64:67], off offset:3328
	global_load_dwordx4 v[64:67], v[138:139], off
	s_nop 0
	global_load_dwordx4 v[68:71], v[138:139], off offset:16
	v_add_u32_e32 v76, 0x80, v142
	v_ashrrev_i32_e32 v77, 31, v76
	v_lshlrev_b64 v[72:73], 10, v[76:77]
	v_lshl_add_u64 v[72:73], s[22:23], 0, v[72:73]
	v_lshl_add_u64 v[78:79], v[72:73], 0, v[140:141]
	global_load_dwordx4 v[72:75], v[78:79], off
	s_waitcnt vmcnt(0)
	v_pk_add_f32 v[60:61], v[60:61], v[64:65]
	s_nop 0
	v_mul_f32_e32 v60, 0xbfb8aa3b, v60
	v_exp_f32_e32 v60, v60
	v_lshlrev_b64 v[64:65], 12, v[76:77]
	v_pk_add_f32 v[62:63], v[62:63], v[66:67]
	v_pk_add_f32 v[66:67], v[56:57], v[68:69]
	v_add_f32_e32 v60, 1.0, v60
	v_rcp_f32_e32 v57, v60
	v_mul_f32_e32 v61, 0xbfb8aa3b, v61
	v_exp_f32_e32 v61, v61
	v_pk_add_f32 v[58:59], v[58:59], v[70:71]
	v_add_f32_e32 v61, 1.0, v61
	v_rcp_f32_e32 v69, v61
	v_mul_f32_e32 v62, 0xbfb8aa3b, v62
	v_exp_f32_e32 v62, v62
	v_mov_b32_e32 v60, v69
	v_add_f32_e32 v61, 1.0, v62
	v_lshlrev_b32_e32 v56, 16, v72
	v_mul_f32_e32 v56, v57, v56
	v_and_b32_e32 v57, 0xffff0000, v72
	v_mul_f32_e32 v57, v60, v57
	v_mul_f32_e32 v63, 0xbfb8aa3b, v63
	v_exp_f32_e32 v63, v63
	s_nop 0
	v_add_f32_e32 v62, 1.0, v63
	v_rcp_f32_e32 v68, v62
	v_rcp_f32_e32 v60, v61
	v_cvt_pk_bf16_f32 v56, v56, v57
	v_lshlrev_b32_e32 v57, 16, v73
	v_mul_f32_e32 v63, 0xbfb8aa3b, v66
	v_exp_f32_e32 v63, v63
	v_mov_b32_e32 v61, v68
	v_mul_f32_e32 v57, v60, v57
	v_add_f32_e32 v62, 1.0, v63
	v_and_b32_e32 v60, 0xffff0000, v73
	v_mul_f32_e32 v60, v61, v60
	v_mul_f32_e32 v67, 0xbfb8aa3b, v67
	v_exp_f32_e32 v67, v67
	s_nop 0
	v_add_f32_e32 v63, 1.0, v67
	v_rcp_f32_e32 v67, v63
	v_rcp_f32_e32 v61, v62
	v_mul_f32_e32 v58, 0xbfb8aa3b, v58
	v_exp_f32_e32 v58, v58
	v_mov_b32_e32 v62, v67
	v_add_f32_e32 v63, 1.0, v58
	v_rcp_f32_e32 v67, v63
	v_cvt_pk_bf16_f32 v57, v57, v60
	v_lshlrev_b32_e32 v60, 16, v74
	v_mul_f32_e32 v60, v61, v60
	v_and_b32_e32 v61, 0xffff0000, v74
	v_mul_f32_e32 v58, v62, v61
	v_mul_f32_e32 v59, 0xbfb8aa3b, v59
	v_exp_f32_e32 v59, v59
	s_nop 0
	v_add_f32_e32 v59, 1.0, v59
	v_rcp_f32_e32 v59, v59
	v_mov_b32_e32 v61, v67
	v_cvt_pk_bf16_f32 v58, v60, v58
	v_lshlrev_b32_e32 v60, 16, v75
	v_mul_f32_e32 v60, v61, v60
	v_and_b32_e32 v61, 0xffff0000, v75
	v_mul_f32_e32 v59, v59, v61
	v_cvt_pk_bf16_f32 v59, v60, v59
	v_lshl_add_u64 v[60:61], s[24:25], 0, v[64:65]
	v_lshl_add_u64 v[68:69], v[60:61], 0, v[140:141]
	global_store_dwordx4 v[68:69], v[56:59], off offset:3072
	global_load_dwordx4 v[56:59], v[138:139], off offset:512
	s_nop 0
	global_load_dwordx4 v[60:63], v[138:139], off offset:528
	global_load_dwordx4 v[64:67], v[78:79], off offset:256
	s_waitcnt vmcnt(0)
; __device__ __forceinline__ unsigned cvt_pk_bf16(float lo, float hi) { unsigned r; asm("v_cvt_pk_bf16_f32 %0, %1, %2" : "=v"(r) : "v"(lo), "v"(hi)); return r; }
; __device__ __forceinline__ float bflo(unsigned w) { return __uint_as_float(w << 16); }
; __device__ __forceinline__ float bfhi(unsigned w) { return __uint_as_float(w & 0xffff0000u); }
; __device__ __forceinline__ float sigmoidf_(float x) { return 1.f / (1.f + __expf(-x)); }
;     __device__ __forceinline__ void operator()(const f32x4 (&acc)[2][2][4][2], const pg8::Unit& u, int wr_, int wc_, int fr_, int fq_) const {
;     ...
;             for (int m = 0; m < 4; ++m) { const int row = row0 + ai * 128 + m * 16;
; #pragma unroll
;                 for (int bj = 0; bj < 2; ++bj) { const int col = col0 + bj * 128;
;                     const f32x4 b0 = *(const f32x4*)(bias + col), b1 = *(const f32x4*)(bias + col + 4);
;                     const f32x4 v0 = acc[ai][bj][m][0] + b0, v1 = acc[ai][bj][m][1] + b1;
;                     const u32x4 z = *(const u32x4*)(Z + (size_t)row * 512 + col);
;                     u32x4 w;
;                     w.x = cvt_pk_bf16(bflo(z.x) * sigmoidf_(v0[0]), bfhi(z.x) * sigmoidf_(v0[1]));
;                     w.y = cvt_pk_bf16(bflo(z.y) * sigmoidf_(v0[2]), bfhi(z.y) * sigmoidf_(v0[3]));
;                     w.z = cvt_pk_bf16(bflo(z.z) * sigmoidf_(v1[0]), bfhi(z.z) * sigmoidf_(v1[1]));
;                     w.w = cvt_pk_bf16(bflo(z.w) * sigmoidf_(v1[2]), bfhi(z.w) * sigmoidf_(v1[3]));
;                     *(u32x4*)(MIX + (size_t)row * 2048 + 1536 + col) = w; } }
	v_pk_add_f32 v[52:53], v[52:53], v[56:57]
	s_nop 0
	v_mul_f32_e32 v52, 0xbfb8aa3b, v52
	v_exp_f32_e32 v52, v52
	v_pk_add_f32 v[54:55], v[54:55], v[58:59]
	v_mul_f32_e32 v53, 0xbfb8aa3b, v53
	v_pk_add_f32 v[56:57], v[48:49], v[60:61]
	v_add_f32_e32 v52, 1.0, v52
	v_rcp_f32_e32 v49, v52
	v_exp_f32_e32 v53, v53
	v_mul_f32_e32 v54, 0xbfb8aa3b, v54
	v_exp_f32_e32 v54, v54
	v_add_f32_e32 v53, 1.0, v53
	v_rcp_f32_e32 v59, v53
	v_lshlrev_b32_e32 v48, 16, v64
	v_mul_f32_e32 v48, v49, v48
	v_mov_b32_e32 v52, v59
	v_add_f32_e32 v53, 1.0, v54
	v_and_b32_e32 v49, 0xffff0000, v64
	v_mul_f32_e32 v49, v52, v49
	v_mul_f32_e32 v55, 0xbfb8aa3b, v55
	v_exp_f32_e32 v55, v55
	s_nop 0
	v_add_f32_e32 v54, 1.0, v55
	v_rcp_f32_e32 v58, v54
	v_rcp_f32_e32 v52, v53
	v_cvt_pk_bf16_f32 v48, v48, v49
	v_lshlrev_b32_e32 v49, 16, v65
	v_mul_f32_e32 v55, 0xbfb8aa3b, v56
	v_exp_f32_e32 v55, v55
	v_mov_b32_e32 v53, v58
	v_mul_f32_e32 v49, v52, v49
	v_add_f32_e32 v54, 1.0, v55
	v_and_b32_e32 v52, 0xffff0000, v65
	v_mul_f32_e32 v52, v53, v52
	v_mul_f32_e32 v57, 0xbfb8aa3b, v57
	v_exp_f32_e32 v57, v57
	s_nop 0
	v_add_f32_e32 v55, 1.0, v57
	v_rcp_f32_e32 v57, v55
	v_rcp_f32_e32 v53, v54
	v_pk_add_f32 v[50:51], v[50:51], v[62:63]
	v_cvt_pk_bf16_f32 v49, v49, v52
	v_mul_f32_e32 v50, 0xbfb8aa3b, v50
	v_exp_f32_e32 v50, v50
	v_mov_b32_e32 v54, v57
	v_add_f32_e32 v55, 1.0, v50
	v_rcp_f32_e32 v57, v55
	v_lshlrev_b32_e32 v52, 16, v66
	v_mul_f32_e32 v52, v53, v52
	v_and_b32_e32 v53, 0xffff0000, v66
	v_mul_f32_e32 v50, v54, v53
	v_mul_f32_e32 v51, 0xbfb8aa3b, v51
	v_exp_f32_e32 v51, v51
	s_nop 0
	v_add_f32_e32 v51, 1.0, v51
	v_rcp_f32_e32 v51, v51
	v_mov_b32_e32 v53, v57
	v_cvt_pk_bf16_f32 v50, v52, v50
	v_lshlrev_b32_e32 v52, 16, v67
	v_mul_f32_e32 v52, v53, v52
	v_and_b32_e32 v53, 0xffff0000, v67
	v_mul_f32_e32 v51, v51, v53
	v_cvt_pk_bf16_f32 v51, v52, v51
	global_store_dwordx4 v[68:69], v[48:51], off offset:3328
	global_load_dwordx4 v[48:51], v[138:139], off
	s_nop 0
	global_load_dwordx4 v[52:55], v[138:139], off offset:16
	v_add_u32_e32 v60, 0x90, v142
	v_ashrrev_i32_e32 v61, 31, v60
	v_lshlrev_b64 v[56:57], 10, v[60:61]
	v_lshl_add_u64 v[56:57], s[22:23], 0, v[56:57]
	v_lshl_add_u64 v[62:63], v[56:57], 0, v[140:141]
	global_load_dwordx4 v[56:59], v[62:63], off
	s_waitcnt vmcnt(0)
	v_pk_add_f32 v[44:45], v[44:45], v[48:49]
	s_nop 0
	v_mul_f32_e32 v44, 0xbfb8aa3b, v44
	v_exp_f32_e32 v44, v44
	v_lshlrev_b64 v[48:49], 12, v[60:61]
	v_pk_add_f32 v[46:47], v[46:47], v[50:51]
	v_pk_add_f32 v[50:51], v[40:41], v[52:53]
	v_add_f32_e32 v44, 1.0, v44
	v_rcp_f32_e32 v41, v44
	v_mul_f32_e32 v45, 0xbfb8aa3b, v45
	v_exp_f32_e32 v45, v45
	v_pk_add_f32 v[42:43], v[42:43], v[54:55]
	v_add_f32_e32 v45, 1.0, v45
	v_rcp_f32_e32 v53, v45
	v_mul_f32_e32 v46, 0xbfb8aa3b, v46
	v_exp_f32_e32 v46, v46
	v_mov_b32_e32 v44, v53
	v_add_f32_e32 v45, 1.0, v46
	v_lshlrev_b32_e32 v40, 16, v56
	v_mul_f32_e32 v40, v41, v40
	v_and_b32_e32 v41, 0xffff0000, v56
	v_mul_f32_e32 v41, v44, v41
	v_mul_f32_e32 v47, 0xbfb8aa3b, v47
	v_exp_f32_e32 v47, v47
	s_nop 0
	v_add_f32_e32 v46, 1.0, v47
	v_rcp_f32_e32 v52, v46
	v_rcp_f32_e32 v44, v45
	v_cvt_pk_bf16_f32 v40, v40, v41
	v_lshlrev_b32_e32 v41, 16, v57
	v_mul_f32_e32 v47, 0xbfb8aa3b, v50
	v_exp_f32_e32 v47, v47
	v_mov_b32_e32 v45, v52
	v_mul_f32_e32 v41, v44, v41
	v_add_f32_e32 v46, 1.0, v47
	v_and_b32_e32 v44, 0xffff0000, v57
	v_mul_f32_e32 v44, v45, v44
	v_mul_f32_e32 v51, 0xbfb8aa3b, v51
	v_exp_f32_e32 v51, v51
	s_nop 0
	v_add_f32_e32 v47, 1.0, v51
	v_rcp_f32_e32 v51, v47
	v_rcp_f32_e32 v45, v46
	v_mul_f32_e32 v42, 0xbfb8aa3b, v42
	v_exp_f32_e32 v42, v42
	v_mov_b32_e32 v46, v51
	v_add_f32_e32 v47, 1.0, v42
	v_rcp_f32_e32 v51, v47
	v_cvt_pk_bf16_f32 v41, v41, v44
	v_lshlrev_b32_e32 v44, 16, v58
	v_mul_f32_e32 v44, v45, v44
	v_and_b32_e32 v45, 0xffff0000, v58
	v_mul_f32_e32 v42, v46, v45
	v_mul_f32_e32 v43, 0xbfb8aa3b, v43
	v_exp_f32_e32 v43, v43
	s_nop 0
	v_add_f32_e32 v43, 1.0, v43
	v_rcp_f32_e32 v43, v43
	v_mov_b32_e32 v45, v51
	v_cvt_pk_bf16_f32 v42, v44, v42
	v_lshlrev_b32_e32 v44, 16, v59
	v_mul_f32_e32 v44, v45, v44
	v_and_b32_e32 v45, 0xffff0000, v59
	v_mul_f32_e32 v43, v43, v45
	v_cvt_pk_bf16_f32 v43, v44, v43
	v_lshl_add_u64 v[44:45], s[24:25], 0, v[48:49]
	v_lshl_add_u64 v[52:53], v[44:45], 0, v[140:141]
	global_store_dwordx4 v[52:53], v[40:43], off offset:3072
	global_load_dwordx4 v[40:43], v[138:139], off offset:512
	s_nop 0
	global_load_dwordx4 v[44:47], v[138:139], off offset:528
	global_load_dwordx4 v[48:51], v[62:63], off offset:256
	s_waitcnt vmcnt(0)
; __device__ __forceinline__ unsigned cvt_pk_bf16(float lo, float hi) { unsigned r; asm("v_cvt_pk_bf16_f32 %0, %1, %2" : "=v"(r) : "v"(lo), "v"(hi)); return r; }
; __device__ __forceinline__ float bflo(unsigned w) { return __uint_as_float(w << 16); }
; __device__ __forceinline__ float bfhi(unsigned w) { return __uint_as_float(w & 0xffff0000u); }
; __device__ __forceinline__ float sigmoidf_(float x) { return 1.f / (1.f + __expf(-x)); }
;     __device__ __forceinline__ void operator()(const f32x4 (&acc)[2][2][4][2], const pg8::Unit& u, int wr_, int wc_, int fr_, int fq_) const {
;     ...
;             for (int m = 0; m < 4; ++m) { const int row = row0 + ai * 128 + m * 16;
; #pragma unroll
;                 for (int bj = 0; bj < 2; ++bj) { const int col = col0 + bj * 128;
;                     const f32x4 b0 = *(const f32x4*)(bias + col), b1 = *(const f32x4*)(bias + col + 4);
;                     const f32x4 v0 = acc[ai][bj][m][0] + b0, v1 = acc[ai][bj][m][1] + b1;
;                     const u32x4 z = *(const u32x4*)(Z + (size_t)row * 512 + col);
;                     u32x4 w;
;                     w.x = cvt_pk_bf16(bflo(z.x) * sigmoidf_(v0[0]), bfhi(z.x) * sigmoidf_(v0[1]));
;                     w.y = cvt_pk_bf16(bflo(z.y) * sigmoidf_(v0[2]), bfhi(z.y) * sigmoidf_(v0[3]));
;                     w.z = cvt_pk_bf16(bflo(z.z) * sigmoidf_(v1[0]), bfhi(z.z) * sigmoidf_(v1[1]));
;                     w.w = cvt_pk_bf16(bflo(z.w) * sigmoidf_(v1[2]), bfhi(z.w) * sigmoidf_(v1[3]));
;                     *(u32x4*)(MIX + (size_t)row * 2048 + 1536 + col) = w; } }
	v_pk_add_f32 v[36:37], v[36:37], v[40:41]
	s_nop 0
	v_mul_f32_e32 v36, 0xbfb8aa3b, v36
	v_exp_f32_e32 v36, v36
	v_pk_add_f32 v[38:39], v[38:39], v[42:43]
	v_mul_f32_e32 v37, 0xbfb8aa3b, v37
	v_pk_add_f32 v[40:41], v[32:33], v[44:45]
	v_add_f32_e32 v36, 1.0, v36
	v_rcp_f32_e32 v33, v36
	v_exp_f32_e32 v37, v37
	v_mul_f32_e32 v38, 0xbfb8aa3b, v38
	v_exp_f32_e32 v38, v38
	v_add_f32_e32 v37, 1.0, v37
	v_rcp_f32_e32 v43, v37
	v_lshlrev_b32_e32 v32, 16, v48
	v_mul_f32_e32 v32, v33, v32
	v_mov_b32_e32 v36, v43
	v_add_f32_e32 v37, 1.0, v38
	v_and_b32_e32 v33, 0xffff0000, v48
	v_mul_f32_e32 v33, v36, v33
	v_mul_f32_e32 v39, 0xbfb8aa3b, v39
	v_exp_f32_e32 v39, v39
	s_nop 0
	v_add_f32_e32 v38, 1.0, v39
	v_rcp_f32_e32 v42, v38
	v_rcp_f32_e32 v36, v37
	v_cvt_pk_bf16_f32 v32, v32, v33
	v_lshlrev_b32_e32 v33, 16, v49
	v_mul_f32_e32 v39, 0xbfb8aa3b, v40
	v_exp_f32_e32 v39, v39
	v_mov_b32_e32 v37, v42
	v_mul_f32_e32 v33, v36, v33
	v_add_f32_e32 v38, 1.0, v39
	v_and_b32_e32 v36, 0xffff0000, v49
	v_mul_f32_e32 v36, v37, v36
	v_mul_f32_e32 v41, 0xbfb8aa3b, v41
	v_exp_f32_e32 v41, v41
	s_nop 0
	v_add_f32_e32 v39, 1.0, v41
	v_rcp_f32_e32 v41, v39
	v_rcp_f32_e32 v37, v38
	v_pk_add_f32 v[34:35], v[34:35], v[46:47]
	v_cvt_pk_bf16_f32 v33, v33, v36
	v_mul_f32_e32 v34, 0xbfb8aa3b, v34
	v_exp_f32_e32 v34, v34
	v_mov_b32_e32 v38, v41
	v_add_f32_e32 v39, 1.0, v34
	v_rcp_f32_e32 v41, v39
	v_lshlrev_b32_e32 v36, 16, v50
	v_mul_f32_e32 v36, v37, v36
	v_and_b32_e32 v37, 0xffff0000, v50
	v_mul_f32_e32 v34, v38, v37
	v_mul_f32_e32 v35, 0xbfb8aa3b, v35
	v_exp_f32_e32 v35, v35
	s_nop 0
	v_add_f32_e32 v35, 1.0, v35
	v_rcp_f32_e32 v35, v35
	v_mov_b32_e32 v37, v41
	v_cvt_pk_bf16_f32 v34, v36, v34
	v_lshlrev_b32_e32 v36, 16, v51
	v_mul_f32_e32 v36, v37, v36
	v_and_b32_e32 v37, 0xffff0000, v51
	v_mul_f32_e32 v35, v35, v37
	v_cvt_pk_bf16_f32 v35, v36, v35
	global_store_dwordx4 v[52:53], v[32:35], off offset:3328
	global_load_dwordx4 v[32:35], v[138:139], off
	s_nop 0
	global_load_dwordx4 v[36:39], v[138:139], off offset:16
	v_add_u32_e32 v44, 0xa0, v142
	v_ashrrev_i32_e32 v45, 31, v44
	v_lshlrev_b64 v[40:41], 10, v[44:45]
	v_lshl_add_u64 v[40:41], s[22:23], 0, v[40:41]
	v_lshl_add_u64 v[46:47], v[40:41], 0, v[140:141]
	global_load_dwordx4 v[40:43], v[46:47], off
	s_waitcnt vmcnt(0)
	v_pk_add_f32 v[28:29], v[28:29], v[32:33]
	s_nop 0
	v_mul_f32_e32 v28, 0xbfb8aa3b, v28
	v_exp_f32_e32 v28, v28
	v_lshlrev_b64 v[32:33], 12, v[44:45]
	v_pk_add_f32 v[30:31], v[30:31], v[34:35]
	v_pk_add_f32 v[34:35], v[24:25], v[36:37]
	v_add_f32_e32 v28, 1.0, v28
	v_rcp_f32_e32 v25, v28
	v_mul_f32_e32 v29, 0xbfb8aa3b, v29
	v_exp_f32_e32 v29, v29
	v_pk_add_f32 v[26:27], v[26:27], v[38:39]
	v_add_f32_e32 v29, 1.0, v29
	v_rcp_f32_e32 v37, v29
	v_mul_f32_e32 v30, 0xbfb8aa3b, v30
	v_exp_f32_e32 v30, v30
	v_mov_b32_e32 v28, v37
	v_add_f32_e32 v29, 1.0, v30
	v_lshlrev_b32_e32 v24, 16, v40
	v_mul_f32_e32 v24, v25, v24
	v_and_b32_e32 v25, 0xffff0000, v40
	v_mul_f32_e32 v25, v28, v25
	v_mul_f32_e32 v31, 0xbfb8aa3b, v31
	v_exp_f32_e32 v31, v31
	s_nop 0
	v_add_f32_e32 v30, 1.0, v31
	v_rcp_f32_e32 v36, v30
	v_rcp_f32_e32 v28, v29
	v_cvt_pk_bf16_f32 v24, v24, v25
	v_lshlrev_b32_e32 v25, 16, v41
	v_mul_f32_e32 v31, 0xbfb8aa3b, v34
	v_exp_f32_e32 v31, v31
	v_mov_b32_e32 v29, v36
	v_mul_f32_e32 v25, v28, v25
	v_add_f32_e32 v30, 1.0, v31
	v_and_b32_e32 v28, 0xffff0000, v41
	v_mul_f32_e32 v28, v29, v28
	v_mul_f32_e32 v35, 0xbfb8aa3b, v35
	v_exp_f32_e32 v35, v35
	s_nop 0
	v_add_f32_e32 v31, 1.0, v35
	v_rcp_f32_e32 v35, v31
	v_rcp_f32_e32 v29, v30
	v_mul_f32_e32 v26, 0xbfb8aa3b, v26
	v_exp_f32_e32 v26, v26
	v_mov_b32_e32 v30, v35
	v_add_f32_e32 v31, 1.0, v26
	v_rcp_f32_e32 v35, v31
	v_cvt_pk_bf16_f32 v25, v25, v28
	v_lshlrev_b32_e32 v28, 16, v42
	v_mul_f32_e32 v28, v29, v28
	v_and_b32_e32 v29, 0xffff0000, v42
	v_mul_f32_e32 v26, v30, v29
	v_mul_f32_e32 v27, 0xbfb8aa3b, v27
	v_exp_f32_e32 v27, v27
	s_nop 0
	v_add_f32_e32 v27, 1.0, v27
	v_rcp_f32_e32 v27, v27
	v_mov_b32_e32 v29, v35
	v_cvt_pk_bf16_f32 v26, v28, v26
	v_lshlrev_b32_e32 v28, 16, v43
	v_mul_f32_e32 v28, v29, v28
	v_and_b32_e32 v29, 0xffff0000, v43
	v_mul_f32_e32 v27, v27, v29
	v_cvt_pk_bf16_f32 v27, v28, v27
	v_lshl_add_u64 v[28:29], s[24:25], 0, v[32:33]
	v_lshl_add_u64 v[36:37], v[28:29], 0, v[140:141]
	global_store_dwordx4 v[36:37], v[24:27], off offset:3072
	global_load_dwordx4 v[24:27], v[138:139], off offset:512
	s_nop 0
	global_load_dwordx4 v[28:31], v[138:139], off offset:528
	global_load_dwordx4 v[32:35], v[46:47], off offset:256
	s_waitcnt vmcnt(0)
; __device__ __forceinline__ unsigned cvt_pk_bf16(float lo, float hi) { unsigned r; asm("v_cvt_pk_bf16_f32 %0, %1, %2" : "=v"(r) : "v"(lo), "v"(hi)); return r; }
; __device__ __forceinline__ float bflo(unsigned w) { return __uint_as_float(w << 16); }
; __device__ __forceinline__ float bfhi(unsigned w) { return __uint_as_float(w & 0xffff0000u); }
; __device__ __forceinline__ float sigmoidf_(float x) { return 1.f / (1.f + __expf(-x)); }
; template <class Epi, class Sched>
; __device__ __forceinline__ void gemm_phase(LAS unsigned char* lds, const Gemm g, const Sched& S, const Epi& E) {
;     ...
;         E(acc, cur, wr, wc, fr, fq);
;         if (!has_next) break;
; #pragma unroll
;         for (int a = 0; a < 2; ++a)
; #pragma unroll
;             for (int b = 0; b < 2; ++b)
; #pragma unroll
;                 for (int m = 0; m < 4; ++m)
; #pragma unroll
;                     for (int n = 0; n < 2; ++n) acc[a][b][m][n] = (f32x4){0.f, 0.f, 0.f, 0.f};
;         cur = nxt; cA = nA; cB = nB; ++ui;
;     }
;     __device__ __forceinline__ void operator()(const f32x4 (&acc)[2][2][4][2], const pg8::Unit& u, int wr_, int wc_, int fr_, int fq_) const {
;     ...
;             for (int m = 0; m < 4; ++m) { const int row = row0 + ai * 128 + m * 16;
; #pragma unroll
;                 for (int bj = 0; bj < 2; ++bj) { const int col = col0 + bj * 128;
;                     const f32x4 b0 = *(const f32x4*)(bias + col), b1 = *(const f32x4*)(bias + col + 4);
;                     const f32x4 v0 = acc[ai][bj][m][0] + b0, v1 = acc[ai][bj][m][1] + b1;
;                     const u32x4 z = *(const u32x4*)(Z + (size_t)row * 512 + col);
;                     u32x4 w;
;                     w.x = cvt_pk_bf16(bflo(z.x) * sigmoidf_(v0[0]), bfhi(z.x) * sigmoidf_(v0[1]));
;                     w.y = cvt_pk_bf16(bflo(z.y) * sigmoidf_(v0[2]), bfhi(z.y) * sigmoidf_(v0[3]));
;                     w.z = cvt_pk_bf16(bflo(z.z) * sigmoidf_(v1[0]), bfhi(z.z) * sigmoidf_(v1[1]));
;                     w.w = cvt_pk_bf16(bflo(z.w) * sigmoidf_(v1[2]), bfhi(z.w) * sigmoidf_(v1[3]));
;                     *(u32x4*)(MIX + (size_t)row * 2048 + 1536 + col) = w; } }
	v_pk_add_f32 v[20:21], v[20:21], v[24:25]
	s_nop 0
	v_mul_f32_e32 v20, 0xbfb8aa3b, v20
	v_exp_f32_e32 v20, v20
	v_pk_add_f32 v[22:23], v[22:23], v[26:27]
	v_mul_f32_e32 v21, 0xbfb8aa3b, v21
	v_pk_add_f32 v[24:25], v[16:17], v[28:29]
	v_add_f32_e32 v20, 1.0, v20
	v_rcp_f32_e32 v17, v20
	v_exp_f32_e32 v21, v21
	v_mul_f32_e32 v22, 0xbfb8aa3b, v22
	v_exp_f32_e32 v22, v22
	v_add_f32_e32 v21, 1.0, v21
	v_rcp_f32_e32 v27, v21
	v_lshlrev_b32_e32 v16, 16, v32
	v_mul_f32_e32 v16, v17, v16
	v_mov_b32_e32 v20, v27
	v_add_f32_e32 v21, 1.0, v22
	v_and_b32_e32 v17, 0xffff0000, v32
	v_mul_f32_e32 v17, v20, v17
	v_mul_f32_e32 v23, 0xbfb8aa3b, v23
	v_exp_f32_e32 v23, v23
	s_nop 0
	v_add_f32_e32 v22, 1.0, v23
	v_rcp_f32_e32 v26, v22
	v_rcp_f32_e32 v20, v21
	v_cvt_pk_bf16_f32 v16, v16, v17
	v_lshlrev_b32_e32 v17, 16, v33
	v_mul_f32_e32 v23, 0xbfb8aa3b, v24
	v_exp_f32_e32 v23, v23
	v_mov_b32_e32 v21, v26
	v_mul_f32_e32 v17, v20, v17
	v_add_f32_e32 v22, 1.0, v23
	v_and_b32_e32 v20, 0xffff0000, v33
	v_mul_f32_e32 v20, v21, v20
	v_mul_f32_e32 v25, 0xbfb8aa3b, v25
	v_exp_f32_e32 v25, v25
	s_nop 0
	v_add_f32_e32 v23, 1.0, v25
	v_rcp_f32_e32 v25, v23
	v_rcp_f32_e32 v21, v22
	v_pk_add_f32 v[18:19], v[18:19], v[30:31]
	v_cvt_pk_bf16_f32 v17, v17, v20
	v_mul_f32_e32 v18, 0xbfb8aa3b, v18
	v_exp_f32_e32 v18, v18
	v_mov_b32_e32 v22, v25
	v_add_f32_e32 v23, 1.0, v18
	v_rcp_f32_e32 v25, v23
	v_lshlrev_b32_e32 v20, 16, v34
	v_mul_f32_e32 v20, v21, v20
	v_and_b32_e32 v21, 0xffff0000, v34
	v_mul_f32_e32 v18, v22, v21
	v_mul_f32_e32 v19, 0xbfb8aa3b, v19
	v_exp_f32_e32 v19, v19
	s_nop 0
	v_add_f32_e32 v19, 1.0, v19
	v_rcp_f32_e32 v19, v19
	v_mov_b32_e32 v21, v25
	v_cvt_pk_bf16_f32 v18, v20, v18
	v_lshlrev_b32_e32 v20, 16, v35
	v_mul_f32_e32 v20, v21, v20
	v_and_b32_e32 v21, 0xffff0000, v35
	v_mul_f32_e32 v19, v19, v21
	v_cvt_pk_bf16_f32 v19, v20, v19
	global_store_dwordx4 v[36:37], v[16:19], off offset:3328
	global_load_dwordx4 v[16:19], v[138:139], off
	s_nop 0
	global_load_dwordx4 v[20:23], v[138:139], off offset:16
	v_add_u32_e32 v28, 0xb0, v142
	v_ashrrev_i32_e32 v29, 31, v28
	v_lshlrev_b64 v[24:25], 10, v[28:29]
	v_lshl_add_u64 v[24:25], s[22:23], 0, v[24:25]
	v_lshl_add_u64 v[30:31], v[24:25], 0, v[140:141]
	global_load_dwordx4 v[24:27], v[30:31], off
	s_waitcnt vmcnt(0)
	v_pk_add_f32 v[12:13], v[12:13], v[16:17]
	s_nop 0
	v_mul_f32_e32 v12, 0xbfb8aa3b, v12
	v_exp_f32_e32 v12, v12
	v_lshlrev_b64 v[16:17], 12, v[28:29]
	v_pk_add_f32 v[14:15], v[14:15], v[18:19]
	v_pk_add_f32 v[18:19], v[8:9], v[20:21]
	v_add_f32_e32 v12, 1.0, v12
	v_rcp_f32_e32 v9, v12
	v_mul_f32_e32 v13, 0xbfb8aa3b, v13
	v_exp_f32_e32 v13, v13
	v_pk_add_f32 v[10:11], v[10:11], v[22:23]
	v_add_f32_e32 v13, 1.0, v13
	v_rcp_f32_e32 v21, v13
	v_mul_f32_e32 v14, 0xbfb8aa3b, v14
	v_exp_f32_e32 v14, v14
	v_mov_b32_e32 v12, v21
	v_add_f32_e32 v13, 1.0, v14
	v_lshlrev_b32_e32 v8, 16, v24
	v_mul_f32_e32 v8, v9, v8
	v_and_b32_e32 v9, 0xffff0000, v24
	v_mul_f32_e32 v9, v12, v9
	v_mul_f32_e32 v15, 0xbfb8aa3b, v15
	v_exp_f32_e32 v15, v15
	s_nop 0
	v_add_f32_e32 v14, 1.0, v15
	v_rcp_f32_e32 v20, v14
	v_rcp_f32_e32 v12, v13
	v_cvt_pk_bf16_f32 v8, v8, v9
	v_lshlrev_b32_e32 v9, 16, v25
	v_mul_f32_e32 v15, 0xbfb8aa3b, v18
	v_exp_f32_e32 v15, v15
	v_mov_b32_e32 v13, v20
	v_mul_f32_e32 v9, v12, v9
	v_add_f32_e32 v14, 1.0, v15
	v_and_b32_e32 v12, 0xffff0000, v25
	v_mul_f32_e32 v12, v13, v12
	v_mul_f32_e32 v19, 0xbfb8aa3b, v19
	v_exp_f32_e32 v19, v19
	s_nop 0
	v_add_f32_e32 v15, 1.0, v19
	v_rcp_f32_e32 v19, v15
	v_rcp_f32_e32 v13, v14
	v_mul_f32_e32 v10, 0xbfb8aa3b, v10
	v_exp_f32_e32 v10, v10
	v_mov_b32_e32 v14, v19
	v_add_f32_e32 v15, 1.0, v10
	v_rcp_f32_e32 v19, v15
	v_cvt_pk_bf16_f32 v9, v9, v12
	v_lshlrev_b32_e32 v12, 16, v26
	v_mul_f32_e32 v12, v13, v12
	v_and_b32_e32 v13, 0xffff0000, v26
	v_mul_f32_e32 v10, v14, v13
	v_mul_f32_e32 v11, 0xbfb8aa3b, v11
	v_exp_f32_e32 v11, v11
	s_nop 0
	v_add_f32_e32 v11, 1.0, v11
	v_rcp_f32_e32 v11, v11
	v_mov_b32_e32 v13, v19
	v_cvt_pk_bf16_f32 v10, v12, v10
	v_lshlrev_b32_e32 v12, 16, v27
	v_mul_f32_e32 v12, v13, v12
	v_and_b32_e32 v13, 0xffff0000, v27
	v_mul_f32_e32 v11, v11, v13
	v_cvt_pk_bf16_f32 v11, v12, v11
	v_lshl_add_u64 v[12:13], s[24:25], 0, v[16:17]
	v_lshl_add_u64 v[20:21], v[12:13], 0, v[140:141]
	global_store_dwordx4 v[20:21], v[8:11], off offset:3072
	global_load_dwordx4 v[8:11], v[138:139], off offset:512
	s_nop 0
	global_load_dwordx4 v[12:15], v[138:139], off offset:528
	global_load_dwordx4 v[16:19], v[30:31], off offset:256
	s_waitcnt vmcnt(0)
	v_pk_add_f32 v[4:5], v[4:5], v[8:9]
	s_nop 0
	v_mul_f32_e32 v4, 0xbfb8aa3b, v4
	v_exp_f32_e32 v4, v4
	v_pk_add_f32 v[6:7], v[6:7], v[10:11]
	v_mul_f32_e32 v5, 0xbfb8aa3b, v5
	v_pk_add_f32 v[8:9], v[0:1], v[12:13]
	v_add_f32_e32 v4, 1.0, v4
	v_rcp_f32_e32 v1, v4
	v_exp_f32_e32 v5, v5
	v_mul_f32_e32 v6, 0xbfb8aa3b, v6
	v_exp_f32_e32 v6, v6
	v_add_f32_e32 v5, 1.0, v5
	v_rcp_f32_e32 v11, v5
	v_lshlrev_b32_e32 v0, 16, v16
	v_mul_f32_e32 v0, v1, v0
	v_mov_b32_e32 v4, v11
	v_add_f32_e32 v5, 1.0, v6
	v_and_b32_e32 v1, 0xffff0000, v16
	v_mul_f32_e32 v1, v4, v1
	v_mul_f32_e32 v7, 0xbfb8aa3b, v7
	v_exp_f32_e32 v7, v7
	s_nop 0
	v_add_f32_e32 v6, 1.0, v7
	v_rcp_f32_e32 v10, v6
	v_rcp_f32_e32 v4, v5
	v_cvt_pk_bf16_f32 v0, v0, v1
	v_lshlrev_b32_e32 v1, 16, v17
	v_mul_f32_e32 v7, 0xbfb8aa3b, v8
	v_exp_f32_e32 v7, v7
	v_mov_b32_e32 v5, v10
	v_mul_f32_e32 v1, v4, v1
	v_add_f32_e32 v6, 1.0, v7
	v_and_b32_e32 v4, 0xffff0000, v17
	v_mul_f32_e32 v4, v5, v4
	v_mul_f32_e32 v9, 0xbfb8aa3b, v9
	v_exp_f32_e32 v9, v9
	s_nop 0
	v_add_f32_e32 v7, 1.0, v9
	v_rcp_f32_e32 v9, v7
	v_rcp_f32_e32 v5, v6
	v_pk_add_f32 v[2:3], v[2:3], v[14:15]
	v_cvt_pk_bf16_f32 v1, v1, v4
	v_mul_f32_e32 v2, 0xbfb8aa3b, v2
	v_exp_f32_e32 v2, v2
	v_mov_b32_e32 v6, v9
	v_add_f32_e32 v7, 1.0, v2
	v_rcp_f32_e32 v9, v7
	v_lshlrev_b32_e32 v4, 16, v18
	v_mul_f32_e32 v4, v5, v4
	v_and_b32_e32 v5, 0xffff0000, v18
	v_mul_f32_e32 v2, v6, v5
	v_mul_f32_e32 v3, 0xbfb8aa3b, v3
	v_exp_f32_e32 v3, v3
	s_nop 0
	v_add_f32_e32 v3, 1.0, v3
	v_rcp_f32_e32 v3, v3
	v_mov_b32_e32 v5, v9
	v_cvt_pk_bf16_f32 v2, v4, v2
	v_lshlrev_b32_e32 v4, 16, v19
	v_mul_f32_e32 v4, v5, v4
	v_and_b32_e32 v5, 0xffff0000, v19
	v_mul_f32_e32 v3, v3, v5
	s_and_b64 vcc, exec, s[2:3]
	s_mov_b32 s5, s48
	s_mov_b32 s4, s50
	v_cvt_pk_bf16_f32 v3, v4, v3
	global_store_dwordx4 v[20:21], v[0:3], off offset:3328
	s_cbranch_vccz .LBB0_443
	s_waitcnt vmcnt(0)
	s_cmpk_gt_u32 s13, 0xff
	s_cbranch_scc1 .LBB0_450
	s_barrier

; __device__ __forceinline__ unsigned cvt_pk_bf16(float lo, float hi) { unsigned r; asm("v_cvt_pk_bf16_f32 %0, %1, %2" : "=v"(r) : "v"(lo), "v"(hi)); return r; }
; __device__ __forceinline__ float bflo(unsigned w) { return __uint_as_float(w << 16); }
; __device__ __forceinline__ float bfhi(unsigned w) { return __uint_as_float(w & 0xffff0000u); }
; __device__ __forceinline__ float gelu_tanh(float x) { const float u = 0.7978845608028654f * (x + 0.044715f * x * x * x); return x / (1.f + __expf(-2.f * u)); }
; __device__ __forceinline__ void phase_conv(PRef p, int layer, int nseg) {
;     ...
;             for (int xi = 0; xi < 4; ++xi) {
;                 float acc[8];
; #pragma unroll
;                 for (int j = 0; j < 8; ++j) acc[j] = bias[j];
; #pragma unroll
;                 for (int ky = 0; ky < 3; ++ky)
; #pragma unroll
;                     for (int kx = 0; kx < 3; ++kx) { const u32x4 gq = gc[ky][xi + kx]; const int k = ky * 3 + kx;
;                         acc[0] += w[k][0] * bflo(gq.x); acc[1] += w[k][1] * bfhi(gq.x); acc[2] += w[k][2] * bflo(gq.y); acc[3] += w[k][3] * bfhi(gq.y);
;                         acc[4] += w[k][4] * bflo(gq.z); acc[5] += w[k][5] * bfhi(gq.z); acc[6] += w[k][6] * bflo(gq.w); acc[7] += w[k][7] * bfhi(gq.w); }
;                 u32x4 o;
;                 o.x = cvt_pk_bf16(gelu_tanh(acc[0]) * bflo(vv[xi].x), gelu_tanh(acc[1]) * bfhi(vv[xi].x));
;                 o.y = cvt_pk_bf16(gelu_tanh(acc[2]) * bflo(vv[xi].y), gelu_tanh(acc[3]) * bfhi(vv[xi].y));
;                 o.z = cvt_pk_bf16(gelu_tanh(acc[4]) * bflo(vv[xi].z), gelu_tanh(acc[5]) * bfhi(vv[xi].z));
;                 o.w = cvt_pk_bf16(gelu_tanh(acc[6]) * bflo(vv[xi].w), gelu_tanh(acc[7]) * bfhi(vv[xi].w));
;                 *(u32x4*)((bf16_t*)lp[1] + (size_t)(xb + xi) * NUP + NFF) = o; } }
.LBB0_551:
	s_or_b64 exec, exec, s[2:3]
	s_waitcnt vmcnt(0)
	v_lshlrev_b32_e32 v180, 16, v132
	v_and_b32_e32 v132, 0xffff0000, v132
	v_fma_f32 v181, v5, v132, v77
	v_lshlrev_b32_e32 v132, 16, v133
	v_fma_f32 v182, v6, v132, v78
	v_and_b32_e32 v132, 0xffff0000, v133
	v_fma_f32 v183, v7, v132, v79
	v_lshlrev_b32_e32 v132, 16, v134
	v_fma_f32 v184, v0, v132, v72
	v_and_b32_e32 v132, 0xffff0000, v134
	v_fma_f32 v134, v1, v132, v73
	v_lshlrev_b32_e32 v132, 16, v135
	v_fma_f32 v185, v2, v132, v74
	v_and_b32_e32 v132, 0xffff0000, v135
	v_lshlrev_b32_e32 v199, 16, v136
	v_lshlrev_b32_e32 v198, 16, v124
	v_fma_f32 v180, v4, v180, v76
	v_fma_f32 v135, v3, v132, v75
	v_and_b32_e32 v197, 0xffff0000, v136
	v_fma_f32 v132, v8, v198, v180
	v_and_b32_e32 v196, 0xffff0000, v124
	v_fma_f32 v180, v9, v199, v132
	v_lshlrev_b32_e32 v194, 16, v125
	v_fma_f32 v124, v16, v196, v181
	v_lshlrev_b32_e32 v195, 16, v137
	v_fma_f32 v136, v17, v197, v124
	v_mad_i64_i32 v[120:121], s[4:5], v80, s28, v[170:171]
	v_fma_f32 v124, v10, v194, v182
	v_and_b32_e32 v193, 0xffff0000, v137
	v_and_b32_e32 v192, 0xffff0000, v125
	v_add_co_u32_e32 v200, vcc, 0x2000, v120
	v_fma_f32 v132, v11, v195, v124
	s_nop 0
	v_addc_co_u32_e32 v201, vcc, 0, v121, vcc
	v_mad_i64_i32 v[80:81], s[4:5], v81, s28, v[170:171]
	v_fma_f32 v124, v18, v192, v183
	v_lshlrev_b32_e32 v191, 16, v138
	v_lshlrev_b32_e32 v190, 16, v126
	v_add_co_u32_e32 v178, vcc, 0x2000, v80
	v_fma_f32 v133, v19, v193, v124
	s_nop 0
	v_addc_co_u32_e32 v179, vcc, 0, v81, vcc
	global_load_dwordx4 v[140:143], v[200:201], off offset:3072
	global_load_dwordx4 v[128:131], v[178:179], off offset:3072
	v_fma_f32 v124, v12, v190, v184
	v_and_b32_e32 v189, 0xffff0000, v138
	v_and_b32_e32 v188, 0xffff0000, v126
	v_fma_f32 v137, v13, v191, v124
	v_lshlrev_b32_e32 v186, 16, v127
	v_fma_f32 v124, v20, v188, v134
	v_lshlrev_b32_e32 v187, 16, v139
	v_fma_f32 v126, v21, v189, v124
	v_and_b32_e32 v184, 0xffff0000, v127
	v_fma_f32 v124, v14, v186, v185
	v_and_b32_e32 v185, 0xffff0000, v139
	v_fma_f32 v134, v15, v187, v124
	v_lshlrev_b32_e32 v203, 16, v152
	v_fma_f32 v124, v22, v184, v135
	v_lshlrev_b32_e32 v202, 16, v148
	v_fma_f32 v127, v23, v185, v124
	v_and_b32_e32 v205, 0xffff0000, v152
	v_fma_f32 v124, v24, v202, v180
	v_and_b32_e32 v204, 0xffff0000, v148
	v_fma_f32 v135, v25, v203, v124
	v_lshlrev_b32_e32 v206, 16, v149
	v_fma_f32 v124, v32, v204, v136
	v_lshlrev_b32_e32 v207, 16, v153
	v_fma_f32 v136, v33, v205, v124
	v_and_b32_e32 v209, 0xffff0000, v153
	v_fma_f32 v124, v26, v206, v132
	v_and_b32_e32 v208, 0xffff0000, v149
	v_fma_f32 v132, v27, v207, v124
	v_lshlrev_b32_e32 v211, 16, v154
	v_fma_f32 v124, v34, v208, v133
	v_lshlrev_b32_e32 v210, 16, v150
	v_fma_f32 v133, v35, v209, v124
	v_and_b32_e32 v213, 0xffff0000, v154
	v_fma_f32 v124, v28, v210, v137
	v_and_b32_e32 v212, 0xffff0000, v150
	v_fma_f32 v137, v29, v211, v124
	v_lshlrev_b32_e32 v214, 16, v151
	v_fma_f32 v124, v36, v212, v126
	v_lshlrev_b32_e32 v215, 16, v155
	v_fma_f32 v126, v37, v213, v124
	v_and_b32_e32 v217, 0xffff0000, v155
	v_fma_f32 v124, v30, v214, v134
	v_and_b32_e32 v216, 0xffff0000, v151
	v_fma_f32 v134, v31, v215, v124
	v_lshlrev_b32_e32 v183, 16, v164
	v_fma_f32 v124, v38, v216, v127
	v_lshlrev_b32_e32 v182, 16, v144
	v_fma_f32 v138, v39, v217, v124
	v_and_b32_e32 v181, 0xffff0000, v164
	v_fma_f32 v124, v40, v182, v135
	v_and_b32_e32 v180, 0xffff0000, v144
	v_fma_f32 v135, v41, v183, v124
	v_lshlrev_b32_e32 v152, 16, v145
	v_fma_f32 v124, v48, v180, v136
	v_lshlrev_b32_e32 v153, 16, v165
	v_fma_f32 v139, v49, v181, v124
	v_and_b32_e32 v149, 0xffff0000, v165
	v_fma_f32 v124, v42, v152, v132
	v_and_b32_e32 v148, 0xffff0000, v145
	v_fma_f32 v150, v43, v153, v124
	v_lshlrev_b32_e32 v145, 16, v166
	v_fma_f32 v124, v50, v148, v133
	v_lshlrev_b32_e32 v144, 16, v146
	v_fma_f32 v202, v51, v149, v124
	v_and_b32_e32 v136, 0xffff0000, v146
	v_fma_f32 v124, v44, v144, v137
	v_and_b32_e32 v137, 0xffff0000, v166
	v_fma_f32 v206, v45, v145, v124
	v_lshlrev_b32_e32 v132, 16, v147
	v_fma_f32 v124, v52, v136, v126
	v_lshlrev_b32_e32 v133, 16, v167
	v_fma_f32 v210, v53, v137, v124
	v_lshlrev_b32_e32 v166, 16, v156
	v_fma_f32 v124, v46, v132, v134
	v_fma_f32 v214, v47, v133, v124
	v_and_b32_e32 v125, 0xffff0000, v167
	v_and_b32_e32 v124, 0xffff0000, v147
	v_lshlrev_b32_e32 v167, 16, v160
	v_fma_f32 v126, v54, v124, v138
	v_fma_f32 v221, v55, v125, v126
	v_and_b32_e32 v165, 0xffff0000, v160
	v_fma_f32 v126, v56, v166, v135
	v_and_b32_e32 v164, 0xffff0000, v156
	v_fma_f32 v224, v57, v167, v126
	v_lshlrev_b32_e32 v154, 16, v157
	v_fma_f32 v126, v64, v164, v139
	v_lshlrev_b32_e32 v155, 16, v161
	v_fma_f32 v160, v65, v165, v126
	v_mul_f32_e32 v156, 0x3d372713, v224
	v_fma_f32 v126, v58, v154, v150
	v_and_b32_e32 v151, 0xffff0000, v161
	v_and_b32_e32 v150, 0xffff0000, v157
	v_mul_f32_e32 v156, v224, v156
	v_fma_f32 v225, v59, v155, v126
	v_fma_f32 v156, v224, v156, v224
	v_fma_f32 v126, v66, v150, v202
	v_lshlrev_b32_e32 v147, 16, v162
	v_lshlrev_b32_e32 v146, 16, v158
	v_mul_f32_e32 v156, 0x3f4c422a, v156
	v_fma_f32 v161, v67, v151, v126
	v_mul_f32_e32 v156, -2.0, v156
	v_fma_f32 v126, v60, v146, v206
	v_and_b32_e32 v139, 0xffff0000, v162
	v_and_b32_e32 v138, 0xffff0000, v158
	v_mul_f32_e32 v156, 0x3fb8aa3b, v156
	v_fma_f32 v202, v61, v147, v126
	v_exp_f32_e32 v156, v156
	v_fma_f32 v126, v68, v138, v210
	v_lshlrev_b32_e32 v134, 16, v159
	v_lshlrev_b32_e32 v135, 16, v163
	v_fma_f32 v158, v69, v139, v126
	v_mad_i64_i32 v[80:81], s[4:5], v82, s28, v[170:171]
	v_fma_f32 v126, v62, v134, v214
	v_fma_f32 v162, v63, v135, v126
	v_and_b32_e32 v126, 0xffff0000, v159
	v_add_f32_e32 v159, 1.0, v156
	v_and_b32_e32 v127, 0xffff0000, v163
	v_rcp_f32_e32 v206, v159
	v_add_co_u32_e32 v176, vcc, 0x2000, v80
	s_nop 0
	s_nop 0
	v_addc_co_u32_e32 v177, vcc, 0, v81, vcc
	v_mad_i64_i32 v[80:81], s[4:5], v83, s28, v[170:171]
	v_add_co_u32_e32 v174, vcc, 0x2000, v80
	v_fma_f32 v156, v70, v126, v221
	s_nop 0
	v_addc_co_u32_e32 v175, vcc, 0, v81, vcc
	v_fma_f32 v156, v71, v127, v156
	v_mul_f32_e32 v214, 0x3d372713, v160
	v_mul_f32_e32 v214, v160, v214
	v_fma_f32 v214, v160, v214, v160
	v_mul_f32_e32 v214, 0x3f4c422a, v214
	v_mul_f32_e32 v214, -2.0, v214
	v_mul_f32_e32 v214, 0x3fb8aa3b, v214
	v_exp_f32_e32 v214, v214
	v_mul_f32_e32 v157, v224, v206
	v_add_f32_e32 v163, 1.0, v214
	v_rcp_f32_e32 v210, v163
	s_waitcnt vmcnt(1)
; __device__ __forceinline__ unsigned cvt_pk_bf16(float lo, float hi) { unsigned r; asm("v_cvt_pk_bf16_f32 %0, %1, %2" : "=v"(r) : "v"(lo), "v"(hi)); return r; }
; __device__ __forceinline__ float bflo(unsigned w) { return __uint_as_float(w << 16); }
; __device__ __forceinline__ float bfhi(unsigned w) { return __uint_as_float(w & 0xffff0000u); }
; __device__ __forceinline__ float gelu_tanh(float x) { const float u = 0.7978845608028654f * (x + 0.044715f * x * x * x); return x / (1.f + __expf(-2.f * u)); }
; __device__ __forceinline__ void phase_conv(PRef p, int layer, int nseg) {
;     ...
;             for (int xi = 0; xi < 4; ++xi) {
;                 float acc[8];
; #pragma unroll
;                 for (int j = 0; j < 8; ++j) acc[j] = bias[j];
; #pragma unroll
;                 for (int ky = 0; ky < 3; ++ky)
; #pragma unroll
;                     for (int kx = 0; kx < 3; ++kx) { const u32x4 gq = gc[ky][xi + kx]; const int k = ky * 3 + kx;
;                         acc[0] += w[k][0] * bflo(gq.x); acc[1] += w[k][1] * bfhi(gq.x); acc[2] += w[k][2] * bflo(gq.y); acc[3] += w[k][3] * bfhi(gq.y);
;                         acc[4] += w[k][4] * bflo(gq.z); acc[5] += w[k][5] * bfhi(gq.z); acc[6] += w[k][6] * bflo(gq.w); acc[7] += w[k][7] * bfhi(gq.w); }
;                 u32x4 o;
;                 o.x = cvt_pk_bf16(gelu_tanh(acc[0]) * bflo(vv[xi].x), gelu_tanh(acc[1]) * bfhi(vv[xi].x));
;                 o.y = cvt_pk_bf16(gelu_tanh(acc[2]) * bflo(vv[xi].y), gelu_tanh(acc[3]) * bfhi(vv[xi].y));
;                 o.z = cvt_pk_bf16(gelu_tanh(acc[4]) * bflo(vv[xi].z), gelu_tanh(acc[5]) * bfhi(vv[xi].z));
;                 o.w = cvt_pk_bf16(gelu_tanh(acc[6]) * bflo(vv[xi].w), gelu_tanh(acc[7]) * bfhi(vv[xi].w));
;                 *(u32x4*)((bf16_t*)lp[1] + (size_t)(xb + xi) * NUP + NFF) = o; } }
	v_lshlrev_b32_e32 v159, 16, v140
	v_mul_f32_e32 v157, v157, v159
	v_and_b32_e32 v140, 0xffff0000, v140
	v_mul_f32_e32 v206, 0x3d372713, v225
	v_mul_f32_e32 v206, v225, v206
	v_fma_f32 v206, v225, v206, v225
	v_mul_f32_e32 v206, 0x3f4c422a, v206
	v_mul_f32_e32 v206, -2.0, v206
	v_mul_f32_e32 v206, 0x3fb8aa3b, v206
	v_exp_f32_e32 v206, v206
	v_mul_f32_e32 v159, v160, v210
	v_mul_f32_e32 v140, v159, v140
	v_add_f32_e32 v160, 1.0, v206
	v_rcp_f32_e32 v206, v160
	v_cvt_pk_bf16_f32 v140, v157, v140
	global_load_dwordx4 v[120:123], v[176:177], off offset:3072
	global_load_dwordx4 v[80:83], v[174:175], off offset:3072
	v_fma_f32 v198, v4, v198, v76
	v_mul_f32_e32 v210, 0x3d372713, v161
	v_mul_f32_e32 v210, v161, v210
	v_fma_f32 v210, v161, v210, v161
	v_mul_f32_e32 v210, 0x3f4c422a, v210
	v_mul_f32_e32 v210, -2.0, v210
	v_mul_f32_e32 v210, 0x3fb8aa3b, v210
	v_exp_f32_e32 v210, v210
	v_mul_f32_e32 v157, v225, v206
	v_add_f32_e32 v159, 1.0, v210
	v_rcp_f32_e32 v206, v159
	v_lshlrev_b32_e32 v160, 16, v141
	v_mul_f32_e32 v157, v157, v160
	v_and_b32_e32 v141, 0xffff0000, v141
	v_mul_f32_e32 v163, 0x3d372713, v202
	v_mul_f32_e32 v163, v202, v163
	v_fma_f32 v163, v202, v163, v202
	v_mul_f32_e32 v163, 0x3f4c422a, v163
	v_mul_f32_e32 v163, -2.0, v163
	v_mul_f32_e32 v163, 0x3fb8aa3b, v163
	v_exp_f32_e32 v163, v163
	v_mul_f32_e32 v159, v161, v206
	v_mul_f32_e32 v141, v159, v141
	v_add_f32_e32 v160, 1.0, v163
	v_rcp_f32_e32 v163, v160
	v_cvt_pk_bf16_f32 v141, v157, v141
	v_fma_f32 v210, v5, v196, v77
	s_waitcnt vmcnt(2)
	v_lshlrev_b32_e32 v232, 16, v129
	v_mul_f32_e32 v206, 0x3d372713, v158
	v_mul_f32_e32 v206, v158, v206
	v_fma_f32 v206, v158, v206, v158
	v_mul_f32_e32 v206, 0x3f4c422a, v206
	v_mul_f32_e32 v206, -2.0, v206
	v_mul_f32_e32 v206, 0x3fb8aa3b, v206
	v_exp_f32_e32 v206, v206
	v_mul_f32_e32 v157, v202, v163
	v_add_f32_e32 v159, 1.0, v206
	v_rcp_f32_e32 v163, v159
	v_lshlrev_b32_e32 v160, 16, v142
	v_mul_f32_e32 v157, v157, v160
	v_and_b32_e32 v142, 0xffff0000, v142
	v_mul_f32_e32 v161, 0x3d372713, v162
	v_mul_f32_e32 v161, v162, v161
	v_fma_f32 v161, v162, v161, v162
	v_mul_f32_e32 v161, 0x3f4c422a, v161
	v_mul_f32_e32 v161, -2.0, v161
	v_mul_f32_e32 v161, 0x3fb8aa3b, v161
	v_exp_f32_e32 v161, v161
	v_mul_f32_e32 v158, v158, v163
	v_mul_f32_e32 v142, v158, v142
	v_add_f32_e32 v159, 1.0, v161
	v_rcp_f32_e32 v161, v159
	v_cvt_pk_bf16_f32 v142, v157, v142
	v_fma_f32 v214, v6, v194, v78
	v_and_b32_e32 v194, 0xffff0000, v131
	v_mul_f32_e32 v163, 0x3d372713, v156
	v_mul_f32_e32 v163, v156, v163
	v_fma_f32 v163, v156, v163, v156
	v_mul_f32_e32 v163, 0x3f4c422a, v163
	v_mul_f32_e32 v163, -2.0, v163
	v_mul_f32_e32 v163, 0x3fb8aa3b, v163
	v_exp_f32_e32 v163, v163
	v_mul_f32_e32 v157, v162, v161
	v_add_f32_e32 v158, 1.0, v163
	v_rcp_f32_e32 v161, v158
	v_lshlrev_b32_e32 v159, 16, v143
	v_mul_f32_e32 v157, v157, v159
	v_and_b32_e32 v143, 0xffff0000, v143
	v_mul_f32_e32 v156, v156, v161
	v_mul_f32_e32 v143, v156, v143
	v_cvt_pk_bf16_f32 v143, v157, v143
	v_pk_mov_b32 v[156:157], v[206:207], v[152:153] op_sel:[1,0]
	v_lshlrev_b32_e32 v207, 16, v108
	v_lshlrev_b32_e32 v206, 16, v104
	v_pk_mov_b32 v[158:159], v[208:209], v[148:149] op_sel:[1,0]
	v_pk_mov_b32 v[160:161], v[210:211], v[144:145] op_sel:[1,0]
	v_lshlrev_b32_e32 v149, 16, v128
	v_and_b32_e32 v153, 0xffff0000, v128
	v_and_b32_e32 v145, 0xffff0000, v129
	v_pk_mov_b32 v[128:129], v[198:199], v[206:207] op_sel:[1,0]
	global_store_dwordx4 v[200:201], v[140:143], off offset:3072
	v_pk_mul_f32 v[128:129], v[8:9], v[128:129]
	v_pk_mov_b32 v[162:163], v[212:213], v[136:137] op_sel:[1,0]
	v_pk_mov_b32 v[140:141], v[202:203], v[182:183] op_sel:[1,0]
	v_add_f32_e32 v128, v198, v128
	v_pk_mul_f32 v[140:141], v[24:25], v[140:141]
	v_add_f32_e32 v128, v128, v129
	v_add_f32_e32 v128, v128, v140
	v_pk_mov_b32 v[200:201], v[214:215], v[132:133] op_sel:[1,0]
	v_lshlrev_b32_e32 v137, 16, v130
	v_and_b32_e32 v133, 0xffff0000, v130
	v_fma_f32 v130, v4, v199, v76
	v_add_f32_e32 v233, v128, v141
	v_and_b32_e32 v209, 0xffff0000, v108
	v_fma_f32 v128, v8, v206, v130
	v_and_b32_e32 v208, 0xffff0000, v104
	v_fma_f32 v234, v9, v207, v128
	v_pk_mov_b32 v[128:129], v[196:197], v[208:209] op_sel:[1,0]
	v_pk_mov_b32 v[142:143], v[204:205], v[180:181] op_sel:[1,0]
	v_pk_mul_f32 v[128:129], v[16:17], v[128:129]
	v_pk_mul_f32 v[142:143], v[32:33], v[142:143]
	v_add_f32_e32 v104, v210, v128
	v_add_f32_e32 v104, v104, v129
	v_pk_mul_f32 v[202:203], v[30:31], v[200:201]
	v_pk_mov_b32 v[200:201], v[216:217], v[124:125] op_sel:[1,0]
	v_lshlrev_b32_e32 v125, 16, v131
	v_fma_f32 v131, v5, v197, v77
	v_add_f32_e32 v104, v104, v142
	v_add_f32_e32 v235, v104, v143
	v_fma_f32 v104, v16, v208, v131
	v_lshlrev_b32_e32 v210, 16, v105
	v_lshlrev_b32_e32 v211, 16, v109
	v_fma_f32 v236, v17, v209, v104
	v_pk_mov_b32 v[128:129], v[194:195], v[210:211] op_sel:[1,0]
	v_pk_mul_f32 v[156:157], v[26:27], v[156:157]
	v_pk_mul_f32 v[128:129], v[10:11], v[128:129]
	v_fma_f32 v181, v6, v195, v78
	v_add_f32_e32 v104, v214, v128
	v_add_f32_e32 v104, v104, v129
	v_add_f32_e32 v104, v104, v156
	v_add_f32_e32 v237, v104, v157
	v_fma_f32 v104, v10, v210, v181
	v_and_b32_e32 v213, 0xffff0000, v109
	v_and_b32_e32 v212, 0xffff0000, v105
	v_fma_f32 v238, v11, v211, v104
	v_pk_mov_b32 v[104:105], v[192:193], v[212:213] op_sel:[1,0]
	v_fma_f32 v221, v7, v192, v79
	v_pk_mul_f32 v[104:105], v[18:19], v[104:105]
	v_pk_mul_f32 v[158:159], v[34:35], v[158:159]
	v_add_f32_e32 v104, v221, v104
	v_add_f32_e32 v104, v104, v105
	v_add_f32_e32 v104, v104, v158
	v_fma_f32 v183, v7, v193, v79
	v_add_f32_e32 v221, v104, v159
	v_fma_f32 v190, v0, v190, v72
	v_fma_f32 v104, v18, v212, v183
	v_lshlrev_b32_e32 v215, 16, v110
	v_lshlrev_b32_e32 v214, 16, v106
	v_fma_f32 v239, v19, v213, v104
	v_pk_mov_b32 v[104:105], v[190:191], v[214:215] op_sel:[1,0]
	v_pk_mul_f32 v[160:161], v[28:29], v[160:161]
	v_pk_mul_f32 v[104:105], v[12:13], v[104:105]
	s_waitcnt vmcnt(2)
; __device__ __forceinline__ unsigned cvt_pk_bf16(float lo, float hi) { unsigned r; asm("v_cvt_pk_bf16_f32 %0, %1, %2" : "=v"(r) : "v"(lo), "v"(hi)); return r; }
; __device__ __forceinline__ float bflo(unsigned w) { return __uint_as_float(w << 16); }
; __device__ __forceinline__ float bfhi(unsigned w) { return __uint_as_float(w & 0xffff0000u); }
; __device__ __forceinline__ float gelu_tanh(float x) { const float u = 0.7978845608028654f * (x + 0.044715f * x * x * x); return x / (1.f + __expf(-2.f * u)); }
; __device__ __forceinline__ void phase_conv(PRef p, int layer, int nseg) {
;     ...
;             for (int xi = 0; xi < 4; ++xi) {
;                 float acc[8];
; #pragma unroll
;                 for (int j = 0; j < 8; ++j) acc[j] = bias[j];
; #pragma unroll
;                 for (int ky = 0; ky < 3; ++ky)
; #pragma unroll
;                     for (int kx = 0; kx < 3; ++kx) { const u32x4 gq = gc[ky][xi + kx]; const int k = ky * 3 + kx;
;                         acc[0] += w[k][0] * bflo(gq.x); acc[1] += w[k][1] * bfhi(gq.x); acc[2] += w[k][2] * bflo(gq.y); acc[3] += w[k][3] * bfhi(gq.y);
;                         acc[4] += w[k][4] * bflo(gq.z); acc[5] += w[k][5] * bfhi(gq.z); acc[6] += w[k][6] * bflo(gq.w); acc[7] += w[k][7] * bfhi(gq.w); }
;                 u32x4 o;
;                 o.x = cvt_pk_bf16(gelu_tanh(acc[0]) * bflo(vv[xi].x), gelu_tanh(acc[1]) * bfhi(vv[xi].x));
;                 o.y = cvt_pk_bf16(gelu_tanh(acc[2]) * bflo(vv[xi].y), gelu_tanh(acc[3]) * bfhi(vv[xi].y));
;                 o.z = cvt_pk_bf16(gelu_tanh(acc[4]) * bflo(vv[xi].z), gelu_tanh(acc[5]) * bfhi(vv[xi].z));
;                 o.w = cvt_pk_bf16(gelu_tanh(acc[6]) * bflo(vv[xi].w), gelu_tanh(acc[7]) * bfhi(vv[xi].w));
;                 *(u32x4*)((bf16_t*)lp[1] + (size_t)(xb + xi) * NUP + NFF) = o; } }
	v_lshlrev_b32_e32 v181, 16, v120
	v_add_f32_e32 v104, v190, v104
	v_add_f32_e32 v104, v104, v105
	v_add_f32_e32 v104, v104, v160
	v_and_b32_e32 v240, 0xffff0000, v120
	v_lshlrev_b32_e32 v241, 16, v121
	v_and_b32_e32 v242, 0xffff0000, v121
	v_lshlrev_b32_e32 v243, 16, v122
	v_and_b32_e32 v199, 0xffff0000, v122
	v_lshlrev_b32_e32 v121, 16, v123
	v_and_b32_e32 v120, 0xffff0000, v123
	v_lshlrev_b32_e32 v123, 16, v100
	v_mov_b32_e32 v122, v207
	v_pk_mul_f32 v[204:205], v[38:39], v[200:201]
	v_fma_f32 v200, v0, v191, v72
	v_add_f32_e32 v201, v104, v161
	v_fma_f32 v183, v4, v206, v76
	v_pk_mul_f32 v[122:123], v[8:9], v[122:123]
	v_fma_f32 v104, v12, v214, v200
	v_and_b32_e32 v217, 0xffff0000, v110
	v_and_b32_e32 v216, 0xffff0000, v106
	v_add_f32_e32 v122, v183, v122
	v_fma_f32 v200, v13, v215, v104
	v_pk_mov_b32 v[104:105], v[188:189], v[216:217] op_sel:[1,0]
	v_add_f32_e32 v207, v122, v123
	v_and_b32_e32 v123, 0xffff0000, v100
	v_mov_b32_e32 v122, v209
	v_fma_f32 v224, v1, v188, v73
	v_pk_mul_f32 v[104:105], v[20:21], v[104:105]
	v_fma_f32 v206, v5, v208, v77
	v_pk_mul_f32 v[122:123], v[16:17], v[122:123]
	v_add_f32_e32 v104, v224, v104
	v_add_f32_e32 v100, v206, v122
	v_pk_mul_f32 v[162:163], v[36:37], v[162:163]
	v_add_f32_e32 v104, v104, v105
	v_add_f32_e32 v206, v100, v123
	v_lshlrev_b32_e32 v123, 16, v101
	v_mov_b32_e32 v122, v211
	v_add_f32_e32 v104, v104, v162
	v_fma_f32 v208, v6, v210, v78
	v_pk_mul_f32 v[122:123], v[10:11], v[122:123]
	v_fma_f32 v225, v1, v189, v73
	v_add_f32_e32 v198, v104, v163
	v_add_f32_e32 v100, v208, v122
	v_fma_f32 v186, v2, v186, v74
	v_fma_f32 v104, v20, v216, v225
	v_lshlrev_b32_e32 v224, 16, v107
	v_lshlrev_b32_e32 v225, 16, v111
	v_add_f32_e32 v208, v100, v123
	v_and_b32_e32 v101, 0xffff0000, v101
	v_mov_b32_e32 v100, v213
	v_fma_f32 v197, v21, v217, v104
	v_pk_mov_b32 v[104:105], v[186:187], v[224:225] op_sel:[1,0]
	v_fma_f32 v210, v7, v212, v79
	v_pk_mul_f32 v[100:101], v[18:19], v[100:101]
	v_pk_mul_f32 v[104:105], v[14:15], v[104:105]
	v_add_f32_e32 v100, v210, v100
	v_add_f32_e32 v104, v186, v104
	v_add_f32_e32 v209, v100, v101
	v_lshlrev_b32_e32 v101, 16, v102
	v_mov_b32_e32 v100, v215
	v_add_f32_e32 v104, v104, v105
	v_fma_f32 v212, v0, v214, v72
	v_pk_mul_f32 v[100:101], v[12:13], v[100:101]
	v_add_f32_e32 v104, v104, v202
	v_add_f32_e32 v100, v212, v100
	v_fma_f32 v227, v2, v187, v74
	v_add_f32_e32 v196, v104, v203
	v_add_f32_e32 v210, v100, v101
	v_and_b32_e32 v101, 0xffff0000, v102
	v_mov_b32_e32 v100, v217
	v_fma_f32 v104, v14, v224, v227
	v_and_b32_e32 v203, 0xffff0000, v111
	v_and_b32_e32 v202, 0xffff0000, v107
	v_fma_f32 v214, v1, v216, v73
	v_pk_mul_f32 v[100:101], v[20:21], v[100:101]
	v_fma_f32 v195, v15, v225, v104
	v_pk_mov_b32 v[104:105], v[184:185], v[202:203] op_sel:[1,0]
	v_add_f32_e32 v100, v214, v100
	v_fma_f32 v226, v3, v184, v75
	v_pk_mul_f32 v[104:105], v[22:23], v[104:105]
	v_add_f32_e32 v123, v100, v101
	v_lshlrev_b32_e32 v101, 16, v103
	v_mov_b32_e32 v100, v225
	v_add_f32_e32 v104, v226, v104
	v_fma_f32 v216, v2, v224, v74
	v_pk_mul_f32 v[100:101], v[14:15], v[100:101]
	v_add_f32_e32 v104, v104, v105
	v_add_f32_e32 v100, v216, v100
	v_add_f32_e32 v104, v104, v204
	v_add_f32_e32 v122, v100, v101
	v_and_b32_e32 v101, 0xffff0000, v103
	v_mov_b32_e32 v100, v203
	v_add_f32_e32 v193, v104, v205
	v_pk_mul_f32 v[104:105], v[22:23], v[202:203]
	v_fma_f32 v202, v3, v202, v75
	v_pk_mul_f32 v[100:101], v[22:23], v[100:101]
	v_fma_f32 v228, v3, v185, v75
	v_add_f32_e32 v100, v202, v100
	v_lshlrev_b32_e32 v202, 16, v88
	v_add_f32_e32 v104, v228, v104
	v_mov_b32_e32 v102, v202
	v_mov_b32_e32 v103, v166
	v_add_f32_e32 v192, v104, v105
	v_lshlrev_b32_e32 v105, 16, v116
	v_lshlrev_b32_e32 v104, 16, v112
	v_pk_mul_f32 v[102:103], v[40:41], v[102:103]
	v_pk_mov_b32 v[106:107], v[166:167], v[104:105] op_sel:[1,0]
	v_add_f32_e32 v100, v100, v101
	v_add_f32_e32 v101, v233, v102
	v_add_f32_e32 v101, v101, v103
	v_fma_f32 v101, v56, v106, v101
	v_fma_f32 v101, v57, v107, v101
	v_mul_f32_e32 v166, 0x3d372713, v101
	v_mul_f32_e32 v166, v101, v166
	v_fma_f32 v166, v101, v166, v101
	v_mul_f32_e32 v166, 0x3f4c422a, v166
	v_mov_b32_e32 v183, v202
	v_mul_f32_e32 v166, -2.0, v166
	v_lshlrev_b32_e32 v203, 16, v96
	v_pk_mul_f32 v[102:103], v[24:25], v[182:183]
	v_mul_f32_e32 v166, 0x3fb8aa3b, v166
	v_exp_f32_e32 v182, v166
	v_add_f32_e32 v102, v234, v102
	v_mov_b32_e32 v166, v203
	v_add_f32_e32 v183, v102, v103
	v_pk_mul_f32 v[226:227], v[56:57], v[104:105]
	v_fma_f32 v102, v40, v166, v183
	v_fma_f32 v102, v41, v167, v102
	v_fma_f32 v102, v56, v104, v102
	v_fma_f32 v102, v57, v105, v102
	v_mul_f32_e32 v167, 0x3d372713, v102
	v_add_f32_e32 v182, 1.0, v182
	v_mul_f32_e32 v167, v102, v167
	v_fma_f32 v167, v102, v167, v102
	v_rcp_f32_e32 v205, v182
	v_mul_f32_e32 v167, 0x3f4c422a, v167
	v_mul_f32_e32 v167, -2.0, v167
	v_mul_f32_e32 v167, 0x3fb8aa3b, v167
	v_exp_f32_e32 v167, v167
	s_nop 0
	v_add_f32_e32 v167, 1.0, v167
	v_rcp_f32_e32 v204, v167
	v_mul_f32_e32 v101, v101, v205
	v_mul_f32_e32 v149, v101, v149
	v_mul_f32_e32 v101, v102, v204
	v_mul_f32_e32 v102, v101, v181
	v_fma_f32 v101, v24, v202, v207
	v_and_b32_e32 v166, 0xffff0000, v88
	v_mov_b32_e32 v182, v166
	v_mov_b32_e32 v183, v164
	v_and_b32_e32 v107, 0xffff0000, v116
	v_and_b32_e32 v106, 0xffff0000, v112
	v_pk_mul_f32 v[182:183], v[48:49], v[182:183]
	v_pk_mov_b32 v[108:109], v[164:165], v[106:107] op_sel:[1,0]
	v_add_f32_e32 v88, v235, v182
	v_pk_mul_f32 v[228:229], v[64:65], v[108:109]
	v_add_f32_e32 v88, v88, v183
	v_fma_f32 v88, v64, v108, v88
	v_fma_f32 v88, v65, v109, v88
	v_fma_f32 v101, v25, v203, v101
	v_and_b32_e32 v167, 0xffff0000, v96
; __device__ __forceinline__ unsigned cvt_pk_bf16(float lo, float hi) { unsigned r; asm("v_cvt_pk_bf16_f32 %0, %1, %2" : "=v"(r) : "v"(lo), "v"(hi)); return r; }
; __device__ __forceinline__ float bflo(unsigned w) { return __uint_as_float(w << 16); }
; __device__ __forceinline__ float bfhi(unsigned w) { return __uint_as_float(w & 0xffff0000u); }
; __device__ __forceinline__ float gelu_tanh(float x) { const float u = 0.7978845608028654f * (x + 0.044715f * x * x * x); return x / (1.f + __expf(-2.f * u)); }
; __device__ __forceinline__ void phase_conv(PRef p, int layer, int nseg) {
;     ...
;             for (int xi = 0; xi < 4; ++xi) {
;                 float acc[8];
; #pragma unroll
;                 for (int j = 0; j < 8; ++j) acc[j] = bias[j];
; #pragma unroll
;                 for (int ky = 0; ky < 3; ++ky)
; #pragma unroll
;                     for (int kx = 0; kx < 3; ++kx) { const u32x4 gq = gc[ky][xi + kx]; const int k = ky * 3 + kx;
;                         acc[0] += w[k][0] * bflo(gq.x); acc[1] += w[k][1] * bfhi(gq.x); acc[2] += w[k][2] * bflo(gq.y); acc[3] += w[k][3] * bfhi(gq.y);
;                         acc[4] += w[k][4] * bflo(gq.z); acc[5] += w[k][5] * bfhi(gq.z); acc[6] += w[k][6] * bflo(gq.w); acc[7] += w[k][7] * bfhi(gq.w); }
;                 u32x4 o;
;                 o.x = cvt_pk_bf16(gelu_tanh(acc[0]) * bflo(vv[xi].x), gelu_tanh(acc[1]) * bfhi(vv[xi].x));
;                 o.y = cvt_pk_bf16(gelu_tanh(acc[2]) * bflo(vv[xi].y), gelu_tanh(acc[3]) * bfhi(vv[xi].y));
;                 o.z = cvt_pk_bf16(gelu_tanh(acc[4]) * bflo(vv[xi].z), gelu_tanh(acc[5]) * bfhi(vv[xi].z));
;                 o.w = cvt_pk_bf16(gelu_tanh(acc[6]) * bflo(vv[xi].w), gelu_tanh(acc[7]) * bfhi(vv[xi].w));
;                 *(u32x4*)((bf16_t*)lp[1] + (size_t)(xb + xi) * NUP + NFF) = o; } }
	v_mul_f32_e32 v96, 0x3d372713, v88
	v_mul_f32_e32 v96, v88, v96
	v_fma_f32 v96, v88, v96, v88
	v_mov_b32_e32 v181, v166
	v_mul_f32_e32 v96, 0x3f4c422a, v96
	v_pk_mul_f32 v[180:181], v[32:33], v[180:181]
	v_mul_f32_e32 v96, -2.0, v96
	v_mul_f32_e32 v96, 0x3fb8aa3b, v96
	v_add_f32_e32 v103, v236, v180
	v_mov_b32_e32 v164, v167
	v_exp_f32_e32 v96, v96
	v_add_f32_e32 v103, v103, v181
	v_pk_mul_f32 v[164:165], v[48:49], v[164:165]
	v_pk_mul_f32 v[230:231], v[64:65], v[106:107]
	v_add_f32_e32 v103, v103, v164
	v_add_f32_e32 v103, v103, v165
	v_fma_f32 v103, v64, v106, v103
	v_add_f32_e32 v96, 1.0, v96
	v_fma_f32 v103, v65, v107, v103
	v_mul_f32_e32 v182, 0x3d372713, v103
	v_rcp_f32_e32 v181, v96
	v_mul_f32_e32 v182, v103, v182
	v_fma_f32 v182, v103, v182, v103
	v_mul_f32_e32 v182, 0x3f4c422a, v182
	v_mul_f32_e32 v182, -2.0, v182
	v_mul_f32_e32 v182, 0x3fb8aa3b, v182
	v_exp_f32_e32 v182, v182
	s_nop 0
	v_add_f32_e32 v180, 1.0, v182
	v_rcp_f32_e32 v183, v180
	v_mul_f32_e32 v88, v88, v181
	v_mul_f32_e32 v88, v88, v153
	v_mul_f32_e32 v96, v103, v183
	v_pk_mul_f32 v[164:165], v[32:33], v[166:167]
	v_mul_f32_e32 v103, v96, v240
	v_add_f32_e32 v96, v206, v164
	v_lshlrev_b32_e32 v164, 16, v89
	v_mov_b32_e32 v166, v164
	v_mov_b32_e32 v167, v154
	v_lshlrev_b32_e32 v108, 16, v113
	v_lshlrev_b32_e32 v109, 16, v117
	v_pk_mul_f32 v[166:167], v[42:43], v[166:167]
	v_pk_mov_b32 v[110:111], v[154:155], v[108:109] op_sel:[1,0]
	v_cvt_pk_bf16_f32 v88, v149, v88
	v_add_f32_e32 v149, v237, v166
	v_pk_mul_f32 v[190:191], v[58:59], v[110:111]
	v_add_f32_e32 v149, v149, v167
	v_fma_f32 v149, v58, v110, v149
	v_fma_f32 v149, v59, v111, v149
	v_mul_f32_e32 v154, 0x3d372713, v149
	v_mul_f32_e32 v154, v149, v154
	v_fma_f32 v154, v149, v154, v149
	v_mul_f32_e32 v154, 0x3f4c422a, v154
	v_mov_b32_e32 v153, v164
	v_mul_f32_e32 v154, -2.0, v154
	v_add_f32_e32 v96, v96, v165
	v_lshlrev_b32_e32 v165, 16, v97
	v_pk_mul_f32 v[152:153], v[26:27], v[152:153]
	v_mul_f32_e32 v154, 0x3fb8aa3b, v154
	v_exp_f32_e32 v166, v154
	v_add_f32_e32 v152, v238, v152
	v_mov_b32_e32 v154, v165
	v_add_f32_e32 v167, v152, v153
	v_pk_mul_f32 v[188:189], v[58:59], v[108:109]
	v_fma_f32 v152, v42, v154, v167
	v_fma_f32 v152, v43, v155, v152
	v_fma_f32 v152, v58, v108, v152
	v_fma_f32 v152, v59, v109, v152
	v_mul_f32_e32 v155, 0x3d372713, v152
	v_add_f32_e32 v166, 1.0, v166
	v_mul_f32_e32 v155, v152, v155
	v_fma_f32 v155, v152, v155, v152
	v_rcp_f32_e32 v181, v166
	v_mul_f32_e32 v155, 0x3f4c422a, v155
	v_mul_f32_e32 v155, -2.0, v155
	v_mul_f32_e32 v155, 0x3fb8aa3b, v155
	v_exp_f32_e32 v155, v155
	s_nop 0
	v_add_f32_e32 v155, 1.0, v155
	v_rcp_f32_e32 v180, v155
	v_mul_f32_e32 v149, v149, v181
	v_mul_f32_e32 v166, v149, v232
	v_mul_f32_e32 v149, v152, v180
	v_mul_f32_e32 v167, v149, v241
	v_fma_f32 v149, v26, v164, v208
	v_and_b32_e32 v152, 0xffff0000, v89
	v_mov_b32_e32 v154, v152
	v_mov_b32_e32 v155, v150
	v_and_b32_e32 v111, 0xffff0000, v117
	v_and_b32_e32 v110, 0xffff0000, v113
	v_pk_mul_f32 v[154:155], v[50:51], v[154:155]
	v_pk_mov_b32 v[112:113], v[150:151], v[110:111] op_sel:[1,0]
	v_add_f32_e32 v89, v221, v154
	v_pk_mul_f32 v[186:187], v[66:67], v[112:113]
	v_add_f32_e32 v89, v89, v155
	v_fma_f32 v89, v66, v112, v89
	v_fma_f32 v89, v67, v113, v89
	v_fma_f32 v164, v27, v165, v149
	v_and_b32_e32 v153, 0xffff0000, v97
	v_mul_f32_e32 v97, 0x3d372713, v89
	v_mov_b32_e32 v149, v152
	v_mul_f32_e32 v97, v89, v97
	v_pk_mul_f32 v[148:149], v[34:35], v[148:149]
	v_fma_f32 v97, v89, v97, v89
	v_mul_f32_e32 v97, 0x3f4c422a, v97
	v_add_f32_e32 v148, v239, v148
	v_mov_b32_e32 v150, v153
	v_mul_f32_e32 v97, -2.0, v97
	v_add_f32_e32 v154, v148, v149
	v_mul_f32_e32 v97, 0x3fb8aa3b, v97
	v_fma_f32 v148, v50, v150, v154
	v_pk_mul_f32 v[184:185], v[66:67], v[110:111]
	v_exp_f32_e32 v97, v97
	v_fma_f32 v148, v51, v151, v148
	v_fma_f32 v148, v66, v110, v148
	v_fma_f32 v148, v67, v111, v148
	v_mul_f32_e32 v151, 0x3d372713, v148
	v_add_f32_e32 v97, 1.0, v97
	v_mul_f32_e32 v151, v148, v151
	v_fma_f32 v151, v148, v151, v148
	v_rcp_f32_e32 v165, v97
	v_mul_f32_e32 v151, 0x3f4c422a, v151
	v_mul_f32_e32 v151, -2.0, v151
	v_mul_f32_e32 v151, 0x3fb8aa3b, v151
	v_exp_f32_e32 v151, v151
	s_nop 0
	v_add_f32_e32 v151, 1.0, v151
	v_rcp_f32_e32 v155, v151
	v_mul_f32_e32 v89, v89, v165
	v_mul_f32_e32 v89, v89, v145
	v_mul_f32_e32 v97, v148, v155
	v_mov_b32_e32 v151, v146
	v_fma_f32 v145, v34, v152, v209
	v_lshlrev_b32_e32 v148, 16, v90
	v_mov_b32_e32 v150, v148
	v_lshlrev_b32_e32 v113, 16, v118
	v_lshlrev_b32_e32 v112, 16, v114
	v_pk_mul_f32 v[150:151], v[44:45], v[150:151]
	v_pk_mov_b32 v[116:117], v[146:147], v[112:113] op_sel:[1,0]
	v_fma_f32 v152, v35, v153, v145
	v_add_f32_e32 v145, v201, v150
	v_pk_mul_f32 v[162:163], v[60:61], v[116:117]
	v_add_f32_e32 v146, v145, v151
	v_fma_f32 v146, v60, v116, v146
	v_fma_f32 v150, v61, v117, v146
	v_mul_f32_e32 v146, 0x3d372713, v150
	v_mul_f32_e32 v146, v150, v146
	v_fma_f32 v146, v150, v146, v150
	v_mul_f32_e32 v146, 0x3f4c422a, v146
	v_mov_b32_e32 v145, v148
	v_mul_f32_e32 v146, -2.0, v146
	v_lshlrev_b32_e32 v149, 16, v98
	v_pk_mul_f32 v[144:145], v[28:29], v[144:145]
	v_mul_f32_e32 v146, 0x3fb8aa3b, v146
	v_exp_f32_e32 v151, v146
	v_add_f32_e32 v144, v200, v144
	v_mov_b32_e32 v146, v149
	v_add_f32_e32 v153, v144, v145
	v_pk_mul_f32 v[160:161], v[60:61], v[112:113]
	v_fma_f32 v144, v44, v146, v153
	v_fma_f32 v144, v45, v147, v144
	v_fma_f32 v144, v60, v112, v144
	v_fma_f32 v144, v61, v113, v144
	v_mul_f32_e32 v147, 0x3d372713, v144
	v_add_f32_e32 v151, 1.0, v151
	v_mul_f32_e32 v147, v144, v147
	v_fma_f32 v147, v144, v147, v144
	v_rcp_f32_e32 v155, v151
	v_mul_f32_e32 v147, 0x3f4c422a, v147
; __device__ __forceinline__ unsigned cvt_pk_bf16(float lo, float hi) { unsigned r; asm("v_cvt_pk_bf16_f32 %0, %1, %2" : "=v"(r) : "v"(lo), "v"(hi)); return r; }
; __device__ __forceinline__ float bflo(unsigned w) { return __uint_as_float(w << 16); }
; __device__ __forceinline__ float bfhi(unsigned w) { return __uint_as_float(w & 0xffff0000u); }
; __device__ __forceinline__ float gelu_tanh(float x) { const float u = 0.7978845608028654f * (x + 0.044715f * x * x * x); return x / (1.f + __expf(-2.f * u)); }
; __device__ __forceinline__ void phase_conv(PRef p, int layer, int nseg) {
;     ...
;             for (int xi = 0; xi < 4; ++xi) {
;                 float acc[8];
; #pragma unroll
;                 for (int j = 0; j < 8; ++j) acc[j] = bias[j];
; #pragma unroll
;                 for (int ky = 0; ky < 3; ++ky)
; #pragma unroll
;                     for (int kx = 0; kx < 3; ++kx) { const u32x4 gq = gc[ky][xi + kx]; const int k = ky * 3 + kx;
;                         acc[0] += w[k][0] * bflo(gq.x); acc[1] += w[k][1] * bfhi(gq.x); acc[2] += w[k][2] * bflo(gq.y); acc[3] += w[k][3] * bfhi(gq.y);
;                         acc[4] += w[k][4] * bflo(gq.z); acc[5] += w[k][5] * bfhi(gq.z); acc[6] += w[k][6] * bflo(gq.w); acc[7] += w[k][7] * bfhi(gq.w); }
;                 u32x4 o;
;                 o.x = cvt_pk_bf16(gelu_tanh(acc[0]) * bflo(vv[xi].x), gelu_tanh(acc[1]) * bfhi(vv[xi].x));
;                 o.y = cvt_pk_bf16(gelu_tanh(acc[2]) * bflo(vv[xi].y), gelu_tanh(acc[3]) * bfhi(vv[xi].y));
;                 o.z = cvt_pk_bf16(gelu_tanh(acc[4]) * bflo(vv[xi].z), gelu_tanh(acc[5]) * bfhi(vv[xi].z));
;                 o.w = cvt_pk_bf16(gelu_tanh(acc[6]) * bflo(vv[xi].w), gelu_tanh(acc[7]) * bfhi(vv[xi].w));
;                 *(u32x4*)((bf16_t*)lp[1] + (size_t)(xb + xi) * NUP + NFF) = o; } }
	v_mul_f32_e32 v147, -2.0, v147
	v_mul_f32_e32 v147, 0x3fb8aa3b, v147
	v_exp_f32_e32 v147, v147
	s_nop 0
	v_add_f32_e32 v147, 1.0, v147
	v_rcp_f32_e32 v154, v147
	v_mul_f32_e32 v145, v150, v155
	v_mul_f32_e32 v150, v145, v137
	v_mul_f32_e32 v137, v144, v154
	v_mul_f32_e32 v151, v137, v243
	v_fma_f32 v137, v28, v148, v210
	v_and_b32_e32 v144, 0xffff0000, v90
	v_mov_b32_e32 v146, v144
	v_mov_b32_e32 v147, v138
	v_and_b32_e32 v117, 0xffff0000, v118
	v_and_b32_e32 v116, 0xffff0000, v114
	v_pk_mul_f32 v[146:147], v[52:53], v[146:147]
	v_pk_mov_b32 v[128:129], v[138:139], v[116:117] op_sel:[1,0]
	v_add_f32_e32 v90, v198, v146
	v_pk_mul_f32 v[158:159], v[68:69], v[128:129]
	v_add_f32_e32 v90, v90, v147
	v_fma_f32 v90, v68, v128, v90
	v_fma_f32 v90, v69, v129, v90
	v_fma_f32 v148, v29, v149, v137
	v_and_b32_e32 v145, 0xffff0000, v98
	v_mul_f32_e32 v98, 0x3d372713, v90
	v_mov_b32_e32 v137, v144
	v_mul_f32_e32 v98, v90, v98
	v_pk_mul_f32 v[136:137], v[36:37], v[136:137]
	v_fma_f32 v98, v90, v98, v90
	v_mul_f32_e32 v98, 0x3f4c422a, v98
	v_add_f32_e32 v136, v197, v136
	v_mov_b32_e32 v138, v145
	v_mul_f32_e32 v98, -2.0, v98
	v_add_f32_e32 v146, v136, v137
	v_mul_f32_e32 v98, 0x3fb8aa3b, v98
	v_fma_f32 v136, v52, v138, v146
	v_pk_mul_f32 v[156:157], v[68:69], v[116:117]
	v_exp_f32_e32 v98, v98
	v_fma_f32 v136, v53, v139, v136
	v_fma_f32 v136, v68, v116, v136
	v_fma_f32 v136, v69, v117, v136
	v_mul_f32_e32 v139, 0x3d372713, v136
	v_add_f32_e32 v98, 1.0, v98
	v_mul_f32_e32 v139, v136, v139
	v_fma_f32 v139, v136, v139, v136
	v_rcp_f32_e32 v149, v98
	v_mul_f32_e32 v139, 0x3f4c422a, v139
	v_mul_f32_e32 v139, -2.0, v139
	v_mul_f32_e32 v139, 0x3fb8aa3b, v139
	v_exp_f32_e32 v139, v139
	s_nop 0
	v_add_f32_e32 v139, 1.0, v139
	v_rcp_f32_e32 v147, v139
	v_mul_f32_e32 v90, v90, v149
	v_mul_f32_e32 v90, v90, v133
	v_mul_f32_e32 v98, v136, v147
	v_mul_f32_e32 v146, v98, v199
	v_fma_f32 v98, v36, v144, v123
	v_lshlrev_b32_e32 v136, 16, v91
	v_mov_b32_e32 v138, v136
	v_mov_b32_e32 v139, v134
	v_lshlrev_b32_e32 v128, 16, v115
	v_lshlrev_b32_e32 v129, 16, v119
	v_pk_mul_f32 v[138:139], v[46:47], v[138:139]
	v_pk_mov_b32 v[130:131], v[134:135], v[128:129] op_sel:[1,0]
	v_fma_f32 v144, v37, v145, v98
	v_add_f32_e32 v98, v196, v138
	v_pk_mul_f32 v[142:143], v[62:63], v[130:131]
	v_add_f32_e32 v98, v98, v139
	v_fma_f32 v98, v62, v130, v98
	v_fma_f32 v98, v63, v131, v98
	v_mul_f32_e32 v123, 0x3d372713, v98
	v_mov_b32_e32 v133, v136
	v_mul_f32_e32 v123, v98, v123
	v_lshlrev_b32_e32 v137, 16, v99
	v_pk_mul_f32 v[132:133], v[30:31], v[132:133]
	v_fma_f32 v123, v98, v123, v98
	v_mul_f32_e32 v123, 0x3f4c422a, v123
	v_add_f32_e32 v132, v195, v132
	v_mov_b32_e32 v134, v137
	v_mul_f32_e32 v123, -2.0, v123
	v_add_f32_e32 v138, v132, v133
	v_mul_f32_e32 v123, 0x3fb8aa3b, v123
	v_fma_f32 v132, v46, v134, v138
	v_pk_mul_f32 v[140:141], v[62:63], v[128:129]
	v_exp_f32_e32 v123, v123
	v_fma_f32 v132, v47, v135, v132
	v_fma_f32 v132, v62, v128, v132
	v_fma_f32 v132, v63, v129, v132
	v_mul_f32_e32 v135, 0x3d372713, v132
	v_add_f32_e32 v123, 1.0, v123
	v_mul_f32_e32 v135, v132, v135
	v_fma_f32 v135, v132, v135, v132
	v_rcp_f32_e32 v142, v123
	v_mul_f32_e32 v135, 0x3f4c422a, v135
	v_mul_f32_e32 v135, -2.0, v135
	v_mul_f32_e32 v135, 0x3fb8aa3b, v135
	v_exp_f32_e32 v135, v135
	s_nop 0
	v_add_f32_e32 v135, 1.0, v135
	v_rcp_f32_e32 v139, v135
	v_mul_f32_e32 v98, v98, v142
	v_mul_f32_e32 v134, v98, v125
	v_mul_f32_e32 v98, v132, v139
	v_pk_mul_f32 v[132:133], v[30:31], v[136:137]
	v_mul_f32_e32 v121, v98, v121
	v_fma_f32 v98, v30, v136, v122
	v_fma_f32 v132, v31, v137, v98
	v_and_b32_e32 v98, 0xffff0000, v91
	v_mov_b32_e32 v122, v98
	v_mov_b32_e32 v123, v126
	v_and_b32_e32 v119, 0xffff0000, v119
	v_and_b32_e32 v118, 0xffff0000, v115
	v_pk_mul_f32 v[122:123], v[54:55], v[122:123]
	v_pk_mov_b32 v[114:115], v[126:127], v[118:119] op_sel:[1,0]
	v_add_f32_e32 v91, v193, v122
	v_pk_mul_f32 v[130:131], v[70:71], v[114:115]
	v_add_f32_e32 v91, v91, v123
	v_fma_f32 v91, v70, v114, v91
	v_mov_b32_e32 v125, v98
	v_fma_f32 v91, v71, v115, v91
	v_pk_mul_f32 v[122:123], v[38:39], v[124:125]
	v_mul_f32_e32 v124, 0x3d372713, v91
	v_mul_f32_e32 v124, v91, v124
	v_fma_f32 v124, v91, v124, v91
	v_and_b32_e32 v99, 0xffff0000, v99
	v_mul_f32_e32 v124, 0x3f4c422a, v124
	v_mul_f32_e32 v124, -2.0, v124
	v_add_f32_e32 v122, v192, v122
	v_mov_b32_e32 v126, v99
	v_mul_f32_e32 v124, 0x3fb8aa3b, v124
	v_add_f32_e32 v125, v122, v123
	v_pk_mul_f32 v[122:123], v[54:55], v[126:127]
	v_exp_f32_e32 v124, v124
	v_fma_f32 v122, v54, v126, v125
	v_fma_f32 v122, v55, v127, v122
	v_fma_f32 v114, v70, v118, v122
	v_fma_f32 v114, v71, v119, v114
	v_add_f32_e32 v124, 1.0, v124
	v_mul_f32_e32 v115, 0x3d372713, v114
	v_mul_f32_e32 v115, v114, v115
	v_rcp_f32_e32 v131, v124
	v_fma_f32 v115, v114, v115, v114
	v_mul_f32_e32 v115, 0x3f4c422a, v115
	v_mul_f32_e32 v115, -2.0, v115
	v_mul_f32_e32 v115, 0x3fb8aa3b, v115
	v_exp_f32_e32 v115, v115
	s_nop 0
	v_add_f32_e32 v115, 1.0, v115
	v_rcp_f32_e32 v126, v115
	v_mul_f32_e32 v91, v91, v131
	v_cvt_pk_bf16_f32 v89, v166, v89
	v_mul_f32_e32 v91, v91, v194
	v_mul_f32_e32 v97, v97, v242
	v_cvt_pk_bf16_f32 v90, v150, v90
	v_mul_f32_e32 v114, v114, v126
	v_cvt_pk_bf16_f32 v91, v134, v91
	global_store_dwordx4 v[178:179], v[88:91], off offset:3072
	v_pk_mov_b32 v[104:105], v[104:105], v[104:105] op_sel:[1,0]
	v_mul_f32_e32 v114, v114, v120
	v_cvt_pk_bf16_f32 v88, v102, v103
	v_cvt_pk_bf16_f32 v89, v167, v97
	v_pk_mul_f32 v[98:99], v[38:39], v[98:99]
	v_cvt_pk_bf16_f32 v90, v151, v146
	v_cvt_pk_bf16_f32 v91, v121, v114
	global_store_dwordx4 v[176:177], v[88:91], off offset:3072
	v_add_f32_e32 v98, v100, v98
; __device__ __forceinline__ unsigned cvt_pk_bf16(float lo, float hi) { unsigned r; asm("v_cvt_pk_bf16_f32 %0, %1, %2" : "=v"(r) : "v"(lo), "v"(hi)); return r; }
; __device__ __forceinline__ float bflo(unsigned w) { return __uint_as_float(w << 16); }
; __device__ __forceinline__ float bfhi(unsigned w) { return __uint_as_float(w & 0xffff0000u); }
; __device__ __forceinline__ float gelu_tanh(float x) { const float u = 0.7978845608028654f * (x + 0.044715f * x * x * x); return x / (1.f + __expf(-2.f * u)); }
; __device__ __forceinline__ void phase_conv(PRef p, int layer, int nseg) {
;     ...
;             for (int xi = 0; xi < 4; ++xi) {
;                 float acc[8];
; #pragma unroll
;                 for (int j = 0; j < 8; ++j) acc[j] = bias[j];
; #pragma unroll
;                 for (int ky = 0; ky < 3; ++ky)
; #pragma unroll
;                     for (int kx = 0; kx < 3; ++kx) { const u32x4 gq = gc[ky][xi + kx]; const int k = ky * 3 + kx;
;                         acc[0] += w[k][0] * bflo(gq.x); acc[1] += w[k][1] * bfhi(gq.x); acc[2] += w[k][2] * bflo(gq.y); acc[3] += w[k][3] * bfhi(gq.y);
;                         acc[4] += w[k][4] * bflo(gq.z); acc[5] += w[k][5] * bfhi(gq.z); acc[6] += w[k][6] * bflo(gq.w); acc[7] += w[k][7] * bfhi(gq.w); }
;                 u32x4 o;
;                 o.x = cvt_pk_bf16(gelu_tanh(acc[0]) * bflo(vv[xi].x), gelu_tanh(acc[1]) * bfhi(vv[xi].x));
;                 o.y = cvt_pk_bf16(gelu_tanh(acc[2]) * bflo(vv[xi].y), gelu_tanh(acc[3]) * bfhi(vv[xi].y));
;                 o.z = cvt_pk_bf16(gelu_tanh(acc[4]) * bflo(vv[xi].z), gelu_tanh(acc[5]) * bfhi(vv[xi].z));
;                 o.w = cvt_pk_bf16(gelu_tanh(acc[6]) * bflo(vv[xi].w), gelu_tanh(acc[7]) * bfhi(vv[xi].w));
;                 *(u32x4*)((bf16_t*)lp[1] + (size_t)(xb + xi) * NUP + NFF) = o; } }
	v_add_f32_e32 v120, v98, v99
	v_lshlrev_b32_e32 v88, 16, v84
	v_mov_b32_e32 v89, v105
	v_pk_mul_f32 v[88:89], v[40:41], v[88:89]
	v_lshlrev_b32_e32 v90, 16, v85
	v_and_b32_e32 v98, 0xffff0000, v85
	v_add_f32_e32 v85, v101, v88
	v_add_f32_e32 v121, v85, v89
	v_pk_mov_b32 v[88:89], v[106:107], v[106:107] op_sel:[1,0]
	v_and_b32_e32 v84, 0xffff0000, v84
	v_mov_b32_e32 v85, v89
	v_pk_mul_f32 v[84:85], v[48:49], v[84:85]
	v_lshlrev_b32_e32 v100, 16, v86
	v_add_f32_e32 v84, v96, v84
	v_add_f32_e32 v106, v84, v85
	v_pk_mov_b32 v[84:85], v[108:109], v[108:109] op_sel:[1,0]
	v_and_b32_e32 v86, 0xffff0000, v86
	v_mov_b32_e32 v91, v85
	v_pk_mul_f32 v[90:91], v[42:43], v[90:91]
	v_lshlrev_b32_e32 v102, 16, v87
	v_add_f32_e32 v85, v164, v90
	v_add_f32_e32 v107, v85, v91
	v_pk_mov_b32 v[90:91], v[110:111], v[110:111] op_sel:[1,0]
	v_and_b32_e32 v114, 0xffff0000, v87
	v_mov_b32_e32 v99, v91
	v_lshlrev_b32_e32 v105, 16, v92
	v_fma_f32 v85, v50, v98, v152
	v_fma_f32 v108, v51, v99, v85
	v_pk_mov_b32 v[96:97], v[112:113], v[112:113] op_sel:[1,0]
	v_and_b32_e32 v89, 0xffff0000, v92
	v_mov_b32_e32 v101, v97
	v_pk_mul_f32 v[88:89], v[64:65], v[88:89]
	v_fma_f32 v85, v44, v100, v148
	v_fma_f32 v109, v45, v101, v85
	v_pk_mov_b32 v[98:99], v[116:117], v[116:117] op_sel:[1,0]
	v_and_b32_e32 v91, 0xffff0000, v93
	v_mov_b32_e32 v87, v99
	v_pk_mul_f32 v[86:87], v[52:53], v[86:87]
	v_lshlrev_b32_e32 v97, 16, v94
	v_add_f32_e32 v85, v144, v86
	v_add_f32_e32 v110, v85, v87
	v_pk_mov_b32 v[86:87], v[128:129], v[128:129] op_sel:[1,0]
	v_and_b32_e32 v99, 0xffff0000, v94
	v_mov_b32_e32 v103, v87
	v_lshlrev_b32_e32 v87, 16, v95
	v_fma_f32 v85, v46, v102, v132
	v_fma_f32 v111, v47, v103, v85
	v_pk_mov_b32 v[100:101], v[118:119], v[118:119] op_sel:[1,0]
	s_xor_b64 s[2:3], s[56:57], -1
	v_mov_b32_e32 v115, v101
	v_and_b32_e32 v101, 0xffff0000, v95
	v_fma_f32 v85, v54, v114, v120
	v_fma_f32 v112, v55, v115, v85
	v_pk_mul_f32 v[102:103], v[56:57], v[104:105]
	s_mov_b64 s[56:57], 0
	v_fma_f32 v85, v56, v104, v121
	v_fma_f32 v102, v57, v105, v85
	v_add_f32_e32 v85, v106, v88
	v_add_f32_e32 v88, v85, v89
	v_lshlrev_b32_e32 v85, 16, v93
	v_pk_mul_f32 v[84:85], v[58:59], v[84:85]
	s_nop 0
	v_add_f32_e32 v84, v107, v84
	v_add_f32_e32 v89, v84, v85
	s_nop 0
	v_fma_f32 v84, v66, v90, v108
	v_fma_f32 v90, v67, v91, v84
	s_nop 0
	v_fma_f32 v84, v60, v96, v109
	v_fma_f32 v91, v61, v97, v84
	s_nop 0
	v_fma_f32 v84, v68, v98, v110
	v_fma_f32 v92, v69, v99, v84
	v_pk_mul_f32 v[84:85], v[62:63], v[86:87]
	v_mul_f32_e32 v86, 0x3d372713, v102
	v_mul_f32_e32 v86, v102, v86
	v_fma_f32 v86, v102, v86, v102
	v_mul_f32_e32 v86, 0x3f4c422a, v86
	v_mul_f32_e32 v86, -2.0, v86
	v_mul_f32_e32 v86, 0x3fb8aa3b, v86
	v_exp_f32_e32 v86, v86
	v_add_f32_e32 v84, v111, v84
	v_add_f32_e32 v87, v84, v85
	v_add_f32_e32 v86, 1.0, v86
	v_rcp_f32_e32 v94, v86
	v_fma_f32 v84, v70, v100, v112
	v_fma_f32 v84, v71, v101, v84
	v_mul_f32_e32 v96, 0x3d372713, v88
	v_mul_f32_e32 v96, v88, v96
	v_fma_f32 v96, v88, v96, v88
	v_mul_f32_e32 v96, 0x3f4c422a, v96
	v_mul_f32_e32 v96, -2.0, v96
	v_mul_f32_e32 v96, 0x3fb8aa3b, v96
	v_exp_f32_e32 v96, v96
	v_mul_f32_e32 v85, v102, v94
	v_add_f32_e32 v93, 1.0, v96
	v_rcp_f32_e32 v95, v93
	s_waitcnt vmcnt(3)
	v_lshlrev_b32_e32 v86, 16, v80
	v_mul_f32_e32 v85, v85, v86
	v_and_b32_e32 v80, 0xffff0000, v80
	v_mul_f32_e32 v94, 0x3d372713, v89
	v_mul_f32_e32 v94, v89, v94
	v_fma_f32 v94, v89, v94, v89
	v_mul_f32_e32 v94, 0x3f4c422a, v94
	v_mul_f32_e32 v94, -2.0, v94
	v_mul_f32_e32 v94, 0x3fb8aa3b, v94
	v_exp_f32_e32 v94, v94
	v_mul_f32_e32 v86, v88, v95
	v_mul_f32_e32 v80, v86, v80
	v_add_f32_e32 v88, 1.0, v94
	v_rcp_f32_e32 v94, v88
	v_cvt_pk_bf16_f32 v80, v85, v80
	s_nop 0
	v_mul_f32_e32 v95, 0x3d372713, v90
	v_mul_f32_e32 v95, v90, v95
	v_fma_f32 v95, v90, v95, v90
	v_mul_f32_e32 v95, 0x3f4c422a, v95
	v_mul_f32_e32 v95, -2.0, v95
	v_mul_f32_e32 v95, 0x3fb8aa3b, v95
	v_exp_f32_e32 v95, v95
	v_mul_f32_e32 v85, v89, v94
	v_add_f32_e32 v86, 1.0, v95
	v_rcp_f32_e32 v94, v86
	v_lshlrev_b32_e32 v88, 16, v81
	v_mul_f32_e32 v85, v85, v88
	v_and_b32_e32 v81, 0xffff0000, v81
	v_mul_f32_e32 v93, 0x3d372713, v91
	v_mul_f32_e32 v93, v91, v93
	v_fma_f32 v93, v91, v93, v91
	v_mul_f32_e32 v93, 0x3f4c422a, v93
	v_mul_f32_e32 v93, -2.0, v93
	v_mul_f32_e32 v93, 0x3fb8aa3b, v93
	v_exp_f32_e32 v93, v93
	v_mul_f32_e32 v86, v90, v94
	v_mul_f32_e32 v81, v86, v81
	v_add_f32_e32 v88, 1.0, v93
	v_rcp_f32_e32 v90, v88
	v_cvt_pk_bf16_f32 v81, v85, v81
	s_nop 0
	v_mul_f32_e32 v93, 0x3d372713, v92
	v_mul_f32_e32 v93, v92, v93
	v_fma_f32 v93, v92, v93, v92
	v_mul_f32_e32 v93, 0x3f4c422a, v93
	v_mul_f32_e32 v93, -2.0, v93
	v_mul_f32_e32 v93, 0x3fb8aa3b, v93
	v_exp_f32_e32 v93, v93
	v_mul_f32_e32 v85, v91, v90
	v_add_f32_e32 v86, 1.0, v93
	v_rcp_f32_e32 v90, v86
	v_lshlrev_b32_e32 v88, 16, v82
	v_mul_f32_e32 v85, v85, v88
	v_and_b32_e32 v82, 0xffff0000, v82
	v_mul_f32_e32 v89, 0x3d372713, v87
	v_mul_f32_e32 v89, v87, v89
	v_fma_f32 v89, v87, v89, v87
	v_mul_f32_e32 v89, 0x3f4c422a, v89
	v_mul_f32_e32 v89, -2.0, v89
	v_mul_f32_e32 v89, 0x3fb8aa3b, v89
	v_exp_f32_e32 v89, v89
	v_mul_f32_e32 v86, v92, v90
	v_mul_f32_e32 v82, v86, v82
	v_add_f32_e32 v88, 1.0, v89
	v_rcp_f32_e32 v90, v88
	v_cvt_pk_bf16_f32 v82, v85, v82
	s_nop 0
	v_mul_f32_e32 v91, 0x3d372713, v84
	v_mul_f32_e32 v91, v84, v91
	v_fma_f32 v91, v84, v91, v84
	v_mul_f32_e32 v91, 0x3f4c422a, v91
	v_mul_f32_e32 v91, -2.0, v91
	v_mul_f32_e32 v91, 0x3fb8aa3b, v91
	v_exp_f32_e32 v91, v91
	v_mul_f32_e32 v85, v87, v90
	v_add_f32_e32 v86, 1.0, v91
	v_rcp_f32_e32 v90, v86
	v_lshlrev_b32_e32 v87, 16, v83
	v_mul_f32_e32 v85, v85, v87
	v_and_b32_e32 v83, 0xffff0000, v83
	v_mul_f32_e32 v84, v84, v90
	v_mul_f32_e32 v83, v84, v83
	s_mov_b32 s4, 4
	s_and_b64 vcc, exec, s[2:3]
	v_cvt_pk_bf16_f32 v83, v85, v83
	global_store_dwordx4 v[174:175], v[80:83], off offset:3072
	s_cbranch_vccnz .LBB0_545

; __device__ __forceinline__ unsigned short f2bf(float f) { return (unsigned short)(cvt_pk_bf16(f, 0.f) & 0xffffu); }
; __device__ __forceinline__ void retout_item(PRef p, int layer, int item, unsigned char* shm) {
;     ...
;     { const float* SF = (const float*)(p.ws + O_RETST) + ((size_t)((b * 8 + h) * 2 + 0) * 34 + cidx) * 8192;
;       const float* SB = (const float*)(p.ws + O_RETST) + ((size_t)((b * 8 + h) * 2 + 1) * 34 + cidx) * 8192;
; #pragma unroll 4
;       for (int i = 0; i < 16; ++i) { const int idx = tid + 512 * i, d = idx >> 7, e = idx & 127;
;           sTf[e * 72 + d] = f2bf(SF[idx]); sTb[e * 72 + d] = f2bf(SB[idx]); } }
;     __syncthreads();
;     bf16x8 qa[2];
; #pragma unroll
;     for (int kk = 0; kk < 2; ++kk) qa[kk] = *(const bf16x8*)(A + (size_t)(row0 + 16 * wave + fr) * NIN + C_Q + h * 64 + kk * 32 + fq * 8);
; #pragma unroll
;     for (int nt = 0; nt < 8; ++nt) { f32x4 s = (f32x4){0.f, 0.f, 0.f, 0.f};
; #pragma unroll
;         for (int kk = 0; kk < 2; ++kk) { const bf16x8 kb = *(const bf16x8*)(A + (size_t)(row0 + 16 * nt + fr) * NIN + C_K + h * 64 + kk * 32 + fq * 8);
;             s = __builtin_amdgcn_mfma_f32_16x16x32_bf16(qa[kk], kb, s, 0, 0, 0); }
;         const int m = 16 * nt + fr;
; #pragma unroll
;         for (int r = 0; r < 4; ++r) { const int c = 16 * wave + fq * 4 + r; const float dd = (float)(c - m);
;             const float dec = (m <= c) ? expf(dd * lgf) : expf(-dd * lgb);
;             Pw[(fq * 4 + r) * LDK + m] = f2bf(s[r] * 0.125f * dec); } }
.LBB0_921:
	v_add_u32_e32 v3, s12, v8
	v_add_co_u32_e32 v4, vcc, 0x110000, v0
	v_add_u32_e32 v6, 0x400, v3
	s_nop 0
	v_addc_co_u32_e32 v5, vcc, 0, v1, vcc
	v_add_u32_e32 v14, 0x600, v3
	v_ashrrev_i32_e32 v7, 31, v6
	global_load_dword v9, v[0:1], off
	global_load_dword v10, v[0:1], off offset:2048
	global_load_dword v13, v[4:5], off
	global_load_dword v22, v[4:5], off offset:2048
	v_ashrrev_i32_e32 v15, 31, v14
	v_lshlrev_b64 v[4:5], 2, v[6:7]
	v_lshlrev_b64 v[16:17], 2, v[14:15]
	v_lshl_add_u64 v[18:19], s[36:37], 0, v[4:5]
	v_lshl_add_u64 v[4:5], s[38:39], 0, v[4:5]
	v_lshl_add_u64 v[20:21], s[36:37], 0, v[16:17]
	v_lshl_add_u64 v[16:17], s[38:39], 0, v[16:17]
	global_load_dword v7, v[18:19], off
	s_nop 0
	global_load_dword v4, v[4:5], off
	s_nop 0
	global_load_dword v5, v[20:21], off
	global_load_dword v15, v[16:17], off
	v_ashrrev_i32_e32 v16, 7, v3
	v_add_u32_e32 v3, 0x200, v3
	v_add_u32_e32 v16, v16, v2
	v_ashrrev_i32_e32 v3, 7, v3
	v_ashrrev_i32_e32 v6, 7, v6
	v_lshl_add_u32 v16, v16, 1, 0
	v_add_u32_e32 v3, v3, v2
	s_addk_i32 s12, 0x800
	v_ashrrev_i32_e32 v14, 7, v14
	v_add_u32_e32 v6, v6, v2
	v_lshl_add_u32 v3, v3, 1, 0
	v_lshl_add_u64 v[0:1], v[0:1], 0, s[22:23]
	s_cmpk_lg_i32 s12, 0x2000
	v_add_u32_e32 v14, v14, v2
	v_lshl_add_u32 v6, v6, 1, 0
	v_lshl_add_u32 v14, v14, 1, 0
	s_waitcnt vmcnt(7)
	v_cvt_pk_bf16_f32 v9, v9, v33
	ds_write_b16 v16, v9 offset:34816
	s_waitcnt vmcnt(5)
	v_cvt_pk_bf16_f32 v9, v13, v33
	v_cvt_pk_bf16_f32 v10, v10, v33
	s_waitcnt vmcnt(4)
	v_cvt_pk_bf16_f32 v13, v22, v33
	ds_write_b16 v16, v9 offset:53248
	ds_write_b16 v3, v10 offset:34816
	ds_write_b16 v3, v13 offset:53248
	s_waitcnt vmcnt(3)
	v_cvt_pk_bf16_f32 v3, v7, v33
	s_waitcnt vmcnt(2)
	v_cvt_pk_bf16_f32 v4, v4, v33
	s_waitcnt vmcnt(1)
	v_cvt_pk_bf16_f32 v5, v5, v33
	s_waitcnt vmcnt(0)
	v_cvt_pk_bf16_f32 v7, v15, v33
	ds_write_b16 v6, v3 offset:34816
	ds_write_b16 v6, v4 offset:53248
	ds_write_b16 v14, v5 offset:34816
	ds_write_b16 v14, v7 offset:53248
	s_cbranch_scc1 .LBB0_921
	v_ashrrev_i32_e32 v10, 2, v8
	v_and_b32_e32 v9, 15, v8
	v_and_b32_e32 v14, -16, v10
	v_or_b32_e32 v15, s62, v9
	v_add_u32_e32 v0, v15, v14
	v_mov_b64_e32 v[36:37], s[10:11]
	v_bfe_u32 v13, v8, 4, 2
	v_mad_i64_i32 v[0:1], s[36:37], v0, s46, v[36:37]
	s_mov_b32 s35, s21
	v_lshl_add_u64 v[0:1], v[0:1], 0, s[34:35]
	v_lshlrev_b32_e32 v32, 4, v13
	v_lshl_add_u64 v[0:1], v[0:1], 0, v[32:33]
	s_waitcnt lgkmcnt(0)
	s_barrier
	global_load_dwordx4 v[4:7], v[0:1], off offset:3072
	v_mad_u64_u32 v[2:3], s[36:37], v15, s46, v[36:37]
	v_lshl_add_u64 v[2:3], v[2:3], 0, s[34:35]
	v_lshl_add_u64 v[16:17], v[2:3], 0, v[32:33]
	v_add_co_u32_e32 v2, vcc, s48, v16
	v_mul_lo_u32 v30, v14, s47
	s_nop 0
	v_addc_co_u32_e32 v3, vcc, 0, v17, vcc
	global_load_dwordx4 v[20:23], v[2:3], off
	s_nop 0
	global_load_dwordx4 v[0:3], v[0:1], off offset:3136
	v_lshl_add_u64 v[16:17], v[16:17], 0, s[24:25]
	global_load_dwordx4 v[24:27], v[16:17], off offset:64
	v_mul_f32_e32 v16, 0x3fb8aa3b, v11
	v_mul_f32_e32 v17, 0x3fb8aa3b, v12
	v_rndne_f32_e32 v18, v16
	v_fma_f32 v19, v11, s50, -v16
	v_rndne_f32_e32 v28, v17
	v_fma_f32 v29, v12, s50, -v17
	v_sub_f32_e32 v31, v16, v18
	v_fmac_f32_e32 v19, 0x32a5705f, v11
	v_sub_f32_e32 v17, v17, v28
	v_fmac_f32_e32 v29, 0x32a5705f, v12
	v_add_f32_e32 v19, v31, v19
	v_cvt_i32_f32_e32 v35, v18
	v_add_f32_e32 v17, v17, v29
	v_exp_f32_e32 v19, v19
	v_cvt_i32_f32_e32 v40, v28
	v_exp_f32_e32 v17, v17
	v_lshl_or_b32 v16, v13, 2, v14
	v_ldexp_f32 v19, v19, v35
	v_cmp_ngt_f32_e32 vcc, s51, v11
	v_add_u32_e32 v14, s53, v30
	v_sub_u32_e32 v30, v16, v9
	v_ldexp_f32 v17, v17, v40
	v_cndmask_b32_e32 v19, 0, v19, vcc
	v_cmp_ngt_f32_e32 vcc, s51, v12
	v_cvt_f32_i32_e32 v30, v30
	v_or_b32_e32 v28, 16, v15
	v_cndmask_b32_e32 v17, 0, v17, vcc
	v_cmp_nlt_f32_e32 vcc, s52, v11
	v_mad_u64_u32 v[28:29], s[36:37], v28, s46, v[36:37]
	s_nop 0
	v_cndmask_b32_e32 v11, v63, v19, vcc
	v_cmp_nlt_f32_e32 vcc, s52, v12
	v_lshl_add_u64 v[28:29], v[28:29], 0, s[34:35]
	v_lshl_add_u64 v[38:39], v[28:29], 0, v[32:33]
	v_cndmask_b32_e32 v12, v63, v17, vcc
	v_cmp_lt_i32_e32 vcc, v16, v9
	v_or_b32_e32 v18, 1, v16
	v_sub_u32_e32 v31, v18, v9
	v_cndmask_b32_e64 v17, -v12, v11, vcc
	v_mul_f32_e32 v17, v17, v30
	v_mul_f32_e32 v19, 0x3fb8aa3b, v17
	v_fma_f32 v28, v17, s50, -v19
	v_rndne_f32_e32 v29, v19
	v_fmac_f32_e32 v28, 0x32a5705f, v17
	v_sub_f32_e32 v19, v19, v29
	v_add_f32_e32 v19, v19, v28
	v_add_co_u32_e32 v28, vcc, s48, v38
	v_cvt_i32_f32_e32 v35, v29
	s_nop 0
	v_addc_co_u32_e32 v29, vcc, 0, v39, vcc
	v_cvt_f32_i32_e32 v41, v31
	global_load_dwordx4 v[28:31], v[28:29], off
	v_lshl_add_u64 v[38:39], v[38:39], 0, s[24:25]
	v_exp_f32_e32 v19, v19
	v_cmp_ngt_f32_e32 vcc, s51, v17
	v_lshlrev_b32_e32 v34, 1, v9
	v_mad_u32_u24 v75, v9, s47, v64
	v_ldexp_f32 v19, v19, v35
	v_cndmask_b32_e32 v19, 0, v19, vcc
	v_cmp_nlt_f32_e32 vcc, s52, v17
	s_waitcnt vmcnt(3)
	v_mfma_f32_16x16x32_bf16 v[20:23], v[4:7], v[20:23], 0
	v_cndmask_b32_e32 v17, v63, v19, vcc
	v_cmp_lt_i32_e32 vcc, v18, v9
	v_bitop3_b32 v103, v9, s55, v70 bitop3:0xc8
	s_waitcnt vmcnt(1)
	v_mfma_f32_16x16x32_bf16 v[20:23], v[0:3], v[24:27], v[20:23]
	global_load_dwordx4 v[24:27], v[38:39], off offset:64
	v_cndmask_b32_e64 v19, -v12, v11, vcc
	v_mul_f32_e32 v19, v19, v41
	v_mul_f32_e32 v35, 0x3fb8aa3b, v19
	v_fma_f32 v40, v19, s50, -v35
	s_nop 2
	v_mul_f32_e32 v20, 0x3e000000, v20
	v_mul_f32_e32 v17, v17, v20
	v_cvt_pk_bf16_f32 v20, v17, v33
	v_rndne_f32_e32 v17, v35
	v_fmac_f32_e32 v40, 0x32a5705f, v19
	v_sub_f32_e32 v35, v35, v17
	v_add_f32_e32 v35, v35, v40
	v_exp_f32_e32 v35, v35
	v_cvt_i32_f32_e32 v38, v17
	v_mul_u32_u24_e32 v17, 0x440, v13
	v_add3_u32 v17, v14, v34, v17
	ds_write_b16 v17, v20
	v_ldexp_f32 v20, v35, v38
	v_cmp_ngt_f32_e32 vcc, s51, v19
	v_mul_f32_e32 v21, 0x3e000000, v21
	v_mul_f32_e32 v22, 0x3e000000, v22
	v_cndmask_b32_e32 v20, 0, v20, vcc
	v_cmp_nlt_f32_e32 vcc, s52, v19
	s_waitcnt vmcnt(1)
; __device__ __forceinline__ unsigned short f2bf(float f) { return (unsigned short)(cvt_pk_bf16(f, 0.f) & 0xffffu); }
; __device__ __forceinline__ void retout_item(PRef p, int layer, int item, unsigned char* shm) {
;     ...
;     for (int nt = 0; nt < 8; ++nt) { f32x4 s = (f32x4){0.f, 0.f, 0.f, 0.f};
; #pragma unroll
;         for (int kk = 0; kk < 2; ++kk) { const bf16x8 kb = *(const bf16x8*)(A + (size_t)(row0 + 16 * nt + fr) * NIN + C_K + h * 64 + kk * 32 + fq * 8);
;             s = __builtin_amdgcn_mfma_f32_16x16x32_bf16(qa[kk], kb, s, 0, 0, 0); }
;         const int m = 16 * nt + fr;
; #pragma unroll
;         for (int r = 0; r < 4; ++r) { const int c = 16 * wave + fq * 4 + r; const float dd = (float)(c - m);
;             const float dec = (m <= c) ? expf(dd * lgf) : expf(-dd * lgb);
;             Pw[(fq * 4 + r) * LDK + m] = f2bf(s[r] * 0.125f * dec); } }
	v_mfma_f32_16x16x32_bf16 v[28:31], v[4:7], v[28:31], 0
	v_cndmask_b32_e32 v19, v63, v20, vcc
	v_or_b32_e32 v20, 2, v16
	v_sub_u32_e32 v35, v20, v9
	v_cvt_f32_i32_e32 v35, v35
	v_cmp_lt_i32_e32 vcc, v20, v9
	v_mul_f32_e32 v19, v19, v21
	v_cvt_pk_bf16_f32 v19, v19, v33
	ds_write_b16 v17, v19 offset:272
	v_cndmask_b32_e64 v38, -v12, v11, vcc
	v_mul_f32_e32 v35, v38, v35
	v_mul_f32_e32 v38, 0x3fb8aa3b, v35
	v_fma_f32 v39, v35, s50, -v38
	v_rndne_f32_e32 v40, v38
	v_fmac_f32_e32 v39, 0x32a5705f, v35
	v_sub_f32_e32 v38, v38, v40
	v_add_f32_e32 v38, v38, v39
	v_exp_f32_e32 v38, v38
	v_cvt_i32_f32_e32 v39, v40
	v_cmp_ngt_f32_e32 vcc, s51, v35
	v_lshlrev_b32_e32 v13, 3, v13
	v_bitop3_b32 v105, v9, s45, v72 bitop3:0xc8
	v_ldexp_f32 v19, v38, v39
	v_cndmask_b32_e32 v19, 0, v19, vcc
	v_cmp_nlt_f32_e32 vcc, s52, v35
	v_add_u32_e32 v88, v13, v103
	v_add_u32_e32 v92, v13, v105
	v_cndmask_b32_e32 v21, v63, v19, vcc
	v_or_b32_e32 v19, 3, v16
	v_sub_u32_e32 v35, v19, v9
	v_cvt_f32_i32_e32 v35, v35
	v_cmp_lt_i32_e32 vcc, v19, v9
	v_mul_f32_e32 v21, v21, v22
	v_cvt_pk_bf16_f32 v21, v21, v33
	ds_write_b16 v17, v21 offset:544
	v_cndmask_b32_e64 v38, -v12, v11, vcc
	v_mul_f32_e32 v35, v38, v35
	v_mul_f32_e32 v38, 0x3fb8aa3b, v35
	v_fma_f32 v39, v35, s50, -v38
	v_rndne_f32_e32 v40, v38
	v_fmac_f32_e32 v39, 0x32a5705f, v35
	v_sub_f32_e32 v38, v38, v40
	v_add_f32_e32 v38, v38, v39
	v_exp_f32_e32 v38, v38
	v_cvt_i32_f32_e32 v39, v40
	v_cmp_ngt_f32_e32 vcc, s51, v35
	v_mul_f32_e32 v22, 0x3e000000, v23
	v_bitop3_b32 v97, v9, 56, 48 bitop3:0xc8
	v_ldexp_f32 v21, v38, v39
	v_cndmask_b32_e32 v21, 0, v21, vcc
	v_cmp_nlt_f32_e32 vcc, s52, v35
	v_or_b32_e32 v35, 16, v9
	v_bitop3_b32 v99, v9, s49, 64 bitop3:0xc8
	v_cndmask_b32_e32 v21, v63, v21, vcc
	v_mul_f32_e32 v21, v21, v22
	v_sub_u32_e32 v22, v16, v35
	v_cvt_f32_i32_e32 v22, v22
	v_cmp_lt_i32_e32 vcc, v16, v35
	v_cvt_pk_bf16_f32 v21, v21, v33
	ds_write_b16 v17, v21 offset:816
	v_bitop3_b32 v101, v9, s54, v68 bitop3:0xc8
	v_cndmask_b32_e64 v23, -v12, v11, vcc
	v_mul_f32_e32 v38, v23, v22
	v_mul_f32_e32 v22, 0x3fb8aa3b, v38
	v_fma_f32 v23, v38, s50, -v22
	v_rndne_f32_e32 v39, v22
	v_fmac_f32_e32 v23, 0x32a5705f, v38
	v_sub_f32_e32 v22, v22, v39
	v_add_f32_e32 v22, v22, v23
	v_exp_f32_e32 v40, v22
	s_waitcnt vmcnt(0)
	v_mfma_f32_16x16x32_bf16 v[22:25], v[0:3], v[24:27], v[28:31]
	v_or_b32_e32 v26, 32, v15
	v_mad_u64_u32 v[26:27], s[36:37], v26, s46, v[36:37]
	v_lshl_add_u64 v[26:27], v[26:27], 0, s[34:35]
	v_lshl_add_u64 v[30:31], v[26:27], 0, v[32:33]
	v_add_co_u32_e32 v26, vcc, s48, v30
	v_cvt_i32_f32_e32 v39, v39
	s_nop 0
	v_addc_co_u32_e32 v27, vcc, 0, v31, vcc
	global_load_dwordx4 v[26:29], v[26:27], off
	v_ldexp_f32 v21, v40, v39
	v_cmp_ngt_f32_e32 vcc, s51, v38
	v_mul_f32_e32 v22, 0x3e000000, v22
	v_lshl_add_u64 v[30:31], v[30:31], 0, s[24:25]
	v_cndmask_b32_e32 v21, 0, v21, vcc
	v_cmp_nlt_f32_e32 vcc, s52, v38
	v_mul_f32_e32 v23, 0x3e000000, v23
	v_and_b32_e32 v88, 0x78, v88
	v_cndmask_b32_e32 v21, v63, v21, vcc
	v_mul_f32_e32 v21, v21, v22
	v_sub_u32_e32 v22, v18, v35
	v_cvt_f32_i32_e32 v22, v22
	v_cmp_lt_i32_e32 vcc, v18, v35
	v_cvt_pk_bf16_f32 v21, v21, v33
	ds_write_b16 v17, v21 offset:32
	v_and_b32_e32 v92, 0x78, v92
	v_cndmask_b32_e64 v38, -v12, v11, vcc
	v_mul_f32_e32 v22, v38, v22
	v_mul_f32_e32 v38, 0x3fb8aa3b, v22
	v_fma_f32 v39, v22, s50, -v38
	v_rndne_f32_e32 v40, v38
	v_fmac_f32_e32 v39, 0x32a5705f, v22
	v_sub_f32_e32 v38, v38, v40
	v_add_f32_e32 v38, v38, v39
	v_exp_f32_e32 v42, v38
	v_cvt_i32_f32_e32 v43, v40
	global_load_dwordx4 v[38:41], v[30:31], off offset:64
	v_cmp_ngt_f32_e32 vcc, s51, v22
	v_mad_u32_u24 v96, v9, s47, v65
	v_ldexp_f32 v21, v42, v43
	v_cndmask_b32_e32 v21, 0, v21, vcc
	v_cmp_nlt_f32_e32 vcc, s52, v22
	v_sub_u32_e32 v22, v20, v35
	v_cvt_f32_i32_e32 v22, v22
	v_cndmask_b32_e32 v21, v63, v21, vcc
	v_cmp_lt_i32_e32 vcc, v20, v35
	v_mul_f32_e32 v21, v21, v23
	v_cvt_pk_bf16_f32 v21, v21, v33
	ds_write_b16 v17, v21 offset:304
	v_cndmask_b32_e64 v30, -v12, v11, vcc
	v_mul_f32_e32 v22, v30, v22
	v_mul_f32_e32 v30, 0x3fb8aa3b, v22
	v_fma_f32 v31, v22, s50, -v30
	v_rndne_f32_e32 v42, v30
	v_fmac_f32_e32 v31, 0x32a5705f, v22
	v_sub_f32_e32 v30, v30, v42
	v_add_f32_e32 v30, v30, v31
	v_exp_f32_e32 v30, v30
	v_cvt_i32_f32_e32 v31, v42
	v_cmp_ngt_f32_e32 vcc, s51, v22
	v_mul_f32_e32 v23, 0x3e000000, v24
	v_lshlrev_b32_e32 v58, 1, v97
	v_ldexp_f32 v21, v30, v31
	v_cndmask_b32_e32 v21, 0, v21, vcc
	v_cmp_nlt_f32_e32 vcc, s52, v22
	v_sub_u32_e32 v22, v19, v35
	v_cvt_f32_i32_e32 v22, v22
	v_cndmask_b32_e32 v21, v63, v21, vcc
	v_cmp_lt_i32_e32 vcc, v19, v35
	v_mul_f32_e32 v21, v21, v23
	v_cvt_pk_bf16_f32 v21, v21, v33
	ds_write_b16 v17, v21 offset:576
	v_cndmask_b32_e64 v24, -v12, v11, vcc
	v_mul_f32_e32 v22, v24, v22
	v_mul_f32_e32 v24, 0x3fb8aa3b, v22
	v_fma_f32 v30, v22, s50, -v24
	v_rndne_f32_e32 v31, v24
	v_fmac_f32_e32 v30, 0x32a5705f, v22
	v_sub_f32_e32 v24, v24, v31
	v_add_f32_e32 v24, v24, v30
	v_exp_f32_e32 v24, v24
	v_cvt_i32_f32_e32 v30, v31
	v_cmp_ngt_f32_e32 vcc, s51, v22
	v_mad_u32_u24 v98, v9, s47, v66
	v_lshlrev_b32_e32 v80, 1, v99
	v_ldexp_f32 v21, v24, v30
	v_cndmask_b32_e32 v21, 0, v21, vcc
	v_cmp_nlt_f32_e32 vcc, s52, v22
	v_mul_f32_e32 v22, 0x3e000000, v25
	v_mad_u32_u24 v100, v9, s47, v67
	v_cndmask_b32_e32 v21, v63, v21, vcc
	v_mul_f32_e32 v21, v21, v22
	v_cvt_pk_bf16_f32 v21, v21, v33
	ds_write_b16 v17, v21 offset:848
	v_or_b32_e32 v21, 32, v9
	v_sub_u32_e32 v22, v16, v21
	v_cvt_f32_i32_e32 v30, v22
	v_cmp_lt_i32_e32 vcc, v16, v21
	s_waitcnt vmcnt(1)
; __device__ __forceinline__ unsigned short f2bf(float f) { return (unsigned short)(cvt_pk_bf16(f, 0.f) & 0xffffu); }
; __device__ __forceinline__ void retout_item(PRef p, int layer, int item, unsigned char* shm) {
;     ...
;     for (int nt = 0; nt < 8; ++nt) { f32x4 s = (f32x4){0.f, 0.f, 0.f, 0.f};
; #pragma unroll
;         for (int kk = 0; kk < 2; ++kk) { const bf16x8 kb = *(const bf16x8*)(A + (size_t)(row0 + 16 * nt + fr) * NIN + C_K + h * 64 + kk * 32 + fq * 8);
;             s = __builtin_amdgcn_mfma_f32_16x16x32_bf16(qa[kk], kb, s, 0, 0, 0); }
;         const int m = 16 * nt + fr;
; #pragma unroll
;         for (int r = 0; r < 4; ++r) { const int c = 16 * wave + fq * 4 + r; const float dd = (float)(c - m);
;             const float dec = (m <= c) ? expf(dd * lgf) : expf(-dd * lgb);
;             Pw[(fq * 4 + r) * LDK + m] = f2bf(s[r] * 0.125f * dec); } }
	v_mfma_f32_16x16x32_bf16 v[22:25], v[4:7], v[26:29], 0
	v_lshlrev_b32_e32 v84, 1, v101
	v_cndmask_b32_e64 v26, -v12, v11, vcc
	v_mul_f32_e32 v35, v26, v30
	v_mul_f32_e32 v26, 0x3fb8aa3b, v35
	v_fma_f32 v27, v35, s50, -v26
	v_rndne_f32_e32 v28, v26
	v_fmac_f32_e32 v27, 0x32a5705f, v35
	v_sub_f32_e32 v26, v26, v28
	v_add_f32_e32 v26, v26, v27
	v_exp_f32_e32 v42, v26
	v_or_b32_e32 v26, 48, v15
	v_mad_u64_u32 v[26:27], s[36:37], v26, s46, v[36:37]
	v_lshl_add_u64 v[26:27], v[26:27], 0, s[34:35]
	v_lshl_add_u64 v[30:31], v[26:27], 0, v[32:33]
	v_add_co_u32_e32 v26, vcc, s48, v30
	v_cvt_i32_f32_e32 v43, v28
	s_nop 0
	v_addc_co_u32_e32 v27, vcc, 0, v31, vcc
	global_load_dwordx4 v[26:29], v[26:27], off
	s_waitcnt vmcnt(1)
	v_mfma_f32_16x16x32_bf16 v[22:25], v[0:3], v[38:41], v[22:25]
	v_ldexp_f32 v38, v42, v43
	v_cmp_ngt_f32_e32 vcc, s51, v35
	v_lshl_add_u64 v[30:31], v[30:31], 0, s[24:25]
	v_mad_u32_u24 v102, v9, s47, v69
	v_cndmask_b32_e32 v38, 0, v38, vcc
	v_cmp_nlt_f32_e32 vcc, s52, v35
	s_nop 1
	v_mul_f32_e32 v22, 0x3e000000, v22
	v_mul_f32_e32 v23, 0x3e000000, v23
	v_cndmask_b32_e32 v35, v63, v38, vcc
	v_sub_u32_e32 v38, v18, v21
	v_cvt_f32_i32_e32 v38, v38
	v_cmp_lt_i32_e32 vcc, v18, v21
	v_mul_f32_e32 v22, v35, v22
	v_cvt_pk_bf16_f32 v22, v22, v33
	ds_write_b16 v17, v22 offset:64
	v_cndmask_b32_e64 v39, -v12, v11, vcc
	v_mul_f32_e32 v42, v39, v38
	global_load_dwordx4 v[38:41], v[30:31], off offset:64
	v_mul_f32_e32 v30, 0x3fb8aa3b, v42
	v_fma_f32 v31, v42, s50, -v30
	v_rndne_f32_e32 v43, v30
	v_fmac_f32_e32 v31, 0x32a5705f, v42
	v_sub_f32_e32 v30, v30, v43
	v_add_f32_e32 v30, v30, v31
	v_exp_f32_e32 v30, v30
	v_cvt_i32_f32_e32 v31, v43
	v_cmp_ngt_f32_e32 vcc, s51, v42
	v_mul_f32_e32 v24, 0x3e000000, v24
	v_lshlrev_b32_e32 v88, 1, v88
	v_ldexp_f32 v22, v30, v31
	v_sub_u32_e32 v30, v20, v21
	v_cvt_f32_i32_e32 v30, v30
	v_cndmask_b32_e32 v22, 0, v22, vcc
	v_cmp_nlt_f32_e32 vcc, s52, v42
	v_mad_u32_u24 v104, v9, s47, v71
	v_lshlrev_b32_e32 v92, 1, v92
	v_cndmask_b32_e32 v22, v63, v22, vcc
	v_cmp_lt_i32_e32 vcc, v20, v21
	v_mul_f32_e32 v22, v22, v23
	v_cvt_pk_bf16_f32 v22, v22, v33
	v_sub_u32_e32 v23, v19, v21
	v_cndmask_b32_e64 v31, -v12, v11, vcc
	v_mul_f32_e32 v30, v31, v30
	v_mul_f32_e32 v31, 0x3fb8aa3b, v30
	v_fma_f32 v35, v30, s50, -v31
	v_rndne_f32_e32 v42, v31
	v_fmac_f32_e32 v35, 0x32a5705f, v30
	v_sub_f32_e32 v31, v31, v42
	v_add_f32_e32 v31, v31, v35
	v_exp_f32_e32 v31, v31
	v_cvt_i32_f32_e32 v35, v42
	ds_write_b16 v17, v22 offset:336
	v_cmp_ngt_f32_e32 vcc, s51, v30
	v_cvt_f32_i32_e32 v23, v23
	v_ldexp_f32 v22, v31, v35
	v_cndmask_b32_e32 v22, 0, v22, vcc
	v_cmp_nlt_f32_e32 vcc, s52, v30
	v_or_b32_e32 v35, 48, v9
	v_mad_u32_u24 v106, v9, s47, v73
	v_cndmask_b32_e32 v22, v63, v22, vcc
	v_cmp_lt_i32_e32 vcc, v19, v21
	v_mul_f32_e32 v22, v22, v24
	v_cvt_pk_bf16_f32 v22, v22, v33
	ds_write_b16 v17, v22 offset:608
	v_cndmask_b32_e64 v21, -v12, v11, vcc
	v_mul_f32_e32 v21, v21, v23
	v_mul_f32_e32 v23, 0x3fb8aa3b, v21
	v_fma_f32 v30, v21, s50, -v23
	v_rndne_f32_e32 v31, v23
	v_fmac_f32_e32 v30, 0x32a5705f, v21
	v_sub_f32_e32 v23, v23, v31
	v_add_f32_e32 v23, v23, v30
	v_exp_f32_e32 v23, v23
	v_cvt_i32_f32_e32 v30, v31
	v_cmp_ngt_f32_e32 vcc, s51, v21
	v_add3_u32 v88, 0, v88, v104
	v_add3_u32 v92, 0, v92, v106
	v_ldexp_f32 v22, v23, v30
	v_cndmask_b32_e32 v22, 0, v22, vcc
	v_cmp_nlt_f32_e32 vcc, s52, v21
	s_lshl_b32 s20, s34, 1
	s_nop 0
	v_cndmask_b32_e32 v21, v63, v22, vcc
	v_mul_f32_e32 v22, 0x3e000000, v25
	v_mul_f32_e32 v21, v21, v22
	v_sub_u32_e32 v22, v16, v35
	v_cvt_f32_i32_e32 v30, v22
	v_cmp_lt_i32_e32 vcc, v16, v35
	s_waitcnt vmcnt(1)
	v_mfma_f32_16x16x32_bf16 v[22:25], v[4:7], v[26:29], 0
	v_cvt_pk_bf16_f32 v21, v21, v33
	ds_write_b16 v17, v21 offset:880
	v_cndmask_b32_e64 v26, -v12, v11, vcc
	v_mul_f32_e32 v42, v26, v30
	v_mul_f32_e32 v26, 0x3fb8aa3b, v42
	v_fma_f32 v27, v42, s50, -v26
	v_rndne_f32_e32 v28, v26
	v_fmac_f32_e32 v27, 0x32a5705f, v42
	v_sub_f32_e32 v26, v26, v28
	v_add_f32_e32 v26, v26, v27
	v_exp_f32_e32 v26, v26
	v_cvt_i32_f32_e32 v27, v28
	s_waitcnt vmcnt(0)
	v_mfma_f32_16x16x32_bf16 v[22:25], v[0:3], v[38:41], v[22:25]
	v_ldexp_f32 v21, v26, v27
	v_or_b32_e32 v26, 64, v15
	v_mad_u64_u32 v[26:27], s[36:37], v26, s46, v[36:37]
	v_lshl_add_u64 v[26:27], v[26:27], 0, s[34:35]
	v_lshl_add_u64 v[30:31], v[26:27], 0, v[32:33]
	v_add_co_u32_e32 v26, vcc, s48, v30
	s_nop 1
	v_mul_f32_e32 v22, 0x3e000000, v22
	v_addc_co_u32_e32 v27, vcc, 0, v31, vcc
	global_load_dwordx4 v[26:29], v[26:27], off
	v_cmp_ngt_f32_e32 vcc, s51, v42
	v_lshl_add_u64 v[30:31], v[30:31], 0, s[24:25]
	v_mul_f32_e32 v23, 0x3e000000, v23
	v_cndmask_b32_e32 v21, 0, v21, vcc
	v_cmp_nlt_f32_e32 vcc, s52, v42
	s_nop 1
	v_cndmask_b32_e32 v21, v63, v21, vcc
	v_mul_f32_e32 v21, v21, v22
	v_sub_u32_e32 v22, v18, v35
	v_cvt_f32_i32_e32 v22, v22
	v_cmp_lt_i32_e32 vcc, v18, v35
	v_cvt_pk_bf16_f32 v21, v21, v33
	ds_write_b16 v17, v21 offset:96
	s_nop 0
	v_cndmask_b32_e64 v38, -v12, v11, vcc
	v_mul_f32_e32 v22, v38, v22
	v_mul_f32_e32 v38, 0x3fb8aa3b, v22
	v_fma_f32 v39, v22, s50, -v38
	v_rndne_f32_e32 v40, v38
	v_fmac_f32_e32 v39, 0x32a5705f, v22
	v_sub_f32_e32 v38, v38, v40
	v_add_f32_e32 v38, v38, v39
	v_exp_f32_e32 v42, v38
	v_cvt_i32_f32_e32 v43, v40
	global_load_dwordx4 v[38:41], v[30:31], off offset:64
	v_cmp_ngt_f32_e32 vcc, s51, v22
	v_ldexp_f32 v21, v42, v43
	s_nop 0
	v_cndmask_b32_e32 v21, 0, v21, vcc
	v_cmp_nlt_f32_e32 vcc, s52, v22
	v_sub_u32_e32 v22, v20, v35
	v_cvt_f32_i32_e32 v22, v22
	v_cndmask_b32_e32 v21, v63, v21, vcc
	v_cmp_lt_i32_e32 vcc, v20, v35
	v_mul_f32_e32 v21, v21, v23
	v_cvt_pk_bf16_f32 v21, v21, v33
	ds_write_b16 v17, v21 offset:368
; __device__ __forceinline__ unsigned short f2bf(float f) { return (unsigned short)(cvt_pk_bf16(f, 0.f) & 0xffffu); }
; __device__ __forceinline__ void retout_item(PRef p, int layer, int item, unsigned char* shm) {
;     ...
;     for (int nt = 0; nt < 8; ++nt) { f32x4 s = (f32x4){0.f, 0.f, 0.f, 0.f};
; #pragma unroll
;         for (int kk = 0; kk < 2; ++kk) { const bf16x8 kb = *(const bf16x8*)(A + (size_t)(row0 + 16 * nt + fr) * NIN + C_K + h * 64 + kk * 32 + fq * 8);
;             s = __builtin_amdgcn_mfma_f32_16x16x32_bf16(qa[kk], kb, s, 0, 0, 0); }
;         const int m = 16 * nt + fr;
; #pragma unroll
;         for (int r = 0; r < 4; ++r) { const int c = 16 * wave + fq * 4 + r; const float dd = (float)(c - m);
;             const float dec = (m <= c) ? expf(dd * lgf) : expf(-dd * lgb);
;             Pw[(fq * 4 + r) * LDK + m] = f2bf(s[r] * 0.125f * dec); } }
	v_cndmask_b32_e64 v30, -v12, v11, vcc
	v_mul_f32_e32 v22, v30, v22
	v_mul_f32_e32 v30, 0x3fb8aa3b, v22
	v_fma_f32 v31, v22, s50, -v30
	v_rndne_f32_e32 v42, v30
	v_fmac_f32_e32 v31, 0x32a5705f, v22
	v_sub_f32_e32 v30, v30, v42
	v_add_f32_e32 v30, v30, v31
	v_exp_f32_e32 v30, v30
	v_cvt_i32_f32_e32 v31, v42
	v_cmp_ngt_f32_e32 vcc, s51, v22
	v_mul_f32_e32 v23, 0x3e000000, v24
	v_ldexp_f32 v21, v30, v31
	v_cndmask_b32_e32 v21, 0, v21, vcc
	v_cmp_nlt_f32_e32 vcc, s52, v22
	v_sub_u32_e32 v22, v19, v35
	v_cvt_f32_i32_e32 v22, v22
	v_cndmask_b32_e32 v21, v63, v21, vcc
	v_cmp_lt_i32_e32 vcc, v19, v35
	v_mul_f32_e32 v21, v21, v23
	v_cvt_pk_bf16_f32 v21, v21, v33
	ds_write_b16 v17, v21 offset:640
	v_cndmask_b32_e64 v24, -v12, v11, vcc
	v_mul_f32_e32 v22, v24, v22
	v_mul_f32_e32 v24, 0x3fb8aa3b, v22
	v_fma_f32 v30, v22, s50, -v24
	v_rndne_f32_e32 v31, v24
	v_fmac_f32_e32 v30, 0x32a5705f, v22
	v_sub_f32_e32 v24, v24, v31
	v_add_f32_e32 v24, v24, v30
	v_exp_f32_e32 v24, v24
	v_cvt_i32_f32_e32 v30, v31
	v_cmp_ngt_f32_e32 vcc, s51, v22
	v_ldexp_f32 v21, v24, v30
	s_nop 0
	v_cndmask_b32_e32 v21, 0, v21, vcc
	v_cmp_nlt_f32_e32 vcc, s52, v22
	v_mul_f32_e32 v22, 0x3e000000, v25
	s_nop 0
	v_cndmask_b32_e32 v21, v63, v21, vcc
	v_mul_f32_e32 v21, v21, v22
	v_cvt_pk_bf16_f32 v21, v21, v33
	ds_write_b16 v17, v21 offset:912
	v_or_b32_e32 v21, 64, v9
	v_sub_u32_e32 v22, v16, v21
	v_cvt_f32_i32_e32 v30, v22
	v_cmp_lt_i32_e32 vcc, v16, v21
	s_waitcnt vmcnt(1)
	v_mfma_f32_16x16x32_bf16 v[22:25], v[4:7], v[26:29], 0
	v_cndmask_b32_e64 v26, -v12, v11, vcc
	v_mul_f32_e32 v35, v26, v30
	v_mul_f32_e32 v26, 0x3fb8aa3b, v35
	v_fma_f32 v27, v35, s50, -v26
	v_rndne_f32_e32 v28, v26
	v_fmac_f32_e32 v27, 0x32a5705f, v35
	v_sub_f32_e32 v26, v26, v28
	v_add_f32_e32 v26, v26, v27
	v_exp_f32_e32 v42, v26
	v_or_b32_e32 v26, 0x50, v15
	v_mad_u64_u32 v[26:27], s[36:37], v26, s46, v[36:37]
	v_lshl_add_u64 v[26:27], v[26:27], 0, s[34:35]
	v_lshl_add_u64 v[30:31], v[26:27], 0, v[32:33]
	v_add_co_u32_e32 v26, vcc, s48, v30
	v_cvt_i32_f32_e32 v43, v28
	s_nop 0
	v_addc_co_u32_e32 v27, vcc, 0, v31, vcc
	global_load_dwordx4 v[26:29], v[26:27], off
	s_waitcnt vmcnt(1)
	v_mfma_f32_16x16x32_bf16 v[22:25], v[0:3], v[38:41], v[22:25]
	v_ldexp_f32 v38, v42, v43
	v_cmp_ngt_f32_e32 vcc, s51, v35
	v_lshl_add_u64 v[30:31], v[30:31], 0, s[24:25]
	s_nop 0
	v_cndmask_b32_e32 v38, 0, v38, vcc
	v_cmp_nlt_f32_e32 vcc, s52, v35
	s_nop 1
	v_mul_f32_e32 v22, 0x3e000000, v22
	v_mul_f32_e32 v23, 0x3e000000, v23
	v_cndmask_b32_e32 v35, v63, v38, vcc
	v_sub_u32_e32 v38, v18, v21
	v_cvt_f32_i32_e32 v38, v38
	v_cmp_lt_i32_e32 vcc, v18, v21
	v_mul_f32_e32 v22, v35, v22
	v_cvt_pk_bf16_f32 v22, v22, v33
	ds_write_b16 v17, v22 offset:128
	v_cndmask_b32_e64 v39, -v12, v11, vcc
	v_mul_f32_e32 v42, v39, v38
	global_load_dwordx4 v[38:41], v[30:31], off offset:64
	v_mul_f32_e32 v30, 0x3fb8aa3b, v42
	v_fma_f32 v31, v42, s50, -v30
	v_rndne_f32_e32 v43, v30
	v_fmac_f32_e32 v31, 0x32a5705f, v42
	v_sub_f32_e32 v30, v30, v43
	v_add_f32_e32 v30, v30, v31
	v_exp_f32_e32 v30, v30
	v_cvt_i32_f32_e32 v31, v43
	v_cmp_ngt_f32_e32 vcc, s51, v42
	v_mul_f32_e32 v24, 0x3e000000, v24
	v_ldexp_f32 v22, v30, v31
	v_sub_u32_e32 v30, v20, v21
	v_cvt_f32_i32_e32 v30, v30
	v_cndmask_b32_e32 v22, 0, v22, vcc
	v_cmp_nlt_f32_e32 vcc, s52, v42
	s_nop 1
	v_cndmask_b32_e32 v22, v63, v22, vcc
	v_cmp_lt_i32_e32 vcc, v20, v21
	v_mul_f32_e32 v22, v22, v23
	v_cvt_pk_bf16_f32 v22, v22, v33
	v_sub_u32_e32 v23, v19, v21
	v_cndmask_b32_e64 v31, -v12, v11, vcc
	v_mul_f32_e32 v30, v31, v30
	v_mul_f32_e32 v31, 0x3fb8aa3b, v30
	v_fma_f32 v35, v30, s50, -v31
	v_rndne_f32_e32 v42, v31
	v_fmac_f32_e32 v35, 0x32a5705f, v30
	v_sub_f32_e32 v31, v31, v42
	v_add_f32_e32 v31, v31, v35
	v_exp_f32_e32 v31, v31
	v_cvt_i32_f32_e32 v35, v42
	ds_write_b16 v17, v22 offset:400
	v_cmp_ngt_f32_e32 vcc, s51, v30
	v_cvt_f32_i32_e32 v23, v23
	v_ldexp_f32 v22, v31, v35
	v_cndmask_b32_e32 v22, 0, v22, vcc
	v_cmp_nlt_f32_e32 vcc, s52, v30
	v_or_b32_e32 v35, 0x50, v9
	s_nop 0
	v_cndmask_b32_e32 v22, v63, v22, vcc
	v_cmp_lt_i32_e32 vcc, v19, v21
	v_mul_f32_e32 v22, v22, v24
	v_cvt_pk_bf16_f32 v22, v22, v33
	ds_write_b16 v17, v22 offset:672
	v_cndmask_b32_e64 v21, -v12, v11, vcc
	v_mul_f32_e32 v21, v21, v23
	v_mul_f32_e32 v23, 0x3fb8aa3b, v21
	v_fma_f32 v30, v21, s50, -v23
	v_rndne_f32_e32 v31, v23
	v_fmac_f32_e32 v30, 0x32a5705f, v21
	v_sub_f32_e32 v23, v23, v31
	v_add_f32_e32 v23, v23, v30
	v_exp_f32_e32 v23, v23
	v_cvt_i32_f32_e32 v30, v31
	v_cmp_ngt_f32_e32 vcc, s51, v21
	v_ldexp_f32 v22, v23, v30
	s_nop 0
	v_cndmask_b32_e32 v22, 0, v22, vcc
	v_cmp_nlt_f32_e32 vcc, s52, v21
	s_nop 1
	v_cndmask_b32_e32 v21, v63, v22, vcc
	v_mul_f32_e32 v22, 0x3e000000, v25
	v_mul_f32_e32 v21, v21, v22
	v_sub_u32_e32 v22, v16, v35
	v_cvt_f32_i32_e32 v30, v22
	v_cmp_lt_i32_e32 vcc, v16, v35
	s_waitcnt vmcnt(1)
	v_mfma_f32_16x16x32_bf16 v[22:25], v[4:7], v[26:29], 0
	v_cvt_pk_bf16_f32 v21, v21, v33
	ds_write_b16 v17, v21 offset:944
	v_cndmask_b32_e64 v26, -v12, v11, vcc
	v_mul_f32_e32 v42, v26, v30
	v_mul_f32_e32 v26, 0x3fb8aa3b, v42
	v_fma_f32 v27, v42, s50, -v26
	v_rndne_f32_e32 v28, v26
	v_fmac_f32_e32 v27, 0x32a5705f, v42
	v_sub_f32_e32 v26, v26, v28
	v_add_f32_e32 v26, v26, v27
	v_exp_f32_e32 v26, v26
	v_cvt_i32_f32_e32 v27, v28
	s_waitcnt vmcnt(0)
; __device__ __forceinline__ unsigned short f2bf(float f) { return (unsigned short)(cvt_pk_bf16(f, 0.f) & 0xffffu); }
; __device__ __forceinline__ void retout_item(PRef p, int layer, int item, unsigned char* shm) {
;     ...
;     for (int nt = 0; nt < 8; ++nt) { f32x4 s = (f32x4){0.f, 0.f, 0.f, 0.f};
; #pragma unroll
;         for (int kk = 0; kk < 2; ++kk) { const bf16x8 kb = *(const bf16x8*)(A + (size_t)(row0 + 16 * nt + fr) * NIN + C_K + h * 64 + kk * 32 + fq * 8);
;             s = __builtin_amdgcn_mfma_f32_16x16x32_bf16(qa[kk], kb, s, 0, 0, 0); }
;         const int m = 16 * nt + fr;
; #pragma unroll
;         for (int r = 0; r < 4; ++r) { const int c = 16 * wave + fq * 4 + r; const float dd = (float)(c - m);
;             const float dec = (m <= c) ? expf(dd * lgf) : expf(-dd * lgb);
;             Pw[(fq * 4 + r) * LDK + m] = f2bf(s[r] * 0.125f * dec); } }
	v_mfma_f32_16x16x32_bf16 v[22:25], v[0:3], v[38:41], v[22:25]
	v_ldexp_f32 v21, v26, v27
	v_or_b32_e32 v26, 0x60, v15
	v_mad_u64_u32 v[26:27], s[36:37], v26, s46, v[36:37]
	v_lshl_add_u64 v[26:27], v[26:27], 0, s[34:35]
	v_lshl_add_u64 v[30:31], v[26:27], 0, v[32:33]
	v_add_co_u32_e32 v26, vcc, s48, v30
	s_nop 1
	v_mul_f32_e32 v22, 0x3e000000, v22
	v_addc_co_u32_e32 v27, vcc, 0, v31, vcc
	global_load_dwordx4 v[26:29], v[26:27], off
	v_cmp_ngt_f32_e32 vcc, s51, v42
	v_lshl_add_u64 v[30:31], v[30:31], 0, s[24:25]
	v_mul_f32_e32 v23, 0x3e000000, v23
	v_cndmask_b32_e32 v21, 0, v21, vcc
	v_cmp_nlt_f32_e32 vcc, s52, v42
	v_or_b32_e32 v15, 0x70, v15
	s_nop 0
	v_cndmask_b32_e32 v21, v63, v21, vcc
	v_mul_f32_e32 v21, v21, v22
	v_sub_u32_e32 v22, v18, v35
	v_cvt_f32_i32_e32 v22, v22
	v_cmp_lt_i32_e32 vcc, v18, v35
	v_cvt_pk_bf16_f32 v21, v21, v33
	ds_write_b16 v17, v21 offset:160
	s_nop 0
	v_cndmask_b32_e64 v38, -v12, v11, vcc
	v_mul_f32_e32 v22, v38, v22
	v_mul_f32_e32 v38, 0x3fb8aa3b, v22
	v_fma_f32 v39, v22, s50, -v38
	v_rndne_f32_e32 v40, v38
	v_fmac_f32_e32 v39, 0x32a5705f, v22
	v_sub_f32_e32 v38, v38, v40
	v_add_f32_e32 v38, v38, v39
	v_exp_f32_e32 v42, v38
	v_cvt_i32_f32_e32 v43, v40
	global_load_dwordx4 v[38:41], v[30:31], off offset:64
	v_cmp_ngt_f32_e32 vcc, s51, v22
	v_ldexp_f32 v21, v42, v43
	s_nop 0
	v_cndmask_b32_e32 v21, 0, v21, vcc
	v_cmp_nlt_f32_e32 vcc, s52, v22
	v_sub_u32_e32 v22, v20, v35
	v_cvt_f32_i32_e32 v22, v22
	v_cndmask_b32_e32 v21, v63, v21, vcc
	v_cmp_lt_i32_e32 vcc, v20, v35
	v_mul_f32_e32 v21, v21, v23
	v_cvt_pk_bf16_f32 v21, v21, v33
	ds_write_b16 v17, v21 offset:432
	v_cndmask_b32_e64 v30, -v12, v11, vcc
	v_mul_f32_e32 v22, v30, v22
	v_mul_f32_e32 v30, 0x3fb8aa3b, v22
	v_fma_f32 v31, v22, s50, -v30
	v_rndne_f32_e32 v42, v30
	v_fmac_f32_e32 v31, 0x32a5705f, v22
	v_sub_f32_e32 v30, v30, v42
	v_add_f32_e32 v30, v30, v31
	v_exp_f32_e32 v30, v30
	v_cvt_i32_f32_e32 v31, v42
	v_cmp_ngt_f32_e32 vcc, s51, v22
	v_mul_f32_e32 v23, 0x3e000000, v24
	v_ldexp_f32 v21, v30, v31
	v_cndmask_b32_e32 v21, 0, v21, vcc
	v_cmp_nlt_f32_e32 vcc, s52, v22
	v_sub_u32_e32 v22, v19, v35
	v_cvt_f32_i32_e32 v22, v22
	v_cndmask_b32_e32 v21, v63, v21, vcc
	v_cmp_lt_i32_e32 vcc, v19, v35
	v_mul_f32_e32 v21, v21, v23
	v_cvt_pk_bf16_f32 v21, v21, v33
	ds_write_b16 v17, v21 offset:704
	v_cndmask_b32_e64 v24, -v12, v11, vcc
	v_mul_f32_e32 v22, v24, v22
	v_mul_f32_e32 v24, 0x3fb8aa3b, v22
	v_fma_f32 v30, v22, s50, -v24
	v_rndne_f32_e32 v31, v24
	v_fmac_f32_e32 v30, 0x32a5705f, v22
	v_sub_f32_e32 v24, v24, v31
	v_add_f32_e32 v24, v24, v30
	v_exp_f32_e32 v24, v24
	v_cvt_i32_f32_e32 v30, v31
	v_cmp_ngt_f32_e32 vcc, s51, v22
	v_ldexp_f32 v21, v24, v30
	s_nop 0
	v_cndmask_b32_e32 v21, 0, v21, vcc
	v_cmp_nlt_f32_e32 vcc, s52, v22
	v_mul_f32_e32 v22, 0x3e000000, v25
	s_nop 0
	v_cndmask_b32_e32 v21, v63, v21, vcc
	v_mul_f32_e32 v21, v21, v22
	v_cvt_pk_bf16_f32 v21, v21, v33
	ds_write_b16 v17, v21 offset:976
	v_or_b32_e32 v21, 0x60, v9
	v_sub_u32_e32 v22, v16, v21
	v_cvt_f32_i32_e32 v30, v22
	v_cmp_lt_i32_e32 vcc, v16, v21
	s_waitcnt vmcnt(1)
	v_mfma_f32_16x16x32_bf16 v[22:25], v[4:7], v[26:29], 0
	v_cndmask_b32_e64 v26, -v12, v11, vcc
	v_mul_f32_e32 v35, v26, v30
	v_mul_f32_e32 v26, 0x3fb8aa3b, v35
	v_fma_f32 v27, v35, s50, -v26
	v_rndne_f32_e32 v28, v26
	v_fmac_f32_e32 v27, 0x32a5705f, v35
	v_sub_f32_e32 v26, v26, v28
	v_add_f32_e32 v26, v26, v27
	v_exp_f32_e32 v42, v26
	v_mad_u64_u32 v[26:27], s[36:37], v15, s46, v[36:37]
	v_lshl_add_u64 v[26:27], v[26:27], 0, s[34:35]
	v_lshl_add_u64 v[30:31], v[26:27], 0, v[32:33]
	v_add_co_u32_e32 v26, vcc, s48, v30
	v_cvt_i32_f32_e32 v43, v28
	s_nop 0
	v_addc_co_u32_e32 v27, vcc, 0, v31, vcc
	global_load_dwordx4 v[26:29], v[26:27], off
	v_ldexp_f32 v15, v42, v43
	v_cmp_ngt_f32_e32 vcc, s51, v35
	s_waitcnt vmcnt(1)
	v_mfma_f32_16x16x32_bf16 v[22:25], v[0:3], v[38:41], v[22:25]
	v_lshl_add_u64 v[30:31], v[30:31], 0, s[24:25]
	v_cndmask_b32_e32 v15, 0, v15, vcc
	v_cmp_nlt_f32_e32 vcc, s52, v35
	v_sub_u32_e32 v35, v18, v21
	v_cvt_f32_i32_e32 v35, v35
	v_cndmask_b32_e32 v15, v63, v15, vcc
	v_cmp_lt_i32_e32 vcc, v18, v21
	s_nop 0
	v_mul_f32_e32 v22, 0x3e000000, v22
	v_mul_f32_e32 v15, v15, v22
	v_cndmask_b32_e64 v38, -v12, v11, vcc
	v_mul_f32_e32 v35, v38, v35
	global_load_dwordx4 v[38:41], v[30:31], off offset:64
	v_mul_f32_e32 v30, 0x3fb8aa3b, v35
	v_fma_f32 v31, v35, s50, -v30
	v_rndne_f32_e32 v42, v30
	v_fmac_f32_e32 v31, 0x32a5705f, v35
	v_sub_f32_e32 v30, v30, v42
	v_add_f32_e32 v30, v30, v31
	v_exp_f32_e32 v30, v30
	v_cvt_i32_f32_e32 v31, v42
	v_cvt_pk_bf16_f32 v15, v15, v33
	v_sub_u32_e32 v22, v20, v21
	ds_write_b16 v17, v15 offset:192
	v_ldexp_f32 v15, v30, v31
	v_cmp_ngt_f32_e32 vcc, s51, v35
	v_cvt_f32_i32_e32 v22, v22
	v_mul_f32_e32 v23, 0x3e000000, v23
	v_cndmask_b32_e32 v15, 0, v15, vcc
	v_cmp_nlt_f32_e32 vcc, s52, v35
	s_nop 1
	v_cndmask_b32_e32 v15, v63, v15, vcc
	v_cmp_lt_i32_e32 vcc, v20, v21
	v_mul_f32_e32 v15, v15, v23
	v_cvt_pk_bf16_f32 v15, v15, v33
	ds_write_b16 v17, v15 offset:464
	v_cndmask_b32_e64 v30, -v12, v11, vcc
	v_mul_f32_e32 v22, v30, v22
	v_mul_f32_e32 v30, 0x3fb8aa3b, v22
	v_fma_f32 v31, v22, s50, -v30
	v_rndne_f32_e32 v35, v30
	v_fmac_f32_e32 v31, 0x32a5705f, v22
	v_sub_f32_e32 v30, v30, v35
	v_add_f32_e32 v30, v30, v31
	v_exp_f32_e32 v30, v30
	v_cvt_i32_f32_e32 v31, v35
	v_cmp_ngt_f32_e32 vcc, s51, v22
	v_mul_f32_e32 v23, 0x3e000000, v24
	v_ldexp_f32 v15, v30, v31
	v_cndmask_b32_e32 v15, 0, v15, vcc
	v_cmp_nlt_f32_e32 vcc, s52, v22
	v_sub_u32_e32 v22, v19, v21
	v_cvt_f32_i32_e32 v22, v22
	v_cndmask_b32_e32 v15, v63, v15, vcc
	v_cmp_lt_i32_e32 vcc, v19, v21
	v_mul_f32_e32 v15, v15, v23
	v_cvt_pk_bf16_f32 v15, v15, v33
	ds_write_b16 v17, v15 offset:736
	v_cndmask_b32_e64 v21, -v12, v11, vcc
	v_mul_f32_e32 v21, v21, v22
	v_mul_f32_e32 v22, 0x3fb8aa3b, v21
	v_fma_f32 v24, v21, s50, -v22
	v_rndne_f32_e32 v30, v22
	v_fmac_f32_e32 v24, 0x32a5705f, v21
	v_sub_f32_e32 v22, v22, v30
	v_add_f32_e32 v22, v22, v24
	v_exp_f32_e32 v22, v22
	v_cvt_i32_f32_e32 v24, v30
	v_cmp_ngt_f32_e32 vcc, s51, v21
	v_ldexp_f32 v15, v22, v24
	s_nop 0
	v_cndmask_b32_e32 v15, 0, v15, vcc
	v_cmp_nlt_f32_e32 vcc, s52, v21
	v_mul_f32_e32 v21, 0x3e000000, v25
	s_nop 0
	v_cndmask_b32_e32 v15, v63, v15, vcc
	v_mul_f32_e32 v15, v15, v21
	v_or_b32_e32 v21, 0x70, v9
	v_sub_u32_e32 v22, v16, v21
	v_cvt_f32_i32_e32 v30, v22
	v_cmp_lt_i32_e32 vcc, v16, v21
	s_waitcnt vmcnt(1)
; __device__ __forceinline__ unsigned short f2bf(float f) { return (unsigned short)(cvt_pk_bf16(f, 0.f) & 0xffffu); }
; __device__ __forceinline__ void retout_item(PRef p, int layer, int item, unsigned char* shm) {
;     ...
;         const int m = 16 * nt + fr;
; #pragma unroll
;         for (int r = 0; r < 4; ++r) { const int c = 16 * wave + fq * 4 + r; const float dd = (float)(c - m);
;             const float dec = (m <= c) ? expf(dd * lgf) : expf(-dd * lgb);
;             Pw[(fq * 4 + r) * LDK + m] = f2bf(s[r] * 0.125f * dec); } }
;     __syncthreads();
;     f32x4 acc[8];
; #pragma unroll
;     for (int et = 0; et < 8; ++et) acc[et] = (f32x4){0.f, 0.f, 0.f, 0.f};
; #pragma unroll
;     for (int kk = 0; kk < 4; ++kk) { const bf16x8 af = *(const bf16x8*)(Pw + fr * LDK + kk * 32 + fq * 8);
; #pragma unroll
;         for (int et = 0; et < 8; ++et) { const bf16x8 bf = *(const bf16x8*)(vT + tsw(16 * et + fr, kk * 32 + fq * 8));
;             acc[et] = __builtin_amdgcn_mfma_f32_16x16x32_bf16(af, bf, acc[et], 0, 0, 0); } }
;     { const int ca = 16 * wave + fr;
;       const float sf = expf((float)(ca + 1) * lgf), sb = expf((float)(128 - ca) * lgb);
; #pragma unroll
;       for (int kk = 0; kk < 2; ++kk) { const bf16x8 af = scale8(qa[kk], sf), ab = scale8(qa[kk], sb);
	v_mfma_f32_16x16x32_bf16 v[22:25], v[4:7], v[26:29], 0
	v_cvt_pk_bf16_f32 v15, v15, v33
	ds_write_b16 v17, v15 offset:1008
	v_cndmask_b32_e64 v26, -v12, v11, vcc
	v_mul_f32_e32 v26, v26, v30
	v_mul_f32_e32 v27, 0x3fb8aa3b, v26
	v_fma_f32 v28, v26, s50, -v27
	v_rndne_f32_e32 v29, v27
	v_fmac_f32_e32 v28, 0x32a5705f, v26
	v_sub_f32_e32 v27, v27, v29
	v_add_f32_e32 v27, v27, v28
	v_exp_f32_e32 v27, v27
	v_cvt_i32_f32_e32 v28, v29
	v_cmp_ngt_f32_e32 vcc, s51, v26
	s_waitcnt vmcnt(0)
	v_mfma_f32_16x16x32_bf16 v[22:25], v[0:3], v[38:41], v[22:25]
	v_add_u32_e32 v30, 0, v32
	v_ldexp_f32 v15, v27, v28
	v_cndmask_b32_e32 v15, 0, v15, vcc
	v_cmp_nlt_f32_e32 vcc, s52, v26
	v_sub_u32_e32 v26, v18, v21
	v_cvt_f32_i32_e32 v26, v26
	v_cndmask_b32_e32 v15, v63, v15, vcc
	v_cmp_lt_i32_e32 vcc, v18, v21
	v_mul_f32_e32 v22, 0x3e000000, v22
	v_mul_f32_e32 v15, v15, v22
	v_cndmask_b32_e64 v18, -v12, v11, vcc
	v_mul_f32_e32 v18, v18, v26
	v_mul_f32_e32 v26, 0x3fb8aa3b, v18
	v_fma_f32 v27, v18, s50, -v26
	v_rndne_f32_e32 v28, v26
	v_fmac_f32_e32 v27, 0x32a5705f, v18
	v_sub_f32_e32 v26, v26, v28
	v_add_f32_e32 v26, v26, v27
	v_exp_f32_e32 v26, v26
	v_cvt_i32_f32_e32 v27, v28
	v_cvt_pk_bf16_f32 v15, v15, v33
	ds_write_b16 v17, v15 offset:224
	v_cmp_ngt_f32_e32 vcc, s51, v18
	v_ldexp_f32 v15, v26, v27
	v_mul_f32_e32 v22, 0x3e000000, v23
	v_cndmask_b32_e32 v15, 0, v15, vcc
	v_cmp_nlt_f32_e32 vcc, s52, v18
	v_sub_u32_e32 v18, v20, v21
	v_cvt_f32_i32_e32 v18, v18
	v_cndmask_b32_e32 v15, v63, v15, vcc
	v_cmp_lt_i32_e32 vcc, v20, v21
	v_mul_f32_e32 v15, v15, v22
	v_cvt_pk_bf16_f32 v15, v15, v33
	ds_write_b16 v17, v15 offset:496
	v_cndmask_b32_e64 v20, -v12, v11, vcc
	v_mul_f32_e32 v18, v20, v18
	v_mul_f32_e32 v20, 0x3fb8aa3b, v18
	v_fma_f32 v23, v18, s50, -v20
	v_rndne_f32_e32 v26, v20
	v_fmac_f32_e32 v23, 0x32a5705f, v18
	v_sub_f32_e32 v20, v20, v26
	v_add_f32_e32 v20, v20, v23
	v_exp_f32_e32 v20, v20
	v_cvt_i32_f32_e32 v23, v26
	v_cmp_ngt_f32_e32 vcc, s51, v18
	v_add3_u32 v76, v30, v58, v98
	v_add3_u32 v80, v30, v80, v100
	v_ldexp_f32 v15, v20, v23
	v_cndmask_b32_e32 v15, 0, v15, vcc
	v_cmp_nlt_f32_e32 vcc, s52, v18
	v_sub_u32_e32 v18, v19, v21
	v_cvt_f32_i32_e32 v18, v18
	v_cndmask_b32_e32 v15, v63, v15, vcc
	v_cmp_lt_i32_e32 vcc, v19, v21
	v_mul_f32_e32 v20, 0x3e000000, v24
	v_mul_f32_e32 v15, v15, v20
	v_cndmask_b32_e64 v19, -v12, v11, vcc
	v_mul_f32_e32 v18, v19, v18
	v_mul_f32_e32 v19, 0x3fb8aa3b, v18
	v_fma_f32 v21, v18, s50, -v19
	v_rndne_f32_e32 v22, v19
	v_fmac_f32_e32 v21, 0x32a5705f, v18
	v_sub_f32_e32 v19, v19, v22
	v_add_f32_e32 v19, v19, v21
	v_exp_f32_e32 v19, v19
	v_cvt_i32_f32_e32 v21, v22
	v_cvt_pk_bf16_f32 v15, v15, v33
	ds_write_b16 v17, v15 offset:768
	v_cmp_ngt_f32_e32 vcc, s51, v18
	v_ldexp_f32 v15, v19, v21
	v_add3_u32 v84, v30, v84, v102
	v_cndmask_b32_e32 v15, 0, v15, vcc
	v_cmp_nlt_f32_e32 vcc, s52, v18
	v_mul_f32_e32 v18, 0x3e000000, v25
	s_nop 0
	v_cndmask_b32_e32 v15, v63, v15, vcc
	v_mul_f32_e32 v15, v15, v18
	v_cvt_pk_bf16_f32 v15, v15, v33
	ds_write_b16 v17, v15 offset:1040
	v_mul_u32_u24_e32 v15, 0x110, v9
	v_add3_u32 v14, v14, v15, v32
	s_waitcnt lgkmcnt(0)
	s_barrier
	ds_read_b128 v[18:21], v14
	v_and_b32_e32 v17, 8, v8
	v_bitop3_b32 v32, v9, 24, 16 bitop3:0xc8
	v_lshlrev_b32_e32 v22, 1, v17
	v_lshlrev_b32_e32 v35, 1, v32
	v_add3_u32 v31, v30, v22, v15
	v_add3_u32 v35, v30, v35, v75
	ds_read_b128 v[22:25], v31
	ds_read_b128 v[26:29], v14 offset:64
	ds_read_b128 v[38:41], v31 offset:64
	ds_read_b128 v[42:45], v35
	ds_read_b128 v[46:49], v31 offset:128
	v_bitop3_b32 v31, v9, 40, 32 bitop3:0xc8
	v_lshlrev_b32_e32 v50, 1, v31
	v_add3_u32 v54, v30, v50, v96
	ds_read_b128 v[50:53], v54
	ds_read_b128 v[54:57], v54 offset:64
	ds_read_b128 v[58:61], v76
	ds_read_b128 v[76:79], v76 offset:64
	ds_read_b128 v[80:83], v80
	ds_read_b128 v[84:87], v84
	ds_read_b128 v[88:91], v88
	ds_read_b128 v[92:95], v92
	s_waitcnt lgkmcnt(12)
	v_mfma_f32_16x16x32_bf16 v[22:25], v[18:21], v[22:25], 0
	v_bfi_b32 v8, -16, v10, v8
	v_add_u32_e32 v10, 1, v8
	v_cvt_f32_i32_e32 v10, v10
	s_waitcnt lgkmcnt(9)
	v_mfma_f32_16x16x32_bf16 v[42:45], v[18:21], v[42:45], 0
	v_sub_u32_e32 v8, 0x80, v8
	v_cvt_f32_i32_e32 v8, v8
	v_mul_f32_e64 v10, v10, -v12
	s_waitcnt lgkmcnt(7)
	v_mfma_f32_16x16x32_bf16 v[50:53], v[18:21], v[50:53], 0
	v_mul_f32_e32 v12, 0x3fb8aa3b, v10
	v_mul_f32_e64 v8, v8, -v11
	v_mul_f32_e32 v11, 0x3fb8aa3b, v8
	s_waitcnt lgkmcnt(5)
	v_mfma_f32_16x16x32_bf16 v[58:61], v[18:21], v[58:61], 0
	v_cmp_ngt_f32_e32 vcc, s51, v10
	s_waitcnt lgkmcnt(3)
	v_mfma_f32_16x16x32_bf16 v[80:83], v[18:21], v[80:83], 0
	s_waitcnt lgkmcnt(2)
	v_mfma_f32_16x16x32_bf16 v[84:87], v[18:21], v[84:87], 0
	s_waitcnt lgkmcnt(1)
	v_mfma_f32_16x16x32_bf16 v[88:91], v[18:21], v[88:91], 0
	s_waitcnt lgkmcnt(0)
	v_mfma_f32_16x16x32_bf16 v[18:21], v[18:21], v[92:95], 0
	v_mfma_f32_16x16x32_bf16 v[22:25], v[26:29], v[38:41], v[22:25]
	ds_read_b128 v[38:41], v35 offset:64
	ds_read_b128 v[92:95], v35 offset:128
	v_or_b32_e32 v35, 32, v13
	s_waitcnt lgkmcnt(1)
	v_mfma_f32_16x16x32_bf16 v[38:41], v[26:29], v[38:41], v[42:45]
	v_mfma_f32_16x16x32_bf16 v[42:45], v[26:29], v[54:57], v[50:53]
	v_add_u32_e32 v54, v35, v99
	v_and_b32_e32 v54, 0x78, v54
	v_lshlrev_b32_e32 v54, 1, v54
	v_add3_u32 v54, 0, v54, v100
	ds_read_b128 v[54:57], v54
	v_mfma_f32_16x16x32_bf16 v[50:53], v[26:29], v[76:79], v[58:61]
	v_add_u32_e32 v76, v35, v103
	v_and_b32_e32 v76, 56, v76
	v_lshlrev_b32_e32 v76, 1, v76
	v_add_u32_e32 v58, v35, v101
	v_add_u32_e32 v35, v35, v105
	v_and_b32_e32 v58, 0x78, v58
	v_and_b32_e32 v35, 56, v35
	v_lshlrev_b32_e32 v58, 1, v58
	v_lshlrev_b32_e32 v35, 1, v35
	v_add3_u32 v58, 0, v58, v102
	v_add3_u32 v76, 0, v76, v104
	v_add3_u32 v35, 0, v35, v106
	ds_read_b128 v[58:61], v58
	ds_read_b128 v[76:79], v76
	s_waitcnt lgkmcnt(2)
; __device__ __forceinline__ void retout_item(PRef p, int layer, int item, unsigned char* shm) {
;     ...
; #pragma unroll
;     for (int kk = 0; kk < 4; ++kk) { const bf16x8 af = *(const bf16x8*)(Pw + fr * LDK + kk * 32 + fq * 8);
; #pragma unroll
;         for (int et = 0; et < 8; ++et) { const bf16x8 bf = *(const bf16x8*)(vT + tsw(16 * et + fr, kk * 32 + fq * 8));
;             acc[et] = __builtin_amdgcn_mfma_f32_16x16x32_bf16(af, bf, acc[et], 0, 0, 0); } }
;     { const int ca = 16 * wave + fr;
;       const float sf = expf((float)(ca + 1) * lgf), sb = expf((float)(128 - ca) * lgb);
; #pragma unroll
;       for (int kk = 0; kk < 2; ++kk) { const bf16x8 af = scale8(qa[kk], sf), ab = scale8(qa[kk], sb);
; #pragma unroll
;           for (int et = 0; et < 8; ++et) { const bf16x8 b1 = *(const bf16x8*)(sTf + (16 * et + fr) * 72 + kk * 32 + fq * 8);
;               acc[et] = __builtin_amdgcn_mfma_f32_16x16x32_bf16(af, b1, acc[et], 0, 0, 0);
;               const bf16x8 b2 = *(const bf16x8*)(sTb + (16 * et + fr) * 72 + kk * 32 + fq * 8);
;               acc[et] = __builtin_amdgcn_mfma_f32_16x16x32_bf16(ab, b2, acc[et], 0, 0, 0); } } }
	v_mfma_f32_16x16x32_bf16 v[54:57], v[26:29], v[54:57], v[80:83]
	s_nop 2
	ds_read_b128 v[80:83], v35
	s_waitcnt lgkmcnt(2)
	v_mfma_f32_16x16x32_bf16 v[58:61], v[26:29], v[58:61], v[84:87]
	s_waitcnt lgkmcnt(1)
	v_mfma_f32_16x16x32_bf16 v[76:79], v[26:29], v[76:79], v[88:91]
	s_waitcnt lgkmcnt(0)
	v_mfma_f32_16x16x32_bf16 v[18:21], v[26:29], v[80:83], v[18:21]
	ds_read_b128 v[26:29], v14 offset:128
	ds_read_b128 v[80:83], v14 offset:192
	v_or_b32_e32 v14, 64, v13
	v_add_u32_e32 v35, v14, v31
	v_and_b32_e32 v35, 0x78, v35
	v_lshlrev_b32_e32 v35, 1, v35
	v_add3_u32 v35, 0, v35, v96
	s_waitcnt lgkmcnt(1)
	v_mfma_f32_16x16x32_bf16 v[22:25], v[26:29], v[46:49], v[22:25]
	ds_read_b128 v[46:49], v35
	v_add_u32_e32 v35, v14, v97
	v_and_b32_e32 v35, 0x78, v35
	v_lshlrev_b32_e32 v35, 1, v35
	v_add3_u32 v35, 0, v35, v98
	ds_read_b128 v[84:87], v35
	v_add_u32_e32 v35, v13, v99
	v_and_b32_e32 v35, 56, v35
	v_lshlrev_b32_e32 v35, 1, v35
	v_add3_u32 v35, 0, v35, v100
	s_waitcnt lgkmcnt(1)
	v_mfma_f32_16x16x32_bf16 v[42:45], v[26:29], v[46:49], v[42:45]
	s_waitcnt lgkmcnt(0)
	v_mfma_f32_16x16x32_bf16 v[46:49], v[26:29], v[84:87], v[50:53]
	s_nop 2
	ds_read_b128 v[50:53], v35
	v_add_u32_e32 v35, v13, v101
	v_and_b32_e32 v35, 56, v35
	v_lshlrev_b32_e32 v35, 1, v35
	v_add3_u32 v35, 0, v35, v102
	ds_read_b128 v[84:87], v35
	v_add_u32_e32 v35, v14, v103
	v_add_u32_e32 v14, v14, v105
	v_and_b32_e32 v35, 0x78, v35
	v_and_b32_e32 v14, 0x78, v14
	v_lshlrev_b32_e32 v35, 1, v35
	v_lshlrev_b32_e32 v14, 1, v14
	v_add3_u32 v35, 0, v35, v104
	v_add3_u32 v14, 0, v14, v106
	s_waitcnt lgkmcnt(1)
	v_mfma_f32_16x16x32_bf16 v[50:53], v[26:29], v[50:53], v[54:57]
	v_or_b32_e32 v13, 0x60, v13
	s_waitcnt lgkmcnt(0)
	v_mfma_f32_16x16x32_bf16 v[54:57], v[26:29], v[84:87], v[58:61]
	ds_read_b128 v[84:87], v14
	v_add_u32_e32 v14, v13, v17
	v_and_b32_e32 v14, 0x78, v14
	ds_read_b128 v[58:61], v35
	v_lshlrev_b32_e32 v14, 1, v14
	v_add3_u32 v14, 0, v14, v15
	v_mfma_f32_16x16x32_bf16 v[38:41], v[26:29], v[92:95], v[38:41]
	v_and_b32_e32 v35, 0xffff0000, v7
	s_waitcnt lgkmcnt(0)
	v_mfma_f32_16x16x32_bf16 v[58:61], v[26:29], v[58:61], v[76:79]
	v_mfma_f32_16x16x32_bf16 v[18:21], v[26:29], v[84:87], v[18:21]
	ds_read_b128 v[26:29], v14
	v_add_u32_e32 v14, v13, v32
	v_and_b32_e32 v14, 0x78, v14
	v_lshlrev_b32_e32 v14, 1, v14
	v_add3_u32 v14, 0, v14, v75
	ds_read_b128 v[76:79], v14
	v_add_u32_e32 v14, v13, v31
	v_and_b32_e32 v14, 56, v14
	v_lshlrev_b32_e32 v14, 1, v14
	v_add3_u32 v14, 0, v14, v96
	s_waitcnt lgkmcnt(1)
	v_mfma_f32_16x16x32_bf16 v[22:25], v[80:83], v[26:29], v[22:25]
	v_lshlrev_b32_e32 v32, 16, v7
	s_waitcnt lgkmcnt(0)
	v_mfma_f32_16x16x32_bf16 v[26:29], v[80:83], v[76:79], v[38:41]
	s_nop 2
	ds_read_b128 v[38:41], v14
	v_add_u32_e32 v14, v13, v97
	v_and_b32_e32 v14, 56, v14
	v_lshlrev_b32_e32 v14, 1, v14
	v_add3_u32 v14, 0, v14, v98
	ds_read_b128 v[76:79], v14
	v_add_u32_e32 v14, v13, v99
	v_and_b32_e32 v14, 0x78, v14
	v_lshlrev_b32_e32 v14, 1, v14
	v_add3_u32 v14, 0, v14, v100
	s_waitcnt lgkmcnt(1)
	v_mfma_f32_16x16x32_bf16 v[38:41], v[80:83], v[38:41], v[42:45]
	s_waitcnt lgkmcnt(0)
	v_mfma_f32_16x16x32_bf16 v[42:45], v[80:83], v[76:79], v[46:49]
	s_nop 2
	ds_read_b128 v[46:49], v14
	v_add_u32_e32 v14, v13, v101
	v_and_b32_e32 v14, 0x78, v14
	v_lshlrev_b32_e32 v14, 1, v14
	v_add3_u32 v14, 0, v14, v102
	ds_read_b128 v[76:79], v14
	v_add_u32_e32 v14, v13, v103
	v_add_u32_e32 v13, v13, v105
	v_and_b32_e32 v14, 0x78, v14
	v_and_b32_e32 v13, 0x78, v13
	v_lshlrev_b32_e32 v14, 1, v14
	v_lshlrev_b32_e32 v13, 1, v13
	v_add3_u32 v14, 0, v14, v104
	v_add3_u32 v13, 0, v13, v106
	s_waitcnt lgkmcnt(1)
	v_mfma_f32_16x16x32_bf16 v[46:49], v[80:83], v[46:49], v[50:53]
	s_waitcnt lgkmcnt(0)
	v_mfma_f32_16x16x32_bf16 v[50:53], v[80:83], v[76:79], v[54:57]
	ds_read_b128 v[76:79], v13
	v_fma_f32 v13, v10, s50, -v12
	v_fmac_f32_e32 v13, 0x32a5705f, v10
	ds_read_b128 v[54:57], v14
	v_rndne_f32_e32 v14, v12
	v_sub_f32_e32 v12, v12, v14
	v_add_f32_e32 v12, v12, v13
	v_exp_f32_e32 v17, v12
	v_cvt_i32_f32_e32 v31, v14
	s_waitcnt lgkmcnt(1)
	v_mfma_f32_16x16x32_bf16 v[12:15], v[80:83], v[76:79], v[18:21]
	v_ldexp_f32 v17, v17, v31
	s_nop 1
	v_fma_f32 v18, v8, s50, -v11
	v_rndne_f32_e32 v19, v11
	v_fmac_f32_e32 v18, 0x32a5705f, v8
	v_sub_f32_e32 v11, v11, v19
	v_add_f32_e32 v11, v11, v18
	v_exp_f32_e32 v11, v11
	v_cvt_i32_f32_e32 v18, v19
	v_cndmask_b32_e32 v17, 0, v17, vcc
	v_cmp_nlt_f32_e32 vcc, s52, v10
	v_and_b32_e32 v19, 0xffff0000, v5
	v_ldexp_f32 v10, v11, v18
	v_cndmask_b32_e32 v17, v63, v17, vcc
	v_cmp_ngt_f32_e32 vcc, s51, v8
	v_and_b32_e32 v11, 0xffff0000, v4
	v_and_b32_e32 v21, 0xffff0000, v6
	v_cndmask_b32_e32 v10, 0, v10, vcc
	v_cmp_nlt_f32_e32 vcc, s52, v8
	v_lshlrev_b32_e32 v8, 16, v4
	v_mul_f32_e32 v4, v17, v11
	v_cndmask_b32_e32 v31, v63, v10, vcc
	v_mul_u32_u24_e32 v10, 0x48, v9
	v_mul_f32_e32 v9, v17, v8
	v_cvt_pk_bf16_f32 v4, v9, v4
	v_lshlrev_b32_e32 v9, 16, v5
	v_mul_f32_e32 v18, v17, v9
	v_mul_f32_e32 v5, v17, v19
	v_cvt_pk_bf16_f32 v5, v18, v5
	v_lshlrev_b32_e32 v18, 16, v6
	v_mul_f32_e32 v20, v17, v18
	v_mul_f32_e32 v6, v17, v21
	v_mul_f32_e32 v8, v31, v8
	v_mul_f32_e32 v11, v31, v11
	v_cvt_pk_bf16_f32 v6, v20, v6
	v_mul_f32_e32 v20, v17, v32
	v_mul_f32_e32 v7, v17, v35
	v_cvt_pk_bf16_f32 v8, v8, v11
	v_mul_f32_e32 v9, v31, v9
	v_mul_f32_e32 v11, v31, v19
	v_lshl_add_u32 v30, v10, 1, v30
	s_waitcnt lgkmcnt(0)
	v_mfma_f32_16x16x32_bf16 v[54:57], v[80:83], v[54:57], v[58:61]
	v_cvt_pk_bf16_f32 v7, v20, v7
	v_cvt_pk_bf16_f32 v9, v9, v11
	v_mul_f32_e32 v11, v31, v18
	s_nop 1
	v_mul_f32_e32 v58, v31, v21
	ds_read_b128 v[18:21], v30 offset:34816
	v_cvt_pk_bf16_f32 v10, v11, v58
	ds_read_b128 v[58:61], v30 offset:53248
	ds_read_b128 v[76:79], v30 offset:34880
	s_waitcnt lgkmcnt(2)
; __device__ __forceinline__ void retout_item(PRef p, int layer, int item, unsigned char* shm) {
;     ...
;       for (int kk = 0; kk < 2; ++kk) { const bf16x8 af = scale8(qa[kk], sf), ab = scale8(qa[kk], sb);
; #pragma unroll
;           for (int et = 0; et < 8; ++et) { const bf16x8 b1 = *(const bf16x8*)(sTf + (16 * et + fr) * 72 + kk * 32 + fq * 8);
;               acc[et] = __builtin_amdgcn_mfma_f32_16x16x32_bf16(af, b1, acc[et], 0, 0, 0);
;               const bf16x8 b2 = *(const bf16x8*)(sTb + (16 * et + fr) * 72 + kk * 32 + fq * 8);
;               acc[et] = __builtin_amdgcn_mfma_f32_16x16x32_bf16(ab, b2, acc[et], 0, 0, 0); } } }
; #pragma unroll
;     for (int r = 0; r < 4; ++r) { float ss = 0.f;
; #pragma unroll
;         for (int et = 0; et < 8; ++et) ss += acc[et][r] * acc[et][r];
;         ss += __shfl_xor(ss, 1); ss += __shfl_xor(ss, 2); ss += __shfl_xor(ss, 4); ss += __shfl_xor(ss, 8);
;         const float rinv = rsqrtf(ss * (1.f / 128.f) + 1e-6f);
	v_mfma_f32_16x16x32_bf16 v[18:21], v[4:7], v[18:21], v[22:25]
	v_mul_f32_e32 v11, v31, v32
	s_nop 1
	v_mul_f32_e32 v22, v31, v35
	v_cvt_pk_bf16_f32 v11, v11, v22
	ds_read_b128 v[22:25], v30 offset:53312
	s_waitcnt lgkmcnt(2)
	v_mfma_f32_16x16x32_bf16 v[18:21], v[8:11], v[58:61], v[18:21]
	ds_read_b128 v[58:61], v30 offset:37120
	ds_read_b128 v[80:83], v30 offset:37184
	v_add_u32_e32 v32, 0x900, v30
	v_mov_b32_e32 v35, v33
	s_waitcnt lgkmcnt(1)
	v_mfma_f32_16x16x32_bf16 v[26:29], v[4:7], v[58:61], v[26:29]
	ds_read_b128 v[58:61], v30 offset:55552
	ds_read_b128 v[84:87], v30 offset:55616
	s_waitcnt lgkmcnt(1)
	v_mfma_f32_16x16x32_bf16 v[58:61], v[8:11], v[58:61], v[26:29]
	s_nop 3
	ds_read_b128 v[26:29], v30 offset:39424
	ds_read_b128 v[88:91], v30 offset:39488
	s_waitcnt lgkmcnt(1)
	v_mfma_f32_16x16x32_bf16 v[26:29], v[4:7], v[26:29], v[38:41]
	s_nop 2
	ds_read_b128 v[38:41], v30 offset:57856
	ds_read_b128 v[92:95], v30 offset:57920
	s_waitcnt lgkmcnt(1)
	v_mfma_f32_16x16x32_bf16 v[38:41], v[8:11], v[38:41], v[26:29]
	s_nop 2
	ds_read_b128 v[26:29], v30 offset:41728
	ds_read_b128 v[96:99], v30 offset:41792
	s_waitcnt lgkmcnt(1)
	v_mfma_f32_16x16x32_bf16 v[26:29], v[4:7], v[26:29], v[42:45]
	s_nop 2
	ds_read_b128 v[42:45], v30 offset:60160
	ds_read_b128 v[100:103], v30 offset:60224
	s_waitcnt lgkmcnt(1)
	v_mfma_f32_16x16x32_bf16 v[42:45], v[8:11], v[42:45], v[26:29]
	s_nop 2
	ds_read_b128 v[26:29], v30 offset:44032
	ds_read_b128 v[104:107], v30 offset:44096
	s_waitcnt lgkmcnt(1)
	v_mfma_f32_16x16x32_bf16 v[26:29], v[4:7], v[26:29], v[46:49]
	s_nop 2
	ds_read_b128 v[46:49], v30 offset:62464
	ds_read_b128 v[108:111], v30 offset:62528
	s_waitcnt lgkmcnt(1)
	v_mfma_f32_16x16x32_bf16 v[46:49], v[8:11], v[46:49], v[26:29]
	s_nop 2
	ds_read_b128 v[26:29], v30 offset:46336
	ds_read_b128 v[112:115], v30 offset:46400
	s_waitcnt lgkmcnt(1)
	v_mfma_f32_16x16x32_bf16 v[26:29], v[4:7], v[26:29], v[50:53]
	s_nop 2
	ds_read_b128 v[50:53], v30 offset:64768
	ds_read_b128 v[116:119], v30 offset:64832
	ds_read_b128 v[120:123], v30 offset:48704
	s_waitcnt lgkmcnt(2)
	v_mfma_f32_16x16x32_bf16 v[50:53], v[8:11], v[50:53], v[26:29]
	s_nop 2
	ds_read_b128 v[26:29], v30 offset:48640
	s_waitcnt lgkmcnt(0)
	v_mfma_f32_16x16x32_bf16 v[26:29], v[4:7], v[26:29], v[54:57]
	s_nop 2
	ds_read_b128 v[54:57], v32 offset:64768
	ds_read_b128 v[124:127], v32 offset:64832
	v_add_u32_e32 v32, 0x1200, v30
	ds_read_b128 v[128:131], v30 offset:51008
	s_waitcnt lgkmcnt(2)
	v_mfma_f32_16x16x32_bf16 v[54:57], v[8:11], v[54:57], v[26:29]
	s_nop 2
	ds_read_b128 v[26:29], v30 offset:50944
	s_waitcnt lgkmcnt(0)
	v_mfma_f32_16x16x32_bf16 v[4:7], v[4:7], v[26:29], v[12:15]
	s_nop 2
	ds_read_b128 v[12:15], v32 offset:64768
	ds_read_b128 v[132:135], v32 offset:64832
	v_xor_b32_e32 v32, 1, v74
	s_waitcnt lgkmcnt(1)
	v_mfma_f32_16x16x32_bf16 v[136:139], v[8:11], v[12:15], v[4:7]
	v_and_b32_e32 v9, 0xffff0000, v3
	s_nop 1
	v_lshlrev_b32_e32 v4, 16, v0
	v_mul_f32_e32 v5, v17, v4
	v_and_b32_e32 v0, 0xffff0000, v0
	v_mul_f32_e32 v6, v17, v0
	v_cvt_pk_bf16_f32 v140, v5, v6
	v_lshlrev_b32_e32 v5, 16, v1
	v_mul_f32_e32 v6, v17, v5
	v_and_b32_e32 v1, 0xffff0000, v1
	v_mul_f32_e32 v7, v17, v1
	v_cvt_pk_bf16_f32 v141, v6, v7
	v_lshlrev_b32_e32 v6, 16, v2
	v_mul_f32_e32 v7, v17, v6
	v_and_b32_e32 v2, 0xffff0000, v2
	v_mul_f32_e32 v8, v17, v2
	v_cvt_pk_bf16_f32 v142, v7, v8
	v_lshlrev_b32_e32 v7, 16, v3
	v_mul_f32_e32 v3, v17, v9
	v_mul_f32_e32 v0, v31, v0
	v_mul_f32_e32 v8, v17, v7
	v_cvt_pk_bf16_f32 v143, v8, v3
	v_mul_f32_e32 v3, v31, v4
	v_cvt_pk_bf16_f32 v144, v3, v0
	v_mul_f32_e32 v0, v31, v5
	v_mul_f32_e32 v1, v31, v1
	v_cvt_pk_bf16_f32 v145, v0, v1
	v_mul_f32_e32 v0, v31, v6
	v_mul_f32_e32 v1, v31, v2
	v_cvt_pk_bf16_f32 v146, v0, v1
	v_mfma_f32_16x16x32_bf16 v[0:3], v[140:143], v[76:79], v[18:21]
	v_mul_f32_e32 v4, v31, v7
	v_mul_f32_e32 v5, v31, v9
	v_cvt_pk_bf16_f32 v147, v4, v5
	s_nop 0
	v_mfma_f32_16x16x32_bf16 v[28:31], v[144:147], v[22:25], v[0:3]
	v_mfma_f32_16x16x32_bf16 v[0:3], v[140:143], v[80:83], v[58:61]
	v_mfma_f32_16x16x32_bf16 v[24:27], v[144:147], v[84:87], v[0:3]
	v_mfma_f32_16x16x32_bf16 v[0:3], v[140:143], v[88:91], v[38:41]
	s_nop 2
	v_add_u32_e32 v38, s62, v16
	v_mad_i64_i32 v[16:17], s[34:35], v38, s46, v[36:37]
	v_lshl_add_u64 v[16:17], v[16:17], 0, s[20:21]
	v_mfma_f32_16x16x32_bf16 v[20:23], v[144:147], v[92:95], v[0:3]
	s_add_u32 s34, s13, s20
	s_addc_u32 s35, s14, 0
	v_mfma_f32_16x16x32_bf16 v[0:3], v[140:143], v[96:99], v[42:45]
	s_nop 2
	v_lshl_add_u64 v[44:45], v[16:17], 0, v[34:35]
	v_add_co_u32_e32 v16, vcc, s48, v44
	v_mfma_f32_16x16x32_bf16 v[12:15], v[144:147], v[100:103], v[0:3]
	s_nop 0
	v_addc_co_u32_e32 v17, vcc, 0, v45, vcc
	global_load_ushort v39, v[16:17], off offset:3072
	v_mfma_f32_16x16x32_bf16 v[0:3], v[140:143], v[104:107], v[46:49]
	v_mfma_f32_16x16x32_bf16 v[8:11], v[144:147], v[108:111], v[0:3]
	s_nop 1
	v_mul_f32_e32 v47, v24, v24
	v_fmac_f32_e32 v47, v28, v28
	v_xor_b32_e32 v49, 8, v74
	v_mfma_f32_16x16x32_bf16 v[0:3], v[140:143], v[112:115], v[50:53]
	v_mfma_f32_16x16x32_bf16 v[40:43], v[140:143], v[128:131], v[136:139]
	v_mfma_f32_16x16x32_bf16 v[4:7], v[144:147], v[116:119], v[0:3]
	v_mfma_f32_16x16x32_bf16 v[0:3], v[140:143], v[120:123], v[54:57]
	s_waitcnt lgkmcnt(0)
	v_mfma_f32_16x16x32_bf16 v[16:19], v[144:147], v[132:135], v[40:43]
	s_waitcnt vmcnt(0)
; __device__ __forceinline__ float bf2f(unsigned short b) { return __uint_as_float(((unsigned)b) << 16); }
; __device__ __forceinline__ unsigned short f2bf(float f) { return (unsigned short)(cvt_pk_bf16(f, 0.f) & 0xffffu); }
; __device__ __forceinline__ float sigmoidf_(float x) { return 1.f / (1.f + __expf(-x)); }
; __device__ __forceinline__ void retout_item(PRef p, int layer, int item, unsigned char* shm) {
;     ...
; #pragma unroll
;     for (int r = 0; r < 4; ++r) { float ss = 0.f;
; #pragma unroll
;         for (int et = 0; et < 8; ++et) ss += acc[et][r] * acc[et][r];
;         ss += __shfl_xor(ss, 1); ss += __shfl_xor(ss, 2); ss += __shfl_xor(ss, 4); ss += __shfl_xor(ss, 8);
;         const float rinv = rsqrtf(ss * (1.f / 128.f) + 1e-6f);
;         const size_t row = (size_t)(row0 + 16 * wave + fq * 4 + r);
; #pragma unroll
;         for (int et = 0; et < 8; ++et) { const int e = 16 * et + fr; const float gg = bf2f(A[row * NIN + C_G + h * 128 + e]);
;             MIX[row * 2048 + 512 + h * 128 + e] = f2bf(acc[et][r] * rinv * gg * sigmoidf_(gg)); } }
	v_lshlrev_b32_e32 v54, 16, v39
	s_nop 1
	v_and_b32_e32 v40, 64, v74
	v_add_u32_e32 v46, 64, v40
	v_lshl_add_u64 v[40:41], v[44:45], 0, s[26:27]
	v_mov_b32_e32 v42, v20
	v_mov_b32_e32 v43, v12
	global_load_ushort v48, v[40:41], off offset:32
	v_pk_mul_f32 v[42:43], v[42:43], v[42:43]
	v_mfma_f32_16x16x32_bf16 v[0:3], v[144:147], v[124:127], v[0:3]
	v_add_f32_e32 v42, v47, v42
	v_add_f32_e32 v44, v42, v43
	v_mov_b32_e32 v42, v8
	v_mov_b32_e32 v43, v4
	v_pk_mul_f32 v[42:43], v[42:43], v[42:43]
	v_cmp_lt_i32_e32 vcc, v32, v46
	v_add_f32_e32 v42, v44, v42
	v_add_f32_e32 v44, v42, v43
	v_mov_b32_e32 v42, v0
	v_mov_b32_e32 v43, v16
	v_pk_mul_f32 v[42:43], v[42:43], v[42:43]
	v_cndmask_b32_e32 v32, v74, v32, vcc
	v_add_f32_e32 v42, v44, v42
	v_lshlrev_b32_e32 v32, 2, v32
	v_add_f32_e32 v42, v42, v43
	ds_bpermute_b32 v43, v32, v42
	v_xor_b32_e32 v44, 2, v74
	v_cmp_lt_i32_e32 vcc, v44, v46
	v_xor_b32_e32 v45, 4, v74
	v_mul_f32_e32 v39, 0xbfb8aa3b, v54
	v_cndmask_b32_e32 v44, v74, v44, vcc
	v_lshlrev_b32_e32 v44, 2, v44
	s_waitcnt lgkmcnt(0)
	v_add_f32_e32 v42, v42, v43
	ds_bpermute_b32 v47, v44, v42
	global_load_ushort v43, v[40:41], off offset:64
	v_cmp_lt_i32_e32 vcc, v45, v46
	v_exp_f32_e32 v55, v39
	v_ashrrev_i32_e32 v39, 31, v38
	v_cndmask_b32_e32 v45, v74, v45, vcc
	v_lshlrev_b32_e32 v45, 2, v45
	s_waitcnt lgkmcnt(0)
	v_add_f32_e32 v42, v42, v47
	ds_bpermute_b32 v47, v45, v42
	v_cmp_lt_i32_e32 vcc, v49, v46
	s_waitcnt lgkmcnt(0)
	v_add_f32_e32 v42, v42, v47
	v_cndmask_b32_e32 v46, v74, v49, vcc
	v_lshlrev_b32_e32 v46, 2, v46
	ds_bpermute_b32 v47, v46, v42
	s_waitcnt lgkmcnt(0)
	v_add_f32_e32 v42, v42, v47
	v_fmamk_f32 v42, v42, 0x3c000000, v62
	v_mul_f32_e32 v47, 0x4b800000, v42
	v_cmp_gt_f32_e32 vcc, s56, v42
	s_nop 1
	v_cndmask_b32_e32 v42, v42, v47, vcc
	global_load_ushort v47, v[40:41], off offset:96
	global_load_ushort v50, v[40:41], off offset:128
	global_load_ushort v51, v[40:41], off offset:160
	global_load_ushort v52, v[40:41], off offset:192
	global_load_ushort v53, v[40:41], off offset:224
	v_rsq_f32_e32 v42, v42
	v_lshlrev_b64 v[40:41], 12, v[38:39]
	v_add_f32_e32 v39, 1.0, v55
	v_lshl_add_u64 v[40:41], s[34:35], 0, v[40:41]
	v_mul_f32_e32 v49, 0x45800000, v42
	v_cndmask_b32_e32 v56, v42, v49, vcc
	v_rcp_f32_e32 v39, v39
	v_mul_f32_e32 v28, v28, v56
	v_mul_f32_e32 v28, v28, v54
	v_lshl_add_u64 v[40:41], v[40:41], 0, v[34:35]
	v_mul_f32_e32 v28, v39, v28
	v_cvt_pk_bf16_f32 v28, v28, v33
	s_waitcnt vmcnt(6)
	v_lshlrev_b32_e32 v42, 16, v48
	v_mul_f32_e32 v48, 0xbfb8aa3b, v42
	v_exp_f32_e32 v48, v48
	global_store_short v[40:41], v28, off
	v_mul_f32_e32 v24, v24, v56
	v_mul_f32_e32 v24, v24, v42
	v_add_f32_e32 v39, 1.0, v48
	v_rcp_f32_e32 v28, v39
	v_mul_f32_e32 v20, v20, v56
	v_mul_f32_e32 v12, v12, v56
	v_mul_f32_e32 v8, v8, v56
	v_mul_f32_e32 v24, v24, v28
	v_cvt_pk_bf16_f32 v24, v24, v33
	global_store_short v[40:41], v24, off offset:32
	v_mul_f32_e32 v4, v4, v56
	s_waitcnt vmcnt(7)
	v_lshlrev_b32_e32 v42, 16, v43
	v_mul_f32_e32 v43, 0xbfb8aa3b, v42
	v_exp_f32_e32 v43, v43
	v_mul_f32_e32 v20, v20, v42
	v_mul_f32_e32 v0, v0, v56
	v_add_f32_e32 v28, 1.0, v43
	v_rcp_f32_e32 v24, v28
	s_nop 0
	v_mul_f32_e32 v20, v20, v24
	v_cvt_pk_bf16_f32 v20, v20, v33
	global_store_short v[40:41], v20, off offset:64
	s_waitcnt vmcnt(7)
	v_lshlrev_b32_e32 v39, 16, v47
	v_mul_f32_e32 v42, 0xbfb8aa3b, v39
	v_exp_f32_e32 v42, v42
	v_mul_f32_e32 v12, v12, v39
	v_add_f32_e32 v24, 1.0, v42
	v_rcp_f32_e32 v20, v24
	s_nop 0
	s_waitcnt vmcnt(6)
	v_lshlrev_b32_e32 v28, 16, v50
	v_mul_f32_e32 v39, 0xbfb8aa3b, v28
	v_exp_f32_e32 v39, v39
	v_mul_f32_e32 v12, v12, v20
	v_cvt_pk_bf16_f32 v12, v12, v33
	v_add_f32_e32 v20, 1.0, v39
	v_rcp_f32_e32 v39, v20
	global_store_short v[40:41], v12, off offset:96
	v_mul_f32_e32 v8, v8, v28
	s_waitcnt vmcnt(6)
	v_lshlrev_b32_e32 v24, 16, v51
	v_mul_f32_e32 v28, 0xbfb8aa3b, v24
	v_exp_f32_e32 v28, v28
	v_mov_b32_e32 v12, v39
	v_mul_f32_e32 v8, v8, v12
	v_cvt_pk_bf16_f32 v8, v8, v33
	v_add_f32_e32 v12, 1.0, v28
	v_rcp_f32_e32 v28, v12
	global_store_short v[40:41], v8, off offset:128
	v_mul_f32_e32 v4, v4, v24
	v_or_b32_e32 v42, 1, v38
	s_waitcnt vmcnt(6)
	v_lshlrev_b32_e32 v20, 16, v52
	v_mul_f32_e32 v24, 0xbfb8aa3b, v20
	v_mad_i64_i32 v[48:49], s[36:37], v42, s46, v[36:37]
	v_exp_f32_e32 v24, v24
	v_lshl_add_u64 v[48:49], v[48:49], 0, s[20:21]
	v_lshl_add_u64 v[48:49], v[48:49], 0, v[34:35]
	v_add_co_u32_e32 v50, vcc, s48, v48
	v_mov_b32_e32 v8, v28
	s_nop 0
	v_addc_co_u32_e32 v51, vcc, 0, v49, vcc
	v_mul_f32_e32 v4, v4, v8
	v_add_f32_e32 v8, 1.0, v24
	global_load_ushort v24, v[50:51], off offset:3072
	v_rcp_f32_e32 v28, v8
	v_cvt_pk_bf16_f32 v4, v4, v33
	global_store_short v[40:41], v4, off offset:160
	v_mul_f32_e32 v0, v0, v20
	v_mov_b32_e32 v4, v28
	s_waitcnt vmcnt(7)
	v_lshlrev_b32_e32 v8, 16, v53
	v_mul_f32_e32 v0, v0, v4
	v_mul_f32_e32 v4, 0xbfb8aa3b, v8
	v_lshl_add_u64 v[48:49], v[48:49], 0, s[26:27]
	v_exp_f32_e32 v39, v4
	v_mul_f32_e32 v4, v25, v25
	v_mov_b32_e32 v12, v21
	global_load_ushort v28, v[48:49], off offset:32
	global_load_ushort v47, v[48:49], off offset:64
	v_fmac_f32_e32 v4, v29, v29
	v_mul_f32_e32 v20, v16, v56
	v_fma_f32 v4, v12, v12, v4
	v_fma_f32 v12, v13, v13, v4
	v_mov_b32_e32 v4, v9
	v_mov_b32_e32 v16, v1
	v_fma_f32 v4, v4, v4, v12
	v_fma_f32 v4, v5, v5, v4
	v_pk_mul_f32 v[50:51], v[16:17], v[16:17]
	v_add_f32_e32 v16, 1.0, v39
	v_add_f32_e32 v4, v4, v50
	v_add_f32_e32 v4, v4, v51
	ds_bpermute_b32 v12, v32, v4
	v_rcp_f32_e32 v43, v16
	v_cvt_pk_bf16_f32 v0, v0, v33
	s_waitcnt lgkmcnt(0)
	v_add_f32_e32 v4, v4, v12
	ds_bpermute_b32 v12, v44, v4
	global_store_short v[40:41], v0, off offset:192
	v_mul_f32_e32 v0, v20, v8
	s_waitcnt lgkmcnt(0)
; __device__ __forceinline__ float bf2f(unsigned short b) { return __uint_as_float(((unsigned)b) << 16); }
; __device__ __forceinline__ unsigned short f2bf(float f) { return (unsigned short)(cvt_pk_bf16(f, 0.f) & 0xffffu); }
; __device__ __forceinline__ float sigmoidf_(float x) { return 1.f / (1.f + __expf(-x)); }
; __device__ __forceinline__ void retout_item(PRef p, int layer, int item, unsigned char* shm) {
;     ...
; #pragma unroll
;     for (int r = 0; r < 4; ++r) { float ss = 0.f;
; #pragma unroll
;         for (int et = 0; et < 8; ++et) ss += acc[et][r] * acc[et][r];
;         ss += __shfl_xor(ss, 1); ss += __shfl_xor(ss, 2); ss += __shfl_xor(ss, 4); ss += __shfl_xor(ss, 8);
;         const float rinv = rsqrtf(ss * (1.f / 128.f) + 1e-6f);
;         const size_t row = (size_t)(row0 + 16 * wave + fq * 4 + r);
; #pragma unroll
;         for (int et = 0; et < 8; ++et) { const int e = 16 * et + fr; const float gg = bf2f(A[row * NIN + C_G + h * 128 + e]);
;             MIX[row * 2048 + 512 + h * 128 + e] = f2bf(acc[et][r] * rinv * gg * sigmoidf_(gg)); } }
	v_add_f32_e32 v4, v4, v12
	ds_bpermute_b32 v8, v45, v4
	s_waitcnt lgkmcnt(0)
	v_add_f32_e32 v4, v4, v8
	ds_bpermute_b32 v8, v46, v4
	v_mov_b32_e32 v12, v43
	s_waitcnt lgkmcnt(0)
	v_add_f32_e32 v4, v4, v8
	v_fmamk_f32 v4, v4, 0x3c000000, v62
	v_mul_f32_e32 v8, 0x4b800000, v4
	v_cmp_gt_f32_e32 vcc, s56, v4
	v_mul_f32_e32 v0, v0, v12
	v_cvt_pk_bf16_f32 v0, v0, v33
	global_store_short v[40:41], v0, off offset:224
	v_cndmask_b32_e32 v4, v4, v8, vcc
	global_load_ushort v8, v[48:49], off offset:96
	global_load_ushort v12, v[48:49], off offset:128
	global_load_ushort v16, v[48:49], off offset:160
	global_load_ushort v20, v[48:49], off offset:192
	global_load_ushort v39, v[48:49], off offset:224
	v_rsq_f32_e32 v4, v4
	v_ashrrev_i32_e32 v43, 31, v42
	v_mul_f32_e32 v0, 0x45800000, v4
	v_cndmask_b32_e32 v49, v4, v0, vcc
	v_mul_f32_e32 v29, v29, v49
	s_waitcnt vmcnt(10)
	v_lshlrev_b32_e32 v24, 16, v24
	v_mul_f32_e32 v40, 0xbfb8aa3b, v24
	v_exp_f32_e32 v48, v40
	v_lshlrev_b64 v[40:41], 12, v[42:43]
	v_mul_f32_e32 v24, v29, v24
	v_lshl_add_u64 v[40:41], s[34:35], 0, v[40:41]
	v_add_f32_e32 v0, 1.0, v48
	v_rcp_f32_e32 v0, v0
	v_mul_f32_e32 v1, v1, v49
	v_mul_f32_e32 v17, v17, v49
	v_mul_f32_e32 v0, v0, v24
	s_waitcnt vmcnt(8)
	v_lshlrev_b32_e32 v4, 16, v28
	v_mul_f32_e32 v28, 0xbfb8aa3b, v4
	v_exp_f32_e32 v42, v28
	v_lshl_add_u64 v[28:29], v[40:41], 0, v[34:35]
	v_cvt_pk_bf16_f32 v0, v0, v33
	global_store_short v[28:29], v0, off
	v_add_f32_e32 v24, 1.0, v42
	v_rcp_f32_e32 v41, v24
	v_mul_f32_e32 v0, v25, v49
	v_mul_f32_e32 v0, v0, v4
	s_waitcnt vmcnt(8)
	v_lshlrev_b32_e32 v25, 16, v47
	v_mul_f32_e32 v40, 0xbfb8aa3b, v25
	v_exp_f32_e32 v40, v40
	v_mov_b32_e32 v4, v41
	v_mul_f32_e32 v0, v0, v4
	v_cvt_pk_bf16_f32 v0, v0, v33
	v_add_f32_e32 v4, 1.0, v40
	v_rcp_f32_e32 v4, v4
	global_store_short v[28:29], v0, off offset:32
	v_mul_f32_e32 v0, v21, v49
	v_mul_f32_e32 v0, v0, v25
	v_mul_f32_e32 v0, v0, v4
	v_cvt_pk_bf16_f32 v0, v0, v33
	s_waitcnt vmcnt(6)
	v_lshlrev_b32_e32 v8, 16, v8
	v_mul_f32_e32 v24, 0xbfb8aa3b, v8
	v_exp_f32_e32 v24, v24
	global_store_short v[28:29], v0, off offset:64
	v_mul_f32_e32 v0, v13, v49
	v_mul_f32_e32 v0, v0, v8
	v_add_f32_e32 v4, 1.0, v24
	v_rcp_f32_e32 v4, v4
	s_waitcnt vmcnt(6)
	v_lshlrev_b32_e32 v12, 16, v12
	v_mul_f32_e32 v13, 0xbfb8aa3b, v12
	v_exp_f32_e32 v13, v13
	v_mul_f32_e32 v0, v0, v4
	v_cvt_pk_bf16_f32 v0, v0, v33
	v_add_f32_e32 v4, 1.0, v13
	v_rcp_f32_e32 v4, v4
	global_store_short v[28:29], v0, off offset:96
	v_mul_f32_e32 v0, v9, v49
	v_mul_f32_e32 v0, v0, v12
	s_waitcnt vmcnt(6)
	v_lshlrev_b32_e32 v9, 16, v16
	v_mul_f32_e32 v12, 0xbfb8aa3b, v9
	v_exp_f32_e32 v12, v12
	v_mul_f32_e32 v0, v0, v4
	v_cvt_pk_bf16_f32 v0, v0, v33
	v_add_f32_e32 v4, 1.0, v12
	v_rcp_f32_e32 v4, v4
	global_store_short v[28:29], v0, off offset:128
	v_mul_f32_e32 v0, v5, v49
	v_mul_f32_e32 v0, v0, v9
	s_waitcnt vmcnt(6)
	v_lshlrev_b32_e32 v12, 16, v20
	v_mul_f32_e32 v8, 0xbfb8aa3b, v12
	v_exp_f32_e32 v8, v8
	v_mul_f32_e32 v0, v0, v4
	v_cvt_pk_bf16_f32 v13, v0, v33
	v_or_b32_e32 v0, 2, v38
	v_mad_i64_i32 v[4:5], s[36:37], v0, s46, v[36:37]
	v_lshl_add_u64 v[4:5], v[4:5], 0, s[20:21]
	v_add_f32_e32 v16, 1.0, v8
	v_lshl_add_u64 v[4:5], v[4:5], 0, v[34:35]
	v_add_co_u32_e32 v8, vcc, s48, v4
	v_rcp_f32_e32 v21, v16
	s_nop 0
	v_addc_co_u32_e32 v9, vcc, 0, v5, vcc
	global_load_ushort v24, v[8:9], off offset:3072
	v_mul_f32_e32 v1, v1, v12
	v_mov_b32_e32 v8, v21
	v_mul_f32_e32 v1, v1, v8
	v_cvt_pk_bf16_f32 v1, v1, v33
	global_store_short v[28:29], v1, off offset:192
	s_waitcnt vmcnt(7)
	v_lshlrev_b32_e32 v1, 16, v39
	v_mul_f32_e32 v8, 0xbfb8aa3b, v1
	global_store_short v[28:29], v13, off offset:160
	v_exp_f32_e32 v12, v8
	v_mul_f32_e32 v13, v26, v26
	v_mov_b32_e32 v8, v22
	v_mov_b32_e32 v9, v14
	v_fmac_f32_e32 v13, v30, v30
	v_pk_mul_f32 v[8:9], v[8:9], v[8:9]
	v_lshl_add_u64 v[4:5], v[4:5], 0, s[26:27]
	v_add_f32_e32 v8, v13, v8
	global_load_ushort v16, v[4:5], off offset:32
	global_load_ushort v21, v[4:5], off offset:64
	v_add_f32_e32 v13, v8, v9
	v_mov_b32_e32 v8, v10
	v_mov_b32_e32 v9, v6
	v_pk_mul_f32 v[8:9], v[8:9], v[8:9]
	v_add_f32_e32 v12, 1.0, v12
	v_add_f32_e32 v8, v13, v8
	v_add_f32_e32 v13, v8, v9
	v_mov_b32_e32 v8, v2
	v_mov_b32_e32 v9, v18
	v_pk_mul_f32 v[8:9], v[8:9], v[8:9]
	v_mul_f32_e32 v1, v17, v1
	v_add_f32_e32 v8, v13, v8
	v_add_f32_e32 v8, v8, v9
	ds_bpermute_b32 v9, v32, v8
	v_rcp_f32_e32 v12, v12
	s_waitcnt lgkmcnt(0)
	v_add_f32_e32 v8, v8, v9
	ds_bpermute_b32 v9, v44, v8
	s_waitcnt lgkmcnt(0)
	v_add_f32_e32 v8, v8, v9
	ds_bpermute_b32 v9, v45, v8
	s_waitcnt lgkmcnt(0)
	v_add_f32_e32 v8, v8, v9
	ds_bpermute_b32 v9, v46, v8
	v_mul_f32_e32 v1, v1, v12
	v_cvt_pk_bf16_f32 v1, v1, v33
	s_waitcnt lgkmcnt(0)
	v_add_f32_e32 v8, v8, v9
	v_fmamk_f32 v8, v8, 0x3c000000, v62
	v_mul_f32_e32 v9, 0x4b800000, v8
	v_cmp_gt_f32_e32 vcc, s56, v8
	global_store_short v[28:29], v1, off offset:224
	s_nop 0
	v_cndmask_b32_e32 v8, v8, v9, vcc
	global_load_ushort v9, v[4:5], off offset:96
	global_load_ushort v12, v[4:5], off offset:128
	global_load_ushort v13, v[4:5], off offset:160
	global_load_ushort v17, v[4:5], off offset:192
	s_nop 0
	global_load_ushort v5, v[4:5], off offset:224
	v_rsq_f32_e32 v8, v8
	s_waitcnt vmcnt(10)
	v_lshlrev_b32_e32 v4, 16, v24
	v_mul_f32_e32 v20, 0xbfb8aa3b, v4
	v_exp_f32_e32 v20, v20
	v_mul_f32_e32 v1, 0x45800000, v8
	v_cndmask_b32_e32 v24, v8, v1, vcc
	v_mul_f32_e32 v28, v30, v24
	v_add_f32_e32 v8, 1.0, v20
	v_rcp_f32_e32 v8, v8
	v_mul_f32_e32 v4, v28, v4
	v_ashrrev_i32_e32 v1, 31, v0
	v_lshlrev_b64 v[0:1], 12, v[0:1]
	v_mul_f32_e32 v4, v8, v4
	v_lshl_add_u64 v[0:1], s[34:35], 0, v[0:1]
	v_cvt_pk_bf16_f32 v4, v4, v33
	s_waitcnt vmcnt(7)
; __device__ __forceinline__ float bf2f(unsigned short b) { return __uint_as_float(((unsigned)b) << 16); }
; __device__ __forceinline__ unsigned short f2bf(float f) { return (unsigned short)(cvt_pk_bf16(f, 0.f) & 0xffffu); }
; __device__ __forceinline__ float sigmoidf_(float x) { return 1.f / (1.f + __expf(-x)); }
; __device__ __forceinline__ void retout_item(PRef p, int layer, int item, unsigned char* shm) {
;     ...
; #pragma unroll
;     for (int r = 0; r < 4; ++r) { float ss = 0.f;
; #pragma unroll
;         for (int et = 0; et < 8; ++et) ss += acc[et][r] * acc[et][r];
;         ss += __shfl_xor(ss, 1); ss += __shfl_xor(ss, 2); ss += __shfl_xor(ss, 4); ss += __shfl_xor(ss, 8);
;         const float rinv = rsqrtf(ss * (1.f / 128.f) + 1e-6f);
;         const size_t row = (size_t)(row0 + 16 * wave + fq * 4 + r);
; #pragma unroll
;         for (int et = 0; et < 8; ++et) { const int e = 16 * et + fr; const float gg = bf2f(A[row * NIN + C_G + h * 128 + e]);
;             MIX[row * 2048 + 512 + h * 128 + e] = f2bf(acc[et][r] * rinv * gg * sigmoidf_(gg)); } }
	v_lshlrev_b32_e32 v16, 16, v16
	v_mul_f32_e32 v20, 0xbfb8aa3b, v16
	v_exp_f32_e32 v20, v20
	v_lshl_add_u64 v[0:1], v[0:1], 0, v[34:35]
	global_store_short v[0:1], v4, off
	v_mul_f32_e32 v4, v26, v24
	v_add_f32_e32 v8, 1.0, v20
	v_rcp_f32_e32 v8, v8
	v_mul_f32_e32 v4, v4, v16
	v_mul_f32_e32 v2, v2, v24
	s_waitcnt vmcnt(7)
	v_lshlrev_b32_e32 v20, 16, v21
	v_mul_f32_e32 v21, 0xbfb8aa3b, v20
	v_exp_f32_e32 v21, v21
	v_mul_f32_e32 v4, v4, v8
	v_add_f32_e32 v8, 1.0, v21
	v_rcp_f32_e32 v8, v8
	v_cvt_pk_bf16_f32 v4, v4, v33
	global_store_short v[0:1], v4, off offset:32
	v_mul_f32_e32 v4, v22, v24
	v_mul_f32_e32 v4, v4, v20
	s_waitcnt vmcnt(6)
	v_lshlrev_b32_e32 v9, 16, v9
	v_mul_f32_e32 v20, 0xbfb8aa3b, v9
	v_exp_f32_e32 v20, v20
	v_mul_f32_e32 v4, v4, v8
	v_cvt_pk_bf16_f32 v4, v4, v33
	global_store_short v[0:1], v4, off offset:64
	v_add_f32_e32 v8, 1.0, v20
	v_rcp_f32_e32 v8, v8
	v_mul_f32_e32 v4, v14, v24
	v_mul_f32_e32 v4, v4, v9
	s_waitcnt vmcnt(6)
	v_lshlrev_b32_e32 v12, 16, v12
	v_mul_f32_e32 v14, 0xbfb8aa3b, v12
	v_exp_f32_e32 v14, v14
	v_mul_f32_e32 v4, v4, v8
	v_cvt_pk_bf16_f32 v4, v4, v33
	v_add_f32_e32 v8, 1.0, v14
	v_rcp_f32_e32 v8, v8
	global_store_short v[0:1], v4, off offset:96
	v_mul_f32_e32 v4, v10, v24
	v_mul_f32_e32 v4, v4, v12
	s_waitcnt vmcnt(6)
	v_lshlrev_b32_e32 v10, 16, v13
	v_mul_f32_e32 v12, 0xbfb8aa3b, v10
	v_exp_f32_e32 v12, v12
	v_mul_f32_e32 v4, v4, v8
	v_cvt_pk_bf16_f32 v4, v4, v33
	v_add_f32_e32 v8, 1.0, v12
	v_rcp_f32_e32 v12, v8
	global_store_short v[0:1], v4, off offset:128
	v_mul_f32_e32 v4, v6, v24
	v_mul_f32_e32 v4, v4, v10
	s_waitcnt vmcnt(6)
	v_lshlrev_b32_e32 v10, 16, v17
	v_mul_f32_e32 v9, 0xbfb8aa3b, v10
	v_exp_f32_e32 v9, v9
	v_mov_b32_e32 v6, v12
	v_mul_f32_e32 v4, v4, v6
	v_cvt_pk_bf16_f32 v6, v4, v33
	v_or_b32_e32 v4, 3, v38
	v_add_f32_e32 v14, 1.0, v9
	v_mad_i64_i32 v[8:9], s[36:37], v4, s46, v[36:37]
	v_lshl_add_u64 v[8:9], v[8:9], 0, s[20:21]
	v_lshl_add_u64 v[8:9], v[8:9], 0, v[34:35]
	v_add_co_u32_e32 v12, vcc, s48, v8
	global_store_short v[0:1], v6, off offset:160
	s_nop 0
	v_addc_co_u32_e32 v13, vcc, 0, v9, vcc
	global_load_ushort v16, v[12:13], off offset:3072
	v_rcp_f32_e32 v6, v14
	v_mul_f32_e32 v2, v2, v10
	s_waitcnt vmcnt(7)
	v_lshlrev_b32_e32 v5, 16, v5
	v_lshl_add_u64 v[8:9], v[8:9], 0, s[26:27]
	v_mul_f32_e32 v2, v2, v6
	v_mul_f32_e32 v6, 0xbfb8aa3b, v5
	v_exp_f32_e32 v20, v6
	v_mul_f32_e32 v6, v27, v27
	v_mov_b32_e32 v14, v23
	v_fmac_f32_e32 v6, v31, v31
	global_load_ushort v17, v[8:9], off offset:32
	v_fma_f32 v6, v14, v14, v6
	v_fma_f32 v14, v15, v15, v6
	v_mov_b32_e32 v6, v11
	v_mul_f32_e32 v10, v18, v24
	v_fma_f32 v6, v6, v6, v14
	v_mov_b32_e32 v18, v3
	v_fma_f32 v6, v7, v7, v6
	v_cvt_pk_bf16_f32 v2, v2, v33
	global_store_short v[0:1], v2, off offset:192
	v_fma_f32 v6, v18, v18, v6
	v_fma_f32 v6, v19, v19, v6
	ds_bpermute_b32 v12, v32, v6
	v_add_f32_e32 v13, 1.0, v20
	v_rcp_f32_e32 v18, v13
	s_waitcnt lgkmcnt(0)
	v_add_f32_e32 v6, v6, v12
	ds_bpermute_b32 v12, v44, v6
	global_load_ushort v20, v[8:9], off offset:64
	v_mul_f32_e32 v2, v10, v5
	s_waitcnt lgkmcnt(0)
	v_add_f32_e32 v5, v6, v12
	ds_bpermute_b32 v6, v45, v5
	s_waitcnt lgkmcnt(0)
	v_add_f32_e32 v5, v5, v6
	ds_bpermute_b32 v6, v46, v5
	v_mov_b32_e32 v10, v18
	s_waitcnt lgkmcnt(0)
	v_add_f32_e32 v5, v5, v6
	v_fmamk_f32 v5, v5, 0x3c000000, v62
	v_mul_f32_e32 v6, 0x4b800000, v5
	v_cmp_gt_f32_e32 vcc, s56, v5
	v_mul_f32_e32 v2, v2, v10
	v_cvt_pk_bf16_f32 v2, v2, v33
	global_store_short v[0:1], v2, off offset:224
	v_cndmask_b32_e32 v5, v5, v6, vcc
	global_load_ushort v6, v[8:9], off offset:96
	global_load_ushort v2, v[8:9], off offset:128
	global_load_ushort v10, v[8:9], off offset:160
	global_load_ushort v12, v[8:9], off offset:192
	s_nop 0
	global_load_ushort v8, v[8:9], off offset:224
	v_rsq_f32_e32 v5, v5
	s_waitcnt vmcnt(9)
	v_lshlrev_b32_e32 v9, 16, v16
	v_mul_f32_e32 v1, 0xbfb8aa3b, v9
	v_exp_f32_e32 v13, v1
	v_mul_f32_e32 v0, 0x45800000, v5
	v_cndmask_b32_e32 v14, v5, v0, vcc
	v_ashrrev_i32_e32 v5, 31, v4
	v_lshlrev_b64 v[0:1], 12, v[4:5]
	v_add_f32_e32 v4, 1.0, v13
	v_rcp_f32_e32 v4, v4
	v_mul_f32_e32 v16, v31, v14
	v_mul_f32_e32 v9, v16, v9
	v_lshl_add_u64 v[0:1], s[34:35], 0, v[0:1]
	s_waitcnt vmcnt(8)
	v_lshlrev_b32_e32 v5, 16, v17
	v_mul_f32_e32 v13, 0xbfb8aa3b, v5
	v_exp_f32_e32 v13, v13
	v_mul_f32_e32 v4, v4, v9
	v_cvt_pk_bf16_f32 v4, v4, v33
	v_lshl_add_u64 v[0:1], v[0:1], 0, v[34:35]
	v_add_f32_e32 v9, 1.0, v13
	global_store_short v[0:1], v4, off
	v_mul_f32_e32 v4, v27, v14
	v_mul_f32_e32 v4, v4, v5
	s_waitcnt vmcnt(7)
	v_lshlrev_b32_e32 v13, 16, v20
	v_mul_f32_e32 v16, 0xbfb8aa3b, v13
	v_exp_f32_e32 v16, v16
	v_rcp_f32_e32 v5, v9
	s_nop 0
	v_mul_f32_e32 v4, v4, v5
	v_cvt_pk_bf16_f32 v4, v4, v33
	v_add_f32_e32 v5, 1.0, v16
	v_rcp_f32_e32 v5, v5
	global_store_short v[0:1], v4, off offset:32
	v_mul_f32_e32 v4, v23, v14
	v_mul_f32_e32 v4, v4, v13
	s_waitcnt vmcnt(6)
	v_lshlrev_b32_e32 v6, 16, v6
	v_mul_f32_e32 v13, 0xbfb8aa3b, v6
	v_exp_f32_e32 v13, v13
	v_mul_f32_e32 v4, v4, v5
	v_cvt_pk_bf16_f32 v4, v4, v33
	global_store_short v[0:1], v4, off offset:64
	v_add_f32_e32 v5, 1.0, v13
	v_rcp_f32_e32 v5, v5
	v_mul_f32_e32 v4, v15, v14
	v_mul_f32_e32 v4, v4, v6
	s_waitcnt vmcnt(6)
	v_lshlrev_b32_e32 v2, 16, v2
	v_mul_f32_e32 v9, 0xbfb8aa3b, v2
	v_exp_f32_e32 v9, v9
	v_mul_f32_e32 v4, v4, v5
	v_add_f32_e32 v5, 1.0, v9
	v_cvt_pk_bf16_f32 v4, v4, v33
	global_store_short v[0:1], v4, off offset:96
	v_mul_f32_e32 v4, v11, v14
	v_mul_f32_e32 v2, v4, v2
	s_waitcnt vmcnt(6)
	v_lshlrev_b32_e32 v6, 16, v10
	v_mul_f32_e32 v9, 0xbfb8aa3b, v6
	v_exp_f32_e32 v9, v9
	v_rcp_f32_e32 v4, v5
	s_nop 0
	v_mul_f32_e32 v2, v2, v4
	v_cvt_pk_bf16_f32 v2, v2, v33
	v_add_f32_e32 v4, 1.0, v9
	v_rcp_f32_e32 v4, v4
	global_store_short v[0:1], v2, off offset:128
	v_mul_f32_e32 v2, v7, v14
	v_mul_f32_e32 v2, v2, v6
	s_waitcnt vmcnt(6)
	v_lshlrev_b32_e32 v6, 16, v12
	v_mul_f32_e32 v7, 0xbfb8aa3b, v6
	v_exp_f32_e32 v7, v7
	v_mul_f32_e32 v2, v2, v4
	v_cvt_pk_bf16_f32 v2, v2, v33
	v_add_f32_e32 v4, 1.0, v7
	v_rcp_f32_e32 v7, v4
	global_store_short v[0:1], v2, off offset:160
	v_mul_f32_e32 v2, v3, v14
	v_mul_f32_e32 v2, v2, v6
	s_waitcnt vmcnt(6)
	v_lshlrev_b32_e32 v5, 16, v8
	v_mul_f32_e32 v6, 0xbfb8aa3b, v5
	v_exp_f32_e32 v6, v6
	v_mov_b32_e32 v3, v7
	v_mul_f32_e32 v2, v2, v3
	v_cvt_pk_bf16_f32 v2, v2, v33
	v_add_f32_e32 v3, 1.0, v6
	v_rcp_f32_e32 v3, v3
	global_store_short v[0:1], v2, off offset:192
	v_mul_f32_e32 v2, v19, v14
	v_mul_f32_e32 v2, v2, v5
	v_mul_f32_e32 v2, v2, v3
	s_mov_b64 s[34:35], 0
	v_cvt_pk_bf16_f32 v2, v2, v33
	global_store_short v[0:1], v2, off offset:224
	s_barrier

; __device__ __forceinline__ unsigned cvt_pk_bf16(float lo, float hi) { unsigned r; asm("v_cvt_pk_bf16_f32 %0, %1, %2" : "=v"(r) : "v"(lo), "v"(hi)); return r; }
; __device__ __forceinline__ void s5out_item(PRef p, int layer, int item, unsigned char* shm) {
;     ...
; #pragma unroll 4
;         for (int kk = 0; kk < 32; ++kk) {
;             const bf16x8 bfr = *(const bf16x8*)(ul + fr * S5_UP + kk * 64 + fq * 16);
;             const int sq = 2 * kk + (fq >> 1);
; #pragma unroll
;             for (int mi = 0; mi < 4; ++mi) { const bf16x8 af = *(const bf16x8*)(KT + (tb + mi - sq + 63) * 256 + fr * 16 + (fq & 1) * 8);
;                 acc[mi] = __builtin_amdgcn_mfma_f32_16x16x32_bf16(af, bfr, acc[mi], 0, 0, 0); } }
;         const int cidx = nt < 4 ? 4 + 16 * nt + fr : (fr & 3);
; #pragma unroll
;         for (int dir = 0; dir < 2; ++dir) {
;             const bf16_t* G = (const bf16_t*)(p.ws + O_S5G) + (size_t)(dir * 32 + g) * 1024 * 128;
;             const float* ST = (const float*)(p.ws + O_S5ST) + (size_t)((g * 2 + dir) * 4 + b) * 68 * 128 + (size_t)cidx * 128;
; #pragma unroll
;             for (int kk = 0; kk < 4; ++kk) {
;                 const f32x4 x0 = *(const f32x4*)(ST + kk * 32 + fq * 8), x1 = *(const f32x4*)(ST + kk * 32 + fq * 8 + 4);
;                 u32x4 w; w.x = cvt_pk_bf16(x0[0], x0[1]); w.y = cvt_pk_bf16(x0[2], x0[3]); w.z = cvt_pk_bf16(x1[0], x1[1]); w.w = cvt_pk_bf16(x1[2], x1[3]);
;                 const bf16x8 bfr = mk8(w);
; #pragma unroll
;                 for (int mi = 0; mi < 4; ++mi) { const bf16x8 af = *(const bf16x8*)(G + (size_t)((tb + mi) * 16 + fr) * 128 + kk * 32 + fq * 8);
;                     acc[mi] = __builtin_amdgcn_mfma_f32_16x16x32_bf16(af, bfr, acc[mi], 0, 0, 0); } } }
.LBB0_929:
	v_add_u32_e32 v21, s62, v87
	ds_read_b128 v[22:25], v20
	ds_read_b128 v[26:29], v20 offset:64
	ds_read_b128 v[54:57], v21 offset:32256
	ds_read_b128 v[58:61], v21 offset:32768
	ds_read_b128 v[96:99], v21 offset:31744
	ds_read_b128 v[100:103], v21 offset:33280
	s_waitcnt lgkmcnt(3)
	v_mfma_f32_16x16x32_bf16 v[16:19], v[54:57], v[22:25], v[16:19]
	s_addk_i32 s62, 0xf000
	s_cmpk_lg_i32 s62, 0x8000
	s_waitcnt lgkmcnt(2)
	v_mfma_f32_16x16x32_bf16 v[12:15], v[58:61], v[22:25], v[12:15]
	s_waitcnt lgkmcnt(0)
	v_mfma_f32_16x16x32_bf16 v[8:11], v[100:103], v[22:25], v[8:11]
	ds_read_b128 v[100:103], v21 offset:33792
	ds_read_b128 v[104:107], v21 offset:29184
	s_waitcnt lgkmcnt(1)
	v_mfma_f32_16x16x32_bf16 v[4:7], v[100:103], v[22:25], v[4:7]
	ds_read_b128 v[22:25], v21 offset:31232
	ds_read_b128 v[100:103], v21 offset:30720
	s_waitcnt lgkmcnt(1)
	v_mfma_f32_16x16x32_bf16 v[16:19], v[22:25], v[26:29], v[16:19]
	v_mfma_f32_16x16x32_bf16 v[12:15], v[96:99], v[26:29], v[12:15]
	v_mfma_f32_16x16x32_bf16 v[8:11], v[54:57], v[26:29], v[8:11]
	ds_read_b128 v[54:57], v20 offset:128
	ds_read_b128 v[108:111], v20 offset:192
	v_add_u32_e32 v20, 0x100, v20
	v_mfma_f32_16x16x32_bf16 v[4:7], v[58:61], v[26:29], v[4:7]
	ds_read_b128 v[26:29], v21 offset:30208
	ds_read_b128 v[58:61], v21 offset:29696
	s_waitcnt lgkmcnt(1)
	v_mfma_f32_16x16x32_bf16 v[16:19], v[26:29], v[54:57], v[16:19]
	v_mfma_f32_16x16x32_bf16 v[12:15], v[100:103], v[54:57], v[12:15]
	v_mfma_f32_16x16x32_bf16 v[8:11], v[22:25], v[54:57], v[8:11]
	v_mfma_f32_16x16x32_bf16 v[4:7], v[96:99], v[54:57], v[4:7]
	v_mfma_f32_16x16x32_bf16 v[16:19], v[104:107], v[108:111], v[16:19]
	s_waitcnt lgkmcnt(0)
	v_mfma_f32_16x16x32_bf16 v[12:15], v[58:61], v[108:111], v[12:15]
	v_mfma_f32_16x16x32_bf16 v[8:11], v[26:29], v[108:111], v[8:11]
	v_mfma_f32_16x16x32_bf16 v[4:7], v[100:103], v[108:111], v[4:7]
	s_cbranch_scc1 .LBB0_929
	v_lshl_add_u32 v20, s20, 4, v81
	v_mov_b32_e32 v21, v33
	v_lshlrev_b64 v[20:21], 9, v[20:21]
	v_lshl_add_u64 v[124:125], v[34:35], 0, v[20:21]
	v_lshl_add_u64 v[126:127], v[124:125], 0, s[36:37]
	global_load_dwordx4 v[20:23], v[38:39], off
	global_load_dwordx4 v[24:27], v[126:127], off
	global_load_dwordx4 v[28:31], v[126:127], off offset:16
	global_load_dwordx4 v[54:57], v[40:41], off
	global_load_dwordx4 v[58:61], v[42:43], off
	global_load_dwordx4 v[96:99], v[44:45], off
	global_load_dwordx4 v[100:103], v[126:127], off offset:128
	global_load_dwordx4 v[104:107], v[38:39], off offset:64
	global_load_dwordx4 v[108:111], v[126:127], off offset:144
	global_load_dwordx4 v[112:115], v[40:41], off offset:64
	v_lshl_add_u64 v[124:125], v[124:125], 0, s[38:39]
	s_add_i32 s20, s20, 1
	s_cmp_lg_u32 s20, 4
	s_waitcnt vmcnt(8)
	v_cvt_pk_bf16_f32 v24, v24, v25
	v_cvt_pk_bf16_f32 v25, v26, v27
	s_waitcnt vmcnt(7)
	v_cvt_pk_bf16_f32 v26, v28, v29
	v_cvt_pk_bf16_f32 v27, v30, v31
	s_waitcnt vmcnt(3)
	v_cvt_pk_bf16_f32 v100, v100, v101
	v_mfma_f32_16x16x32_bf16 v[16:19], v[20:23], v[24:27], v[16:19]
	global_load_dwordx4 v[20:23], v[42:43], off offset:64
	v_cvt_pk_bf16_f32 v101, v102, v103
	s_waitcnt vmcnt(2)
	v_cvt_pk_bf16_f32 v102, v108, v109
	v_mfma_f32_16x16x32_bf16 v[12:15], v[54:57], v[24:27], v[12:15]
	global_load_dwordx4 v[28:31], v[44:45], off offset:64
	global_load_dwordx4 v[54:57], v[126:127], off offset:256
	global_load_dwordx4 v[116:119], v[38:39], off offset:128
	v_cvt_pk_bf16_f32 v103, v110, v111
	s_waitcnt vmcnt(1)
	v_cvt_pk_bf16_f32 v54, v54, v55
	v_mfma_f32_16x16x32_bf16 v[8:11], v[58:61], v[24:27], v[8:11]
	global_load_dwordx4 v[58:61], v[126:127], off offset:272
	global_load_dwordx4 v[120:123], v[40:41], off offset:128
	v_cvt_pk_bf16_f32 v55, v56, v57
	s_waitcnt vmcnt(1)
	v_cvt_pk_bf16_f32 v56, v58, v59
	v_mfma_f32_16x16x32_bf16 v[4:7], v[96:99], v[24:27], v[4:7]
	global_load_dwordx4 v[24:27], v[42:43], off offset:128
	v_cvt_pk_bf16_f32 v57, v60, v61
	v_mfma_f32_16x16x32_bf16 v[16:19], v[104:107], v[100:103], v[16:19]
	global_load_dwordx4 v[96:99], v[44:45], off offset:128
	global_load_dwordx4 v[104:107], v[126:127], off offset:384
	global_load_dwordx4 v[108:111], v[38:39], off offset:192
	s_waitcnt vmcnt(1)
	v_cvt_pk_bf16_f32 v104, v104, v105
	v_mfma_f32_16x16x32_bf16 v[12:15], v[112:115], v[100:103], v[12:15]
	v_cvt_pk_bf16_f32 v105, v106, v107
	v_mfma_f32_16x16x32_bf16 v[8:11], v[20:23], v[100:103], v[8:11]
	global_load_dwordx4 v[20:23], v[126:127], off offset:400
	global_load_dwordx4 v[112:115], v[40:41], off offset:192
	s_waitcnt vmcnt(1)
	v_cvt_pk_bf16_f32 v106, v20, v21
	v_mfma_f32_16x16x32_bf16 v[4:7], v[28:31], v[100:103], v[4:7]
	global_load_dwordx4 v[28:31], v[42:43], off offset:192
	global_load_dwordx4 v[58:61], v[44:45], off offset:192
	v_cvt_pk_bf16_f32 v107, v22, v23
	v_mfma_f32_16x16x32_bf16 v[16:19], v[116:119], v[54:57], v[16:19]
	global_load_dwordx4 v[100:103], v[124:125], off
	global_load_dwordx4 v[116:119], v[46:47], off
	s_waitcnt vmcnt(1)
	v_cvt_pk_bf16_f32 v100, v100, v101
	v_mfma_f32_16x16x32_bf16 v[12:15], v[120:123], v[54:57], v[12:15]
	v_cvt_pk_bf16_f32 v101, v102, v103
	v_mfma_f32_16x16x32_bf16 v[8:11], v[24:27], v[54:57], v[8:11]
	global_load_dwordx4 v[24:27], v[124:125], off offset:16
	global_load_dwordx4 v[120:123], v[48:49], off
	global_load_dwordx4 v[20:23], v[50:51], off
	s_waitcnt vmcnt(2)
	v_cvt_pk_bf16_f32 v102, v24, v25
	v_mfma_f32_16x16x32_bf16 v[4:7], v[96:99], v[54:57], v[4:7]
	v_cvt_pk_bf16_f32 v103, v26, v27
	v_mfma_f32_16x16x32_bf16 v[16:19], v[108:111], v[104:107], v[16:19]
	global_load_dwordx4 v[54:57], v[52:53], off
	global_load_dwordx4 v[96:99], v[124:125], off offset:128
	global_load_dwordx4 v[108:111], v[46:47], off offset:64
	global_load_dwordx4 v[24:27], v[48:49], off offset:64
	s_waitcnt vmcnt(2)
; __device__ __forceinline__ unsigned cvt_pk_bf16(float lo, float hi) { unsigned r; asm("v_cvt_pk_bf16_f32 %0, %1, %2" : "=v"(r) : "v"(lo), "v"(hi)); return r; }
; __device__ __forceinline__ float bflo(unsigned w) { return __uint_as_float(w << 16); }
; __device__ __forceinline__ float bfhi(unsigned w) { return __uint_as_float(w & 0xffff0000u); }
; __device__ __forceinline__ float gelu_tanh(float x) { const float u = 0.7978845608028654f * (x + 0.044715f * x * x * x); return x / (1.f + __expf(-2.f * u)); }
; __device__ __forceinline__ void s5out_item(PRef p, int layer, int item, unsigned char* shm) {
;     ...
;         if (nt < 4 || fr < 4) {
; #pragma unroll
;             for (int mi = 0; mi < 4; ++mi) { const int t = tb + mi; const size_t row = nt < 4 ? (size_t)(b * 4096 + (16 * nt + fr) * 64 + t) : (size_t)(RL + b * 256 + fr * 64 + t);
;                 const u32x2 uu = *(const u32x2*)(ul + fr * S5_UP + t * 32 + fq * 8);
;                 const f32x4 y = acc[mi];
;                 u32x2 w; w.x = cvt_pk_bf16(gelu_tanh(y[0] + dv[0] * bflo(uu.x)), gelu_tanh(y[1] + dv[1] * bfhi(uu.x)));
;                 w.y = cvt_pk_bf16(gelu_tanh(y[2] + dv[2] * bflo(uu.y)), gelu_tanh(y[3] + dv[3] * bfhi(uu.y)));
;                 *(u32x2*)(Z + row * 512 + g * 16 + fq * 4) = w; } }
	v_cvt_pk_bf16_f32 v96, v96, v97
	v_mfma_f32_16x16x32_bf16 v[8:11], v[28:31], v[104:107], v[8:11]
	global_load_dwordx4 v[28:31], v[124:125], off offset:144
	v_cvt_pk_bf16_f32 v97, v98, v99
	s_waitcnt vmcnt(0)
	v_cvt_pk_bf16_f32 v98, v28, v29
	v_mfma_f32_16x16x32_bf16 v[12:15], v[112:115], v[104:107], v[12:15]
	v_cvt_pk_bf16_f32 v99, v30, v31
	v_mfma_f32_16x16x32_bf16 v[4:7], v[58:61], v[104:107], v[4:7]
	global_load_dwordx4 v[58:61], v[50:51], off offset:64
	global_load_dwordx4 v[104:107], v[52:53], off offset:64
	global_load_dwordx4 v[112:115], v[46:47], off offset:128
	v_mfma_f32_16x16x32_bf16 v[16:19], v[116:119], v[100:103], v[16:19]
	v_mfma_f32_16x16x32_bf16 v[8:11], v[20:23], v[100:103], v[8:11]
	global_load_dwordx4 v[20:23], v[124:125], off offset:272
	global_load_dwordx4 v[116:119], v[124:125], off offset:256
	global_load_dwordx4 v[28:31], v[48:49], off offset:128
	s_waitcnt vmcnt(1)
	v_cvt_pk_bf16_f32 v116, v116, v117
	v_mfma_f32_16x16x32_bf16 v[12:15], v[120:123], v[100:103], v[12:15]
	v_cvt_pk_bf16_f32 v117, v118, v119
	v_cvt_pk_bf16_f32 v118, v20, v21
	v_cvt_pk_bf16_f32 v119, v22, v23
	v_mfma_f32_16x16x32_bf16 v[4:7], v[54:57], v[100:103], v[4:7]
	v_mfma_f32_16x16x32_bf16 v[16:19], v[108:111], v[96:99], v[16:19]
	global_load_dwordx4 v[54:57], v[50:51], off offset:128
	global_load_dwordx4 v[100:103], v[52:53], off offset:128
	global_load_dwordx4 v[108:111], v[46:47], off offset:192
	v_mfma_f32_16x16x32_bf16 v[8:11], v[58:61], v[96:99], v[8:11]
	global_load_dwordx4 v[58:61], v[124:125], off offset:400
	global_load_dwordx4 v[120:123], v[124:125], off offset:384
	v_mfma_f32_16x16x32_bf16 v[12:15], v[24:27], v[96:99], v[12:15]
	global_load_dwordx4 v[24:27], v[50:51], off offset:192
	v_mfma_f32_16x16x32_bf16 v[4:7], v[104:107], v[96:99], v[4:7]
	global_load_dwordx4 v[104:107], v[48:49], off offset:192
	v_mfma_f32_16x16x32_bf16 v[96:99], v[112:115], v[116:119], v[16:19]
	s_waitcnt vmcnt(2)
	v_cvt_pk_bf16_f32 v16, v120, v121
	v_mfma_f32_16x16x32_bf16 v[112:115], v[28:31], v[116:119], v[12:15]
	v_cvt_pk_bf16_f32 v17, v122, v123
	v_cvt_pk_bf16_f32 v18, v58, v59
	v_cvt_pk_bf16_f32 v19, v60, v61
	v_mfma_f32_16x16x32_bf16 v[28:31], v[54:57], v[116:119], v[8:11]
	ds_read_b64 v[54:55], v92 offset:65024
	s_nop 0
	global_load_dwordx4 v[12:15], v[52:53], off offset:192
	ds_read_b64 v[56:57], v93 offset:65024
	ds_read_b64 v[60:61], v94 offset:65024
	ds_read_b64 v[58:59], v95 offset:65024
	v_mfma_f32_16x16x32_bf16 v[8:11], v[108:111], v[16:19], v[96:99]
	s_waitcnt lgkmcnt(3)
	s_nop 1
	v_lshlrev_b32_e32 v96, 16, v54
	s_waitcnt vmcnt(2)
	v_mfma_f32_16x16x32_bf16 v[24:27], v[24:27], v[16:19], v[28:31]
	s_nop 1
	v_fma_f32 v8, v0, v96, v8
	v_mul_f32_e32 v28, 0x3d372713, v8
	v_mul_f32_e32 v28, v8, v28
	v_fma_f32 v28, v8, v28, v8
	v_mul_f32_e32 v28, 0x3f4c422a, v28
	v_mul_f32_e32 v28, -2.0, v28
	v_mul_f32_e32 v28, 0x3fb8aa3b, v28
	v_mfma_f32_16x16x32_bf16 v[20:23], v[100:103], v[116:119], v[4:7]
	v_exp_f32_e32 v28, v28
	s_waitcnt vmcnt(1)
	v_mfma_f32_16x16x32_bf16 v[4:7], v[104:107], v[16:19], v[112:115]
	s_waitcnt vmcnt(0)
	v_mfma_f32_16x16x32_bf16 v[12:15], v[12:15], v[16:19], v[20:23]
	v_add_f32_e32 v18, 1.0, v28
	v_and_b32_e32 v28, 0xffff0000, v54
	v_fma_f32 v9, v1, v28, v9
	v_mul_f32_e32 v28, 0x3d372713, v9
	v_rcp_f32_e32 v20, v18
	v_mul_f32_e32 v28, v9, v28
	v_fma_f32 v28, v9, v28, v9
	v_mul_f32_e32 v28, 0x3f4c422a, v28
	v_mul_f32_e32 v28, -2.0, v28
	v_mul_f32_e32 v28, 0x3fb8aa3b, v28
	v_exp_f32_e32 v28, v28
	s_nop 0
	v_add_f32_e32 v22, 1.0, v28
	v_rcp_f32_e32 v29, v22
	v_mul_f32_e32 v19, v8, v20
	v_lshlrev_b32_e32 v20, 16, v55
	v_fma_f32 v10, v2, v20, v10
	v_mul_f32_e32 v20, 0x3d372713, v10
	v_mov_b32_e32 v8, v19
	v_mul_f32_e32 v20, v10, v20
	v_fma_f32 v20, v10, v20, v10
	v_mul_f32_e32 v20, 0x3f4c422a, v20
	v_mul_f32_e32 v20, -2.0, v20
	v_mul_f32_e32 v20, 0x3fb8aa3b, v20
	v_exp_f32_e32 v20, v20
	v_and_b32_e32 v19, 0xffff0000, v55
	v_fmac_f32_e32 v11, v3, v19
	v_mul_f32_e32 v19, 0x3d372713, v11
	v_add_f32_e32 v20, 1.0, v20
	v_mul_f32_e32 v19, v11, v19
	v_fma_f32 v19, v11, v19, v11
	v_rcp_f32_e32 v28, v20
	v_mul_f32_e32 v19, 0x3f4c422a, v19
	v_mul_f32_e32 v19, -2.0, v19
	v_mul_f32_e32 v19, 0x3fb8aa3b, v19
	v_mul_f32_e32 v9, v9, v29
	v_exp_f32_e32 v19, v19
	v_cvt_pk_bf16_f32 v8, v8, v9
	v_add_f32_e32 v19, 1.0, v19
	v_rcp_f32_e32 v23, v19
	v_mul_f32_e32 v9, v10, v28
	v_add_u32_e32 v21, s12, v82
	v_mul_f32_e32 v10, v11, v23
	s_waitcnt lgkmcnt(2)
; __device__ __forceinline__ unsigned cvt_pk_bf16(float lo, float hi) { unsigned r; asm("v_cvt_pk_bf16_f32 %0, %1, %2" : "=v"(r) : "v"(lo), "v"(hi)); return r; }
; __device__ __forceinline__ float bflo(unsigned w) { return __uint_as_float(w << 16); }
; __device__ __forceinline__ float bfhi(unsigned w) { return __uint_as_float(w & 0xffff0000u); }
; __device__ __forceinline__ float gelu_tanh(float x) { const float u = 0.7978845608028654f * (x + 0.044715f * x * x * x); return x / (1.f + __expf(-2.f * u)); }
; __device__ __forceinline__ void s5out_item(PRef p, int layer, int item, unsigned char* shm) {
;     ...
;         if (nt < 4 || fr < 4) {
; #pragma unroll
;             for (int mi = 0; mi < 4; ++mi) { const int t = tb + mi; const size_t row = nt < 4 ? (size_t)(b * 4096 + (16 * nt + fr) * 64 + t) : (size_t)(RL + b * 256 + fr * 64 + t);
;                 const u32x2 uu = *(const u32x2*)(ul + fr * S5_UP + t * 32 + fq * 8);
;                 const f32x4 y = acc[mi];
;                 u32x2 w; w.x = cvt_pk_bf16(gelu_tanh(y[0] + dv[0] * bflo(uu.x)), gelu_tanh(y[1] + dv[1] * bfhi(uu.x)));
;                 w.y = cvt_pk_bf16(gelu_tanh(y[2] + dv[2] * bflo(uu.y)), gelu_tanh(y[3] + dv[3] * bfhi(uu.y)));
;                 *(u32x2*)(Z + row * 512 + g * 16 + fq * 4) = w; } }
	v_lshlrev_b32_e32 v11, 16, v56
	v_fma_f32 v4, v0, v11, v4
	v_mul_f32_e32 v11, 0x3d372713, v4
	v_mul_f32_e32 v11, v4, v11
	v_fma_f32 v11, v4, v11, v4
	v_mul_f32_e32 v11, 0x3f4c422a, v11
	v_mul_f32_e32 v11, -2.0, v11
	v_mul_f32_e32 v11, 0x3fb8aa3b, v11
	v_exp_f32_e32 v18, v11
	v_add_u32_e32 v16, v21, v75
	v_ashrrev_i32_e32 v17, 31, v16
	v_and_b32_e32 v19, 0xffff0000, v56
	v_cvt_pk_bf16_f32 v9, v9, v10
	v_lshlrev_b64 v[10:11], 10, v[16:17]
	v_add_f32_e32 v16, 1.0, v18
	v_fma_f32 v5, v1, v19, v5
	v_mul_f32_e32 v19, 0x3d372713, v5
	v_rcp_f32_e32 v18, v16
	v_mul_f32_e32 v19, v5, v19
	v_fma_f32 v19, v5, v19, v5
	v_mul_f32_e32 v19, 0x3f4c422a, v19
	v_lshl_add_u64 v[10:11], v[36:37], 0, v[10:11]
	v_mul_f32_e32 v19, -2.0, v19
	global_store_dwordx2 v[10:11], v[8:9], off
	v_mul_f32_e32 v19, 0x3fb8aa3b, v19
	v_exp_f32_e32 v19, v19
	s_nop 0
	v_add_f32_e32 v17, 1.0, v19
	v_rcp_f32_e32 v20, v17
	v_mul_f32_e32 v4, v4, v18
	v_lshlrev_b32_e32 v16, 16, v57
	v_fma_f32 v6, v2, v16, v6
	v_mul_f32_e32 v16, 0x3d372713, v6
	v_mul_f32_e32 v16, v6, v16
	v_fma_f32 v16, v6, v16, v6
	v_mul_f32_e32 v16, 0x3f4c422a, v16
	v_mul_f32_e32 v16, -2.0, v16
	v_mul_f32_e32 v16, 0x3fb8aa3b, v16
	v_exp_f32_e32 v16, v16
	v_and_b32_e32 v11, 0xffff0000, v57
	v_fmac_f32_e32 v7, v3, v11
	v_mul_f32_e32 v11, 0x3d372713, v7
	v_add_f32_e32 v16, 1.0, v16
	v_mul_f32_e32 v11, v7, v11
	v_fma_f32 v11, v7, v11, v7
	v_rcp_f32_e32 v19, v16
	v_mul_f32_e32 v11, 0x3f4c422a, v11
	v_mul_f32_e32 v11, -2.0, v11
	v_mul_f32_e32 v11, 0x3fb8aa3b, v11
	v_mul_f32_e32 v5, v5, v20
	v_exp_f32_e32 v11, v11
	v_cvt_pk_bf16_f32 v4, v4, v5
	v_add_f32_e32 v11, 1.0, v11
	v_rcp_f32_e32 v18, v11
	v_mul_f32_e32 v5, v6, v19
	v_add_u32_e32 v8, v21, v83
	v_mul_f32_e32 v6, v7, v18
	s_waitcnt lgkmcnt(1)
	v_lshlrev_b32_e32 v7, 16, v60
	v_fma_f32 v10, v0, v7, v24
	v_mul_f32_e32 v7, 0x3d372713, v10
	v_mul_f32_e32 v7, v10, v7
	v_fma_f32 v7, v10, v7, v10
	v_mul_f32_e32 v7, 0x3f4c422a, v7
	v_mul_f32_e32 v7, -2.0, v7
	v_mul_f32_e32 v7, 0x3fb8aa3b, v7
	v_exp_f32_e32 v11, v7
	v_ashrrev_i32_e32 v9, 31, v8
	v_and_b32_e32 v16, 0xffff0000, v60
	v_cvt_pk_bf16_f32 v5, v5, v6
	v_lshlrev_b64 v[6:7], 10, v[8:9]
	v_add_f32_e32 v8, 1.0, v11
	v_fma_f32 v16, v1, v16, v25
	v_mul_f32_e32 v17, 0x3d372713, v16
	v_rcp_f32_e32 v11, v8
	v_mul_f32_e32 v17, v16, v17
	v_fma_f32 v17, v16, v17, v16
	v_mul_f32_e32 v17, 0x3f4c422a, v17
	v_lshl_add_u64 v[6:7], v[36:37], 0, v[6:7]
	v_mul_f32_e32 v17, -2.0, v17
	global_store_dwordx2 v[6:7], v[4:5], off
	v_mul_f32_e32 v17, 0x3fb8aa3b, v17
	v_exp_f32_e32 v17, v17
	s_nop 0
	v_add_f32_e32 v9, 1.0, v17
	v_rcp_f32_e32 v18, v9
	v_mul_f32_e32 v6, v10, v11
	v_lshlrev_b32_e32 v10, 16, v61
	v_fma_f32 v10, v2, v10, v26
	v_mul_f32_e32 v11, 0x3d372713, v10
	v_mul_f32_e32 v11, v10, v11
	v_fma_f32 v11, v10, v11, v10
	v_mul_f32_e32 v11, 0x3f4c422a, v11
	v_mul_f32_e32 v11, -2.0, v11
	v_mul_f32_e32 v11, 0x3fb8aa3b, v11
	v_exp_f32_e32 v11, v11
	v_mul_f32_e32 v7, v16, v18
	v_and_b32_e32 v9, 0xffff0000, v61
	v_fmac_f32_e32 v27, v3, v9
	v_mul_f32_e32 v9, 0x3d372713, v27
	v_add_f32_e32 v11, 1.0, v11
	v_mul_f32_e32 v9, v27, v9
	v_fma_f32 v9, v27, v9, v27
	v_rcp_f32_e32 v19, v11
	v_mul_f32_e32 v9, 0x3f4c422a, v9
	v_mul_f32_e32 v9, -2.0, v9
	v_mul_f32_e32 v9, 0x3fb8aa3b, v9
	v_exp_f32_e32 v9, v9
	v_cvt_pk_bf16_f32 v6, v6, v7
	v_add_f32_e32 v9, 1.0, v9
	v_rcp_f32_e32 v17, v9
	v_mul_f32_e32 v7, v10, v19
	v_add_u32_e32 v4, v21, v84
	v_mul_f32_e32 v8, v27, v17
	s_waitcnt lgkmcnt(0)
	v_lshlrev_b32_e32 v9, 16, v58
	v_fma_f32 v9, v0, v9, v12
	v_mul_f32_e32 v10, 0x3d372713, v9
	v_mul_f32_e32 v10, v9, v10
	v_fma_f32 v10, v9, v10, v9
	v_mul_f32_e32 v10, 0x3f4c422a, v10
	v_mul_f32_e32 v10, -2.0, v10
	v_mul_f32_e32 v10, 0x3fb8aa3b, v10
	v_exp_f32_e32 v10, v10
	v_and_b32_e32 v12, 0xffff0000, v58
	v_cvt_pk_bf16_f32 v7, v7, v8
	v_fma_f32 v12, v1, v12, v13
	v_add_f32_e32 v8, 1.0, v10
	v_mul_f32_e32 v13, 0x3d372713, v12
	v_rcp_f32_e32 v11, v8
	v_mul_f32_e32 v13, v12, v13
	v_ashrrev_i32_e32 v5, 31, v4
	v_fma_f32 v13, v12, v13, v12
	v_lshlrev_b64 v[4:5], 10, v[4:5]
	v_mul_f32_e32 v13, 0x3f4c422a, v13
	v_lshl_add_u64 v[4:5], v[36:37], 0, v[4:5]
	v_mul_f32_e32 v13, -2.0, v13
	global_store_dwordx2 v[4:5], v[6:7], off
	v_mul_f32_e32 v13, 0x3fb8aa3b, v13
	v_exp_f32_e32 v13, v13
	s_nop 0
	v_add_f32_e32 v10, 1.0, v13
	v_rcp_f32_e32 v16, v10
	v_mul_f32_e32 v6, v9, v11
	v_lshlrev_b32_e32 v9, 16, v59
	v_fma_f32 v9, v2, v9, v14
	v_mul_f32_e32 v11, 0x3d372713, v9
	v_mul_f32_e32 v11, v9, v11
	v_fma_f32 v11, v9, v11, v9
	v_mul_f32_e32 v11, 0x3f4c422a, v11
	v_mul_f32_e32 v11, -2.0, v11
	v_mul_f32_e32 v11, 0x3fb8aa3b, v11
	v_exp_f32_e32 v11, v11
	v_mul_f32_e32 v7, v12, v16
	v_and_b32_e32 v10, 0xffff0000, v59
	v_fmac_f32_e32 v15, v3, v10
	v_mul_f32_e32 v10, 0x3d372713, v15
	v_add_f32_e32 v11, 1.0, v11
	v_mul_f32_e32 v10, v15, v10
	v_fma_f32 v10, v15, v10, v15
	v_rcp_f32_e32 v14, v11
	v_mul_f32_e32 v10, 0x3f4c422a, v10
	v_mul_f32_e32 v10, -2.0, v10
	v_mul_f32_e32 v10, 0x3fb8aa3b, v10
	v_exp_f32_e32 v10, v10
	v_cvt_pk_bf16_f32 v6, v6, v7
	v_add_f32_e32 v10, 1.0, v10
	v_rcp_f32_e32 v13, v10
	v_mul_f32_e32 v7, v9, v14
	v_add_u32_e32 v4, v21, v85
	v_ashrrev_i32_e32 v5, 31, v4
	v_lshlrev_b64 v[4:5], 10, v[4:5]
	v_lshl_add_u64 v[4:5], v[36:37], 0, v[4:5]
	v_mul_f32_e32 v8, v15, v13
	v_cvt_pk_bf16_f32 v7, v7, v8
	global_store_dwordx2 v[4:5], v[6:7], off
	s_cbranch_scc1 .LBB0_928
	s_barrier
	s_branch .LBB0_918

; #define PG8_STAGE(bufoff, gbase, voff) do { _Pragma("unroll") for (int _i = 0; _i < 2; ++_i) \
;         __builtin_amdgcn_global_load_lds((const unsigned*)((const char*)(gbase) + (size_t)_i * r64##voff + (voff)), (LAS unsigned*)(lds + (bufoff) + ldsw + _i * 8192), 16, 0, 0); } while (0)
; #define PG8_LDA(dst, b, h) do { _Pragma("unroll") for (int m = 0; m < 4; ++m) _Pragma("unroll") for (int k = 0; k < 2; ++k) dst[m][k] = *(const LAS bf16x8*)(lds + PG8_SA(b, h) + aoff + m * 2048 + k * 1024); } while (0)
; #define PG8_LDB(dst, b, h) do { _Pragma("unroll") for (int n = 0; n < 2; ++n) _Pragma("unroll") for (int k = 0; k < 2; ++k) dst[n][k] = *(const LAS bf16x8*)(lds + PG8_SB(b, h) + boff + n * 2048 + k * 1024); } while (0)
; #define PG8_MMA(ai, bj, At, Bt) do { __builtin_amdgcn_s_setprio(1); _Pragma("unroll") for (int m = 0; m < 4; ++m) _Pragma("unroll") for (int n = 0; n < 2; ++n) _Pragma("unroll") for (int k = 0; k < 2; ++k) \
;         acc[ai][bj][m][n] = __builtin_amdgcn_mfma_f32_16x16x32_bf16(Bt[n][k], At[m][k], acc[ai][bj][m][n], 0, 0, 0); __builtin_amdgcn_s_setprio(0); } while (0)
; #define PG8_WAIT_V(n) asm volatile("s_waitcnt vmcnt(" #n ")" ::: "memory")
; #define PG8_WAIT_L(n) asm volatile("s_waitcnt lgkmcnt(" #n ")" ::: "memory")
; #define PG8_BAR __builtin_amdgcn_s_barrier()
; #define PG8_SCHED __builtin_amdgcn_sched_barrier(0)
; template <class Epi, class Sched>
; __device__ __forceinline__ void gemm_phase(LAS unsigned char* lds, const Gemm g, const Sched& S, const Epi& E) {
;     ...
;             PG8_LDB(B0, 0, 0); PG8_SCHED; PG8_LDA(At, 0, 0); PG8_STAGE(PG8_SA(1, 1), a1 + hstepA, voffA);
;             PG8_WAIT_L(8); PG8_BAR; PG8_WAIT_L(0); PG8_MMA(0, 0, At, B0); PG8_BAR; PG8_SCHED;
;             PG8_LDB(B1, 0, 1); PG8_STAGE(PG8_SB(0, 0), b2, voffB);
;             PG8_BAR; PG8_WAIT_L(0); PG8_MMA(0, 1, At, B1); PG8_BAR;
;             PG8_LDA(At, 0, 1); PG8_STAGE(PG8_SA(0, 0), a2, voffA);
;             PG8_BAR; PG8_WAIT_L(0); PG8_MMA(1, 0, At, B0); PG8_BAR; PG8_SCHED;
;             PG8_STAGE(PG8_SB(0, 1), b2 + hstepB, voffB);
;             PG8_WAIT_V(6); PG8_BAR; PG8_MMA(1, 1, At, B1); PG8_BAR;
.LBB0_954:
	ds_read_b128 v[138:141], v147
	ds_read_b128 v[142:145], v147 offset:1024
	ds_read_b128 v[150:153], v147 offset:2048
	ds_read_b128 v[154:157], v147 offset:3072
	s_add_u32 s10, s8, 0x100
	s_addc_u32 s11, s9, 0
	s_cmp_eq_u32 s59, 4
	s_cselect_b32 s61, s12, s11
	s_cselect_b32 s60, s43, s10
	s_cselect_b32 s63, s41, s58
	s_cselect_b32 s62, s56, s57
	v_lshl_add_u64 v[190:191], s[8:9], 0, v[132:133]
	v_lshl_add_u64 v[192:193], v[190:191], 0, s[36:37]
	s_add_i32 m0, s33, 0xc000
	ds_read_b128 v[158:161], v148
	ds_read_b128 v[162:165], v148 offset:1024
	ds_read_b128 v[166:169], v148 offset:2048
	ds_read_b128 v[170:173], v148 offset:3072
	ds_read_b128 v[174:177], v148 offset:4096
	ds_read_b128 v[178:181], v148 offset:5120
	ds_read_b128 v[182:185], v148 offset:6144
	ds_read_b128 v[186:189], v148 offset:7168
	global_load_lds_dwordx4 v[192:193], off
	v_lshl_add_u64 v[190:191], v[190:191], 0, s[38:39]
	s_add_i32 m0, s33, 0xe000
	s_nop 0
	global_load_lds_dwordx4 v[190:191], off
	s_waitcnt lgkmcnt(8)
	s_barrier
	s_waitcnt lgkmcnt(0)
	s_setprio 1
	s_waitcnt lgkmcnt(0)
	v_mfma_f32_16x16x32_bf16 v[124:127], v[138:141], v[158:161], v[124:127]
	v_mfma_f32_16x16x32_bf16 v[120:123], v[150:153], v[158:161], v[120:123]
	v_mfma_f32_16x16x32_bf16 v[108:111], v[138:141], v[166:169], v[108:111]
	v_mfma_f32_16x16x32_bf16 v[104:107], v[150:153], v[166:169], v[104:107]
	v_mfma_f32_16x16x32_bf16 v[92:95], v[138:141], v[174:177], v[92:95]
	v_mfma_f32_16x16x32_bf16 v[88:91], v[150:153], v[174:177], v[88:91]
	v_mfma_f32_16x16x32_bf16 v[76:79], v[138:141], v[182:185], v[76:79]
	v_mfma_f32_16x16x32_bf16 v[72:75], v[150:153], v[182:185], v[72:75]
	v_mfma_f32_16x16x32_bf16 v[124:127], v[142:145], v[162:165], v[124:127]
	v_mfma_f32_16x16x32_bf16 v[120:123], v[154:157], v[162:165], v[120:123]
	v_mfma_f32_16x16x32_bf16 v[108:111], v[142:145], v[170:173], v[108:111]
	v_mfma_f32_16x16x32_bf16 v[104:107], v[154:157], v[170:173], v[104:107]
	v_mfma_f32_16x16x32_bf16 v[92:95], v[142:145], v[178:181], v[92:95]
	v_mfma_f32_16x16x32_bf16 v[88:91], v[154:157], v[178:181], v[88:91]
	v_mfma_f32_16x16x32_bf16 v[76:79], v[142:145], v[186:189], v[76:79]
	v_mfma_f32_16x16x32_bf16 v[72:75], v[154:157], v[186:189], v[72:75]
	s_setprio 0
	s_barrier
	s_add_i32 s8, s54, s29
	v_lshl_add_u64 v[206:207], s[62:63], 0, v[128:129]
	s_mov_b32 m0, s8
	ds_read_b128 v[190:193], v149
	ds_read_b128 v[194:197], v149 offset:1024
	ds_read_b128 v[198:201], v149 offset:2048
	ds_read_b128 v[202:205], v149 offset:3072
	global_load_lds_dwordx4 v[206:207], off
	v_lshl_add_u64 v[208:209], v[206:207], 0, s[16:17]
	s_add_i32 m0, s8, 0x2000
	s_nop 0
	global_load_lds_dwordx4 v[208:209], off
	s_barrier
	s_waitcnt lgkmcnt(0)
	s_setprio 1
	s_waitcnt lgkmcnt(0)
	v_mfma_f32_16x16x32_bf16 v[116:119], v[190:193], v[158:161], v[116:119]
	v_mfma_f32_16x16x32_bf16 v[112:115], v[198:201], v[158:161], v[112:115]
	v_mfma_f32_16x16x32_bf16 v[100:103], v[190:193], v[166:169], v[100:103]
	v_mfma_f32_16x16x32_bf16 v[96:99], v[198:201], v[166:169], v[96:99]
	v_mfma_f32_16x16x32_bf16 v[84:87], v[190:193], v[174:177], v[84:87]
	v_mfma_f32_16x16x32_bf16 v[80:83], v[198:201], v[174:177], v[80:83]
	v_mfma_f32_16x16x32_bf16 v[68:71], v[190:193], v[182:185], v[68:71]
	v_mfma_f32_16x16x32_bf16 v[64:67], v[198:201], v[182:185], v[64:67]
	v_mfma_f32_16x16x32_bf16 v[116:119], v[194:197], v[162:165], v[116:119]
	v_mfma_f32_16x16x32_bf16 v[112:115], v[202:205], v[162:165], v[112:115]
	v_mfma_f32_16x16x32_bf16 v[100:103], v[194:197], v[170:173], v[100:103]
	v_mfma_f32_16x16x32_bf16 v[96:99], v[202:205], v[170:173], v[96:99]
	v_mfma_f32_16x16x32_bf16 v[84:87], v[194:197], v[178:181], v[84:87]
	v_mfma_f32_16x16x32_bf16 v[80:83], v[202:205], v[178:181], v[80:83]
	v_mfma_f32_16x16x32_bf16 v[68:71], v[194:197], v[186:189], v[68:71]
	v_mfma_f32_16x16x32_bf16 v[64:67], v[202:205], v[186:189], v[64:67]
	s_setprio 0
	s_mov_b32 m0, s33
	v_lshl_add_u64 v[208:209], s[60:61], 0, v[130:131]
	s_barrier
	ds_read_b128 v[158:161], v148 offset:16384
	ds_read_b128 v[162:165], v148 offset:17408
	ds_read_b128 v[166:169], v148 offset:18432
	ds_read_b128 v[170:173], v148 offset:19456
	ds_read_b128 v[174:177], v148 offset:20480
	ds_read_b128 v[178:181], v148 offset:21504
	ds_read_b128 v[182:185], v148 offset:22528
	ds_read_b128 v[186:189], v148 offset:23552
	global_load_lds_dwordx4 v[208:209], off
	v_lshl_add_u64 v[210:211], v[208:209], 0, s[16:17]
	s_mov_b32 m0, s48
	s_nop 0
	global_load_lds_dwordx4 v[210:211], off
	s_barrier
	s_waitcnt lgkmcnt(0)
	s_setprio 1
	s_waitcnt lgkmcnt(0)
	v_mfma_f32_16x16x32_bf16 v[60:63], v[138:141], v[158:161], v[60:63]
	v_mfma_f32_16x16x32_bf16 v[56:59], v[150:153], v[158:161], v[56:59]
	v_mfma_f32_16x16x32_bf16 v[44:47], v[138:141], v[166:169], v[44:47]
	v_mfma_f32_16x16x32_bf16 v[40:43], v[150:153], v[166:169], v[40:43]
	v_mfma_f32_16x16x32_bf16 v[28:31], v[138:141], v[174:177], v[28:31]
	v_mfma_f32_16x16x32_bf16 v[24:27], v[150:153], v[174:177], v[24:27]
	v_mfma_f32_16x16x32_bf16 v[12:15], v[138:141], v[182:185], v[12:15]
	v_mfma_f32_16x16x32_bf16 v[8:11], v[150:153], v[182:185], v[8:11]
	v_mfma_f32_16x16x32_bf16 v[60:63], v[142:145], v[162:165], v[60:63]
	v_mfma_f32_16x16x32_bf16 v[56:59], v[154:157], v[162:165], v[56:59]
	v_mfma_f32_16x16x32_bf16 v[44:47], v[142:145], v[170:173], v[44:47]
	v_mfma_f32_16x16x32_bf16 v[40:43], v[154:157], v[170:173], v[40:43]
	v_mfma_f32_16x16x32_bf16 v[28:31], v[142:145], v[178:181], v[28:31]
	v_mfma_f32_16x16x32_bf16 v[24:27], v[154:157], v[178:181], v[24:27]
	v_mfma_f32_16x16x32_bf16 v[12:15], v[142:145], v[186:189], v[12:15]
	v_mfma_f32_16x16x32_bf16 v[8:11], v[154:157], v[186:189], v[8:11]
	s_setprio 0
	s_barrier
; #define PG8_STAGE(bufoff, gbase, voff) do { _Pragma("unroll") for (int _i = 0; _i < 2; ++_i) \
;         __builtin_amdgcn_global_load_lds((const unsigned*)((const char*)(gbase) + (size_t)_i * r64##voff + (voff)), (LAS unsigned*)(lds + (bufoff) + ldsw + _i * 8192), 16, 0, 0); } while (0)
; #define PG8_LDA(dst, b, h) do { _Pragma("unroll") for (int m = 0; m < 4; ++m) _Pragma("unroll") for (int k = 0; k < 2; ++k) dst[m][k] = *(const LAS bf16x8*)(lds + PG8_SA(b, h) + aoff + m * 2048 + k * 1024); } while (0)
; #define PG8_LDB(dst, b, h) do { _Pragma("unroll") for (int n = 0; n < 2; ++n) _Pragma("unroll") for (int k = 0; k < 2; ++k) dst[n][k] = *(const LAS bf16x8*)(lds + PG8_SB(b, h) + boff + n * 2048 + k * 1024); } while (0)
; #define PG8_MMA(ai, bj, At, Bt) do { __builtin_amdgcn_s_setprio(1); _Pragma("unroll") for (int m = 0; m < 4; ++m) _Pragma("unroll") for (int n = 0; n < 2; ++n) _Pragma("unroll") for (int k = 0; k < 2; ++k) \
;         acc[ai][bj][m][n] = __builtin_amdgcn_mfma_f32_16x16x32_bf16(Bt[n][k], At[m][k], acc[ai][bj][m][n], 0, 0, 0); __builtin_amdgcn_s_setprio(0); } while (0)
; #define PG8_WAIT_V(n) asm volatile("s_waitcnt vmcnt(" #n ")" ::: "memory")
; #define PG8_WAIT_L(n) asm volatile("s_waitcnt lgkmcnt(" #n ")" ::: "memory")
; #define PG8_BAR __builtin_amdgcn_s_barrier()
; #define PG8_SCHED __builtin_amdgcn_sched_barrier(0)
; template <class Epi, class Sched>
; __device__ __forceinline__ void gemm_phase(LAS unsigned char* lds, const Gemm g, const Sched& S, const Epi& E) {
;     ...
;             PG8_STAGE(PG8_SB(0, 1), b2 + hstepB, voffB);
;             PG8_WAIT_V(6); PG8_BAR; PG8_MMA(1, 1, At, B1); PG8_BAR;
;             PG8_LDB(B0, 1, 0); PG8_SCHED; PG8_LDA(At, 1, 0); PG8_STAGE(PG8_SA(0, 1), a2 + hstepA, voffA);
;             PG8_WAIT_L(8); PG8_BAR; PG8_WAIT_L(0); PG8_MMA(0, 0, At, B0); PG8_BAR; PG8_SCHED;
;             PG8_LDB(B1, 1, 1); PG8_STAGE(PG8_SB(1, 0), b3, voffB);
;             PG8_BAR; PG8_WAIT_L(0); PG8_MMA(0, 1, At, B1); PG8_BAR;
;             PG8_LDA(At, 1, 1); PG8_STAGE(PG8_SA(1, 0), a3, voffA);
;             PG8_BAR; PG8_WAIT_L(0); PG8_MMA(1, 0, At, B0); PG8_BAR; PG8_SCHED;
	s_add_i32 s8, s55, s29
	v_lshl_add_u64 v[138:139], v[206:207], 0, s[18:19]
	s_mov_b32 m0, s8
	s_nop 0
	global_load_lds_dwordx4 v[138:139], off
	v_lshl_add_u64 v[138:139], v[206:207], 0, s[20:21]
	s_add_i32 m0, s8, 0x2000
	s_nop 0
	global_load_lds_dwordx4 v[138:139], off
	s_waitcnt vmcnt(6)
	s_barrier
	s_setprio 1
	v_mfma_f32_16x16x32_bf16 v[52:55], v[190:193], v[158:161], v[52:55]
	v_mfma_f32_16x16x32_bf16 v[48:51], v[198:201], v[158:161], v[48:51]
	v_mfma_f32_16x16x32_bf16 v[36:39], v[190:193], v[166:169], v[36:39]
	v_mfma_f32_16x16x32_bf16 v[32:35], v[198:201], v[166:169], v[32:35]
	v_mfma_f32_16x16x32_bf16 v[20:23], v[190:193], v[174:177], v[20:23]
	v_mfma_f32_16x16x32_bf16 v[16:19], v[198:201], v[174:177], v[16:19]
	v_mfma_f32_16x16x32_bf16 v[4:7], v[190:193], v[182:185], v[4:7]
	v_mfma_f32_16x16x32_bf16 v[0:3], v[198:201], v[182:185], v[0:3]
	v_mfma_f32_16x16x32_bf16 v[52:55], v[194:197], v[162:165], v[52:55]
	v_mfma_f32_16x16x32_bf16 v[48:51], v[202:205], v[162:165], v[48:51]
	v_mfma_f32_16x16x32_bf16 v[36:39], v[194:197], v[170:173], v[36:39]
	v_mfma_f32_16x16x32_bf16 v[32:35], v[202:205], v[170:173], v[32:35]
	v_mfma_f32_16x16x32_bf16 v[20:23], v[194:197], v[178:181], v[20:23]
	v_mfma_f32_16x16x32_bf16 v[16:19], v[202:205], v[178:181], v[16:19]
	v_mfma_f32_16x16x32_bf16 v[4:7], v[194:197], v[186:189], v[4:7]
	v_mfma_f32_16x16x32_bf16 v[0:3], v[202:205], v[186:189], v[0:3]
	s_setprio 0
	s_add_i32 s8, 0, 0x18000
	v_add_u32_e32 v154, s8, v146
	s_barrier
	ds_read_b128 v[138:141], v154
	ds_read_b128 v[142:145], v154 offset:1024
	ds_read_b128 v[150:153], v154 offset:2048
	ds_read_b128 v[154:157], v154 offset:3072
	s_mov_b32 m0, s49
	v_lshl_add_u64 v[190:191], v[208:209], 0, s[18:19]
	ds_read_b128 v[158:161], v148 offset:32768
	ds_read_b128 v[162:165], v148 offset:33792
	ds_read_b128 v[166:169], v148 offset:34816
	ds_read_b128 v[170:173], v148 offset:35840
	ds_read_b128 v[174:177], v148 offset:36864
	ds_read_b128 v[178:181], v148 offset:37888
	ds_read_b128 v[182:185], v148 offset:38912
	ds_read_b128 v[186:189], v148 offset:39936
	global_load_lds_dwordx4 v[190:191], off
	v_lshl_add_u64 v[190:191], v[208:209], 0, s[20:21]
	s_mov_b32 m0, s50
	s_nop 0
	global_load_lds_dwordx4 v[190:191], off
	s_waitcnt lgkmcnt(8)
	s_barrier
	s_waitcnt lgkmcnt(0)
	s_setprio 1
	s_waitcnt lgkmcnt(0)
	v_mfma_f32_16x16x32_bf16 v[124:127], v[138:141], v[158:161], v[124:127]
	v_mfma_f32_16x16x32_bf16 v[120:123], v[150:153], v[158:161], v[120:123]
	v_mfma_f32_16x16x32_bf16 v[108:111], v[138:141], v[166:169], v[108:111]
	v_mfma_f32_16x16x32_bf16 v[104:107], v[150:153], v[166:169], v[104:107]
	v_mfma_f32_16x16x32_bf16 v[92:95], v[138:141], v[174:177], v[92:95]
	v_mfma_f32_16x16x32_bf16 v[88:91], v[150:153], v[174:177], v[88:91]
	v_mfma_f32_16x16x32_bf16 v[76:79], v[138:141], v[182:185], v[76:79]
	v_mfma_f32_16x16x32_bf16 v[72:75], v[150:153], v[182:185], v[72:75]
	v_mfma_f32_16x16x32_bf16 v[124:127], v[142:145], v[162:165], v[124:127]
	v_mfma_f32_16x16x32_bf16 v[120:123], v[154:157], v[162:165], v[120:123]
	v_mfma_f32_16x16x32_bf16 v[108:111], v[142:145], v[170:173], v[108:111]
	v_mfma_f32_16x16x32_bf16 v[104:107], v[154:157], v[170:173], v[104:107]
	v_mfma_f32_16x16x32_bf16 v[92:95], v[142:145], v[178:181], v[92:95]
	v_mfma_f32_16x16x32_bf16 v[88:91], v[154:157], v[178:181], v[88:91]
	v_mfma_f32_16x16x32_bf16 v[76:79], v[142:145], v[186:189], v[76:79]
	v_mfma_f32_16x16x32_bf16 v[72:75], v[154:157], v[186:189], v[72:75]
	s_setprio 0
	s_barrier
	s_add_i32 s9, 0, 0x1c000
	s_add_i32 s8, s8, s29
	v_add_u32_e32 v202, s9, v146
	v_lshl_add_u64 v[210:211], v[206:207], 0, s[30:31]
	s_mov_b32 m0, s8
	ds_read_b128 v[190:193], v202
	ds_read_b128 v[194:197], v202 offset:1024
	ds_read_b128 v[198:201], v202 offset:2048
	ds_read_b128 v[202:205], v202 offset:3072
	global_load_lds_dwordx4 v[210:211], off
	v_lshl_add_u64 v[210:211], v[206:207], 0, s[34:35]
	s_add_i32 m0, s8, 0x2000
	s_nop 0
	global_load_lds_dwordx4 v[210:211], off
	s_barrier
	s_waitcnt lgkmcnt(0)
	s_setprio 1
	s_waitcnt lgkmcnt(0)
	v_mfma_f32_16x16x32_bf16 v[116:119], v[190:193], v[158:161], v[116:119]
	v_mfma_f32_16x16x32_bf16 v[112:115], v[198:201], v[158:161], v[112:115]
	v_mfma_f32_16x16x32_bf16 v[100:103], v[190:193], v[166:169], v[100:103]
	v_mfma_f32_16x16x32_bf16 v[96:99], v[198:201], v[166:169], v[96:99]
	v_mfma_f32_16x16x32_bf16 v[84:87], v[190:193], v[174:177], v[84:87]
	v_mfma_f32_16x16x32_bf16 v[80:83], v[198:201], v[174:177], v[80:83]
	v_mfma_f32_16x16x32_bf16 v[68:71], v[190:193], v[182:185], v[68:71]
	v_mfma_f32_16x16x32_bf16 v[64:67], v[198:201], v[182:185], v[64:67]
	v_mfma_f32_16x16x32_bf16 v[116:119], v[194:197], v[162:165], v[116:119]
	v_mfma_f32_16x16x32_bf16 v[112:115], v[202:205], v[162:165], v[112:115]
	v_mfma_f32_16x16x32_bf16 v[100:103], v[194:197], v[170:173], v[100:103]
	v_mfma_f32_16x16x32_bf16 v[96:99], v[202:205], v[170:173], v[96:99]
	v_mfma_f32_16x16x32_bf16 v[84:87], v[194:197], v[178:181], v[84:87]
	v_mfma_f32_16x16x32_bf16 v[80:83], v[202:205], v[178:181], v[80:83]
	v_mfma_f32_16x16x32_bf16 v[68:71], v[194:197], v[186:189], v[68:71]
	v_mfma_f32_16x16x32_bf16 v[64:67], v[202:205], v[186:189], v[64:67]
	s_setprio 0
	s_mov_b32 m0, s52
	v_lshl_add_u64 v[210:211], v[208:209], 0, s[30:31]
	s_barrier
	ds_read_b128 v[158:161], v148 offset:49152
	ds_read_b128 v[162:165], v148 offset:50176
	ds_read_b128 v[166:169], v148 offset:51200
	ds_read_b128 v[170:173], v148 offset:52224
	ds_read_b128 v[174:177], v148 offset:53248
	ds_read_b128 v[178:181], v148 offset:54272
	ds_read_b128 v[182:185], v148 offset:55296
	ds_read_b128 v[186:189], v148 offset:56320
	global_load_lds_dwordx4 v[210:211], off
	v_lshl_add_u64 v[208:209], v[208:209], 0, s[34:35]
	s_mov_b32 m0, s53
	s_nop 0
	global_load_lds_dwordx4 v[208:209], off
	s_barrier
; __device__ __forceinline__ int otid() { int t = (int)__builtin_amdgcn_workitem_id_x(); asm volatile("" : "+v"(t)); return t; }
; __device__ __forceinline__ unsigned cvt_pk_bf16(float lo, float hi) { unsigned r; asm("v_cvt_pk_bf16_f32 %0, %1, %2" : "=v"(r) : "v"(lo), "v"(hi)); return r; }
; __device__ __forceinline__ float bflo(unsigned w) { return __uint_as_float(w << 16); }
; __device__ __forceinline__ float bfhi(unsigned w) { return __uint_as_float(w & 0xffff0000u); }
; __device__ __forceinline__ float sigmoidf_(float x) { return 1.f / (1.f + __expf(-x)); }
; template <class Epi, class Sched>
; __device__ __forceinline__ void gemm_phase(LAS unsigned char* lds, const Gemm g, const Sched& S, const Epi& E) {
;     ...
;             PG8_BAR; PG8_WAIT_L(0); PG8_MMA(1, 0, At, B0); PG8_BAR; PG8_SCHED;
;             PG8_STAGE(PG8_SB(1, 1), b3 + hstepB, voffB);
;             PG8_WAIT_V(6); PG8_BAR; PG8_MMA(1, 1, At, B1); PG8_BAR;
;     __device__ __forceinline__ void operator()(const f32x4 (&acc)[2][2][4][2], const pg8::Unit& u, int wr_, int wc_, int fr_, int fq_) const {
;         const int t2_ = otid(), wr = t2_ >> 8, wc = (t2_ >> 6) & 3, fr = t2_ & 15, fq = (t2_ >> 4) & 3; (void)wr_; (void)wc_; (void)fr_; (void)fq_;
;         const int row0 = u.pm * 256 + wr * 64 + fr, col0 = u.pn * 256 + wc * 32 + 8 * fq;
; #pragma unroll
;         for (int ai = 0; ai < 2; ++ai)
; #pragma unroll
;             for (int m = 0; m < 4; ++m) { const int row = row0 + ai * 128 + m * 16;
; #pragma unroll
;                 for (int bj = 0; bj < 2; ++bj) { const int col = col0 + bj * 128;
;                     const f32x4 b0 = *(const f32x4*)(bias + col), b1 = *(const f32x4*)(bias + col + 4);
;                     const f32x4 v0 = acc[ai][bj][m][0] + b0, v1 = acc[ai][bj][m][1] + b1;
;                     const u32x4 z = *(const u32x4*)(Z + (size_t)row * 512 + col);
;                     u32x4 w;
;                     w.x = cvt_pk_bf16(bflo(z.x) * sigmoidf_(v0[0]), bfhi(z.x) * sigmoidf_(v0[1]));
;                     w.y = cvt_pk_bf16(bflo(z.y) * sigmoidf_(v0[2]), bfhi(z.y) * sigmoidf_(v0[3]));
;                     w.z = cvt_pk_bf16(bflo(z.z) * sigmoidf_(v1[0]), bfhi(z.z) * sigmoidf_(v1[1]));
;                     w.w = cvt_pk_bf16(bflo(z.w) * sigmoidf_(v1[2]), bfhi(z.w) * sigmoidf_(v1[3]));
;                     *(u32x4*)(MIX + (size_t)row * 2048 + 1536 + col) = w; } }
	s_waitcnt lgkmcnt(0)
	s_setprio 1
	s_waitcnt lgkmcnt(0)
	v_mfma_f32_16x16x32_bf16 v[60:63], v[138:141], v[158:161], v[60:63]
	v_mfma_f32_16x16x32_bf16 v[56:59], v[150:153], v[158:161], v[56:59]
	v_mfma_f32_16x16x32_bf16 v[44:47], v[138:141], v[166:169], v[44:47]
	v_mfma_f32_16x16x32_bf16 v[40:43], v[150:153], v[166:169], v[40:43]
	v_mfma_f32_16x16x32_bf16 v[28:31], v[138:141], v[174:177], v[28:31]
	v_mfma_f32_16x16x32_bf16 v[24:27], v[150:153], v[174:177], v[24:27]
	v_mfma_f32_16x16x32_bf16 v[12:15], v[138:141], v[182:185], v[12:15]
	v_mfma_f32_16x16x32_bf16 v[8:11], v[150:153], v[182:185], v[8:11]
	v_mfma_f32_16x16x32_bf16 v[60:63], v[142:145], v[162:165], v[60:63]
	v_mfma_f32_16x16x32_bf16 v[56:59], v[154:157], v[162:165], v[56:59]
	v_mfma_f32_16x16x32_bf16 v[44:47], v[142:145], v[170:173], v[44:47]
	v_mfma_f32_16x16x32_bf16 v[40:43], v[154:157], v[170:173], v[40:43]
	v_mfma_f32_16x16x32_bf16 v[28:31], v[142:145], v[178:181], v[28:31]
	v_mfma_f32_16x16x32_bf16 v[24:27], v[154:157], v[178:181], v[24:27]
	v_mfma_f32_16x16x32_bf16 v[12:15], v[142:145], v[186:189], v[12:15]
	v_mfma_f32_16x16x32_bf16 v[8:11], v[154:157], v[186:189], v[8:11]
	s_setprio 0
	s_barrier
	s_add_i32 s8, s9, s29
	v_lshl_add_u64 v[138:139], v[206:207], 0, s[36:37]
	s_mov_b32 m0, s8
	s_nop 0
	global_load_lds_dwordx4 v[138:139], off
	v_lshl_add_u64 v[138:139], v[206:207], 0, s[38:39]
	s_add_i32 m0, s8, 0x2000
	s_nop 0
	global_load_lds_dwordx4 v[138:139], off
	s_waitcnt vmcnt(6)
	s_barrier
	s_setprio 1
	v_mfma_f32_16x16x32_bf16 v[52:55], v[190:193], v[158:161], v[52:55]
	v_mfma_f32_16x16x32_bf16 v[48:51], v[198:201], v[158:161], v[48:51]
	v_mfma_f32_16x16x32_bf16 v[36:39], v[190:193], v[166:169], v[36:39]
	v_mfma_f32_16x16x32_bf16 v[32:35], v[198:201], v[166:169], v[32:35]
	v_mfma_f32_16x16x32_bf16 v[20:23], v[190:193], v[174:177], v[20:23]
	v_mfma_f32_16x16x32_bf16 v[16:19], v[198:201], v[174:177], v[16:19]
	v_mfma_f32_16x16x32_bf16 v[4:7], v[190:193], v[182:185], v[4:7]
	v_mfma_f32_16x16x32_bf16 v[0:3], v[198:201], v[182:185], v[0:3]
	v_mfma_f32_16x16x32_bf16 v[52:55], v[194:197], v[162:165], v[52:55]
	v_mfma_f32_16x16x32_bf16 v[48:51], v[202:205], v[162:165], v[48:51]
	v_mfma_f32_16x16x32_bf16 v[36:39], v[194:197], v[170:173], v[36:39]
	v_mfma_f32_16x16x32_bf16 v[32:35], v[202:205], v[170:173], v[32:35]
	v_mfma_f32_16x16x32_bf16 v[20:23], v[194:197], v[178:181], v[20:23]
	v_mfma_f32_16x16x32_bf16 v[16:19], v[202:205], v[178:181], v[16:19]
	v_mfma_f32_16x16x32_bf16 v[4:7], v[194:197], v[186:189], v[4:7]
	v_mfma_f32_16x16x32_bf16 v[0:3], v[202:205], v[186:189], v[0:3]
	s_setprio 0
	s_add_i32 s59, s59, 2
	s_add_u32 s57, s57, 0x100
	s_addc_u32 s58, s58, 0
	s_cmp_lt_u32 s59, 6
	s_mov_b64 s[8:9], s[10:11]
	s_barrier
	s_cbranch_scc1 .LBB0_954
	v_mov_b32_e32 v142, v222
	s_lshl_b32 s6, s6, 8
	v_lshrrev_b32_e32 v138, 1, v142
	v_and_b32_e32 v138, 0x78, v138
	v_lshl_or_b32 v140, s7, 8, v138
	v_ashrrev_i32_e32 v141, 31, v140
	v_lshl_add_u64 v[138:139], v[140:141], 2, s[22:23]
	global_load_dwordx4 v[150:153], v[138:139], off offset:2064
	global_load_dwordx4 v[154:157], v[138:139], off offset:2048
	v_ashrrev_i32_e32 v143, 2, v142
	v_and_b32_e32 v143, 0xffffffc0, v143
	v_and_or_b32 v142, v142, 15, s6
	v_add_u32_e32 v142, v142, v143
	v_ashrrev_i32_e32 v143, 31, v142
	v_lshlrev_b64 v[144:145], 10, v[142:143]
	v_lshl_add_u64 v[144:145], s[24:25], 0, v[144:145]
	v_lshlrev_b64 v[140:141], 1, v[140:141]
	v_lshl_add_u64 v[144:145], v[144:145], 0, v[140:141]
	global_load_dwordx4 v[158:161], v[144:145], off
	v_lshlrev_b64 v[162:163], 12, v[142:143]
	s_waitcnt vmcnt(0)
	v_pk_add_f32 v[150:151], v[120:121], v[150:151]
	v_pk_add_f32 v[124:125], v[124:125], v[154:155]
	v_pk_add_f32 v[126:127], v[126:127], v[156:157]
	v_mul_f32_e32 v120, 0xbfb8aa3b, v124
	v_mul_f32_e32 v121, 0xbfb8aa3b, v125
	v_exp_f32_e32 v120, v120
	v_mul_f32_e32 v124, 0xbfb8aa3b, v126
	v_mul_f32_e32 v126, 0xbfb8aa3b, v150
	v_exp_f32_e32 v121, v121
	v_mul_f32_e32 v125, 0xbfb8aa3b, v127
	v_exp_f32_e32 v124, v124
	v_exp_f32_e32 v126, v126
	v_exp_f32_e32 v125, v125
	v_add_f32_e32 v120, 1.0, v120
	v_add_f32_e32 v121, 1.0, v121
	v_add_f32_e32 v124, 1.0, v124
	v_add_f32_e32 v126, 1.0, v126
	v_rcp_f32_e32 v120, v120
	v_lshlrev_b32_e32 v127, 16, v158
	v_and_b32_e32 v143, 0xffff0000, v158
	v_add_f32_e32 v125, 1.0, v125
	v_rcp_f32_e32 v121, v121
	v_rcp_f32_e32 v124, v124
	v_rcp_f32_e32 v171, v126
	v_rcp_f32_e32 v170, v125
	v_pk_add_f32 v[122:123], v[122:123], v[152:153]
	v_lshlrev_b32_e32 v150, 16, v159
	v_and_b32_e32 v152, 0xffff0000, v159
	v_mul_f32_e32 v120, v120, v127
	v_mul_f32_e32 v121, v121, v143
	v_cvt_pk_bf16_f32 v120, v120, v121
	v_mul_f32_e32 v121, v124, v150
	v_mov_b32_e32 v124, v170
	v_mul_f32_e32 v124, v124, v152
	v_cvt_pk_bf16_f32 v121, v121, v124
	v_mul_f32_e32 v127, 0xbfb8aa3b, v151
	v_exp_f32_e32 v127, v127
	v_mul_f32_e32 v122, 0xbfb8aa3b, v122
	v_add_f32_e32 v125, 1.0, v127
	v_rcp_f32_e32 v125, v125
	v_exp_f32_e32 v122, v122
	v_mov_b32_e32 v124, v171
	v_and_b32_e32 v126, 0xffff0000, v160
	v_add_f32_e32 v127, 1.0, v122
	v_rcp_f32_e32 v150, v127
	v_mul_f32_e32 v122, v125, v126
	v_mul_f32_e32 v123, 0xbfb8aa3b, v123
	v_exp_f32_e32 v123, v123
	s_nop 0
	v_add_f32_e32 v123, 1.0, v123
	v_rcp_f32_e32 v123, v123
	v_mov_b32_e32 v125, v150
	v_lshlrev_b32_e32 v153, 16, v160
	v_mul_f32_e32 v124, v124, v153
	v_cvt_pk_bf16_f32 v122, v124, v122
	v_lshlrev_b32_e32 v124, 16, v161
	v_mul_f32_e32 v124, v125, v124
	v_and_b32_e32 v125, 0xffff0000, v161
	v_mul_f32_e32 v123, v123, v125
	v_cvt_pk_bf16_f32 v123, v124, v123
	v_lshl_add_u64 v[124:125], s[26:27], 0, v[162:163]
	v_lshl_add_u64 v[154:155], v[124:125], 0, v[140:141]
	global_store_dwordx4 v[154:155], v[120:123], off offset:3072
	global_load_dwordx4 v[120:123], v[138:139], off offset:2560
	s_nop 0
	global_load_dwordx4 v[124:127], v[138:139], off offset:2576
	global_load_dwordx4 v[150:153], v[144:145], off offset:256
	s_mov_b64 s[10:11], s[46:47]
	s_mov_b64 s[8:9], s[44:45]
	s_waitcnt vmcnt(0)
; __device__ __forceinline__ unsigned cvt_pk_bf16(float lo, float hi) { unsigned r; asm("v_cvt_pk_bf16_f32 %0, %1, %2" : "=v"(r) : "v"(lo), "v"(hi)); return r; }
; __device__ __forceinline__ float bflo(unsigned w) { return __uint_as_float(w << 16); }
; __device__ __forceinline__ float bfhi(unsigned w) { return __uint_as_float(w & 0xffff0000u); }
; __device__ __forceinline__ float sigmoidf_(float x) { return 1.f / (1.f + __expf(-x)); }
;     __device__ __forceinline__ void operator()(const f32x4 (&acc)[2][2][4][2], const pg8::Unit& u, int wr_, int wc_, int fr_, int fq_) const {
;     ...
;         for (int ai = 0; ai < 2; ++ai)
; #pragma unroll
;             for (int m = 0; m < 4; ++m) { const int row = row0 + ai * 128 + m * 16;
; #pragma unroll
;                 for (int bj = 0; bj < 2; ++bj) { const int col = col0 + bj * 128;
;                     const f32x4 b0 = *(const f32x4*)(bias + col), b1 = *(const f32x4*)(bias + col + 4);
;                     const f32x4 v0 = acc[ai][bj][m][0] + b0, v1 = acc[ai][bj][m][1] + b1;
;                     const u32x4 z = *(const u32x4*)(Z + (size_t)row * 512 + col);
;                     u32x4 w;
;                     w.x = cvt_pk_bf16(bflo(z.x) * sigmoidf_(v0[0]), bfhi(z.x) * sigmoidf_(v0[1]));
;                     w.y = cvt_pk_bf16(bflo(z.y) * sigmoidf_(v0[2]), bfhi(z.y) * sigmoidf_(v0[3]));
;                     w.z = cvt_pk_bf16(bflo(z.z) * sigmoidf_(v1[0]), bfhi(z.z) * sigmoidf_(v1[1]));
;                     w.w = cvt_pk_bf16(bflo(z.w) * sigmoidf_(v1[2]), bfhi(z.w) * sigmoidf_(v1[3]));
;                     *(u32x4*)(MIX + (size_t)row * 2048 + 1536 + col) = w; } }
	v_pk_add_f32 v[116:117], v[116:117], v[120:121]
	v_pk_add_f32 v[120:121], v[112:113], v[124:125]
	v_mul_f32_e32 v112, 0xbfb8aa3b, v116
	v_exp_f32_e32 v112, v112
	v_pk_add_f32 v[118:119], v[118:119], v[122:123]
	v_mul_f32_e32 v113, 0xbfb8aa3b, v117
	v_exp_f32_e32 v113, v113
	v_add_f32_e32 v112, 1.0, v112
	v_rcp_f32_e32 v112, v112
	v_pk_add_f32 v[114:115], v[114:115], v[126:127]
	v_add_f32_e32 v113, 1.0, v113
	v_rcp_f32_e32 v113, v113
	v_lshlrev_b32_e32 v116, 16, v150
	v_mul_f32_e32 v112, v112, v116
	v_mul_f32_e32 v118, 0xbfb8aa3b, v118
	v_exp_f32_e32 v118, v118
	s_nop 0
	v_add_f32_e32 v116, 1.0, v118
	v_rcp_f32_e32 v116, v116
	v_and_b32_e32 v117, 0xffff0000, v150
	v_mul_f32_e32 v113, v113, v117
	v_mul_f32_e32 v119, 0xbfb8aa3b, v119
	v_exp_f32_e32 v119, v119
	s_nop 0
	v_add_f32_e32 v118, 1.0, v119
	v_rcp_f32_e32 v122, v118
	v_cvt_pk_bf16_f32 v112, v112, v113
	v_lshlrev_b32_e32 v113, 16, v151
	v_mul_f32_e32 v119, 0xbfb8aa3b, v120
	v_exp_f32_e32 v119, v119
	v_mov_b32_e32 v117, v122
	v_mul_f32_e32 v113, v116, v113
	v_add_f32_e32 v118, 1.0, v119
	v_and_b32_e32 v116, 0xffff0000, v151
	v_mul_f32_e32 v116, v117, v116
	v_mul_f32_e32 v121, 0xbfb8aa3b, v121
	v_exp_f32_e32 v121, v121
	s_nop 0
	v_add_f32_e32 v119, 1.0, v121
	v_rcp_f32_e32 v121, v119
	v_rcp_f32_e32 v117, v118
	v_mul_f32_e32 v114, 0xbfb8aa3b, v114
	v_exp_f32_e32 v114, v114
	v_mov_b32_e32 v118, v121
	v_add_f32_e32 v119, 1.0, v114
	v_rcp_f32_e32 v121, v119
	v_cvt_pk_bf16_f32 v113, v113, v116
	v_lshlrev_b32_e32 v116, 16, v152
	v_mul_f32_e32 v116, v117, v116
	v_and_b32_e32 v117, 0xffff0000, v152
	v_mul_f32_e32 v114, v118, v117
	v_mul_f32_e32 v115, 0xbfb8aa3b, v115
	v_exp_f32_e32 v115, v115
	s_nop 0
	v_add_f32_e32 v115, 1.0, v115
	v_rcp_f32_e32 v115, v115
	v_mov_b32_e32 v117, v121
	v_cvt_pk_bf16_f32 v114, v116, v114
	v_lshlrev_b32_e32 v116, 16, v153
	v_mul_f32_e32 v116, v117, v116
	v_and_b32_e32 v117, 0xffff0000, v153
	v_mul_f32_e32 v115, v115, v117
	v_cvt_pk_bf16_f32 v115, v116, v115
	global_store_dwordx4 v[154:155], v[112:115], off offset:3328
	global_load_dwordx4 v[112:115], v[138:139], off offset:2048
	s_nop 0
	global_load_dwordx4 v[116:119], v[138:139], off offset:2064
	v_or_b32_e32 v124, 16, v142
	v_ashrrev_i32_e32 v125, 31, v124
	v_lshlrev_b64 v[120:121], 10, v[124:125]
	v_lshl_add_u64 v[120:121], s[24:25], 0, v[120:121]
	v_lshl_add_u64 v[126:127], v[120:121], 0, v[140:141]
	global_load_dwordx4 v[120:123], v[126:127], off
	s_waitcnt vmcnt(0)
	v_pk_add_f32 v[108:109], v[108:109], v[112:113]
	s_nop 0
	v_mul_f32_e32 v108, 0xbfb8aa3b, v108
	v_exp_f32_e32 v108, v108
	v_lshlrev_b64 v[112:113], 12, v[124:125]
	v_pk_add_f32 v[110:111], v[110:111], v[114:115]
	v_pk_add_f32 v[114:115], v[104:105], v[116:117]
	v_add_f32_e32 v108, 1.0, v108
	v_rcp_f32_e32 v105, v108
	v_mul_f32_e32 v109, 0xbfb8aa3b, v109
	v_exp_f32_e32 v109, v109
	v_pk_add_f32 v[106:107], v[106:107], v[118:119]
	v_add_f32_e32 v109, 1.0, v109
	v_rcp_f32_e32 v117, v109
	v_mul_f32_e32 v110, 0xbfb8aa3b, v110
	v_exp_f32_e32 v110, v110
	v_mov_b32_e32 v108, v117
	v_add_f32_e32 v109, 1.0, v110
	v_lshlrev_b32_e32 v104, 16, v120
	v_mul_f32_e32 v104, v105, v104
	v_and_b32_e32 v105, 0xffff0000, v120
	v_mul_f32_e32 v105, v108, v105
	v_mul_f32_e32 v111, 0xbfb8aa3b, v111
	v_exp_f32_e32 v111, v111
	s_nop 0
	v_add_f32_e32 v110, 1.0, v111
	v_rcp_f32_e32 v116, v110
	v_rcp_f32_e32 v108, v109
	v_cvt_pk_bf16_f32 v104, v104, v105
	v_lshlrev_b32_e32 v105, 16, v121
	v_mul_f32_e32 v111, 0xbfb8aa3b, v114
	v_exp_f32_e32 v111, v111
	v_mov_b32_e32 v109, v116
	v_mul_f32_e32 v105, v108, v105
	v_add_f32_e32 v110, 1.0, v111
	v_and_b32_e32 v108, 0xffff0000, v121
	v_mul_f32_e32 v108, v109, v108
	v_mul_f32_e32 v115, 0xbfb8aa3b, v115
	v_exp_f32_e32 v115, v115
	s_nop 0
	v_add_f32_e32 v111, 1.0, v115
	v_rcp_f32_e32 v115, v111
	v_rcp_f32_e32 v109, v110
	v_mul_f32_e32 v106, 0xbfb8aa3b, v106
	v_exp_f32_e32 v106, v106
	v_mov_b32_e32 v110, v115
	v_add_f32_e32 v111, 1.0, v106
	v_rcp_f32_e32 v115, v111
	v_cvt_pk_bf16_f32 v105, v105, v108
	v_lshlrev_b32_e32 v108, 16, v122
	v_mul_f32_e32 v108, v109, v108
	v_and_b32_e32 v109, 0xffff0000, v122
	v_mul_f32_e32 v106, v110, v109
	v_mul_f32_e32 v107, 0xbfb8aa3b, v107
	v_exp_f32_e32 v107, v107
	s_nop 0
	v_add_f32_e32 v107, 1.0, v107
	v_rcp_f32_e32 v107, v107
	v_mov_b32_e32 v109, v115
	v_cvt_pk_bf16_f32 v106, v108, v106
	v_lshlrev_b32_e32 v108, 16, v123
	v_mul_f32_e32 v108, v109, v108
	v_and_b32_e32 v109, 0xffff0000, v123
	v_mul_f32_e32 v107, v107, v109
	v_cvt_pk_bf16_f32 v107, v108, v107
	v_lshl_add_u64 v[108:109], s[26:27], 0, v[112:113]
	v_lshl_add_u64 v[116:117], v[108:109], 0, v[140:141]
	global_store_dwordx4 v[116:117], v[104:107], off offset:3072
	global_load_dwordx4 v[104:107], v[138:139], off offset:2560
	s_nop 0
	global_load_dwordx4 v[108:111], v[138:139], off offset:2576
	global_load_dwordx4 v[112:115], v[126:127], off offset:256
	s_waitcnt vmcnt(0)
; __device__ __forceinline__ unsigned cvt_pk_bf16(float lo, float hi) { unsigned r; asm("v_cvt_pk_bf16_f32 %0, %1, %2" : "=v"(r) : "v"(lo), "v"(hi)); return r; }
; __device__ __forceinline__ float bflo(unsigned w) { return __uint_as_float(w << 16); }
; __device__ __forceinline__ float bfhi(unsigned w) { return __uint_as_float(w & 0xffff0000u); }
; __device__ __forceinline__ float sigmoidf_(float x) { return 1.f / (1.f + __expf(-x)); }
;     __device__ __forceinline__ void operator()(const f32x4 (&acc)[2][2][4][2], const pg8::Unit& u, int wr_, int wc_, int fr_, int fq_) const {
;     ...
;         for (int ai = 0; ai < 2; ++ai)
; #pragma unroll
;             for (int m = 0; m < 4; ++m) { const int row = row0 + ai * 128 + m * 16;
; #pragma unroll
;                 for (int bj = 0; bj < 2; ++bj) { const int col = col0 + bj * 128;
;                     const f32x4 b0 = *(const f32x4*)(bias + col), b1 = *(const f32x4*)(bias + col + 4);
;                     const f32x4 v0 = acc[ai][bj][m][0] + b0, v1 = acc[ai][bj][m][1] + b1;
;                     const u32x4 z = *(const u32x4*)(Z + (size_t)row * 512 + col);
;                     u32x4 w;
;                     w.x = cvt_pk_bf16(bflo(z.x) * sigmoidf_(v0[0]), bfhi(z.x) * sigmoidf_(v0[1]));
;                     w.y = cvt_pk_bf16(bflo(z.y) * sigmoidf_(v0[2]), bfhi(z.y) * sigmoidf_(v0[3]));
;                     w.z = cvt_pk_bf16(bflo(z.z) * sigmoidf_(v1[0]), bfhi(z.z) * sigmoidf_(v1[1]));
;                     w.w = cvt_pk_bf16(bflo(z.w) * sigmoidf_(v1[2]), bfhi(z.w) * sigmoidf_(v1[3]));
;                     *(u32x4*)(MIX + (size_t)row * 2048 + 1536 + col) = w; } }
	v_pk_add_f32 v[100:101], v[100:101], v[104:105]
	s_nop 0
	v_mul_f32_e32 v100, 0xbfb8aa3b, v100
	v_exp_f32_e32 v100, v100
	v_pk_add_f32 v[102:103], v[102:103], v[106:107]
	v_mul_f32_e32 v101, 0xbfb8aa3b, v101
	v_pk_add_f32 v[104:105], v[96:97], v[108:109]
	v_add_f32_e32 v100, 1.0, v100
	v_rcp_f32_e32 v97, v100
	v_exp_f32_e32 v101, v101
	v_mul_f32_e32 v102, 0xbfb8aa3b, v102
	v_exp_f32_e32 v102, v102
	v_add_f32_e32 v101, 1.0, v101
	v_rcp_f32_e32 v107, v101
	v_lshlrev_b32_e32 v96, 16, v112
	v_mul_f32_e32 v96, v97, v96
	v_mov_b32_e32 v100, v107
	v_add_f32_e32 v101, 1.0, v102
	v_and_b32_e32 v97, 0xffff0000, v112
	v_mul_f32_e32 v97, v100, v97
	v_mul_f32_e32 v103, 0xbfb8aa3b, v103
	v_exp_f32_e32 v103, v103
	s_nop 0
	v_add_f32_e32 v102, 1.0, v103
	v_rcp_f32_e32 v106, v102
	v_rcp_f32_e32 v100, v101
	v_cvt_pk_bf16_f32 v96, v96, v97
	v_lshlrev_b32_e32 v97, 16, v113
	v_mul_f32_e32 v103, 0xbfb8aa3b, v104
	v_exp_f32_e32 v103, v103
	v_mov_b32_e32 v101, v106
	v_mul_f32_e32 v97, v100, v97
	v_add_f32_e32 v102, 1.0, v103
	v_and_b32_e32 v100, 0xffff0000, v113
	v_mul_f32_e32 v100, v101, v100
	v_mul_f32_e32 v105, 0xbfb8aa3b, v105
	v_exp_f32_e32 v105, v105
	s_nop 0
	v_add_f32_e32 v103, 1.0, v105
	v_rcp_f32_e32 v105, v103
	v_rcp_f32_e32 v101, v102
	v_pk_add_f32 v[98:99], v[98:99], v[110:111]
	v_cvt_pk_bf16_f32 v97, v97, v100
	v_mul_f32_e32 v98, 0xbfb8aa3b, v98
	v_exp_f32_e32 v98, v98
	v_mov_b32_e32 v102, v105
	v_add_f32_e32 v103, 1.0, v98
	v_rcp_f32_e32 v105, v103
	v_lshlrev_b32_e32 v100, 16, v114
	v_mul_f32_e32 v100, v101, v100
	v_and_b32_e32 v101, 0xffff0000, v114
	v_mul_f32_e32 v98, v102, v101
	v_mul_f32_e32 v99, 0xbfb8aa3b, v99
	v_exp_f32_e32 v99, v99
	s_nop 0
	v_add_f32_e32 v99, 1.0, v99
	v_rcp_f32_e32 v99, v99
	v_mov_b32_e32 v101, v105
	v_cvt_pk_bf16_f32 v98, v100, v98
	v_lshlrev_b32_e32 v100, 16, v115
	v_mul_f32_e32 v100, v101, v100
	v_and_b32_e32 v101, 0xffff0000, v115
	v_mul_f32_e32 v99, v99, v101
	v_cvt_pk_bf16_f32 v99, v100, v99
	global_store_dwordx4 v[116:117], v[96:99], off offset:3328
	global_load_dwordx4 v[96:99], v[138:139], off offset:2048
	s_nop 0
	global_load_dwordx4 v[100:103], v[138:139], off offset:2064
	v_or_b32_e32 v108, 32, v142
	v_ashrrev_i32_e32 v109, 31, v108
	v_lshlrev_b64 v[104:105], 10, v[108:109]
	v_lshl_add_u64 v[104:105], s[24:25], 0, v[104:105]
	v_lshl_add_u64 v[110:111], v[104:105], 0, v[140:141]
	global_load_dwordx4 v[104:107], v[110:111], off
	s_waitcnt vmcnt(0)
	v_pk_add_f32 v[92:93], v[92:93], v[96:97]
	s_nop 0
	v_mul_f32_e32 v92, 0xbfb8aa3b, v92
	v_exp_f32_e32 v92, v92
	v_lshlrev_b64 v[96:97], 12, v[108:109]
	v_pk_add_f32 v[94:95], v[94:95], v[98:99]
	v_pk_add_f32 v[98:99], v[88:89], v[100:101]
	v_add_f32_e32 v92, 1.0, v92
	v_rcp_f32_e32 v89, v92
	v_mul_f32_e32 v93, 0xbfb8aa3b, v93
	v_exp_f32_e32 v93, v93
	v_pk_add_f32 v[90:91], v[90:91], v[102:103]
	v_add_f32_e32 v93, 1.0, v93
	v_rcp_f32_e32 v101, v93
	v_mul_f32_e32 v94, 0xbfb8aa3b, v94
	v_exp_f32_e32 v94, v94
	v_mov_b32_e32 v92, v101
	v_add_f32_e32 v93, 1.0, v94
	v_lshlrev_b32_e32 v88, 16, v104
	v_mul_f32_e32 v88, v89, v88
	v_and_b32_e32 v89, 0xffff0000, v104
	v_mul_f32_e32 v89, v92, v89
	v_mul_f32_e32 v95, 0xbfb8aa3b, v95
	v_exp_f32_e32 v95, v95
	s_nop 0
	v_add_f32_e32 v94, 1.0, v95
	v_rcp_f32_e32 v100, v94
	v_rcp_f32_e32 v92, v93
	v_cvt_pk_bf16_f32 v88, v88, v89
	v_lshlrev_b32_e32 v89, 16, v105
	v_mul_f32_e32 v95, 0xbfb8aa3b, v98
	v_exp_f32_e32 v95, v95
	v_mov_b32_e32 v93, v100
	v_mul_f32_e32 v89, v92, v89
	v_add_f32_e32 v94, 1.0, v95
	v_and_b32_e32 v92, 0xffff0000, v105
	v_mul_f32_e32 v92, v93, v92
	v_mul_f32_e32 v99, 0xbfb8aa3b, v99
	v_exp_f32_e32 v99, v99
	s_nop 0
	v_add_f32_e32 v95, 1.0, v99
	v_rcp_f32_e32 v99, v95
	v_rcp_f32_e32 v93, v94
	v_mul_f32_e32 v90, 0xbfb8aa3b, v90
	v_exp_f32_e32 v90, v90
	v_mov_b32_e32 v94, v99
	v_add_f32_e32 v95, 1.0, v90
	v_rcp_f32_e32 v99, v95
	v_cvt_pk_bf16_f32 v89, v89, v92
	v_lshlrev_b32_e32 v92, 16, v106
	v_mul_f32_e32 v92, v93, v92
	v_and_b32_e32 v93, 0xffff0000, v106
	v_mul_f32_e32 v90, v94, v93
	v_mul_f32_e32 v91, 0xbfb8aa3b, v91
	v_exp_f32_e32 v91, v91
	s_nop 0
	v_add_f32_e32 v91, 1.0, v91
	v_rcp_f32_e32 v91, v91
	v_mov_b32_e32 v93, v99
	v_cvt_pk_bf16_f32 v90, v92, v90
	v_lshlrev_b32_e32 v92, 16, v107
	v_mul_f32_e32 v92, v93, v92
	v_and_b32_e32 v93, 0xffff0000, v107
	v_mul_f32_e32 v91, v91, v93
	v_cvt_pk_bf16_f32 v91, v92, v91
	v_lshl_add_u64 v[92:93], s[26:27], 0, v[96:97]
	v_lshl_add_u64 v[100:101], v[92:93], 0, v[140:141]
	global_store_dwordx4 v[100:101], v[88:91], off offset:3072
	global_load_dwordx4 v[88:91], v[138:139], off offset:2560
	s_nop 0
	global_load_dwordx4 v[92:95], v[138:139], off offset:2576
	global_load_dwordx4 v[96:99], v[110:111], off offset:256
	s_waitcnt vmcnt(0)
; __device__ __forceinline__ unsigned cvt_pk_bf16(float lo, float hi) { unsigned r; asm("v_cvt_pk_bf16_f32 %0, %1, %2" : "=v"(r) : "v"(lo), "v"(hi)); return r; }
; __device__ __forceinline__ float bflo(unsigned w) { return __uint_as_float(w << 16); }
; __device__ __forceinline__ float bfhi(unsigned w) { return __uint_as_float(w & 0xffff0000u); }
; __device__ __forceinline__ float sigmoidf_(float x) { return 1.f / (1.f + __expf(-x)); }
;     __device__ __forceinline__ void operator()(const f32x4 (&acc)[2][2][4][2], const pg8::Unit& u, int wr_, int wc_, int fr_, int fq_) const {
;     ...
;         for (int ai = 0; ai < 2; ++ai)
; #pragma unroll
;             for (int m = 0; m < 4; ++m) { const int row = row0 + ai * 128 + m * 16;
; #pragma unroll
;                 for (int bj = 0; bj < 2; ++bj) { const int col = col0 + bj * 128;
;                     const f32x4 b0 = *(const f32x4*)(bias + col), b1 = *(const f32x4*)(bias + col + 4);
;                     const f32x4 v0 = acc[ai][bj][m][0] + b0, v1 = acc[ai][bj][m][1] + b1;
;                     const u32x4 z = *(const u32x4*)(Z + (size_t)row * 512 + col);
;                     u32x4 w;
;                     w.x = cvt_pk_bf16(bflo(z.x) * sigmoidf_(v0[0]), bfhi(z.x) * sigmoidf_(v0[1]));
;                     w.y = cvt_pk_bf16(bflo(z.y) * sigmoidf_(v0[2]), bfhi(z.y) * sigmoidf_(v0[3]));
;                     w.z = cvt_pk_bf16(bflo(z.z) * sigmoidf_(v1[0]), bfhi(z.z) * sigmoidf_(v1[1]));
;                     w.w = cvt_pk_bf16(bflo(z.w) * sigmoidf_(v1[2]), bfhi(z.w) * sigmoidf_(v1[3]));
;                     *(u32x4*)(MIX + (size_t)row * 2048 + 1536 + col) = w; } }
	v_pk_add_f32 v[84:85], v[84:85], v[88:89]
	s_nop 0
	v_mul_f32_e32 v84, 0xbfb8aa3b, v84
	v_exp_f32_e32 v84, v84
	v_pk_add_f32 v[86:87], v[86:87], v[90:91]
	v_mul_f32_e32 v85, 0xbfb8aa3b, v85
	v_pk_add_f32 v[88:89], v[80:81], v[92:93]
	v_add_f32_e32 v84, 1.0, v84
	v_rcp_f32_e32 v81, v84
	v_exp_f32_e32 v85, v85
	v_mul_f32_e32 v86, 0xbfb8aa3b, v86
	v_exp_f32_e32 v86, v86
	v_add_f32_e32 v85, 1.0, v85
	v_rcp_f32_e32 v91, v85
	v_lshlrev_b32_e32 v80, 16, v96
	v_mul_f32_e32 v80, v81, v80
	v_mov_b32_e32 v84, v91
	v_add_f32_e32 v85, 1.0, v86
	v_and_b32_e32 v81, 0xffff0000, v96
	v_mul_f32_e32 v81, v84, v81
	v_mul_f32_e32 v87, 0xbfb8aa3b, v87
	v_exp_f32_e32 v87, v87
	s_nop 0
	v_add_f32_e32 v86, 1.0, v87
	v_rcp_f32_e32 v90, v86
	v_rcp_f32_e32 v84, v85
	v_cvt_pk_bf16_f32 v80, v80, v81
	v_lshlrev_b32_e32 v81, 16, v97
	v_mul_f32_e32 v87, 0xbfb8aa3b, v88
	v_exp_f32_e32 v87, v87
	v_mov_b32_e32 v85, v90
	v_mul_f32_e32 v81, v84, v81
	v_add_f32_e32 v86, 1.0, v87
	v_and_b32_e32 v84, 0xffff0000, v97
	v_mul_f32_e32 v84, v85, v84
	v_mul_f32_e32 v89, 0xbfb8aa3b, v89
	v_exp_f32_e32 v89, v89
	s_nop 0
	v_add_f32_e32 v87, 1.0, v89
	v_rcp_f32_e32 v89, v87
	v_rcp_f32_e32 v85, v86
	v_pk_add_f32 v[82:83], v[82:83], v[94:95]
	v_cvt_pk_bf16_f32 v81, v81, v84
	v_mul_f32_e32 v82, 0xbfb8aa3b, v82
	v_exp_f32_e32 v82, v82
	v_mov_b32_e32 v86, v89
	v_add_f32_e32 v87, 1.0, v82
	v_rcp_f32_e32 v89, v87
	v_lshlrev_b32_e32 v84, 16, v98
	v_mul_f32_e32 v84, v85, v84
	v_and_b32_e32 v85, 0xffff0000, v98
	v_mul_f32_e32 v82, v86, v85
	v_mul_f32_e32 v83, 0xbfb8aa3b, v83
	v_exp_f32_e32 v83, v83
	s_nop 0
	v_add_f32_e32 v83, 1.0, v83
	v_rcp_f32_e32 v83, v83
	v_mov_b32_e32 v85, v89
	v_cvt_pk_bf16_f32 v82, v84, v82
	v_lshlrev_b32_e32 v84, 16, v99
	v_mul_f32_e32 v84, v85, v84
	v_and_b32_e32 v85, 0xffff0000, v99
	v_mul_f32_e32 v83, v83, v85
	v_cvt_pk_bf16_f32 v83, v84, v83
	global_store_dwordx4 v[100:101], v[80:83], off offset:3328
	global_load_dwordx4 v[80:83], v[138:139], off offset:2048
	s_nop 0
	global_load_dwordx4 v[84:87], v[138:139], off offset:2064
	v_or_b32_e32 v92, 48, v142
	v_ashrrev_i32_e32 v93, 31, v92
	v_lshlrev_b64 v[88:89], 10, v[92:93]
	v_lshl_add_u64 v[88:89], s[24:25], 0, v[88:89]
	v_lshl_add_u64 v[94:95], v[88:89], 0, v[140:141]
	global_load_dwordx4 v[88:91], v[94:95], off
	s_waitcnt vmcnt(0)
	v_pk_add_f32 v[76:77], v[76:77], v[80:81]
	s_nop 0
	v_mul_f32_e32 v76, 0xbfb8aa3b, v76
	v_exp_f32_e32 v76, v76
	v_lshlrev_b64 v[80:81], 12, v[92:93]
	v_pk_add_f32 v[78:79], v[78:79], v[82:83]
	v_pk_add_f32 v[82:83], v[72:73], v[84:85]
	v_add_f32_e32 v76, 1.0, v76
	v_rcp_f32_e32 v73, v76
	v_mul_f32_e32 v77, 0xbfb8aa3b, v77
	v_exp_f32_e32 v77, v77
	v_pk_add_f32 v[74:75], v[74:75], v[86:87]
	v_add_f32_e32 v77, 1.0, v77
	v_rcp_f32_e32 v85, v77
	v_mul_f32_e32 v78, 0xbfb8aa3b, v78
	v_exp_f32_e32 v78, v78
	v_mov_b32_e32 v76, v85
	v_add_f32_e32 v77, 1.0, v78
	v_lshlrev_b32_e32 v72, 16, v88
	v_mul_f32_e32 v72, v73, v72
	v_and_b32_e32 v73, 0xffff0000, v88
	v_mul_f32_e32 v73, v76, v73
	v_mul_f32_e32 v79, 0xbfb8aa3b, v79
	v_exp_f32_e32 v79, v79
	s_nop 0
	v_add_f32_e32 v78, 1.0, v79
	v_rcp_f32_e32 v84, v78
	v_rcp_f32_e32 v76, v77
	v_cvt_pk_bf16_f32 v72, v72, v73
	v_lshlrev_b32_e32 v73, 16, v89
	v_mul_f32_e32 v79, 0xbfb8aa3b, v82
	v_exp_f32_e32 v79, v79
	v_mov_b32_e32 v77, v84
	v_mul_f32_e32 v73, v76, v73
	v_add_f32_e32 v78, 1.0, v79
	v_and_b32_e32 v76, 0xffff0000, v89
	v_mul_f32_e32 v76, v77, v76
	v_mul_f32_e32 v83, 0xbfb8aa3b, v83
	v_exp_f32_e32 v83, v83
	s_nop 0
	v_add_f32_e32 v79, 1.0, v83
	v_rcp_f32_e32 v83, v79
	v_rcp_f32_e32 v77, v78
	v_mul_f32_e32 v74, 0xbfb8aa3b, v74
	v_exp_f32_e32 v74, v74
	v_mov_b32_e32 v78, v83
	v_add_f32_e32 v79, 1.0, v74
	v_rcp_f32_e32 v83, v79
	v_cvt_pk_bf16_f32 v73, v73, v76
	v_lshlrev_b32_e32 v76, 16, v90
	v_mul_f32_e32 v76, v77, v76
	v_and_b32_e32 v77, 0xffff0000, v90
	v_mul_f32_e32 v74, v78, v77
	v_mul_f32_e32 v75, 0xbfb8aa3b, v75
	v_exp_f32_e32 v75, v75
	s_nop 0
	v_add_f32_e32 v75, 1.0, v75
	v_rcp_f32_e32 v75, v75
	v_mov_b32_e32 v77, v83
	v_cvt_pk_bf16_f32 v74, v76, v74
	v_lshlrev_b32_e32 v76, 16, v91
	v_mul_f32_e32 v76, v77, v76
	v_and_b32_e32 v77, 0xffff0000, v91
	v_mul_f32_e32 v75, v75, v77
	v_cvt_pk_bf16_f32 v75, v76, v75
	v_lshl_add_u64 v[76:77], s[26:27], 0, v[80:81]
	v_lshl_add_u64 v[84:85], v[76:77], 0, v[140:141]
	global_store_dwordx4 v[84:85], v[72:75], off offset:3072
	global_load_dwordx4 v[72:75], v[138:139], off offset:2560
	s_nop 0
	global_load_dwordx4 v[76:79], v[138:139], off offset:2576
	global_load_dwordx4 v[80:83], v[94:95], off offset:256
	s_waitcnt vmcnt(0)
; __device__ __forceinline__ unsigned cvt_pk_bf16(float lo, float hi) { unsigned r; asm("v_cvt_pk_bf16_f32 %0, %1, %2" : "=v"(r) : "v"(lo), "v"(hi)); return r; }
; __device__ __forceinline__ float bflo(unsigned w) { return __uint_as_float(w << 16); }
; __device__ __forceinline__ float bfhi(unsigned w) { return __uint_as_float(w & 0xffff0000u); }
; __device__ __forceinline__ float sigmoidf_(float x) { return 1.f / (1.f + __expf(-x)); }
;     __device__ __forceinline__ void operator()(const f32x4 (&acc)[2][2][4][2], const pg8::Unit& u, int wr_, int wc_, int fr_, int fq_) const {
;     ...
;         for (int ai = 0; ai < 2; ++ai)
; #pragma unroll
;             for (int m = 0; m < 4; ++m) { const int row = row0 + ai * 128 + m * 16;
; #pragma unroll
;                 for (int bj = 0; bj < 2; ++bj) { const int col = col0 + bj * 128;
;                     const f32x4 b0 = *(const f32x4*)(bias + col), b1 = *(const f32x4*)(bias + col + 4);
;                     const f32x4 v0 = acc[ai][bj][m][0] + b0, v1 = acc[ai][bj][m][1] + b1;
;                     const u32x4 z = *(const u32x4*)(Z + (size_t)row * 512 + col);
;                     u32x4 w;
;                     w.x = cvt_pk_bf16(bflo(z.x) * sigmoidf_(v0[0]), bfhi(z.x) * sigmoidf_(v0[1]));
;                     w.y = cvt_pk_bf16(bflo(z.y) * sigmoidf_(v0[2]), bfhi(z.y) * sigmoidf_(v0[3]));
;                     w.z = cvt_pk_bf16(bflo(z.z) * sigmoidf_(v1[0]), bfhi(z.z) * sigmoidf_(v1[1]));
;                     w.w = cvt_pk_bf16(bflo(z.w) * sigmoidf_(v1[2]), bfhi(z.w) * sigmoidf_(v1[3]));
;                     *(u32x4*)(MIX + (size_t)row * 2048 + 1536 + col) = w; } }
	v_pk_add_f32 v[68:69], v[68:69], v[72:73]
	s_nop 0
	v_mul_f32_e32 v68, 0xbfb8aa3b, v68
	v_exp_f32_e32 v68, v68
	v_pk_add_f32 v[70:71], v[70:71], v[74:75]
	v_mul_f32_e32 v69, 0xbfb8aa3b, v69
	v_pk_add_f32 v[72:73], v[64:65], v[76:77]
	v_add_f32_e32 v68, 1.0, v68
	v_rcp_f32_e32 v65, v68
	v_exp_f32_e32 v69, v69
	v_mul_f32_e32 v70, 0xbfb8aa3b, v70
	v_exp_f32_e32 v70, v70
	v_add_f32_e32 v69, 1.0, v69
	v_rcp_f32_e32 v75, v69
	v_lshlrev_b32_e32 v64, 16, v80
	v_mul_f32_e32 v64, v65, v64
	v_mov_b32_e32 v68, v75
	v_add_f32_e32 v69, 1.0, v70
	v_and_b32_e32 v65, 0xffff0000, v80
	v_mul_f32_e32 v65, v68, v65
	v_mul_f32_e32 v71, 0xbfb8aa3b, v71
	v_exp_f32_e32 v71, v71
	s_nop 0
	v_add_f32_e32 v70, 1.0, v71
	v_rcp_f32_e32 v74, v70
	v_rcp_f32_e32 v68, v69
	v_cvt_pk_bf16_f32 v64, v64, v65
	v_lshlrev_b32_e32 v65, 16, v81
	v_mul_f32_e32 v71, 0xbfb8aa3b, v72
	v_exp_f32_e32 v71, v71
	v_mov_b32_e32 v69, v74
	v_mul_f32_e32 v65, v68, v65
	v_add_f32_e32 v70, 1.0, v71
	v_and_b32_e32 v68, 0xffff0000, v81
	v_mul_f32_e32 v68, v69, v68
	v_mul_f32_e32 v73, 0xbfb8aa3b, v73
	v_exp_f32_e32 v73, v73
	s_nop 0
	v_add_f32_e32 v71, 1.0, v73
	v_rcp_f32_e32 v73, v71
	v_rcp_f32_e32 v69, v70
	v_pk_add_f32 v[66:67], v[66:67], v[78:79]
	v_cvt_pk_bf16_f32 v65, v65, v68
	v_mul_f32_e32 v66, 0xbfb8aa3b, v66
	v_exp_f32_e32 v66, v66
	v_mov_b32_e32 v70, v73
	v_add_f32_e32 v71, 1.0, v66
	v_rcp_f32_e32 v73, v71
	v_lshlrev_b32_e32 v68, 16, v82
	v_mul_f32_e32 v68, v69, v68
	v_and_b32_e32 v69, 0xffff0000, v82
	v_mul_f32_e32 v66, v70, v69
	v_mul_f32_e32 v67, 0xbfb8aa3b, v67
	v_exp_f32_e32 v67, v67
	s_nop 0
	v_add_f32_e32 v67, 1.0, v67
	v_rcp_f32_e32 v67, v67
	v_mov_b32_e32 v69, v73
	v_cvt_pk_bf16_f32 v66, v68, v66
	v_lshlrev_b32_e32 v68, 16, v83
	v_mul_f32_e32 v68, v69, v68
	v_and_b32_e32 v69, 0xffff0000, v83
	v_mul_f32_e32 v67, v67, v69
	v_cvt_pk_bf16_f32 v67, v68, v67
	global_store_dwordx4 v[84:85], v[64:67], off offset:3328
	global_load_dwordx4 v[64:67], v[138:139], off offset:2048
	s_nop 0
	global_load_dwordx4 v[68:71], v[138:139], off offset:2064
	v_add_u32_e32 v76, 0x80, v142
	v_ashrrev_i32_e32 v77, 31, v76
	v_lshlrev_b64 v[72:73], 10, v[76:77]
	v_lshl_add_u64 v[72:73], s[24:25], 0, v[72:73]
	v_lshl_add_u64 v[78:79], v[72:73], 0, v[140:141]
	global_load_dwordx4 v[72:75], v[78:79], off
	s_waitcnt vmcnt(0)
	v_pk_add_f32 v[60:61], v[60:61], v[64:65]
	s_nop 0
	v_mul_f32_e32 v60, 0xbfb8aa3b, v60
	v_exp_f32_e32 v60, v60
	v_lshlrev_b64 v[64:65], 12, v[76:77]
	v_pk_add_f32 v[62:63], v[62:63], v[66:67]
	v_pk_add_f32 v[66:67], v[56:57], v[68:69]
	v_add_f32_e32 v60, 1.0, v60
	v_rcp_f32_e32 v57, v60
	v_mul_f32_e32 v61, 0xbfb8aa3b, v61
	v_exp_f32_e32 v61, v61
	v_pk_add_f32 v[58:59], v[58:59], v[70:71]
	v_add_f32_e32 v61, 1.0, v61
	v_rcp_f32_e32 v69, v61
	v_mul_f32_e32 v62, 0xbfb8aa3b, v62
	v_exp_f32_e32 v62, v62
	v_mov_b32_e32 v60, v69
	v_add_f32_e32 v61, 1.0, v62
	v_lshlrev_b32_e32 v56, 16, v72
	v_mul_f32_e32 v56, v57, v56
	v_and_b32_e32 v57, 0xffff0000, v72
	v_mul_f32_e32 v57, v60, v57
	v_mul_f32_e32 v63, 0xbfb8aa3b, v63
	v_exp_f32_e32 v63, v63
	s_nop 0
	v_add_f32_e32 v62, 1.0, v63
	v_rcp_f32_e32 v68, v62
	v_rcp_f32_e32 v60, v61
	v_cvt_pk_bf16_f32 v56, v56, v57
	v_lshlrev_b32_e32 v57, 16, v73
	v_mul_f32_e32 v63, 0xbfb8aa3b, v66
	v_exp_f32_e32 v63, v63
	v_mov_b32_e32 v61, v68
	v_mul_f32_e32 v57, v60, v57
	v_add_f32_e32 v62, 1.0, v63
	v_and_b32_e32 v60, 0xffff0000, v73
	v_mul_f32_e32 v60, v61, v60
	v_mul_f32_e32 v67, 0xbfb8aa3b, v67
	v_exp_f32_e32 v67, v67
	s_nop 0
	v_add_f32_e32 v63, 1.0, v67
	v_rcp_f32_e32 v67, v63
	v_rcp_f32_e32 v61, v62
	v_mul_f32_e32 v58, 0xbfb8aa3b, v58
	v_exp_f32_e32 v58, v58
	v_mov_b32_e32 v62, v67
	v_add_f32_e32 v63, 1.0, v58
	v_rcp_f32_e32 v67, v63
	v_cvt_pk_bf16_f32 v57, v57, v60
	v_lshlrev_b32_e32 v60, 16, v74
	v_mul_f32_e32 v60, v61, v60
	v_and_b32_e32 v61, 0xffff0000, v74
	v_mul_f32_e32 v58, v62, v61
	v_mul_f32_e32 v59, 0xbfb8aa3b, v59
	v_exp_f32_e32 v59, v59
	s_nop 0
	v_add_f32_e32 v59, 1.0, v59
	v_rcp_f32_e32 v59, v59
	v_mov_b32_e32 v61, v67
	v_cvt_pk_bf16_f32 v58, v60, v58
	v_lshlrev_b32_e32 v60, 16, v75
	v_mul_f32_e32 v60, v61, v60
	v_and_b32_e32 v61, 0xffff0000, v75
	v_mul_f32_e32 v59, v59, v61
	v_cvt_pk_bf16_f32 v59, v60, v59
	v_lshl_add_u64 v[60:61], s[26:27], 0, v[64:65]
	v_lshl_add_u64 v[68:69], v[60:61], 0, v[140:141]
	global_store_dwordx4 v[68:69], v[56:59], off offset:3072
	global_load_dwordx4 v[56:59], v[138:139], off offset:2560
	s_nop 0
	global_load_dwordx4 v[60:63], v[138:139], off offset:2576
	global_load_dwordx4 v[64:67], v[78:79], off offset:256
	s_waitcnt vmcnt(0)
; __device__ __forceinline__ unsigned cvt_pk_bf16(float lo, float hi) { unsigned r; asm("v_cvt_pk_bf16_f32 %0, %1, %2" : "=v"(r) : "v"(lo), "v"(hi)); return r; }
; __device__ __forceinline__ float bflo(unsigned w) { return __uint_as_float(w << 16); }
; __device__ __forceinline__ float bfhi(unsigned w) { return __uint_as_float(w & 0xffff0000u); }
; __device__ __forceinline__ float sigmoidf_(float x) { return 1.f / (1.f + __expf(-x)); }
;     __device__ __forceinline__ void operator()(const f32x4 (&acc)[2][2][4][2], const pg8::Unit& u, int wr_, int wc_, int fr_, int fq_) const {
;     ...
;         for (int ai = 0; ai < 2; ++ai)
; #pragma unroll
;             for (int m = 0; m < 4; ++m) { const int row = row0 + ai * 128 + m * 16;
; #pragma unroll
;                 for (int bj = 0; bj < 2; ++bj) { const int col = col0 + bj * 128;
;                     const f32x4 b0 = *(const f32x4*)(bias + col), b1 = *(const f32x4*)(bias + col + 4);
;                     const f32x4 v0 = acc[ai][bj][m][0] + b0, v1 = acc[ai][bj][m][1] + b1;
;                     const u32x4 z = *(const u32x4*)(Z + (size_t)row * 512 + col);
;                     u32x4 w;
;                     w.x = cvt_pk_bf16(bflo(z.x) * sigmoidf_(v0[0]), bfhi(z.x) * sigmoidf_(v0[1]));
;                     w.y = cvt_pk_bf16(bflo(z.y) * sigmoidf_(v0[2]), bfhi(z.y) * sigmoidf_(v0[3]));
;                     w.z = cvt_pk_bf16(bflo(z.z) * sigmoidf_(v1[0]), bfhi(z.z) * sigmoidf_(v1[1]));
;                     w.w = cvt_pk_bf16(bflo(z.w) * sigmoidf_(v1[2]), bfhi(z.w) * sigmoidf_(v1[3]));
;                     *(u32x4*)(MIX + (size_t)row * 2048 + 1536 + col) = w; } }
	v_pk_add_f32 v[52:53], v[52:53], v[56:57]
	s_nop 0
	v_mul_f32_e32 v52, 0xbfb8aa3b, v52
	v_exp_f32_e32 v52, v52
	v_pk_add_f32 v[54:55], v[54:55], v[58:59]
	v_mul_f32_e32 v53, 0xbfb8aa3b, v53
	v_pk_add_f32 v[56:57], v[48:49], v[60:61]
	v_add_f32_e32 v52, 1.0, v52
	v_rcp_f32_e32 v49, v52
	v_exp_f32_e32 v53, v53
	v_mul_f32_e32 v54, 0xbfb8aa3b, v54
	v_exp_f32_e32 v54, v54
	v_add_f32_e32 v53, 1.0, v53
	v_rcp_f32_e32 v59, v53
	v_lshlrev_b32_e32 v48, 16, v64
	v_mul_f32_e32 v48, v49, v48
	v_mov_b32_e32 v52, v59
	v_add_f32_e32 v53, 1.0, v54
	v_and_b32_e32 v49, 0xffff0000, v64
	v_mul_f32_e32 v49, v52, v49
	v_mul_f32_e32 v55, 0xbfb8aa3b, v55
	v_exp_f32_e32 v55, v55
	s_nop 0
	v_add_f32_e32 v54, 1.0, v55
	v_rcp_f32_e32 v58, v54
	v_rcp_f32_e32 v52, v53
	v_cvt_pk_bf16_f32 v48, v48, v49
	v_lshlrev_b32_e32 v49, 16, v65
	v_mul_f32_e32 v55, 0xbfb8aa3b, v56
	v_exp_f32_e32 v55, v55
	v_mov_b32_e32 v53, v58
	v_mul_f32_e32 v49, v52, v49
	v_add_f32_e32 v54, 1.0, v55
	v_and_b32_e32 v52, 0xffff0000, v65
	v_mul_f32_e32 v52, v53, v52
	v_mul_f32_e32 v57, 0xbfb8aa3b, v57
	v_exp_f32_e32 v57, v57
	s_nop 0
	v_add_f32_e32 v55, 1.0, v57
	v_rcp_f32_e32 v57, v55
	v_rcp_f32_e32 v53, v54
	v_pk_add_f32 v[50:51], v[50:51], v[62:63]
	v_cvt_pk_bf16_f32 v49, v49, v52
	v_mul_f32_e32 v50, 0xbfb8aa3b, v50
	v_exp_f32_e32 v50, v50
	v_mov_b32_e32 v54, v57
	v_add_f32_e32 v55, 1.0, v50
	v_rcp_f32_e32 v57, v55
	v_lshlrev_b32_e32 v52, 16, v66
	v_mul_f32_e32 v52, v53, v52
	v_and_b32_e32 v53, 0xffff0000, v66
	v_mul_f32_e32 v50, v54, v53
	v_mul_f32_e32 v51, 0xbfb8aa3b, v51
	v_exp_f32_e32 v51, v51
	s_nop 0
	v_add_f32_e32 v51, 1.0, v51
	v_rcp_f32_e32 v51, v51
	v_mov_b32_e32 v53, v57
	v_cvt_pk_bf16_f32 v50, v52, v50
	v_lshlrev_b32_e32 v52, 16, v67
	v_mul_f32_e32 v52, v53, v52
	v_and_b32_e32 v53, 0xffff0000, v67
	v_mul_f32_e32 v51, v51, v53
	v_cvt_pk_bf16_f32 v51, v52, v51
	global_store_dwordx4 v[68:69], v[48:51], off offset:3328
	global_load_dwordx4 v[48:51], v[138:139], off offset:2048
	s_nop 0
	global_load_dwordx4 v[52:55], v[138:139], off offset:2064
	v_add_u32_e32 v60, 0x90, v142
	v_ashrrev_i32_e32 v61, 31, v60
	v_lshlrev_b64 v[56:57], 10, v[60:61]
	v_lshl_add_u64 v[56:57], s[24:25], 0, v[56:57]
	v_lshl_add_u64 v[62:63], v[56:57], 0, v[140:141]
	global_load_dwordx4 v[56:59], v[62:63], off
	s_waitcnt vmcnt(0)
	v_pk_add_f32 v[44:45], v[44:45], v[48:49]
	s_nop 0
	v_mul_f32_e32 v44, 0xbfb8aa3b, v44
	v_exp_f32_e32 v44, v44
	v_lshlrev_b64 v[48:49], 12, v[60:61]
	v_pk_add_f32 v[46:47], v[46:47], v[50:51]
	v_pk_add_f32 v[50:51], v[40:41], v[52:53]
	v_add_f32_e32 v44, 1.0, v44
	v_rcp_f32_e32 v41, v44
	v_mul_f32_e32 v45, 0xbfb8aa3b, v45
	v_exp_f32_e32 v45, v45
	v_pk_add_f32 v[42:43], v[42:43], v[54:55]
	v_add_f32_e32 v45, 1.0, v45
	v_rcp_f32_e32 v53, v45
	v_mul_f32_e32 v46, 0xbfb8aa3b, v46
	v_exp_f32_e32 v46, v46
	v_mov_b32_e32 v44, v53
	v_add_f32_e32 v45, 1.0, v46
	v_lshlrev_b32_e32 v40, 16, v56
	v_mul_f32_e32 v40, v41, v40
	v_and_b32_e32 v41, 0xffff0000, v56
	v_mul_f32_e32 v41, v44, v41
	v_mul_f32_e32 v47, 0xbfb8aa3b, v47
	v_exp_f32_e32 v47, v47
	s_nop 0
	v_add_f32_e32 v46, 1.0, v47
	v_rcp_f32_e32 v52, v46
	v_rcp_f32_e32 v44, v45
	v_cvt_pk_bf16_f32 v40, v40, v41
	v_lshlrev_b32_e32 v41, 16, v57
	v_mul_f32_e32 v47, 0xbfb8aa3b, v50
	v_exp_f32_e32 v47, v47
	v_mov_b32_e32 v45, v52
	v_mul_f32_e32 v41, v44, v41
	v_add_f32_e32 v46, 1.0, v47
	v_and_b32_e32 v44, 0xffff0000, v57
	v_mul_f32_e32 v44, v45, v44
	v_mul_f32_e32 v51, 0xbfb8aa3b, v51
	v_exp_f32_e32 v51, v51
	s_nop 0
	v_add_f32_e32 v47, 1.0, v51
	v_rcp_f32_e32 v51, v47
	v_rcp_f32_e32 v45, v46
	v_mul_f32_e32 v42, 0xbfb8aa3b, v42
	v_exp_f32_e32 v42, v42
	v_mov_b32_e32 v46, v51
	v_add_f32_e32 v47, 1.0, v42
	v_rcp_f32_e32 v51, v47
	v_cvt_pk_bf16_f32 v41, v41, v44
	v_lshlrev_b32_e32 v44, 16, v58
	v_mul_f32_e32 v44, v45, v44
	v_and_b32_e32 v45, 0xffff0000, v58
	v_mul_f32_e32 v42, v46, v45
	v_mul_f32_e32 v43, 0xbfb8aa3b, v43
	v_exp_f32_e32 v43, v43
	s_nop 0
	v_add_f32_e32 v43, 1.0, v43
	v_rcp_f32_e32 v43, v43
	v_mov_b32_e32 v45, v51
	v_cvt_pk_bf16_f32 v42, v44, v42
	v_lshlrev_b32_e32 v44, 16, v59
	v_mul_f32_e32 v44, v45, v44
	v_and_b32_e32 v45, 0xffff0000, v59
	v_mul_f32_e32 v43, v43, v45
	v_cvt_pk_bf16_f32 v43, v44, v43
	v_lshl_add_u64 v[44:45], s[26:27], 0, v[48:49]
	v_lshl_add_u64 v[52:53], v[44:45], 0, v[140:141]
	global_store_dwordx4 v[52:53], v[40:43], off offset:3072
	global_load_dwordx4 v[40:43], v[138:139], off offset:2560
	s_nop 0
	global_load_dwordx4 v[44:47], v[138:139], off offset:2576
	global_load_dwordx4 v[48:51], v[62:63], off offset:256
	s_waitcnt vmcnt(0)
; __device__ __forceinline__ unsigned cvt_pk_bf16(float lo, float hi) { unsigned r; asm("v_cvt_pk_bf16_f32 %0, %1, %2" : "=v"(r) : "v"(lo), "v"(hi)); return r; }
; __device__ __forceinline__ float bflo(unsigned w) { return __uint_as_float(w << 16); }
; __device__ __forceinline__ float bfhi(unsigned w) { return __uint_as_float(w & 0xffff0000u); }
; __device__ __forceinline__ float sigmoidf_(float x) { return 1.f / (1.f + __expf(-x)); }
;     __device__ __forceinline__ void operator()(const f32x4 (&acc)[2][2][4][2], const pg8::Unit& u, int wr_, int wc_, int fr_, int fq_) const {
;     ...
;         for (int ai = 0; ai < 2; ++ai)
; #pragma unroll
;             for (int m = 0; m < 4; ++m) { const int row = row0 + ai * 128 + m * 16;
; #pragma unroll
;                 for (int bj = 0; bj < 2; ++bj) { const int col = col0 + bj * 128;
;                     const f32x4 b0 = *(const f32x4*)(bias + col), b1 = *(const f32x4*)(bias + col + 4);
;                     const f32x4 v0 = acc[ai][bj][m][0] + b0, v1 = acc[ai][bj][m][1] + b1;
;                     const u32x4 z = *(const u32x4*)(Z + (size_t)row * 512 + col);
;                     u32x4 w;
;                     w.x = cvt_pk_bf16(bflo(z.x) * sigmoidf_(v0[0]), bfhi(z.x) * sigmoidf_(v0[1]));
;                     w.y = cvt_pk_bf16(bflo(z.y) * sigmoidf_(v0[2]), bfhi(z.y) * sigmoidf_(v0[3]));
;                     w.z = cvt_pk_bf16(bflo(z.z) * sigmoidf_(v1[0]), bfhi(z.z) * sigmoidf_(v1[1]));
;                     w.w = cvt_pk_bf16(bflo(z.w) * sigmoidf_(v1[2]), bfhi(z.w) * sigmoidf_(v1[3]));
;                     *(u32x4*)(MIX + (size_t)row * 2048 + 1536 + col) = w; } }
	v_pk_add_f32 v[36:37], v[36:37], v[40:41]
	s_nop 0
	v_mul_f32_e32 v36, 0xbfb8aa3b, v36
	v_exp_f32_e32 v36, v36
	v_pk_add_f32 v[38:39], v[38:39], v[42:43]
	v_mul_f32_e32 v37, 0xbfb8aa3b, v37
	v_pk_add_f32 v[40:41], v[32:33], v[44:45]
	v_add_f32_e32 v36, 1.0, v36
	v_rcp_f32_e32 v33, v36
	v_exp_f32_e32 v37, v37
	v_mul_f32_e32 v38, 0xbfb8aa3b, v38
	v_exp_f32_e32 v38, v38
	v_add_f32_e32 v37, 1.0, v37
	v_rcp_f32_e32 v43, v37
	v_lshlrev_b32_e32 v32, 16, v48
	v_mul_f32_e32 v32, v33, v32
	v_mov_b32_e32 v36, v43
	v_add_f32_e32 v37, 1.0, v38
	v_and_b32_e32 v33, 0xffff0000, v48
	v_mul_f32_e32 v33, v36, v33
	v_mul_f32_e32 v39, 0xbfb8aa3b, v39
	v_exp_f32_e32 v39, v39
	s_nop 0
	v_add_f32_e32 v38, 1.0, v39
	v_rcp_f32_e32 v42, v38
	v_rcp_f32_e32 v36, v37
	v_cvt_pk_bf16_f32 v32, v32, v33
	v_lshlrev_b32_e32 v33, 16, v49
	v_mul_f32_e32 v39, 0xbfb8aa3b, v40
	v_exp_f32_e32 v39, v39
	v_mov_b32_e32 v37, v42
	v_mul_f32_e32 v33, v36, v33
	v_add_f32_e32 v38, 1.0, v39
	v_and_b32_e32 v36, 0xffff0000, v49
	v_mul_f32_e32 v36, v37, v36
	v_mul_f32_e32 v41, 0xbfb8aa3b, v41
	v_exp_f32_e32 v41, v41
	s_nop 0
	v_add_f32_e32 v39, 1.0, v41
	v_rcp_f32_e32 v41, v39
	v_rcp_f32_e32 v37, v38
	v_pk_add_f32 v[34:35], v[34:35], v[46:47]
	v_cvt_pk_bf16_f32 v33, v33, v36
	v_mul_f32_e32 v34, 0xbfb8aa3b, v34
	v_exp_f32_e32 v34, v34
	v_mov_b32_e32 v38, v41
	v_add_f32_e32 v39, 1.0, v34
	v_rcp_f32_e32 v41, v39
	v_lshlrev_b32_e32 v36, 16, v50
	v_mul_f32_e32 v36, v37, v36
	v_and_b32_e32 v37, 0xffff0000, v50
	v_mul_f32_e32 v34, v38, v37
	v_mul_f32_e32 v35, 0xbfb8aa3b, v35
	v_exp_f32_e32 v35, v35
	s_nop 0
	v_add_f32_e32 v35, 1.0, v35
	v_rcp_f32_e32 v35, v35
	v_mov_b32_e32 v37, v41
	v_cvt_pk_bf16_f32 v34, v36, v34
	v_lshlrev_b32_e32 v36, 16, v51
	v_mul_f32_e32 v36, v37, v36
	v_and_b32_e32 v37, 0xffff0000, v51
	v_mul_f32_e32 v35, v35, v37
	v_cvt_pk_bf16_f32 v35, v36, v35
	global_store_dwordx4 v[52:53], v[32:35], off offset:3328
	global_load_dwordx4 v[32:35], v[138:139], off offset:2048
	s_nop 0
	global_load_dwordx4 v[36:39], v[138:139], off offset:2064
	v_add_u32_e32 v44, 0xa0, v142
	v_ashrrev_i32_e32 v45, 31, v44
	v_lshlrev_b64 v[40:41], 10, v[44:45]
	v_lshl_add_u64 v[40:41], s[24:25], 0, v[40:41]
	v_lshl_add_u64 v[46:47], v[40:41], 0, v[140:141]
	global_load_dwordx4 v[40:43], v[46:47], off
	s_waitcnt vmcnt(0)
	v_pk_add_f32 v[28:29], v[28:29], v[32:33]
	s_nop 0
	v_mul_f32_e32 v28, 0xbfb8aa3b, v28
	v_exp_f32_e32 v28, v28
	v_lshlrev_b64 v[32:33], 12, v[44:45]
	v_pk_add_f32 v[30:31], v[30:31], v[34:35]
	v_pk_add_f32 v[34:35], v[24:25], v[36:37]
	v_add_f32_e32 v28, 1.0, v28
	v_rcp_f32_e32 v25, v28
	v_mul_f32_e32 v29, 0xbfb8aa3b, v29
	v_exp_f32_e32 v29, v29
	v_pk_add_f32 v[26:27], v[26:27], v[38:39]
	v_add_f32_e32 v29, 1.0, v29
	v_rcp_f32_e32 v37, v29
	v_mul_f32_e32 v30, 0xbfb8aa3b, v30
	v_exp_f32_e32 v30, v30
	v_mov_b32_e32 v28, v37
	v_add_f32_e32 v29, 1.0, v30
	v_lshlrev_b32_e32 v24, 16, v40
	v_mul_f32_e32 v24, v25, v24
	v_and_b32_e32 v25, 0xffff0000, v40
	v_mul_f32_e32 v25, v28, v25
	v_mul_f32_e32 v31, 0xbfb8aa3b, v31
	v_exp_f32_e32 v31, v31
	s_nop 0
	v_add_f32_e32 v30, 1.0, v31
	v_rcp_f32_e32 v36, v30
	v_rcp_f32_e32 v28, v29
	v_cvt_pk_bf16_f32 v24, v24, v25
	v_lshlrev_b32_e32 v25, 16, v41
	v_mul_f32_e32 v31, 0xbfb8aa3b, v34
	v_exp_f32_e32 v31, v31
	v_mov_b32_e32 v29, v36
	v_mul_f32_e32 v25, v28, v25
	v_add_f32_e32 v30, 1.0, v31
	v_and_b32_e32 v28, 0xffff0000, v41
	v_mul_f32_e32 v28, v29, v28
	v_mul_f32_e32 v35, 0xbfb8aa3b, v35
	v_exp_f32_e32 v35, v35
	s_nop 0
	v_add_f32_e32 v31, 1.0, v35
	v_rcp_f32_e32 v35, v31
	v_rcp_f32_e32 v29, v30
	v_mul_f32_e32 v26, 0xbfb8aa3b, v26
	v_exp_f32_e32 v26, v26
	v_mov_b32_e32 v30, v35
	v_add_f32_e32 v31, 1.0, v26
	v_rcp_f32_e32 v35, v31
	v_cvt_pk_bf16_f32 v25, v25, v28
	v_lshlrev_b32_e32 v28, 16, v42
	v_mul_f32_e32 v28, v29, v28
	v_and_b32_e32 v29, 0xffff0000, v42
	v_mul_f32_e32 v26, v30, v29
	v_mul_f32_e32 v27, 0xbfb8aa3b, v27
	v_exp_f32_e32 v27, v27
	s_nop 0
	v_add_f32_e32 v27, 1.0, v27
	v_rcp_f32_e32 v27, v27
	v_mov_b32_e32 v29, v35
	v_cvt_pk_bf16_f32 v26, v28, v26
	v_lshlrev_b32_e32 v28, 16, v43
	v_mul_f32_e32 v28, v29, v28
	v_and_b32_e32 v29, 0xffff0000, v43
	v_mul_f32_e32 v27, v27, v29
	v_cvt_pk_bf16_f32 v27, v28, v27
	v_lshl_add_u64 v[28:29], s[26:27], 0, v[32:33]
	v_lshl_add_u64 v[36:37], v[28:29], 0, v[140:141]
	global_store_dwordx4 v[36:37], v[24:27], off offset:3072
	global_load_dwordx4 v[24:27], v[138:139], off offset:2560
	s_nop 0
	global_load_dwordx4 v[28:31], v[138:139], off offset:2576
	global_load_dwordx4 v[32:35], v[46:47], off offset:256
	s_waitcnt vmcnt(0)
; __device__ __forceinline__ unsigned cvt_pk_bf16(float lo, float hi) { unsigned r; asm("v_cvt_pk_bf16_f32 %0, %1, %2" : "=v"(r) : "v"(lo), "v"(hi)); return r; }
; __device__ __forceinline__ float bflo(unsigned w) { return __uint_as_float(w << 16); }
; __device__ __forceinline__ float bfhi(unsigned w) { return __uint_as_float(w & 0xffff0000u); }
; __device__ __forceinline__ float sigmoidf_(float x) { return 1.f / (1.f + __expf(-x)); }
; #define PG8_WAIT_V(n) asm volatile("s_waitcnt vmcnt(" #n ")" ::: "memory")
; #define PG8_BAR __builtin_amdgcn_s_barrier()
; template <class Epi, class Sched>
; __device__ __forceinline__ void gemm_phase(LAS unsigned char* lds, const Gemm g, const Sched& S, const Epi& E) {
;     ...
;         if (!has_next) break;
; #pragma unroll
;         for (int a = 0; a < 2; ++a)
; #pragma unroll
;             for (int b = 0; b < 2; ++b)
; #pragma unroll
;                 for (int m = 0; m < 4; ++m)
; #pragma unroll
;                     for (int n = 0; n < 2; ++n) acc[a][b][m][n] = (f32x4){0.f, 0.f, 0.f, 0.f};
;         cur = nxt; cA = nA; cB = nB; ++ui;
;     }
;     PG8_WAIT_V(0);
;     if (wr == 0) PG8_BAR;
;     PG8_BAR;
;     __device__ __forceinline__ void operator()(const f32x4 (&acc)[2][2][4][2], const pg8::Unit& u, int wr_, int wc_, int fr_, int fq_) const {
;     ...
;         for (int ai = 0; ai < 2; ++ai)
; #pragma unroll
;             for (int m = 0; m < 4; ++m) { const int row = row0 + ai * 128 + m * 16;
; #pragma unroll
;                 for (int bj = 0; bj < 2; ++bj) { const int col = col0 + bj * 128;
;                     const f32x4 b0 = *(const f32x4*)(bias + col), b1 = *(const f32x4*)(bias + col + 4);
;                     const f32x4 v0 = acc[ai][bj][m][0] + b0, v1 = acc[ai][bj][m][1] + b1;
;                     const u32x4 z = *(const u32x4*)(Z + (size_t)row * 512 + col);
;                     u32x4 w;
;                     w.x = cvt_pk_bf16(bflo(z.x) * sigmoidf_(v0[0]), bfhi(z.x) * sigmoidf_(v0[1]));
;                     w.y = cvt_pk_bf16(bflo(z.y) * sigmoidf_(v0[2]), bfhi(z.y) * sigmoidf_(v0[3]));
;                     w.z = cvt_pk_bf16(bflo(z.z) * sigmoidf_(v1[0]), bfhi(z.z) * sigmoidf_(v1[1]));
;                     w.w = cvt_pk_bf16(bflo(z.w) * sigmoidf_(v1[2]), bfhi(z.w) * sigmoidf_(v1[3]));
;                     *(u32x4*)(MIX + (size_t)row * 2048 + 1536 + col) = w; } }
	v_pk_add_f32 v[20:21], v[20:21], v[24:25]
	s_nop 0
	v_mul_f32_e32 v20, 0xbfb8aa3b, v20
	v_exp_f32_e32 v20, v20
	v_pk_add_f32 v[22:23], v[22:23], v[26:27]
	v_mul_f32_e32 v21, 0xbfb8aa3b, v21
	v_pk_add_f32 v[24:25], v[16:17], v[28:29]
	v_add_f32_e32 v20, 1.0, v20
	v_rcp_f32_e32 v17, v20
	v_exp_f32_e32 v21, v21
	v_mul_f32_e32 v22, 0xbfb8aa3b, v22
	v_exp_f32_e32 v22, v22
	v_add_f32_e32 v21, 1.0, v21
	v_rcp_f32_e32 v27, v21
	v_lshlrev_b32_e32 v16, 16, v32
	v_mul_f32_e32 v16, v17, v16
	v_mov_b32_e32 v20, v27
	v_add_f32_e32 v21, 1.0, v22
	v_and_b32_e32 v17, 0xffff0000, v32
	v_mul_f32_e32 v17, v20, v17
	v_mul_f32_e32 v23, 0xbfb8aa3b, v23
	v_exp_f32_e32 v23, v23
	s_nop 0
	v_add_f32_e32 v22, 1.0, v23
	v_rcp_f32_e32 v26, v22
	v_rcp_f32_e32 v20, v21
	v_cvt_pk_bf16_f32 v16, v16, v17
	v_lshlrev_b32_e32 v17, 16, v33
	v_mul_f32_e32 v23, 0xbfb8aa3b, v24
	v_exp_f32_e32 v23, v23
	v_mov_b32_e32 v21, v26
	v_mul_f32_e32 v17, v20, v17
	v_add_f32_e32 v22, 1.0, v23
	v_and_b32_e32 v20, 0xffff0000, v33
	v_mul_f32_e32 v20, v21, v20
	v_mul_f32_e32 v25, 0xbfb8aa3b, v25
	v_exp_f32_e32 v25, v25
	s_nop 0
	v_add_f32_e32 v23, 1.0, v25
	v_rcp_f32_e32 v25, v23
	v_rcp_f32_e32 v21, v22
	v_pk_add_f32 v[18:19], v[18:19], v[30:31]
	v_cvt_pk_bf16_f32 v17, v17, v20
	v_mul_f32_e32 v18, 0xbfb8aa3b, v18
	v_exp_f32_e32 v18, v18
	v_mov_b32_e32 v22, v25
	v_add_f32_e32 v23, 1.0, v18
	v_rcp_f32_e32 v25, v23
	v_lshlrev_b32_e32 v20, 16, v34
	v_mul_f32_e32 v20, v21, v20
	v_and_b32_e32 v21, 0xffff0000, v34
	v_mul_f32_e32 v18, v22, v21
	v_mul_f32_e32 v19, 0xbfb8aa3b, v19
	v_exp_f32_e32 v19, v19
	s_nop 0
	v_add_f32_e32 v19, 1.0, v19
	v_rcp_f32_e32 v19, v19
	v_mov_b32_e32 v21, v25
	v_cvt_pk_bf16_f32 v18, v20, v18
	v_lshlrev_b32_e32 v20, 16, v35
	v_mul_f32_e32 v20, v21, v20
	v_and_b32_e32 v21, 0xffff0000, v35
	v_mul_f32_e32 v19, v19, v21
	v_cvt_pk_bf16_f32 v19, v20, v19
	global_store_dwordx4 v[36:37], v[16:19], off offset:3328
	global_load_dwordx4 v[16:19], v[138:139], off offset:2048
	s_nop 0
	global_load_dwordx4 v[20:23], v[138:139], off offset:2064
	v_add_u32_e32 v28, 0xb0, v142
	v_ashrrev_i32_e32 v29, 31, v28
	v_lshlrev_b64 v[24:25], 10, v[28:29]
	v_lshl_add_u64 v[24:25], s[24:25], 0, v[24:25]
	v_lshl_add_u64 v[30:31], v[24:25], 0, v[140:141]
	global_load_dwordx4 v[24:27], v[30:31], off
	s_waitcnt vmcnt(0)
	v_pk_add_f32 v[12:13], v[12:13], v[16:17]
	s_nop 0
	v_mul_f32_e32 v12, 0xbfb8aa3b, v12
	v_exp_f32_e32 v12, v12
	v_lshlrev_b64 v[16:17], 12, v[28:29]
	v_pk_add_f32 v[14:15], v[14:15], v[18:19]
	v_pk_add_f32 v[18:19], v[8:9], v[20:21]
	v_add_f32_e32 v12, 1.0, v12
	v_rcp_f32_e32 v9, v12
	v_mul_f32_e32 v13, 0xbfb8aa3b, v13
	v_exp_f32_e32 v13, v13
	v_pk_add_f32 v[10:11], v[10:11], v[22:23]
	v_add_f32_e32 v13, 1.0, v13
	v_rcp_f32_e32 v21, v13
	v_mul_f32_e32 v14, 0xbfb8aa3b, v14
	v_exp_f32_e32 v14, v14
	v_mov_b32_e32 v12, v21
	v_add_f32_e32 v13, 1.0, v14
	v_lshlrev_b32_e32 v8, 16, v24
	v_mul_f32_e32 v8, v9, v8
	v_and_b32_e32 v9, 0xffff0000, v24
	v_mul_f32_e32 v9, v12, v9
	v_mul_f32_e32 v15, 0xbfb8aa3b, v15
	v_exp_f32_e32 v15, v15
	s_nop 0
	v_add_f32_e32 v14, 1.0, v15
	v_rcp_f32_e32 v20, v14
	v_rcp_f32_e32 v12, v13
	v_cvt_pk_bf16_f32 v8, v8, v9
	v_lshlrev_b32_e32 v9, 16, v25
	v_mul_f32_e32 v15, 0xbfb8aa3b, v18
	v_exp_f32_e32 v15, v15
	v_mov_b32_e32 v13, v20
	v_mul_f32_e32 v9, v12, v9
	v_add_f32_e32 v14, 1.0, v15
	v_and_b32_e32 v12, 0xffff0000, v25
	v_mul_f32_e32 v12, v13, v12
	v_mul_f32_e32 v19, 0xbfb8aa3b, v19
	v_exp_f32_e32 v19, v19
	s_nop 0
	v_add_f32_e32 v15, 1.0, v19
	v_rcp_f32_e32 v19, v15
	v_rcp_f32_e32 v13, v14
	v_mul_f32_e32 v10, 0xbfb8aa3b, v10
	v_exp_f32_e32 v10, v10
	v_mov_b32_e32 v14, v19
	v_add_f32_e32 v15, 1.0, v10
	v_rcp_f32_e32 v19, v15
	v_cvt_pk_bf16_f32 v9, v9, v12
	v_lshlrev_b32_e32 v12, 16, v26
	v_mul_f32_e32 v12, v13, v12
	v_and_b32_e32 v13, 0xffff0000, v26
	v_mul_f32_e32 v10, v14, v13
	v_mul_f32_e32 v11, 0xbfb8aa3b, v11
	v_exp_f32_e32 v11, v11
	s_nop 0
	v_add_f32_e32 v11, 1.0, v11
	v_rcp_f32_e32 v11, v11
	v_mov_b32_e32 v13, v19
	v_cvt_pk_bf16_f32 v10, v12, v10
	v_lshlrev_b32_e32 v12, 16, v27
	v_mul_f32_e32 v12, v13, v12
	v_and_b32_e32 v13, 0xffff0000, v27
	v_mul_f32_e32 v11, v11, v13
	v_cvt_pk_bf16_f32 v11, v12, v11
	v_lshl_add_u64 v[12:13], s[26:27], 0, v[16:17]
	v_lshl_add_u64 v[20:21], v[12:13], 0, v[140:141]
	global_store_dwordx4 v[20:21], v[8:11], off offset:3072
	global_load_dwordx4 v[8:11], v[138:139], off offset:2560
	s_nop 0
	global_load_dwordx4 v[12:15], v[138:139], off offset:2576
	global_load_dwordx4 v[16:19], v[30:31], off offset:256
	s_waitcnt vmcnt(0)
	v_pk_add_f32 v[4:5], v[4:5], v[8:9]
	s_nop 0
	v_mul_f32_e32 v4, 0xbfb8aa3b, v4
	v_exp_f32_e32 v4, v4
	v_pk_add_f32 v[6:7], v[6:7], v[10:11]
	v_mul_f32_e32 v5, 0xbfb8aa3b, v5
	v_pk_add_f32 v[8:9], v[0:1], v[12:13]
	v_add_f32_e32 v4, 1.0, v4
	v_rcp_f32_e32 v1, v4
	v_exp_f32_e32 v5, v5
	v_mul_f32_e32 v6, 0xbfb8aa3b, v6
	v_exp_f32_e32 v6, v6
	v_add_f32_e32 v5, 1.0, v5
	v_rcp_f32_e32 v11, v5
	v_lshlrev_b32_e32 v0, 16, v16
	v_mul_f32_e32 v0, v1, v0
	v_mov_b32_e32 v4, v11
	v_add_f32_e32 v5, 1.0, v6
	v_and_b32_e32 v1, 0xffff0000, v16
	v_mul_f32_e32 v1, v4, v1
	v_mul_f32_e32 v7, 0xbfb8aa3b, v7
	v_exp_f32_e32 v7, v7
	s_nop 0
	v_add_f32_e32 v6, 1.0, v7
	v_rcp_f32_e32 v10, v6
	v_rcp_f32_e32 v4, v5
	v_cvt_pk_bf16_f32 v0, v0, v1
	v_lshlrev_b32_e32 v1, 16, v17
	v_mul_f32_e32 v7, 0xbfb8aa3b, v8
	v_exp_f32_e32 v7, v7
	v_mov_b32_e32 v5, v10
	v_mul_f32_e32 v1, v4, v1
	v_add_f32_e32 v6, 1.0, v7
	v_and_b32_e32 v4, 0xffff0000, v17
	v_mul_f32_e32 v4, v5, v4
	v_mul_f32_e32 v9, 0xbfb8aa3b, v9
	v_exp_f32_e32 v9, v9
	s_nop 0
	v_add_f32_e32 v7, 1.0, v9
	v_rcp_f32_e32 v9, v7
	v_rcp_f32_e32 v5, v6
	v_pk_add_f32 v[2:3], v[2:3], v[14:15]
	v_cvt_pk_bf16_f32 v1, v1, v4
	v_mul_f32_e32 v2, 0xbfb8aa3b, v2
	v_exp_f32_e32 v2, v2
	v_mov_b32_e32 v6, v9
	v_add_f32_e32 v7, 1.0, v2
	v_rcp_f32_e32 v9, v7
	v_lshlrev_b32_e32 v4, 16, v18
	v_mul_f32_e32 v4, v5, v4
	v_and_b32_e32 v5, 0xffff0000, v18
	v_mul_f32_e32 v2, v6, v5
	v_mul_f32_e32 v3, 0xbfb8aa3b, v3
	v_exp_f32_e32 v3, v3
	s_nop 0
	v_add_f32_e32 v3, 1.0, v3
	v_rcp_f32_e32 v3, v3
	v_mov_b32_e32 v5, v9
	v_cvt_pk_bf16_f32 v2, v4, v2
	v_lshlrev_b32_e32 v4, 16, v19
	v_mul_f32_e32 v4, v5, v4
	v_and_b32_e32 v5, 0xffff0000, v19
	v_mul_f32_e32 v3, v3, v5
	s_andn2_b64 vcc, exec, s[4:5]
	s_mov_b32 s7, s40
	s_mov_b32 s6, s42
	v_cvt_pk_bf16_f32 v3, v4, v3
	global_store_dwordx4 v[20:21], v[0:3], off offset:3328
	s_cbranch_vccnz .LBB0_951
	s_waitcnt vmcnt(0)
	s_cmpk_gt_u32 s2, 0xff
	s_cbranch_scc1 .LBB0_958
	s_barrier

; __device__ __forceinline__ unsigned cvt_pk_bf16(float lo, float hi) { unsigned r; asm("v_cvt_pk_bf16_f32 %0, %1, %2" : "=v"(r) : "v"(lo), "v"(hi)); return r; }
; __device__ __forceinline__ float bflo(unsigned w) { return __uint_as_float(w << 16); }
; __device__ __forceinline__ float bfhi(unsigned w) { return __uint_as_float(w & 0xffff0000u); }
; __device__ __forceinline__ float gelu_tanh(float x) { const float u = 0.7978845608028654f * (x + 0.044715f * x * x * x); return x / (1.f + __expf(-2.f * u)); }
; __device__ __forceinline__ void phase_conv(PRef p, int layer, int nseg) {
;     ...
;             for (int xi = 0; xi < 4; ++xi) {
;                 float acc[8];
; #pragma unroll
;                 for (int j = 0; j < 8; ++j) acc[j] = bias[j];
; #pragma unroll
;                 for (int ky = 0; ky < 3; ++ky)
; #pragma unroll
;                     for (int kx = 0; kx < 3; ++kx) { const u32x4 gq = gc[ky][xi + kx]; const int k = ky * 3 + kx;
;                         acc[0] += w[k][0] * bflo(gq.x); acc[1] += w[k][1] * bfhi(gq.x); acc[2] += w[k][2] * bflo(gq.y); acc[3] += w[k][3] * bfhi(gq.y);
;                         acc[4] += w[k][4] * bflo(gq.z); acc[5] += w[k][5] * bfhi(gq.z); acc[6] += w[k][6] * bflo(gq.w); acc[7] += w[k][7] * bfhi(gq.w); }
;                 u32x4 o;
;                 o.x = cvt_pk_bf16(gelu_tanh(acc[0]) * bflo(vv[xi].x), gelu_tanh(acc[1]) * bfhi(vv[xi].x));
;                 o.y = cvt_pk_bf16(gelu_tanh(acc[2]) * bflo(vv[xi].y), gelu_tanh(acc[3]) * bfhi(vv[xi].y));
;                 o.z = cvt_pk_bf16(gelu_tanh(acc[4]) * bflo(vv[xi].z), gelu_tanh(acc[5]) * bfhi(vv[xi].z));
;                 o.w = cvt_pk_bf16(gelu_tanh(acc[6]) * bflo(vv[xi].w), gelu_tanh(acc[7]) * bfhi(vv[xi].w));
;                 *(u32x4*)((bf16_t*)lp[1] + (size_t)(xb + xi) * NUP + NFF) = o; } }
.LBB0_1042:
	s_or_b64 exec, exec, s[8:9]
	s_waitcnt vmcnt(0)
	v_lshlrev_b32_e32 v136, 16, v96
	v_and_b32_e32 v96, 0xffff0000, v96
	v_fma_f32 v182, v33, v96, v41
	v_lshlrev_b32_e32 v96, 16, v97
	v_fma_f32 v183, v34, v96, v42
	v_and_b32_e32 v96, 0xffff0000, v97
	v_fma_f32 v184, v35, v96, v43
	v_lshlrev_b32_e32 v96, 16, v98
	v_fma_f32 v185, v36, v96, v44
	v_and_b32_e32 v96, 0xffff0000, v98
	v_fma_f32 v98, v37, v96, v45
	v_lshlrev_b32_e32 v96, 16, v99
	v_fma_f32 v186, v38, v96, v46
	v_and_b32_e32 v96, 0xffff0000, v99
	v_lshlrev_b32_e32 v203, 16, v100
	v_lshlrev_b32_e32 v202, 16, v92
	v_fma_f32 v136, v32, v136, v40
	v_fma_f32 v99, v39, v96, v47
	v_and_b32_e32 v201, 0xffff0000, v100
	v_fma_f32 v96, v174, v202, v136
	v_and_b32_e32 v200, 0xffff0000, v92
	v_fma_f32 v136, v175, v203, v96
	v_lshlrev_b32_e32 v198, 16, v93
	v_fma_f32 v92, v16, v200, v182
	v_lshlrev_b32_e32 v199, 16, v101
	v_fma_f32 v100, v17, v201, v92
	v_mad_i64_i32 v[48:49], s[8:9], v90, s51, v[140:141]
	v_fma_f32 v92, v166, v198, v183
	v_and_b32_e32 v197, 0xffff0000, v101
	v_and_b32_e32 v196, 0xffff0000, v93
	v_add_co_u32_e32 v204, vcc, 0x2000, v48
	v_fma_f32 v96, v167, v199, v92
	s_nop 0
	v_addc_co_u32_e32 v205, vcc, 0, v49, vcc
	v_mad_i64_i32 v[48:49], s[8:9], v91, s51, v[140:141]
	v_fma_f32 v92, v18, v196, v184
	v_lshlrev_b32_e32 v195, 16, v102
	v_lshlrev_b32_e32 v194, 16, v94
	v_add_co_u32_e32 v180, vcc, 0x2000, v48
	v_fma_f32 v97, v19, v197, v92
	s_nop 0
	v_addc_co_u32_e32 v181, vcc, 0, v49, vcc
	global_load_dwordx4 v[108:111], v[204:205], off offset:3072
	global_load_dwordx4 v[104:107], v[180:181], off offset:3072
	v_fma_f32 v92, v158, v194, v185
	v_and_b32_e32 v193, 0xffff0000, v102
	v_and_b32_e32 v192, 0xffff0000, v94
	v_fma_f32 v101, v159, v195, v92
	v_lshlrev_b32_e32 v190, 16, v95
	v_fma_f32 v92, v20, v192, v98
	v_lshlrev_b32_e32 v191, 16, v103
	v_fma_f32 v94, v21, v193, v92
	v_and_b32_e32 v189, 0xffff0000, v103
	v_fma_f32 v92, v150, v190, v186
	v_and_b32_e32 v188, 0xffff0000, v95
	v_fma_f32 v98, v151, v191, v92
	v_lshlrev_b32_e32 v207, 16, v116
	v_fma_f32 v92, v22, v188, v99
	v_lshlrev_b32_e32 v206, 16, v112
	v_fma_f32 v95, v23, v189, v92
	v_and_b32_e32 v209, 0xffff0000, v116
	v_fma_f32 v92, v172, v206, v136
	v_and_b32_e32 v208, 0xffff0000, v112
	v_fma_f32 v99, v173, v207, v92
	v_lshlrev_b32_e32 v210, 16, v113
	v_fma_f32 v92, v8, v208, v100
	v_lshlrev_b32_e32 v211, 16, v117
	v_fma_f32 v100, v9, v209, v92
	v_and_b32_e32 v213, 0xffff0000, v117
	v_fma_f32 v92, v164, v210, v96
	v_and_b32_e32 v212, 0xffff0000, v113
	v_fma_f32 v96, v165, v211, v92
	v_lshlrev_b32_e32 v215, 16, v118
	v_fma_f32 v92, v10, v212, v97
	v_lshlrev_b32_e32 v214, 16, v114
	v_fma_f32 v97, v11, v213, v92
	v_and_b32_e32 v217, 0xffff0000, v118
	v_fma_f32 v92, v156, v214, v101
	v_and_b32_e32 v216, 0xffff0000, v114
	v_fma_f32 v101, v157, v215, v92
	v_lshlrev_b32_e32 v218, 16, v115
	v_fma_f32 v92, v12, v216, v94
	v_lshlrev_b32_e32 v219, 16, v119
	v_fma_f32 v94, v13, v217, v92
	v_and_b32_e32 v221, 0xffff0000, v119
	v_fma_f32 v92, v148, v218, v98
	v_and_b32_e32 v220, 0xffff0000, v115
	v_fma_f32 v98, v149, v219, v92
	v_lshlrev_b32_e32 v187, 16, v132
	v_fma_f32 v92, v14, v220, v95
	v_lshlrev_b32_e32 v186, 16, v120
	v_fma_f32 v102, v15, v221, v92
	v_and_b32_e32 v185, 0xffff0000, v132
	v_fma_f32 v92, v170, v186, v99
	v_and_b32_e32 v184, 0xffff0000, v120
	v_fma_f32 v99, v171, v187, v92
	v_lshlrev_b32_e32 v182, 16, v121
	v_fma_f32 v92, v28, v184, v100
	v_lshlrev_b32_e32 v183, 16, v133
	v_fma_f32 v103, v29, v185, v92
	v_and_b32_e32 v117, 0xffff0000, v133
	v_fma_f32 v92, v162, v182, v96
	v_and_b32_e32 v116, 0xffff0000, v121
	v_fma_f32 v114, v163, v183, v92
	v_lshlrev_b32_e32 v113, 16, v134
	v_fma_f32 v92, v30, v116, v97
	v_lshlrev_b32_e32 v112, 16, v122
	v_fma_f32 v115, v31, v117, v92
	v_and_b32_e32 v100, 0xffff0000, v122
	v_fma_f32 v92, v154, v112, v101
	v_and_b32_e32 v101, 0xffff0000, v134
	v_fma_f32 v136, v155, v113, v92
	v_lshlrev_b32_e32 v96, 16, v123
	v_fma_f32 v92, v4, v100, v94
	v_lshlrev_b32_e32 v97, 16, v135
	v_fma_f32 v134, v5, v101, v92
	v_lshlrev_b32_e32 v133, 16, v128
	v_fma_f32 v92, v146, v96, v98
	v_fma_f32 v206, v147, v97, v92
	v_and_b32_e32 v93, 0xffff0000, v135
	v_and_b32_e32 v92, 0xffff0000, v123
	v_lshlrev_b32_e32 v132, 16, v124
	v_fma_f32 v94, v6, v92, v102
	v_fma_f32 v135, v7, v93, v94
	v_and_b32_e32 v123, 0xffff0000, v128
	v_fma_f32 v94, v168, v132, v99
	v_and_b32_e32 v122, 0xffff0000, v124
	v_fma_f32 v210, v169, v133, v94
	v_lshlrev_b32_e32 v120, 16, v125
	v_fma_f32 v94, v24, v122, v103
	v_lshlrev_b32_e32 v121, 16, v129
	v_fma_f32 v128, v25, v123, v94
	v_mul_f32_e32 v124, 0x3d372713, v210
	v_fma_f32 v94, v160, v120, v114
	v_and_b32_e32 v119, 0xffff0000, v129
	v_and_b32_e32 v118, 0xffff0000, v125
	v_mul_f32_e32 v124, v210, v124
	v_fma_f32 v214, v161, v121, v94
	v_fma_f32 v124, v210, v124, v210
	v_fma_f32 v94, v26, v118, v115
	v_lshlrev_b32_e32 v115, 16, v130
	v_lshlrev_b32_e32 v114, 16, v126
	v_mul_f32_e32 v124, 0x3f4c422a, v124
	v_fma_f32 v129, v27, v119, v94
	v_mul_f32_e32 v124, -2.0, v124
	v_fma_f32 v94, v152, v114, v136
	v_and_b32_e32 v103, 0xffff0000, v130
	v_and_b32_e32 v102, 0xffff0000, v126
	v_mul_f32_e32 v124, 0x3fb8aa3b, v124
	v_fma_f32 v136, v153, v115, v94
	v_exp_f32_e32 v124, v124
	v_fma_f32 v94, v0, v102, v134
	v_lshlrev_b32_e32 v98, 16, v127
	v_lshlrev_b32_e32 v99, 16, v131
	v_fma_f32 v126, v1, v103, v94
	v_mad_i64_i32 v[48:49], s[8:9], v176, s51, v[140:141]
	v_fma_f32 v94, v144, v98, v206
	v_fma_f32 v130, v145, v99, v94
	v_and_b32_e32 v94, 0xffff0000, v127
	v_add_f32_e32 v127, 1.0, v124
	v_and_b32_e32 v95, 0xffff0000, v131
	v_rcp_f32_e32 v134, v127
	v_add_co_u32_e32 v178, vcc, 0x2000, v48
	s_nop 0
	s_nop 0
	v_addc_co_u32_e32 v179, vcc, 0, v49, vcc
	v_mad_i64_i32 v[48:49], s[8:9], v177, s51, v[140:141]
	v_add_co_u32_e32 v176, vcc, 0x2000, v48
	v_fma_f32 v124, v2, v94, v135
	s_nop 0
	v_addc_co_u32_e32 v177, vcc, 0, v49, vcc
	v_fma_f32 v124, v3, v95, v124
	v_mul_f32_e32 v206, 0x3d372713, v128
	v_mul_f32_e32 v206, v128, v206
	v_fma_f32 v206, v128, v206, v128
	v_mul_f32_e32 v206, 0x3f4c422a, v206
	v_mul_f32_e32 v206, -2.0, v206
	v_mul_f32_e32 v206, 0x3fb8aa3b, v206
	v_exp_f32_e32 v206, v206
	v_mul_f32_e32 v125, v210, v134
	v_add_f32_e32 v131, 1.0, v206
	v_rcp_f32_e32 v135, v131
	s_waitcnt vmcnt(1)
; __device__ __forceinline__ unsigned cvt_pk_bf16(float lo, float hi) { unsigned r; asm("v_cvt_pk_bf16_f32 %0, %1, %2" : "=v"(r) : "v"(lo), "v"(hi)); return r; }
; __device__ __forceinline__ float bflo(unsigned w) { return __uint_as_float(w << 16); }
; __device__ __forceinline__ float bfhi(unsigned w) { return __uint_as_float(w & 0xffff0000u); }
; __device__ __forceinline__ float gelu_tanh(float x) { const float u = 0.7978845608028654f * (x + 0.044715f * x * x * x); return x / (1.f + __expf(-2.f * u)); }
; __device__ __forceinline__ void phase_conv(PRef p, int layer, int nseg) {
;     ...
;             for (int xi = 0; xi < 4; ++xi) {
;                 float acc[8];
; #pragma unroll
;                 for (int j = 0; j < 8; ++j) acc[j] = bias[j];
; #pragma unroll
;                 for (int ky = 0; ky < 3; ++ky)
; #pragma unroll
;                     for (int kx = 0; kx < 3; ++kx) { const u32x4 gq = gc[ky][xi + kx]; const int k = ky * 3 + kx;
;                         acc[0] += w[k][0] * bflo(gq.x); acc[1] += w[k][1] * bfhi(gq.x); acc[2] += w[k][2] * bflo(gq.y); acc[3] += w[k][3] * bfhi(gq.y);
;                         acc[4] += w[k][4] * bflo(gq.z); acc[5] += w[k][5] * bfhi(gq.z); acc[6] += w[k][6] * bflo(gq.w); acc[7] += w[k][7] * bfhi(gq.w); }
;                 u32x4 o;
;                 o.x = cvt_pk_bf16(gelu_tanh(acc[0]) * bflo(vv[xi].x), gelu_tanh(acc[1]) * bfhi(vv[xi].x));
;                 o.y = cvt_pk_bf16(gelu_tanh(acc[2]) * bflo(vv[xi].y), gelu_tanh(acc[3]) * bfhi(vv[xi].y));
;                 o.z = cvt_pk_bf16(gelu_tanh(acc[4]) * bflo(vv[xi].z), gelu_tanh(acc[5]) * bfhi(vv[xi].z));
;                 o.w = cvt_pk_bf16(gelu_tanh(acc[6]) * bflo(vv[xi].w), gelu_tanh(acc[7]) * bfhi(vv[xi].w));
;                 *(u32x4*)((bf16_t*)lp[1] + (size_t)(xb + xi) * NUP + NFF) = o; } }
	v_lshlrev_b32_e32 v127, 16, v108
	v_mul_f32_e32 v125, v125, v127
	v_and_b32_e32 v108, 0xffff0000, v108
	v_mul_f32_e32 v134, 0x3d372713, v214
	v_mul_f32_e32 v134, v214, v134
	v_fma_f32 v134, v214, v134, v214
	v_mul_f32_e32 v134, 0x3f4c422a, v134
	v_mul_f32_e32 v134, -2.0, v134
	v_mul_f32_e32 v134, 0x3fb8aa3b, v134
	v_exp_f32_e32 v134, v134
	v_mul_f32_e32 v127, v128, v135
	v_mul_f32_e32 v108, v127, v108
	v_add_f32_e32 v128, 1.0, v134
	v_rcp_f32_e32 v134, v128
	v_cvt_pk_bf16_f32 v108, v125, v108
	global_load_dwordx4 v[88:91], v[178:179], off offset:3072
	global_load_dwordx4 v[48:51], v[176:177], off offset:3072
	v_fma_f32 v202, v32, v202, v40
	v_mul_f32_e32 v135, 0x3d372713, v129
	v_mul_f32_e32 v135, v129, v135
	v_fma_f32 v135, v129, v135, v129
	v_mul_f32_e32 v135, 0x3f4c422a, v135
	v_mul_f32_e32 v135, -2.0, v135
	v_mul_f32_e32 v135, 0x3fb8aa3b, v135
	v_exp_f32_e32 v135, v135
	v_mul_f32_e32 v125, v214, v134
	v_add_f32_e32 v127, 1.0, v135
	v_rcp_f32_e32 v134, v127
	v_lshlrev_b32_e32 v128, 16, v109
	v_mul_f32_e32 v125, v125, v128
	v_and_b32_e32 v109, 0xffff0000, v109
	v_mul_f32_e32 v131, 0x3d372713, v136
	v_mul_f32_e32 v131, v136, v131
	v_fma_f32 v131, v136, v131, v136
	v_mul_f32_e32 v131, 0x3f4c422a, v131
	v_mul_f32_e32 v131, -2.0, v131
	v_mul_f32_e32 v131, 0x3fb8aa3b, v131
	v_exp_f32_e32 v131, v131
	v_mul_f32_e32 v127, v129, v134
	v_mul_f32_e32 v109, v127, v109
	v_add_f32_e32 v128, 1.0, v131
	v_rcp_f32_e32 v131, v128
	v_cvt_pk_bf16_f32 v109, v125, v109
	v_fma_f32 v210, v33, v200, v41
	v_fma_f32 v214, v35, v196, v43
	v_mul_f32_e32 v134, 0x3d372713, v126
	v_mul_f32_e32 v134, v126, v134
	v_fma_f32 v134, v126, v134, v126
	v_mul_f32_e32 v134, 0x3f4c422a, v134
	v_mul_f32_e32 v134, -2.0, v134
	v_mul_f32_e32 v134, 0x3fb8aa3b, v134
	v_exp_f32_e32 v134, v134
	v_mul_f32_e32 v125, v136, v131
	v_add_f32_e32 v127, 1.0, v134
	v_rcp_f32_e32 v131, v127
	v_lshlrev_b32_e32 v128, 16, v110
	v_mul_f32_e32 v125, v125, v128
	v_and_b32_e32 v110, 0xffff0000, v110
	v_mul_f32_e32 v129, 0x3d372713, v130
	v_mul_f32_e32 v129, v130, v129
	v_fma_f32 v129, v130, v129, v130
	v_mul_f32_e32 v129, 0x3f4c422a, v129
	v_mul_f32_e32 v129, -2.0, v129
	v_mul_f32_e32 v129, 0x3fb8aa3b, v129
	v_exp_f32_e32 v129, v129
	v_mul_f32_e32 v126, v126, v131
	v_mul_f32_e32 v110, v126, v110
	v_add_f32_e32 v127, 1.0, v129
	v_rcp_f32_e32 v129, v127
	v_cvt_pk_bf16_f32 v110, v125, v110
	s_waitcnt vmcnt(2)
	v_lshlrev_b32_e32 v234, 16, v105
	v_fma_f32 v218, v37, v192, v45
	v_mul_f32_e32 v131, 0x3d372713, v124
	v_mul_f32_e32 v131, v124, v131
	v_fma_f32 v131, v124, v131, v124
	v_mul_f32_e32 v131, 0x3f4c422a, v131
	v_mul_f32_e32 v131, -2.0, v131
	v_mul_f32_e32 v131, 0x3fb8aa3b, v131
	v_exp_f32_e32 v131, v131
	v_mul_f32_e32 v125, v130, v129
	v_add_f32_e32 v126, 1.0, v131
	v_rcp_f32_e32 v129, v126
	v_lshlrev_b32_e32 v127, 16, v111
	v_mul_f32_e32 v125, v125, v127
	v_and_b32_e32 v111, 0xffff0000, v111
	v_mul_f32_e32 v124, v124, v129
	v_mul_f32_e32 v111, v124, v111
	v_cvt_pk_bf16_f32 v111, v125, v111
	global_store_dwordx4 v[204:205], v[108:111], off offset:3072
	v_pk_mov_b32 v[124:125], v[210:211], v[182:183] op_sel:[1,0]
	v_pk_mov_b32 v[126:127], v[212:213], v[116:117] op_sel:[1,0]
	v_pk_mov_b32 v[108:109], v[206:207], v[186:187] op_sel:[1,0]
	v_lshlrev_b32_e32 v207, 16, v76
	v_lshlrev_b32_e32 v206, 16, v72
	v_pk_mov_b32 v[128:129], v[214:215], v[112:113] op_sel:[1,0]
	v_lshlrev_b32_e32 v117, 16, v104
	v_and_b32_e32 v183, 0xffff0000, v104
	v_and_b32_e32 v113, 0xffff0000, v105
	v_pk_mov_b32 v[104:105], v[202:203], v[206:207] op_sel:[1,0]
	v_pk_mul_f32 v[108:109], v[172:173], v[108:109]
	v_pk_mul_f32 v[104:105], v[174:175], v[104:105]
	v_pk_mov_b32 v[130:131], v[216:217], v[100:101] op_sel:[1,0]
	v_add_f32_e32 v104, v202, v104
	v_add_f32_e32 v104, v104, v105
	v_add_f32_e32 v104, v104, v108
	v_pk_mov_b32 v[134:135], v[218:219], v[96:97] op_sel:[1,0]
	v_lshlrev_b32_e32 v101, 16, v106
	v_and_b32_e32 v97, 0xffff0000, v106
	v_fma_f32 v106, v32, v203, v40
	v_add_f32_e32 v203, v104, v109
	v_pk_mov_b32 v[110:111], v[208:209], v[184:185] op_sel:[1,0]
	v_fma_f32 v104, v174, v206, v106
	v_and_b32_e32 v209, 0xffff0000, v76
	v_and_b32_e32 v208, 0xffff0000, v72
	v_fma_f32 v235, v175, v207, v104
	v_pk_mov_b32 v[104:105], v[200:201], v[208:209] op_sel:[1,0]
	v_pk_mul_f32 v[110:111], v[8:9], v[110:111]
	v_pk_mul_f32 v[104:105], v[16:17], v[104:105]
	v_pk_mov_b32 v[204:205], v[220:221], v[92:93] op_sel:[1,0]
	v_add_f32_e32 v72, v210, v104
	v_add_f32_e32 v72, v72, v105
	v_lshlrev_b32_e32 v93, 16, v107
	v_and_b32_e32 v136, 0xffff0000, v107
	v_fma_f32 v107, v33, v201, v41
	v_add_f32_e32 v72, v72, v110
	v_fma_f32 v198, v34, v198, v42
	v_add_f32_e32 v236, v72, v111
	v_fma_f32 v72, v16, v208, v107
	v_lshlrev_b32_e32 v210, 16, v73
	v_lshlrev_b32_e32 v211, 16, v77
	v_fma_f32 v237, v17, v209, v72
	v_pk_mov_b32 v[104:105], v[198:199], v[210:211] op_sel:[1,0]
	v_pk_mul_f32 v[124:125], v[164:165], v[124:125]
	v_pk_mul_f32 v[104:105], v[166:167], v[104:105]
	v_fma_f32 v185, v34, v199, v42
	v_add_f32_e32 v72, v198, v104
	v_add_f32_e32 v72, v72, v105
	v_add_f32_e32 v72, v72, v124
	v_add_f32_e32 v238, v72, v125
	v_fma_f32 v72, v166, v210, v185
	v_and_b32_e32 v213, 0xffff0000, v77
	v_and_b32_e32 v212, 0xffff0000, v73
	v_fma_f32 v239, v167, v211, v72
	v_pk_mov_b32 v[72:73], v[196:197], v[212:213] op_sel:[1,0]
	v_pk_mul_f32 v[126:127], v[10:11], v[126:127]
	v_pk_mul_f32 v[72:73], v[18:19], v[72:73]
	v_fma_f32 v187, v35, v197, v43
	v_add_f32_e32 v72, v214, v72
	v_add_f32_e32 v72, v72, v73
	v_add_f32_e32 v72, v72, v126
	v_add_f32_e32 v240, v72, v127
	v_fma_f32 v194, v36, v194, v44
	v_fma_f32 v72, v18, v212, v187
	v_lshlrev_b32_e32 v215, 16, v78
; __device__ __forceinline__ unsigned cvt_pk_bf16(float lo, float hi) { unsigned r; asm("v_cvt_pk_bf16_f32 %0, %1, %2" : "=v"(r) : "v"(lo), "v"(hi)); return r; }
; __device__ __forceinline__ float bflo(unsigned w) { return __uint_as_float(w << 16); }
; __device__ __forceinline__ float bfhi(unsigned w) { return __uint_as_float(w & 0xffff0000u); }
; __device__ __forceinline__ float gelu_tanh(float x) { const float u = 0.7978845608028654f * (x + 0.044715f * x * x * x); return x / (1.f + __expf(-2.f * u)); }
; __device__ __forceinline__ void phase_conv(PRef p, int layer, int nseg) {
;     ...
;             for (int xi = 0; xi < 4; ++xi) {
;                 float acc[8];
; #pragma unroll
;                 for (int j = 0; j < 8; ++j) acc[j] = bias[j];
; #pragma unroll
;                 for (int ky = 0; ky < 3; ++ky)
; #pragma unroll
;                     for (int kx = 0; kx < 3; ++kx) { const u32x4 gq = gc[ky][xi + kx]; const int k = ky * 3 + kx;
;                         acc[0] += w[k][0] * bflo(gq.x); acc[1] += w[k][1] * bfhi(gq.x); acc[2] += w[k][2] * bflo(gq.y); acc[3] += w[k][3] * bfhi(gq.y);
;                         acc[4] += w[k][4] * bflo(gq.z); acc[5] += w[k][5] * bfhi(gq.z); acc[6] += w[k][6] * bflo(gq.w); acc[7] += w[k][7] * bfhi(gq.w); }
;                 u32x4 o;
;                 o.x = cvt_pk_bf16(gelu_tanh(acc[0]) * bflo(vv[xi].x), gelu_tanh(acc[1]) * bfhi(vv[xi].x));
;                 o.y = cvt_pk_bf16(gelu_tanh(acc[2]) * bflo(vv[xi].y), gelu_tanh(acc[3]) * bfhi(vv[xi].y));
;                 o.z = cvt_pk_bf16(gelu_tanh(acc[4]) * bflo(vv[xi].z), gelu_tanh(acc[5]) * bfhi(vv[xi].z));
;                 o.w = cvt_pk_bf16(gelu_tanh(acc[6]) * bflo(vv[xi].w), gelu_tanh(acc[7]) * bfhi(vv[xi].w));
;                 *(u32x4*)((bf16_t*)lp[1] + (size_t)(xb + xi) * NUP + NFF) = o; } }
	v_lshlrev_b32_e32 v214, 16, v74
	v_fma_f32 v241, v19, v213, v72
	v_pk_mov_b32 v[72:73], v[194:195], v[214:215] op_sel:[1,0]
	v_pk_mul_f32 v[128:129], v[156:157], v[128:129]
	v_pk_mul_f32 v[72:73], v[158:159], v[72:73]
	v_fma_f32 v216, v36, v195, v44
	v_add_f32_e32 v72, v194, v72
	v_add_f32_e32 v72, v72, v73
	v_add_f32_e32 v72, v72, v128
	v_add_f32_e32 v202, v72, v129
	v_and_b32_e32 v217, 0xffff0000, v78
	v_fma_f32 v72, v158, v214, v216
	v_and_b32_e32 v216, 0xffff0000, v74
	v_fma_f32 v201, v159, v215, v72
	v_pk_mov_b32 v[72:73], v[192:193], v[216:217] op_sel:[1,0]
	v_pk_mul_f32 v[130:131], v[12:13], v[130:131]
	v_pk_mul_f32 v[72:73], v[20:21], v[72:73]
	v_fma_f32 v219, v37, v193, v45
	v_add_f32_e32 v72, v218, v72
	v_add_f32_e32 v72, v72, v73
	v_add_f32_e32 v72, v72, v130
	v_add_f32_e32 v199, v72, v131
	v_fma_f32 v190, v38, v190, v46
	v_fma_f32 v72, v20, v216, v219
	v_lshlrev_b32_e32 v218, 16, v75
	v_lshlrev_b32_e32 v219, 16, v79
	v_fma_f32 v198, v21, v217, v72
	v_pk_mov_b32 v[72:73], v[190:191], v[218:219] op_sel:[1,0]
	v_pk_mul_f32 v[134:135], v[148:149], v[134:135]
	v_pk_mul_f32 v[72:73], v[150:151], v[72:73]
	v_fma_f32 v220, v38, v191, v46
	v_add_f32_e32 v72, v190, v72
	v_add_f32_e32 v72, v72, v73
	v_add_f32_e32 v72, v72, v134
	v_add_f32_e32 v197, v72, v135
	v_and_b32_e32 v221, 0xffff0000, v79
	v_fma_f32 v72, v150, v218, v220
	v_and_b32_e32 v220, 0xffff0000, v75
	v_fma_f32 v196, v151, v219, v72
	v_pk_mov_b32 v[72:73], v[188:189], v[220:221] op_sel:[1,0]
	v_fma_f32 v227, v39, v188, v47
	v_pk_mul_f32 v[72:73], v[22:23], v[72:73]
	s_waitcnt vmcnt(2)
	v_lshlrev_b32_e32 v185, 16, v88
	v_add_f32_e32 v72, v227, v72
	v_and_b32_e32 v227, 0xffff0000, v88
	v_lshlrev_b32_e32 v242, 16, v89
	v_and_b32_e32 v243, 0xffff0000, v89
	v_lshlrev_b32_e32 v244, 16, v90
	v_and_b32_e32 v200, 0xffff0000, v90
	v_lshlrev_b32_e32 v89, 16, v91
	v_and_b32_e32 v88, 0xffff0000, v91
	v_lshlrev_b32_e32 v91, 16, v68
	v_mov_b32_e32 v90, v207
	v_pk_mul_f32 v[204:205], v[14:15], v[204:205]
	v_add_f32_e32 v72, v72, v73
	v_fma_f32 v187, v32, v206, v40
	v_pk_mul_f32 v[90:91], v[174:175], v[90:91]
	v_add_f32_e32 v72, v72, v204
	v_add_f32_e32 v90, v187, v90
	v_add_f32_e32 v195, v72, v205
	v_pk_mul_f32 v[72:73], v[22:23], v[220:221]
	v_fma_f32 v206, v33, v208, v41
	v_fma_f32 v208, v34, v210, v42
	v_fma_f32 v210, v35, v212, v43
	v_fma_f32 v212, v36, v214, v44
	v_fma_f32 v214, v37, v216, v45
	v_fma_f32 v216, v38, v218, v46
	v_fma_f32 v218, v39, v220, v47
	v_add_f32_e32 v220, v90, v91
	v_and_b32_e32 v91, 0xffff0000, v68
	v_mov_b32_e32 v90, v209
	v_pk_mul_f32 v[90:91], v[16:17], v[90:91]
	v_fma_f32 v228, v39, v189, v47
	v_add_f32_e32 v68, v206, v90
	v_add_f32_e32 v209, v68, v91
	v_lshlrev_b32_e32 v91, 16, v69
	v_mov_b32_e32 v90, v211
	v_pk_mul_f32 v[90:91], v[166:167], v[90:91]
	v_and_b32_e32 v69, 0xffff0000, v69
	v_add_f32_e32 v68, v208, v90
	v_add_f32_e32 v208, v68, v91
	v_mov_b32_e32 v68, v213
	v_pk_mul_f32 v[68:69], v[18:19], v[68:69]
	v_lshlrev_b32_e32 v206, 16, v56
	v_add_f32_e32 v68, v210, v68
	v_add_f32_e32 v210, v68, v69
	v_lshlrev_b32_e32 v69, 16, v70
	v_mov_b32_e32 v68, v215
	v_pk_mul_f32 v[68:69], v[158:159], v[68:69]
	v_add_f32_e32 v72, v228, v72
	v_add_f32_e32 v68, v212, v68
	v_add_f32_e32 v211, v68, v69
	v_and_b32_e32 v69, 0xffff0000, v70
	v_mov_b32_e32 v68, v217
	v_pk_mul_f32 v[68:69], v[20:21], v[68:69]
	v_mov_b32_e32 v70, v206
	v_add_f32_e32 v68, v214, v68
	v_add_f32_e32 v91, v68, v69
	v_lshlrev_b32_e32 v69, 16, v71
	v_mov_b32_e32 v68, v219
	v_pk_mul_f32 v[68:69], v[150:151], v[68:69]
	v_add_f32_e32 v194, v72, v73
	v_add_f32_e32 v68, v216, v68
	v_add_f32_e32 v90, v68, v69
	v_and_b32_e32 v69, 0xffff0000, v71
	v_mov_b32_e32 v68, v221
	v_pk_mul_f32 v[68:69], v[22:23], v[68:69]
	v_mov_b32_e32 v71, v132
	v_lshlrev_b32_e32 v73, 16, v84
	v_lshlrev_b32_e32 v72, 16, v80
	v_add_f32_e32 v68, v218, v68
	v_pk_mul_f32 v[70:71], v[170:171], v[70:71]
	v_pk_mov_b32 v[74:75], v[132:133], v[72:73] op_sel:[1,0]
	v_add_f32_e32 v68, v68, v69
	v_add_f32_e32 v69, v203, v70
	v_pk_mul_f32 v[204:205], v[168:169], v[74:75]
	v_add_f32_e32 v69, v69, v71
	v_fma_f32 v69, v168, v74, v69
	v_fma_f32 v69, v169, v75, v69
	v_mul_f32_e32 v132, 0x3d372713, v69
	v_mul_f32_e32 v132, v69, v132
	v_fma_f32 v132, v69, v132, v69
	v_mul_f32_e32 v132, 0x3f4c422a, v132
	v_mov_b32_e32 v187, v206
	v_mul_f32_e32 v132, -2.0, v132
	v_lshlrev_b32_e32 v207, 16, v64
	v_pk_mul_f32 v[70:71], v[172:173], v[186:187]
	v_mul_f32_e32 v132, 0x3fb8aa3b, v132
	v_exp_f32_e32 v186, v132
	v_add_f32_e32 v70, v235, v70
	v_mov_b32_e32 v132, v207
	v_add_f32_e32 v187, v70, v71
	v_pk_mul_f32 v[228:229], v[168:169], v[72:73]
	v_fma_f32 v70, v170, v132, v187
	v_fma_f32 v70, v171, v133, v70
	v_fma_f32 v70, v168, v72, v70
	v_fma_f32 v70, v169, v73, v70
	v_mul_f32_e32 v133, 0x3d372713, v70
	v_add_f32_e32 v186, 1.0, v186
	v_mul_f32_e32 v133, v70, v133
	v_fma_f32 v133, v70, v133, v70
	v_rcp_f32_e32 v204, v186
	v_mul_f32_e32 v133, 0x3f4c422a, v133
	v_mul_f32_e32 v133, -2.0, v133
	v_mul_f32_e32 v133, 0x3fb8aa3b, v133
	v_exp_f32_e32 v133, v133
	s_nop 0
	v_add_f32_e32 v133, 1.0, v133
	v_rcp_f32_e32 v203, v133
	v_mul_f32_e32 v69, v69, v204
	v_mul_f32_e32 v117, v69, v117
	v_mul_f32_e32 v69, v70, v203
	v_mul_f32_e32 v70, v69, v185
	v_fma_f32 v69, v172, v206, v220
	v_and_b32_e32 v132, 0xffff0000, v56
	v_mov_b32_e32 v186, v132
	v_mov_b32_e32 v187, v122
	v_and_b32_e32 v75, 0xffff0000, v84
	v_and_b32_e32 v74, 0xffff0000, v80
	v_pk_mul_f32 v[186:187], v[28:29], v[186:187]
	v_pk_mov_b32 v[76:77], v[122:123], v[74:75] op_sel:[1,0]
	v_add_f32_e32 v56, v236, v186
	v_pk_mul_f32 v[230:231], v[24:25], v[76:77]
	v_add_f32_e32 v56, v56, v187
	v_fma_f32 v56, v24, v76, v56
; __device__ __forceinline__ unsigned cvt_pk_bf16(float lo, float hi) { unsigned r; asm("v_cvt_pk_bf16_f32 %0, %1, %2" : "=v"(r) : "v"(lo), "v"(hi)); return r; }
; __device__ __forceinline__ float bflo(unsigned w) { return __uint_as_float(w << 16); }
; __device__ __forceinline__ float bfhi(unsigned w) { return __uint_as_float(w & 0xffff0000u); }
; __device__ __forceinline__ float gelu_tanh(float x) { const float u = 0.7978845608028654f * (x + 0.044715f * x * x * x); return x / (1.f + __expf(-2.f * u)); }
; __device__ __forceinline__ void phase_conv(PRef p, int layer, int nseg) {
;     ...
;                 for (int ky = 0; ky < 3; ++ky)
; #pragma unroll
;                     for (int kx = 0; kx < 3; ++kx) { const u32x4 gq = gc[ky][xi + kx]; const int k = ky * 3 + kx;
;                         acc[0] += w[k][0] * bflo(gq.x); acc[1] += w[k][1] * bfhi(gq.x); acc[2] += w[k][2] * bflo(gq.y); acc[3] += w[k][3] * bfhi(gq.y);
;                         acc[4] += w[k][4] * bflo(gq.z); acc[5] += w[k][5] * bfhi(gq.z); acc[6] += w[k][6] * bflo(gq.w); acc[7] += w[k][7] * bfhi(gq.w); }
;                 u32x4 o;
;                 o.x = cvt_pk_bf16(gelu_tanh(acc[0]) * bflo(vv[xi].x), gelu_tanh(acc[1]) * bfhi(vv[xi].x));
;                 o.y = cvt_pk_bf16(gelu_tanh(acc[2]) * bflo(vv[xi].y), gelu_tanh(acc[3]) * bfhi(vv[xi].y));
;                 o.z = cvt_pk_bf16(gelu_tanh(acc[4]) * bflo(vv[xi].z), gelu_tanh(acc[5]) * bfhi(vv[xi].z));
;                 o.w = cvt_pk_bf16(gelu_tanh(acc[6]) * bflo(vv[xi].w), gelu_tanh(acc[7]) * bfhi(vv[xi].w));
;                 *(u32x4*)((bf16_t*)lp[1] + (size_t)(xb + xi) * NUP + NFF) = o; } }
	v_fma_f32 v56, v25, v77, v56
	v_fma_f32 v69, v173, v207, v69
	v_and_b32_e32 v133, 0xffff0000, v64
	v_mul_f32_e32 v64, 0x3d372713, v56
	v_mul_f32_e32 v64, v56, v64
	v_fma_f32 v64, v56, v64, v56
	v_mov_b32_e32 v185, v132
	v_mul_f32_e32 v64, 0x3f4c422a, v64
	v_pk_mul_f32 v[184:185], v[8:9], v[184:185]
	v_mul_f32_e32 v64, -2.0, v64
	v_mul_f32_e32 v64, 0x3fb8aa3b, v64
	v_add_f32_e32 v71, v237, v184
	v_mov_b32_e32 v122, v133
	v_exp_f32_e32 v64, v64
	v_add_f32_e32 v71, v71, v185
	v_pk_mul_f32 v[122:123], v[28:29], v[122:123]
	v_pk_mul_f32 v[232:233], v[24:25], v[74:75]
	v_add_f32_e32 v71, v71, v122
	v_add_f32_e32 v71, v71, v123
	v_fma_f32 v71, v24, v74, v71
	v_add_f32_e32 v64, 1.0, v64
	v_fma_f32 v71, v25, v75, v71
	v_mul_f32_e32 v186, 0x3d372713, v71
	v_rcp_f32_e32 v185, v64
	v_mul_f32_e32 v186, v71, v186
	v_fma_f32 v186, v71, v186, v71
	v_mul_f32_e32 v186, 0x3f4c422a, v186
	v_mul_f32_e32 v186, -2.0, v186
	v_mul_f32_e32 v186, 0x3fb8aa3b, v186
	v_exp_f32_e32 v186, v186
	s_nop 0
	v_add_f32_e32 v184, 1.0, v186
	v_rcp_f32_e32 v187, v184
	v_mul_f32_e32 v56, v56, v185
	v_lshlrev_b32_e32 v76, 16, v81
	v_mul_f32_e32 v64, v71, v187
	v_pk_mul_f32 v[122:123], v[8:9], v[132:133]
	v_mul_f32_e32 v71, v64, v227
	v_add_f32_e32 v64, v209, v122
	v_lshlrev_b32_e32 v122, 16, v57
	v_mov_b32_e32 v132, v122
	v_mov_b32_e32 v133, v120
	v_lshlrev_b32_e32 v77, 16, v85
	v_mul_f32_e32 v56, v56, v183
	v_pk_mul_f32 v[132:133], v[162:163], v[132:133]
	v_pk_mov_b32 v[78:79], v[120:121], v[76:77] op_sel:[1,0]
	v_cvt_pk_bf16_f32 v56, v117, v56
	v_add_f32_e32 v117, v238, v132
	v_pk_mul_f32 v[192:193], v[160:161], v[78:79]
	v_add_f32_e32 v117, v117, v133
	v_fma_f32 v117, v160, v78, v117
	v_fma_f32 v117, v161, v79, v117
	v_mul_f32_e32 v120, 0x3d372713, v117
	v_mul_f32_e32 v120, v117, v120
	v_fma_f32 v120, v117, v120, v117
	v_mul_f32_e32 v120, 0x3f4c422a, v120
	v_mov_b32_e32 v183, v122
	v_mul_f32_e32 v120, -2.0, v120
	v_pk_mul_f32 v[132:133], v[164:165], v[182:183]
	v_mul_f32_e32 v120, 0x3fb8aa3b, v120
	v_add_f32_e32 v64, v64, v123
	v_lshlrev_b32_e32 v123, 16, v65
	v_exp_f32_e32 v182, v120
	v_add_f32_e32 v120, v239, v132
	v_add_f32_e32 v132, v120, v133
	v_mov_b32_e32 v120, v123
	v_pk_mul_f32 v[120:121], v[162:163], v[120:121]
	v_pk_mul_f32 v[190:191], v[160:161], v[76:77]
	v_add_f32_e32 v120, v132, v120
	v_add_f32_e32 v120, v120, v121
	v_fma_f32 v120, v160, v76, v120
	v_add_f32_e32 v133, 1.0, v182
	v_fma_f32 v120, v161, v77, v120
	v_mul_f32_e32 v184, 0x3d372713, v120
	v_rcp_f32_e32 v183, v133
	v_mul_f32_e32 v184, v120, v184
	v_fma_f32 v184, v120, v184, v120
	v_mul_f32_e32 v184, 0x3f4c422a, v184
	v_mul_f32_e32 v184, -2.0, v184
	v_mul_f32_e32 v184, 0x3fb8aa3b, v184
	v_exp_f32_e32 v184, v184
	s_nop 0
	v_add_f32_e32 v182, 1.0, v184
	v_rcp_f32_e32 v185, v182
	v_mul_f32_e32 v117, v117, v183
	v_mul_f32_e32 v132, v117, v234
	v_mul_f32_e32 v117, v120, v185
	v_pk_mul_f32 v[120:121], v[164:165], v[122:123]
	v_mul_f32_e32 v133, v117, v242
	v_add_f32_e32 v117, v208, v120
	v_and_b32_e32 v120, 0xffff0000, v57
	v_mov_b32_e32 v122, v120
	v_mov_b32_e32 v123, v118
	v_and_b32_e32 v79, 0xffff0000, v85
	v_and_b32_e32 v78, 0xffff0000, v81
	v_pk_mul_f32 v[122:123], v[30:31], v[122:123]
	v_pk_mov_b32 v[80:81], v[118:119], v[78:79] op_sel:[1,0]
	v_add_f32_e32 v57, v240, v122
	v_pk_mul_f32 v[188:189], v[26:27], v[80:81]
	v_add_f32_e32 v57, v57, v123
	v_fma_f32 v57, v26, v80, v57
	v_fma_f32 v57, v27, v81, v57
	v_add_f32_e32 v182, v117, v121
	v_and_b32_e32 v121, 0xffff0000, v65
	v_mul_f32_e32 v65, 0x3d372713, v57
	v_mov_b32_e32 v117, v120
	v_mul_f32_e32 v65, v57, v65
	v_pk_mul_f32 v[116:117], v[10:11], v[116:117]
	v_fma_f32 v65, v57, v65, v57
	v_mul_f32_e32 v65, 0x3f4c422a, v65
	v_add_f32_e32 v116, v241, v116
	v_mov_b32_e32 v118, v121
	v_mul_f32_e32 v65, -2.0, v65
	v_add_f32_e32 v122, v116, v117
	v_mul_f32_e32 v65, 0x3fb8aa3b, v65
	v_fma_f32 v116, v30, v118, v122
	v_pk_mul_f32 v[134:135], v[26:27], v[78:79]
	v_exp_f32_e32 v65, v65
	v_fma_f32 v116, v31, v119, v116
	v_fma_f32 v116, v26, v78, v116
	v_fma_f32 v116, v27, v79, v116
	v_mul_f32_e32 v119, 0x3d372713, v116
	v_add_f32_e32 v65, 1.0, v65
	v_mul_f32_e32 v119, v116, v119
	v_fma_f32 v119, v116, v119, v116
	v_rcp_f32_e32 v183, v65
	v_mul_f32_e32 v119, 0x3f4c422a, v119
	v_mul_f32_e32 v119, -2.0, v119
	v_mul_f32_e32 v119, 0x3fb8aa3b, v119
	v_exp_f32_e32 v119, v119
	s_nop 0
	v_add_f32_e32 v119, 1.0, v119
	v_rcp_f32_e32 v123, v119
	v_mul_f32_e32 v57, v57, v183
	v_mul_f32_e32 v57, v57, v113
	v_mul_f32_e32 v65, v116, v123
	v_mov_b32_e32 v119, v114
	v_fma_f32 v113, v10, v120, v210
	v_lshlrev_b32_e32 v116, 16, v58
	v_mov_b32_e32 v118, v116
	v_lshlrev_b32_e32 v81, 16, v86
	v_lshlrev_b32_e32 v80, 16, v82
	v_pk_mul_f32 v[118:119], v[154:155], v[118:119]
	v_pk_mov_b32 v[84:85], v[114:115], v[80:81] op_sel:[1,0]
	v_fma_f32 v120, v11, v121, v113
	v_add_f32_e32 v113, v202, v118
	v_pk_mul_f32 v[130:131], v[152:153], v[84:85]
	v_add_f32_e32 v114, v113, v119
	v_fma_f32 v114, v152, v84, v114
	v_fma_f32 v118, v153, v85, v114
	v_mul_f32_e32 v114, 0x3d372713, v118
	v_mul_f32_e32 v114, v118, v114
	v_fma_f32 v114, v118, v114, v118
	v_mul_f32_e32 v114, 0x3f4c422a, v114
	v_mov_b32_e32 v113, v116
	v_mul_f32_e32 v114, -2.0, v114
	v_lshlrev_b32_e32 v117, 16, v66
	v_pk_mul_f32 v[112:113], v[156:157], v[112:113]
	v_mul_f32_e32 v114, 0x3fb8aa3b, v114
	v_exp_f32_e32 v119, v114
	v_add_f32_e32 v112, v201, v112
	v_mov_b32_e32 v114, v117
	v_add_f32_e32 v121, v112, v113
	v_pk_mul_f32 v[128:129], v[152:153], v[80:81]
	v_fma_f32 v112, v154, v114, v121
	v_fma_f32 v112, v155, v115, v112
	v_fma_f32 v112, v152, v80, v112
	v_fma_f32 v112, v153, v81, v112
	v_mul_f32_e32 v115, 0x3d372713, v112
; __device__ __forceinline__ unsigned cvt_pk_bf16(float lo, float hi) { unsigned r; asm("v_cvt_pk_bf16_f32 %0, %1, %2" : "=v"(r) : "v"(lo), "v"(hi)); return r; }
; __device__ __forceinline__ float bflo(unsigned w) { return __uint_as_float(w << 16); }
; __device__ __forceinline__ float bfhi(unsigned w) { return __uint_as_float(w & 0xffff0000u); }
; __device__ __forceinline__ float gelu_tanh(float x) { const float u = 0.7978845608028654f * (x + 0.044715f * x * x * x); return x / (1.f + __expf(-2.f * u)); }
; __device__ __forceinline__ void phase_conv(PRef p, int layer, int nseg) {
;     ...
;                 for (int ky = 0; ky < 3; ++ky)
; #pragma unroll
;                     for (int kx = 0; kx < 3; ++kx) { const u32x4 gq = gc[ky][xi + kx]; const int k = ky * 3 + kx;
;                         acc[0] += w[k][0] * bflo(gq.x); acc[1] += w[k][1] * bfhi(gq.x); acc[2] += w[k][2] * bflo(gq.y); acc[3] += w[k][3] * bfhi(gq.y);
;                         acc[4] += w[k][4] * bflo(gq.z); acc[5] += w[k][5] * bfhi(gq.z); acc[6] += w[k][6] * bflo(gq.w); acc[7] += w[k][7] * bfhi(gq.w); }
;                 u32x4 o;
;                 o.x = cvt_pk_bf16(gelu_tanh(acc[0]) * bflo(vv[xi].x), gelu_tanh(acc[1]) * bfhi(vv[xi].x));
;                 o.y = cvt_pk_bf16(gelu_tanh(acc[2]) * bflo(vv[xi].y), gelu_tanh(acc[3]) * bfhi(vv[xi].y));
;                 o.z = cvt_pk_bf16(gelu_tanh(acc[4]) * bflo(vv[xi].z), gelu_tanh(acc[5]) * bfhi(vv[xi].z));
;                 o.w = cvt_pk_bf16(gelu_tanh(acc[6]) * bflo(vv[xi].w), gelu_tanh(acc[7]) * bfhi(vv[xi].w));
;                 *(u32x4*)((bf16_t*)lp[1] + (size_t)(xb + xi) * NUP + NFF) = o; } }
	v_add_f32_e32 v119, 1.0, v119
	v_mul_f32_e32 v115, v112, v115
	v_fma_f32 v115, v112, v115, v112
	v_rcp_f32_e32 v123, v119
	v_mul_f32_e32 v115, 0x3f4c422a, v115
	v_mul_f32_e32 v115, -2.0, v115
	v_mul_f32_e32 v115, 0x3fb8aa3b, v115
	v_exp_f32_e32 v115, v115
	s_nop 0
	v_add_f32_e32 v115, 1.0, v115
	v_rcp_f32_e32 v122, v115
	v_mul_f32_e32 v113, v118, v123
	v_mul_f32_e32 v118, v113, v101
	v_mul_f32_e32 v101, v112, v122
	v_mul_f32_e32 v119, v101, v244
	v_fma_f32 v101, v156, v116, v211
	v_and_b32_e32 v112, 0xffff0000, v58
	v_mov_b32_e32 v114, v112
	v_mov_b32_e32 v115, v102
	v_and_b32_e32 v85, 0xffff0000, v86
	v_and_b32_e32 v84, 0xffff0000, v82
	v_pk_mul_f32 v[114:115], v[4:5], v[114:115]
	v_pk_mov_b32 v[104:105], v[102:103], v[84:85] op_sel:[1,0]
	v_add_f32_e32 v58, v199, v114
	v_pk_mul_f32 v[126:127], v[0:1], v[104:105]
	v_add_f32_e32 v58, v58, v115
	v_fma_f32 v58, v0, v104, v58
	v_fma_f32 v58, v1, v105, v58
	v_fma_f32 v116, v157, v117, v101
	v_and_b32_e32 v113, 0xffff0000, v66
	v_mul_f32_e32 v66, 0x3d372713, v58
	v_mov_b32_e32 v101, v112
	v_mul_f32_e32 v66, v58, v66
	v_pk_mul_f32 v[100:101], v[12:13], v[100:101]
	v_fma_f32 v66, v58, v66, v58
	v_mul_f32_e32 v66, 0x3f4c422a, v66
	v_add_f32_e32 v100, v198, v100
	v_mov_b32_e32 v102, v113
	v_mul_f32_e32 v66, -2.0, v66
	v_add_f32_e32 v114, v100, v101
	v_mul_f32_e32 v66, 0x3fb8aa3b, v66
	v_fma_f32 v100, v4, v102, v114
	v_pk_mul_f32 v[124:125], v[0:1], v[84:85]
	v_exp_f32_e32 v66, v66
	v_fma_f32 v100, v5, v103, v100
	v_fma_f32 v100, v0, v84, v100
	v_fma_f32 v100, v1, v85, v100
	v_mul_f32_e32 v103, 0x3d372713, v100
	v_add_f32_e32 v66, 1.0, v66
	v_mul_f32_e32 v103, v100, v103
	v_fma_f32 v103, v100, v103, v100
	v_rcp_f32_e32 v117, v66
	v_mul_f32_e32 v103, 0x3f4c422a, v103
	v_mul_f32_e32 v103, -2.0, v103
	v_mul_f32_e32 v103, 0x3fb8aa3b, v103
	v_exp_f32_e32 v103, v103
	s_nop 0
	v_add_f32_e32 v103, 1.0, v103
	v_rcp_f32_e32 v115, v103
	v_mul_f32_e32 v58, v58, v117
	v_mul_f32_e32 v58, v58, v97
	v_mul_f32_e32 v66, v100, v115
	v_mul_f32_e32 v114, v66, v200
	v_fma_f32 v66, v12, v112, v91
	v_lshlrev_b32_e32 v100, 16, v59
	v_mov_b32_e32 v102, v100
	v_mov_b32_e32 v103, v98
	v_lshlrev_b32_e32 v104, 16, v83
	v_lshlrev_b32_e32 v105, 16, v87
	v_pk_mul_f32 v[102:103], v[146:147], v[102:103]
	v_pk_mov_b32 v[106:107], v[98:99], v[104:105] op_sel:[1,0]
	v_fma_f32 v112, v13, v113, v66
	v_add_f32_e32 v66, v197, v102
	v_pk_mul_f32 v[110:111], v[144:145], v[106:107]
	v_add_f32_e32 v66, v66, v103
	v_fma_f32 v66, v144, v106, v66
	v_fma_f32 v66, v145, v107, v66
	v_mul_f32_e32 v91, 0x3d372713, v66
	v_mov_b32_e32 v97, v100
	v_mul_f32_e32 v91, v66, v91
	v_lshlrev_b32_e32 v101, 16, v67
	v_pk_mul_f32 v[96:97], v[148:149], v[96:97]
	v_fma_f32 v91, v66, v91, v66
	v_mul_f32_e32 v91, 0x3f4c422a, v91
	v_add_f32_e32 v96, v196, v96
	v_mov_b32_e32 v98, v101
	v_mul_f32_e32 v91, -2.0, v91
	v_add_f32_e32 v102, v96, v97
	v_mul_f32_e32 v91, 0x3fb8aa3b, v91
	v_fma_f32 v96, v146, v98, v102
	v_pk_mul_f32 v[108:109], v[144:145], v[104:105]
	v_exp_f32_e32 v91, v91
	v_fma_f32 v96, v147, v99, v96
	v_fma_f32 v96, v144, v104, v96
	v_fma_f32 v96, v145, v105, v96
	v_mul_f32_e32 v99, 0x3d372713, v96
	v_add_f32_e32 v91, 1.0, v91
	v_mul_f32_e32 v99, v96, v99
	v_fma_f32 v99, v96, v99, v96
	v_rcp_f32_e32 v110, v91
	v_mul_f32_e32 v99, 0x3f4c422a, v99
	v_mul_f32_e32 v99, -2.0, v99
	v_mul_f32_e32 v99, 0x3fb8aa3b, v99
	v_exp_f32_e32 v99, v99
	s_nop 0
	v_add_f32_e32 v99, 1.0, v99
	v_rcp_f32_e32 v103, v99
	v_mul_f32_e32 v66, v66, v110
	v_mul_f32_e32 v98, v66, v93
	v_mul_f32_e32 v66, v96, v103
	v_pk_mul_f32 v[96:97], v[148:149], v[100:101]
	v_mul_f32_e32 v89, v66, v89
	v_fma_f32 v66, v148, v100, v90
	v_fma_f32 v96, v149, v101, v66
	v_and_b32_e32 v66, 0xffff0000, v59
	v_mov_b32_e32 v90, v66
	v_mov_b32_e32 v91, v94
	v_and_b32_e32 v87, 0xffff0000, v87
	v_and_b32_e32 v86, 0xffff0000, v83
	v_pk_mul_f32 v[90:91], v[6:7], v[90:91]
	v_pk_mov_b32 v[82:83], v[94:95], v[86:87] op_sel:[1,0]
	v_add_f32_e32 v59, v195, v90
	v_pk_mul_f32 v[106:107], v[2:3], v[82:83]
	v_add_f32_e32 v59, v59, v91
	v_fma_f32 v59, v2, v82, v59
	v_mov_b32_e32 v93, v66
	v_fma_f32 v59, v3, v83, v59
	v_pk_mul_f32 v[90:91], v[14:15], v[92:93]
	v_mul_f32_e32 v92, 0x3d372713, v59
	v_mul_f32_e32 v92, v59, v92
	v_fma_f32 v92, v59, v92, v59
	v_and_b32_e32 v67, 0xffff0000, v67
	v_mul_f32_e32 v92, 0x3f4c422a, v92
	v_mul_f32_e32 v92, -2.0, v92
	v_add_f32_e32 v90, v194, v90
	v_mov_b32_e32 v94, v67
	v_mul_f32_e32 v92, 0x3fb8aa3b, v92
	v_add_f32_e32 v93, v90, v91
	v_pk_mul_f32 v[90:91], v[6:7], v[94:95]
	v_exp_f32_e32 v92, v92
	v_fma_f32 v90, v6, v94, v93
	v_fma_f32 v90, v7, v95, v90
	v_fma_f32 v82, v2, v86, v90
	v_fma_f32 v82, v3, v87, v82
	v_add_f32_e32 v92, 1.0, v92
	v_mul_f32_e32 v83, 0x3d372713, v82
	v_mul_f32_e32 v83, v82, v83
	v_rcp_f32_e32 v99, v92
	v_fma_f32 v83, v82, v83, v82
	v_mul_f32_e32 v83, 0x3f4c422a, v83
	v_mul_f32_e32 v83, -2.0, v83
	v_mul_f32_e32 v83, 0x3fb8aa3b, v83
	v_exp_f32_e32 v83, v83
	s_nop 0
	v_add_f32_e32 v83, 1.0, v83
	v_rcp_f32_e32 v94, v83
	v_mul_f32_e32 v59, v59, v99
	v_cvt_pk_bf16_f32 v57, v132, v57
	v_mul_f32_e32 v59, v59, v136
	v_mul_f32_e32 v65, v65, v243
	v_cvt_pk_bf16_f32 v58, v118, v58
	v_mul_f32_e32 v82, v82, v94
	v_cvt_pk_bf16_f32 v59, v98, v59
	global_store_dwordx4 v[180:181], v[56:59], off offset:3072
	v_pk_mov_b32 v[72:73], v[72:73], v[72:73] op_sel:[1,0]
	v_mul_f32_e32 v82, v82, v88
	v_cvt_pk_bf16_f32 v56, v70, v71
	v_cvt_pk_bf16_f32 v57, v133, v65
	v_pk_mul_f32 v[66:67], v[14:15], v[66:67]
	v_cvt_pk_bf16_f32 v58, v119, v114
	v_cvt_pk_bf16_f32 v59, v89, v82
	global_store_dwordx4 v[178:179], v[56:59], off offset:3072
	v_add_f32_e32 v66, v68, v66
	v_add_f32_e32 v88, v66, v67
; __device__ __forceinline__ unsigned cvt_pk_bf16(float lo, float hi) { unsigned r; asm("v_cvt_pk_bf16_f32 %0, %1, %2" : "=v"(r) : "v"(lo), "v"(hi)); return r; }
; __device__ __forceinline__ float bflo(unsigned w) { return __uint_as_float(w << 16); }
; __device__ __forceinline__ float bfhi(unsigned w) { return __uint_as_float(w & 0xffff0000u); }
; __device__ __forceinline__ float gelu_tanh(float x) { const float u = 0.7978845608028654f * (x + 0.044715f * x * x * x); return x / (1.f + __expf(-2.f * u)); }
; __device__ __forceinline__ void phase_conv(PRef p, int layer, int nseg) {
;     ...
;                 for (int ky = 0; ky < 3; ++ky)
; #pragma unroll
;                     for (int kx = 0; kx < 3; ++kx) { const u32x4 gq = gc[ky][xi + kx]; const int k = ky * 3 + kx;
;                         acc[0] += w[k][0] * bflo(gq.x); acc[1] += w[k][1] * bfhi(gq.x); acc[2] += w[k][2] * bflo(gq.y); acc[3] += w[k][3] * bfhi(gq.y);
;                         acc[4] += w[k][4] * bflo(gq.z); acc[5] += w[k][5] * bfhi(gq.z); acc[6] += w[k][6] * bflo(gq.w); acc[7] += w[k][7] * bfhi(gq.w); }
;                 u32x4 o;
;                 o.x = cvt_pk_bf16(gelu_tanh(acc[0]) * bflo(vv[xi].x), gelu_tanh(acc[1]) * bfhi(vv[xi].x));
;                 o.y = cvt_pk_bf16(gelu_tanh(acc[2]) * bflo(vv[xi].y), gelu_tanh(acc[3]) * bfhi(vv[xi].y));
;                 o.z = cvt_pk_bf16(gelu_tanh(acc[4]) * bflo(vv[xi].z), gelu_tanh(acc[5]) * bfhi(vv[xi].z));
;                 o.w = cvt_pk_bf16(gelu_tanh(acc[6]) * bflo(vv[xi].w), gelu_tanh(acc[7]) * bfhi(vv[xi].w));
;                 *(u32x4*)((bf16_t*)lp[1] + (size_t)(xb + xi) * NUP + NFF) = o; } }
	v_lshlrev_b32_e32 v56, 16, v52
	v_mov_b32_e32 v57, v73
	v_pk_mul_f32 v[56:57], v[170:171], v[56:57]
	v_lshlrev_b32_e32 v58, 16, v53
	v_and_b32_e32 v66, 0xffff0000, v53
	v_add_f32_e32 v53, v69, v56
	v_add_f32_e32 v89, v53, v57
	v_pk_mov_b32 v[56:57], v[74:75], v[74:75] op_sel:[1,0]
	v_and_b32_e32 v52, 0xffff0000, v52
	v_mov_b32_e32 v53, v57
	v_pk_mul_f32 v[52:53], v[28:29], v[52:53]
	v_lshlrev_b32_e32 v68, 16, v54
	v_add_f32_e32 v52, v64, v52
	v_add_f32_e32 v74, v52, v53
	v_pk_mov_b32 v[52:53], v[76:77], v[76:77] op_sel:[1,0]
	v_and_b32_e32 v54, 0xffff0000, v54
	v_mov_b32_e32 v59, v53
	v_pk_mul_f32 v[58:59], v[162:163], v[58:59]
	v_lshlrev_b32_e32 v70, 16, v55
	v_add_f32_e32 v53, v182, v58
	v_add_f32_e32 v75, v53, v59
	v_pk_mov_b32 v[58:59], v[78:79], v[78:79] op_sel:[1,0]
	v_and_b32_e32 v82, 0xffff0000, v55
	v_mov_b32_e32 v67, v59
	v_lshlrev_b32_e32 v73, 16, v60
	v_fma_f32 v53, v30, v66, v120
	v_fma_f32 v76, v31, v67, v53
	v_pk_mov_b32 v[64:65], v[80:81], v[80:81] op_sel:[1,0]
	v_and_b32_e32 v57, 0xffff0000, v60
	v_mov_b32_e32 v69, v65
	v_pk_mul_f32 v[56:57], v[24:25], v[56:57]
	v_fma_f32 v53, v154, v68, v116
	v_fma_f32 v77, v155, v69, v53
	v_pk_mov_b32 v[66:67], v[84:85], v[84:85] op_sel:[1,0]
	v_and_b32_e32 v59, 0xffff0000, v61
	v_mov_b32_e32 v55, v67
	v_pk_mul_f32 v[54:55], v[4:5], v[54:55]
	v_lshlrev_b32_e32 v65, 16, v62
	v_add_f32_e32 v53, v112, v54
	v_add_f32_e32 v78, v53, v55
	v_pk_mov_b32 v[54:55], v[104:105], v[104:105] op_sel:[1,0]
	v_and_b32_e32 v67, 0xffff0000, v62
	v_mov_b32_e32 v71, v55
	v_lshlrev_b32_e32 v55, 16, v63
	v_fma_f32 v53, v146, v70, v96
	v_fma_f32 v79, v147, v71, v53
	v_pk_mov_b32 v[68:69], v[86:87], v[86:87] op_sel:[1,0]
	s_xor_b64 s[44:45], s[44:45], -1
	v_mov_b32_e32 v83, v69
	v_and_b32_e32 v69, 0xffff0000, v63
	v_fma_f32 v53, v6, v82, v88
	v_fma_f32 v80, v7, v83, v53
	v_pk_mul_f32 v[70:71], v[168:169], v[72:73]
	s_nop 0
	v_fma_f32 v53, v168, v72, v89
	v_fma_f32 v70, v169, v73, v53
	v_add_f32_e32 v53, v74, v56
	v_add_f32_e32 v56, v53, v57
	v_lshlrev_b32_e32 v53, 16, v61
	v_pk_mul_f32 v[52:53], v[160:161], v[52:53]
	s_nop 0
	v_add_f32_e32 v52, v75, v52
	v_add_f32_e32 v57, v52, v53
	s_nop 0
	v_fma_f32 v52, v26, v58, v76
	v_fma_f32 v58, v27, v59, v52
	s_nop 0
	v_fma_f32 v52, v152, v64, v77
	v_fma_f32 v59, v153, v65, v52
	s_nop 0
	v_fma_f32 v52, v0, v66, v78
	v_fma_f32 v60, v1, v67, v52
	v_pk_mul_f32 v[52:53], v[144:145], v[54:55]
	v_mul_f32_e32 v54, 0x3d372713, v70
	v_mul_f32_e32 v54, v70, v54
	v_fma_f32 v54, v70, v54, v70
	v_mul_f32_e32 v54, 0x3f4c422a, v54
	v_mul_f32_e32 v54, -2.0, v54
	v_mul_f32_e32 v54, 0x3fb8aa3b, v54
	v_exp_f32_e32 v54, v54
	v_add_f32_e32 v52, v79, v52
	v_add_f32_e32 v55, v52, v53
	v_add_f32_e32 v54, 1.0, v54
	v_rcp_f32_e32 v62, v54
	v_fma_f32 v52, v2, v68, v80
	v_fma_f32 v52, v3, v69, v52
	v_mul_f32_e32 v64, 0x3d372713, v56
	v_mul_f32_e32 v64, v56, v64
	v_fma_f32 v64, v56, v64, v56
	v_mul_f32_e32 v64, 0x3f4c422a, v64
	v_mul_f32_e32 v64, -2.0, v64
	v_mul_f32_e32 v64, 0x3fb8aa3b, v64
	v_exp_f32_e32 v64, v64
	v_mul_f32_e32 v53, v70, v62
	v_add_f32_e32 v61, 1.0, v64
	v_rcp_f32_e32 v63, v61
	s_waitcnt vmcnt(3)
	v_lshlrev_b32_e32 v54, 16, v48
	v_mul_f32_e32 v53, v53, v54
	v_and_b32_e32 v48, 0xffff0000, v48
	v_mul_f32_e32 v62, 0x3d372713, v57
	v_mul_f32_e32 v62, v57, v62
	v_fma_f32 v62, v57, v62, v57
	v_mul_f32_e32 v62, 0x3f4c422a, v62
	v_mul_f32_e32 v62, -2.0, v62
	v_mul_f32_e32 v62, 0x3fb8aa3b, v62
	v_exp_f32_e32 v62, v62
	v_mul_f32_e32 v54, v56, v63
	v_mul_f32_e32 v48, v54, v48
	v_add_f32_e32 v56, 1.0, v62
	v_rcp_f32_e32 v62, v56
	v_cvt_pk_bf16_f32 v48, v53, v48
	s_nop 0
	v_mul_f32_e32 v63, 0x3d372713, v58
	v_mul_f32_e32 v63, v58, v63
	v_fma_f32 v63, v58, v63, v58
	v_mul_f32_e32 v63, 0x3f4c422a, v63
	v_mul_f32_e32 v63, -2.0, v63
	v_mul_f32_e32 v63, 0x3fb8aa3b, v63
	v_exp_f32_e32 v63, v63
	v_mul_f32_e32 v53, v57, v62
	v_add_f32_e32 v54, 1.0, v63
	v_rcp_f32_e32 v62, v54
	v_lshlrev_b32_e32 v56, 16, v49
	v_mul_f32_e32 v53, v53, v56
	v_and_b32_e32 v49, 0xffff0000, v49
	v_mul_f32_e32 v61, 0x3d372713, v59
	v_mul_f32_e32 v61, v59, v61
	v_fma_f32 v61, v59, v61, v59
	v_mul_f32_e32 v61, 0x3f4c422a, v61
	v_mul_f32_e32 v61, -2.0, v61
	v_mul_f32_e32 v61, 0x3fb8aa3b, v61
	v_exp_f32_e32 v61, v61
	v_mul_f32_e32 v54, v58, v62
	v_mul_f32_e32 v49, v54, v49
	v_add_f32_e32 v56, 1.0, v61
	v_rcp_f32_e32 v58, v56
	v_cvt_pk_bf16_f32 v49, v53, v49
	s_nop 0
	v_mul_f32_e32 v61, 0x3d372713, v60
	v_mul_f32_e32 v61, v60, v61
	v_fma_f32 v61, v60, v61, v60
	v_mul_f32_e32 v61, 0x3f4c422a, v61
	v_mul_f32_e32 v61, -2.0, v61
	v_mul_f32_e32 v61, 0x3fb8aa3b, v61
	v_exp_f32_e32 v61, v61
	v_mul_f32_e32 v53, v59, v58
	v_add_f32_e32 v54, 1.0, v61
	v_rcp_f32_e32 v58, v54
	v_lshlrev_b32_e32 v56, 16, v50
	v_mul_f32_e32 v53, v53, v56
	v_and_b32_e32 v50, 0xffff0000, v50
	v_mul_f32_e32 v57, 0x3d372713, v55
	v_mul_f32_e32 v57, v55, v57
	v_fma_f32 v57, v55, v57, v55
	v_mul_f32_e32 v57, 0x3f4c422a, v57
	v_mul_f32_e32 v57, -2.0, v57
	v_mul_f32_e32 v57, 0x3fb8aa3b, v57
	v_exp_f32_e32 v57, v57
	v_mul_f32_e32 v54, v60, v58
	v_mul_f32_e32 v50, v54, v50
	v_add_f32_e32 v56, 1.0, v57
	v_rcp_f32_e32 v58, v56
	v_cvt_pk_bf16_f32 v50, v53, v50
	s_nop 0
	v_mul_f32_e32 v59, 0x3d372713, v52
	v_mul_f32_e32 v59, v52, v59
	v_fma_f32 v59, v52, v59, v52
	v_mul_f32_e32 v59, 0x3f4c422a, v59
	v_mul_f32_e32 v59, -2.0, v59
	v_mul_f32_e32 v59, 0x3fb8aa3b, v59
	v_exp_f32_e32 v59, v59
	v_mul_f32_e32 v53, v55, v58
	v_add_f32_e32 v54, 1.0, v59
	v_rcp_f32_e32 v58, v54
	v_lshlrev_b32_e32 v55, 16, v51
	v_mul_f32_e32 v53, v53, v55
	v_and_b32_e32 v51, 0xffff0000, v51
	v_mul_f32_e32 v52, v52, v58
	v_mul_f32_e32 v51, v52, v51
	s_mov_b32 s8, 4
	s_andn2_b64 vcc, exec, s[44:45]
	s_mov_b64 s[44:45], 0
	v_cvt_pk_bf16_f32 v51, v53, v51
	global_store_dwordx4 v[176:177], v[48:51], off offset:3072
	s_cbranch_vccz .LBB0_1040
